# full-cache-line DMA layout combined with the chained MFMA order
# speedup vs baseline: 1.0200x; 1.0087x over previous
.LBB0_74:
	s_ashr_i32 s27, s26, 31
	s_lshl_b64 s[28:29], s[26:27], 19
	s_add_u32 s28, s3, s28
	s_addc_u32 s29, s35, s29
	s_and_b64 s[30:31], s[4:5], exec
	s_cselect_b32 s27, s29, s49
	s_cselect_b32 s68, s28, s48
	s_ashr_i32 s23, s22, 31
	s_lshl_b64 s[30:31], s[22:23], 19
	s_add_u32 s30, s50, s30
	s_addc_u32 s31, s51, s31
	s_and_b64 s[70:71], s[4:5], exec
	s_cselect_b32 s69, s31, s47
	s_cselect_b32 s70, s30, s46
	s_lshl_b32 s23, s44, 8
	v_add_u32_e32 v0, s23, v148
	s_add_u32 s71, s46, 0x100
	v_ashrrev_i32_e32 v1, 31, v0
	s_addc_u32 s74, s47, 0
	v_lshl_add_u64 v[144:145], v[0:1], 4, s[12:13]
	s_add_u32 s44, s48, 0x40080
	s_addc_u32 s45, s49, 0
	s_mov_b32 s75, -2
	s_mov_b64 s[46:47], 0
	s_cmp_eq_u32 s59, 1
	s_cbranch_scc1 .Lfa_0
	v_add_u32_e32 v153, s64, v147
	ds_read_b128 v[160:163], v153
	v_xor_b32_e32 v253, 64, v153
	ds_read_b128 v[164:167], v253
	ds_read_b128 v[168:171], v153 offset:2048
	ds_read_b128 v[172:175], v253 offset:2048
	v_add_u32_e32 v153, s65, v147
	ds_read_b128 v[176:179], v153
	v_xor_b32_e32 v253, 64, v153
	ds_read_b128 v[180:183], v253
	ds_read_b128 v[186:189], v153 offset:2048
	ds_read_b128 v[190:193], v253 offset:2048
	s_add_u32 s48, s44, 0xfffc0080
	s_addc_u32 s49, s45, -1
	s_and_b64 s[46:47], s[46:47], exec
	s_cselect_b32 s49, s27, s49
	s_cselect_b32 s48, s68, s48
	s_cselect_b32 s47, s69, s74
	s_cselect_b32 s46, s70, s71
	v_lshl_add_u64 v[154:155], s[44:45], 0, v[138:139]
	s_add_i32 m0, s55, 0xc000
	ds_read_b128 v[194:197], v150
	v_xor_b32_e32 v253, 64, v150
	ds_read_b128 v[198:201], v253
	ds_read_b128 v[202:205], v150 offset:2048
	ds_read_b128 v[206:209], v253 offset:2048
	ds_read_b128 v[210:213], v150 offset:4096
	ds_read_b128 v[214:217], v253 offset:4096
	ds_read_b128 v[218:221], v150 offset:6144
	ds_read_b128 v[222:225], v253 offset:6144
	global_load_lds_dwordx4 v[154:155], off
	v_lshl_add_u64 v[154:155], s[44:45], 0, v[136:137]
	s_add_i32 m0, s55, 0xe000
	s_nop 0
	global_load_lds_dwordx4 v[154:155], off
	s_waitcnt vmcnt(16)
	s_waitcnt lgkmcnt(0)
	s_barrier
	s_setprio 1
	s_waitcnt lgkmcnt(0)
	v_mfma_f32_16x16x32_bf16 v[124:127], v[160:163], v[194:197], 0
	v_mfma_f32_16x16x32_bf16 v[116:119], v[168:171], v[194:197], 0
	v_mfma_f32_16x16x32_bf16 v[108:111], v[160:163], v[202:205], 0
	v_mfma_f32_16x16x32_bf16 v[100:103], v[168:171], v[202:205], 0
	v_mfma_f32_16x16x32_bf16 v[92:95], v[160:163], v[210:213], 0
	v_mfma_f32_16x16x32_bf16 v[84:87], v[168:171], v[210:213], 0
	v_mfma_f32_16x16x32_bf16 v[76:79], v[160:163], v[218:221], 0
	v_mfma_f32_16x16x32_bf16 v[68:71], v[168:171], v[218:221], 0
	v_mfma_f32_16x16x32_bf16 v[124:127], v[164:167], v[198:201], v[124:127]
	v_mfma_f32_16x16x32_bf16 v[116:119], v[172:175], v[198:201], v[116:119]
	v_mfma_f32_16x16x32_bf16 v[108:111], v[164:167], v[206:209], v[108:111]
	v_mfma_f32_16x16x32_bf16 v[100:103], v[172:175], v[206:209], v[100:103]
	v_mfma_f32_16x16x32_bf16 v[92:95], v[164:167], v[214:217], v[92:95]
	v_mfma_f32_16x16x32_bf16 v[84:87], v[172:175], v[214:217], v[84:87]
	v_mfma_f32_16x16x32_bf16 v[76:79], v[164:167], v[222:225], v[76:79]
	v_mfma_f32_16x16x32_bf16 v[68:71], v[172:175], v[222:225], v[68:71]
	s_setprio 0
	s_setprio 1
	v_mfma_f32_16x16x32_bf16 v[120:123], v[176:179], v[194:197], 0
	v_mfma_f32_16x16x32_bf16 v[112:115], v[186:189], v[194:197], 0
	v_mfma_f32_16x16x32_bf16 v[104:107], v[176:179], v[202:205], 0
	v_mfma_f32_16x16x32_bf16 v[96:99], v[186:189], v[202:205], 0
	v_mfma_f32_16x16x32_bf16 v[88:91], v[176:179], v[210:213], 0
	v_mfma_f32_16x16x32_bf16 v[80:83], v[186:189], v[210:213], 0
	v_mfma_f32_16x16x32_bf16 v[72:75], v[176:179], v[218:221], 0
	v_mfma_f32_16x16x32_bf16 v[64:67], v[186:189], v[218:221], 0
	v_mfma_f32_16x16x32_bf16 v[120:123], v[180:183], v[198:201], v[120:123]
	v_mfma_f32_16x16x32_bf16 v[112:115], v[190:193], v[198:201], v[112:115]
	v_mfma_f32_16x16x32_bf16 v[104:107], v[180:183], v[206:209], v[104:107]
	v_mfma_f32_16x16x32_bf16 v[96:99], v[190:193], v[206:209], v[96:99]
	v_mfma_f32_16x16x32_bf16 v[88:91], v[180:183], v[214:217], v[88:91]
	v_mfma_f32_16x16x32_bf16 v[80:83], v[190:193], v[214:217], v[80:83]
	v_mfma_f32_16x16x32_bf16 v[72:75], v[180:183], v[222:225], v[72:75]
	v_mfma_f32_16x16x32_bf16 v[64:67], v[190:193], v[222:225], v[64:67]
	s_setprio 0
	s_barrier
	s_add_i32 s76, s64, s52
	v_lshl_add_u64 v[154:155], s[46:47], 0, v[132:133]
	s_mov_b32 m0, s76
	ds_read_b128 v[194:197], v150 offset:16384
	v_xor_b32_e32 v253, 64, v150
	ds_read_b128 v[198:201], v253 offset:16384
	ds_read_b128 v[202:205], v150 offset:18432
	ds_read_b128 v[206:209], v253 offset:18432
	ds_read_b128 v[210:213], v150 offset:20480
	ds_read_b128 v[214:217], v253 offset:20480
	ds_read_b128 v[218:221], v150 offset:22528
	ds_read_b128 v[222:225], v253 offset:22528
	global_load_lds_dwordx4 v[154:155], off
	s_add_i32 m0, s76, 0x2000
	s_add_u32 s76, s46, 0x40000
	v_lshl_add_u64 v[226:227], s[46:47], 0, v[128:129]
	s_addc_u32 s77, s47, 0
	s_add_i32 s78, s65, s52
	global_load_lds_dwordx4 v[226:227], off
	v_lshl_add_u64 v[228:229], s[76:77], 0, v[132:133]
	s_mov_b32 m0, s78
	v_lshl_add_u64 v[230:231], s[48:49], 0, v[130:131]
	global_load_lds_dwordx4 v[228:229], off
	v_lshl_add_u64 v[228:229], s[76:77], 0, v[128:129]
	s_add_i32 m0, s78, 0x2000
	s_nop 0
	global_load_lds_dwordx4 v[228:229], off
	v_lshl_add_u64 v[228:229], s[48:49], 0, v[134:135]
	s_mov_b32 m0, s55
	s_nop 0
	global_load_lds_dwordx4 v[228:229], off
	s_mov_b32 m0, s56
	s_nop 0
	global_load_lds_dwordx4 v[230:231], off
	s_waitcnt vmcnt(16)
	s_waitcnt lgkmcnt(0)
	s_barrier
	s_setprio 1
	s_waitcnt lgkmcnt(0)
	v_mfma_f32_16x16x32_bf16 v[60:63], v[160:163], v[194:197], 0
	v_mfma_f32_16x16x32_bf16 v[52:55], v[168:171], v[194:197], 0
	v_mfma_f32_16x16x32_bf16 v[44:47], v[160:163], v[202:205], 0
	v_mfma_f32_16x16x32_bf16 v[36:39], v[168:171], v[202:205], 0
	v_mfma_f32_16x16x32_bf16 v[28:31], v[160:163], v[210:213], 0
	v_mfma_f32_16x16x32_bf16 v[20:23], v[168:171], v[210:213], 0
	v_mfma_f32_16x16x32_bf16 v[12:15], v[160:163], v[218:221], 0
	v_mfma_f32_16x16x32_bf16 v[4:7], v[168:171], v[218:221], 0
	v_mfma_f32_16x16x32_bf16 v[60:63], v[164:167], v[198:201], v[60:63]
	v_mfma_f32_16x16x32_bf16 v[52:55], v[172:175], v[198:201], v[52:55]
	v_mfma_f32_16x16x32_bf16 v[44:47], v[164:167], v[206:209], v[44:47]
	v_mfma_f32_16x16x32_bf16 v[36:39], v[172:175], v[206:209], v[36:39]
	v_mfma_f32_16x16x32_bf16 v[28:31], v[164:167], v[214:217], v[28:31]
	v_mfma_f32_16x16x32_bf16 v[20:23], v[172:175], v[214:217], v[20:23]
	v_mfma_f32_16x16x32_bf16 v[12:15], v[164:167], v[222:225], v[12:15]
	v_mfma_f32_16x16x32_bf16 v[4:7], v[172:175], v[222:225], v[4:7]
	s_setprio 0
	s_setprio 1
	v_mfma_f32_16x16x32_bf16 v[56:59], v[176:179], v[194:197], 0
	v_mfma_f32_16x16x32_bf16 v[48:51], v[186:189], v[194:197], 0
	v_mfma_f32_16x16x32_bf16 v[40:43], v[176:179], v[202:205], 0
	v_mfma_f32_16x16x32_bf16 v[32:35], v[186:189], v[202:205], 0
	v_mfma_f32_16x16x32_bf16 v[24:27], v[176:179], v[210:213], 0
	v_mfma_f32_16x16x32_bf16 v[16:19], v[186:189], v[210:213], 0
	v_mfma_f32_16x16x32_bf16 v[8:11], v[176:179], v[218:221], 0
	v_mfma_f32_16x16x32_bf16 v[0:3], v[186:189], v[218:221], 0
	v_mfma_f32_16x16x32_bf16 v[56:59], v[180:183], v[198:201], v[56:59]
	v_mfma_f32_16x16x32_bf16 v[48:51], v[190:193], v[198:201], v[48:51]
	v_mfma_f32_16x16x32_bf16 v[40:43], v[180:183], v[206:209], v[40:43]
	v_mfma_f32_16x16x32_bf16 v[32:35], v[190:193], v[206:209], v[32:35]
	v_mfma_f32_16x16x32_bf16 v[24:27], v[180:183], v[214:217], v[24:27]
	v_mfma_f32_16x16x32_bf16 v[16:19], v[190:193], v[214:217], v[16:19]
	v_mfma_f32_16x16x32_bf16 v[8:11], v[180:183], v[222:225], v[8:11]
	v_mfma_f32_16x16x32_bf16 v[0:3], v[190:193], v[222:225], v[0:3]
	s_setprio 0
	s_barrier
	s_add_i32 s76, 0, 0x18000
	v_add_u32_e32 v153, s76, v147
	s_add_i32 s77, 0, 0x1c000
	ds_read_b128 v[160:163], v153
	v_xor_b32_e32 v253, 64, v153
	ds_read_b128 v[164:167], v253
	ds_read_b128 v[168:171], v153 offset:2048
	ds_read_b128 v[172:175], v253 offset:2048
	v_add_u32_e32 v153, s77, v147
	ds_read_b128 v[176:179], v153
	v_xor_b32_e32 v253, 64, v153
	ds_read_b128 v[180:183], v253
	ds_read_b128 v[186:189], v153 offset:2048
	ds_read_b128 v[190:193], v253 offset:2048
	s_add_u32 s48, s48, 0x40000
	s_addc_u32 s49, s49, 0
	s_mov_b32 m0, s57
	v_lshl_add_u64 v[232:233], s[48:49], 0, v[134:135]
	ds_read_b128 v[194:197], v150 offset:32768
	v_xor_b32_e32 v253, 64, v150
	ds_read_b128 v[198:201], v253 offset:32768
	ds_read_b128 v[202:205], v150 offset:34816
	ds_read_b128 v[206:209], v253 offset:34816
	ds_read_b128 v[210:213], v150 offset:36864
	ds_read_b128 v[214:217], v253 offset:36864
	ds_read_b128 v[218:221], v150 offset:38912
	ds_read_b128 v[222:225], v253 offset:38912
	global_load_lds_dwordx4 v[232:233], off
	v_lshl_add_u64 v[232:233], s[48:49], 0, v[130:131]
	s_mov_b32 m0, s58
	s_nop 0
	global_load_lds_dwordx4 v[232:233], off
	s_waitcnt vmcnt(8)
	s_waitcnt lgkmcnt(0)
	s_barrier
	s_setprio 1
	s_waitcnt lgkmcnt(0)
	v_mfma_f32_16x16x32_bf16 v[124:127], v[160:163], v[194:197], v[124:127]
	v_mfma_f32_16x16x32_bf16 v[124:127], v[164:167], v[198:201], v[124:127]
	v_mfma_f32_16x16x32_bf16 v[116:119], v[172:175], v[198:201], v[116:119]
	v_mfma_f32_16x16x32_bf16 v[116:119], v[168:171], v[194:197], v[116:119]
	v_mfma_f32_16x16x32_bf16 v[100:103], v[168:171], v[202:205], v[100:103]
	v_mfma_f32_16x16x32_bf16 v[100:103], v[172:175], v[206:209], v[100:103]
	v_mfma_f32_16x16x32_bf16 v[108:111], v[164:167], v[206:209], v[108:111]
	v_mfma_f32_16x16x32_bf16 v[108:111], v[160:163], v[202:205], v[108:111]
	v_mfma_f32_16x16x32_bf16 v[92:95], v[160:163], v[210:213], v[92:95]
	v_mfma_f32_16x16x32_bf16 v[92:95], v[164:167], v[214:217], v[92:95]
	v_mfma_f32_16x16x32_bf16 v[84:87], v[172:175], v[214:217], v[84:87]
	v_mfma_f32_16x16x32_bf16 v[84:87], v[168:171], v[210:213], v[84:87]
	v_mfma_f32_16x16x32_bf16 v[68:71], v[168:171], v[218:221], v[68:71]
	v_mfma_f32_16x16x32_bf16 v[68:71], v[172:175], v[222:225], v[68:71]
	v_mfma_f32_16x16x32_bf16 v[76:79], v[164:167], v[222:225], v[76:79]
	v_mfma_f32_16x16x32_bf16 v[76:79], v[160:163], v[218:221], v[76:79]
	s_setprio 0
	s_setprio 1
	v_mfma_f32_16x16x32_bf16 v[120:123], v[176:179], v[194:197], v[120:123]
	v_mfma_f32_16x16x32_bf16 v[120:123], v[180:183], v[198:201], v[120:123]
	v_mfma_f32_16x16x32_bf16 v[112:115], v[190:193], v[198:201], v[112:115]
	v_mfma_f32_16x16x32_bf16 v[112:115], v[186:189], v[194:197], v[112:115]
	v_mfma_f32_16x16x32_bf16 v[96:99], v[186:189], v[202:205], v[96:99]
	v_mfma_f32_16x16x32_bf16 v[96:99], v[190:193], v[206:209], v[96:99]
	v_mfma_f32_16x16x32_bf16 v[104:107], v[180:183], v[206:209], v[104:107]
	v_mfma_f32_16x16x32_bf16 v[104:107], v[176:179], v[202:205], v[104:107]
	v_mfma_f32_16x16x32_bf16 v[88:91], v[176:179], v[210:213], v[88:91]
	v_mfma_f32_16x16x32_bf16 v[88:91], v[180:183], v[214:217], v[88:91]
	v_mfma_f32_16x16x32_bf16 v[80:83], v[190:193], v[214:217], v[80:83]
	v_mfma_f32_16x16x32_bf16 v[80:83], v[186:189], v[210:213], v[80:83]
	v_mfma_f32_16x16x32_bf16 v[64:67], v[186:189], v[218:221], v[64:67]
	v_mfma_f32_16x16x32_bf16 v[64:67], v[190:193], v[222:225], v[64:67]
	v_mfma_f32_16x16x32_bf16 v[72:75], v[180:183], v[222:225], v[72:75]
	v_mfma_f32_16x16x32_bf16 v[72:75], v[176:179], v[218:221], v[72:75]
	s_setprio 0
	s_barrier
	s_add_i32 s48, s76, s52
	v_lshl_add_u64 v[154:155], v[154:155], 0, s[14:15]
	s_mov_b32 m0, s48
	ds_read_b128 v[194:197], v150 offset:49152
	v_xor_b32_e32 v253, 64, v150
	ds_read_b128 v[198:201], v253 offset:49152
	ds_read_b128 v[202:205], v150 offset:51200
	ds_read_b128 v[206:209], v253 offset:51200
	ds_read_b128 v[210:213], v150 offset:53248
	ds_read_b128 v[214:217], v253 offset:53248
	ds_read_b128 v[218:221], v150 offset:55296
	ds_read_b128 v[222:225], v253 offset:55296
	global_load_lds_dwordx4 v[154:155], off
	s_add_i32 m0, s48, 0x2000
	s_add_u32 s46, s46, 0x40080
	v_lshl_add_u64 v[154:155], v[226:227], 0, s[14:15]
	s_addc_u32 s47, s47, 0
	s_add_i32 s48, s77, s52
	global_load_lds_dwordx4 v[154:155], off
	v_lshl_add_u64 v[154:155], s[46:47], 0, v[132:133]
	s_mov_b32 m0, s48
	s_nop 0
	global_load_lds_dwordx4 v[154:155], off
	v_lshl_add_u64 v[154:155], s[46:47], 0, v[128:129]
	s_add_i32 m0, s48, 0x2000
	s_nop 0
	global_load_lds_dwordx4 v[154:155], off
	v_lshl_add_u64 v[154:155], v[228:229], 0, s[14:15]
	s_mov_b32 m0, s60
	s_nop 0
	global_load_lds_dwordx4 v[154:155], off
	v_lshl_add_u64 v[154:155], v[230:231], 0, s[14:15]
	s_mov_b32 m0, s61
	s_nop 0
	global_load_lds_dwordx4 v[154:155], off
	s_waitcnt vmcnt(8)
	s_waitcnt lgkmcnt(0)
	s_barrier
	s_setprio 1
	s_waitcnt lgkmcnt(0)
	v_mfma_f32_16x16x32_bf16 v[60:63], v[160:163], v[194:197], v[60:63]
	v_mfma_f32_16x16x32_bf16 v[60:63], v[164:167], v[198:201], v[60:63]
	v_mfma_f32_16x16x32_bf16 v[52:55], v[172:175], v[198:201], v[52:55]
	v_mfma_f32_16x16x32_bf16 v[52:55], v[168:171], v[194:197], v[52:55]
	v_mfma_f32_16x16x32_bf16 v[36:39], v[168:171], v[202:205], v[36:39]
	v_mfma_f32_16x16x32_bf16 v[36:39], v[172:175], v[206:209], v[36:39]
	v_mfma_f32_16x16x32_bf16 v[44:47], v[164:167], v[206:209], v[44:47]
	v_mfma_f32_16x16x32_bf16 v[44:47], v[160:163], v[202:205], v[44:47]
	v_mfma_f32_16x16x32_bf16 v[28:31], v[160:163], v[210:213], v[28:31]
	v_mfma_f32_16x16x32_bf16 v[28:31], v[164:167], v[214:217], v[28:31]
	v_mfma_f32_16x16x32_bf16 v[20:23], v[172:175], v[214:217], v[20:23]
	v_mfma_f32_16x16x32_bf16 v[20:23], v[168:171], v[210:213], v[20:23]
	v_mfma_f32_16x16x32_bf16 v[4:7], v[168:171], v[218:221], v[4:7]
	v_mfma_f32_16x16x32_bf16 v[4:7], v[172:175], v[222:225], v[4:7]
	v_mfma_f32_16x16x32_bf16 v[12:15], v[164:167], v[222:225], v[12:15]
	v_mfma_f32_16x16x32_bf16 v[12:15], v[160:163], v[218:221], v[12:15]
	s_setprio 0
	s_setprio 1
	v_mfma_f32_16x16x32_bf16 v[56:59], v[176:179], v[194:197], v[56:59]
	v_mfma_f32_16x16x32_bf16 v[56:59], v[180:183], v[198:201], v[56:59]
	v_mfma_f32_16x16x32_bf16 v[48:51], v[190:193], v[198:201], v[48:51]
	v_mfma_f32_16x16x32_bf16 v[48:51], v[186:189], v[194:197], v[48:51]
	v_mfma_f32_16x16x32_bf16 v[32:35], v[186:189], v[202:205], v[32:35]
	v_mfma_f32_16x16x32_bf16 v[32:35], v[190:193], v[206:209], v[32:35]
	v_mfma_f32_16x16x32_bf16 v[40:43], v[180:183], v[206:209], v[40:43]
	v_mfma_f32_16x16x32_bf16 v[40:43], v[176:179], v[202:205], v[40:43]
	v_mfma_f32_16x16x32_bf16 v[24:27], v[176:179], v[210:213], v[24:27]
	v_mfma_f32_16x16x32_bf16 v[24:27], v[180:183], v[214:217], v[24:27]
	v_mfma_f32_16x16x32_bf16 v[16:19], v[190:193], v[214:217], v[16:19]
	v_mfma_f32_16x16x32_bf16 v[16:19], v[186:189], v[210:213], v[16:19]
	v_mfma_f32_16x16x32_bf16 v[0:3], v[186:189], v[218:221], v[0:3]
	v_mfma_f32_16x16x32_bf16 v[0:3], v[190:193], v[222:225], v[0:3]
	v_mfma_f32_16x16x32_bf16 v[8:11], v[180:183], v[222:225], v[8:11]
	v_mfma_f32_16x16x32_bf16 v[8:11], v[176:179], v[218:221], v[8:11]
	s_setprio 0
	s_barrier
	s_add_i32 s75, s75, 2
	s_add_u32 s71, s71, 0x100
	s_addc_u32 s74, s74, 0
	s_add_u32 s44, s44, 0x100
	s_addc_u32 s45, s45, 0
	s_branch .LBB0_76
.Lfa_0:
	v_add_u32_e32 v153, s64, v147
	ds_read_b128 v[160:163], v153
	v_xor_b32_e32 v253, 64, v153
	ds_read_b128 v[164:167], v253
	ds_read_b128 v[168:171], v153 offset:2048
	ds_read_b128 v[172:175], v253 offset:2048
	v_add_u32_e32 v153, s65, v147
	ds_read_b128 v[176:179], v153
	v_xor_b32_e32 v253, 64, v153
	ds_read_b128 v[180:183], v253
	ds_read_b128 v[186:189], v153 offset:2048
	ds_read_b128 v[190:193], v253 offset:2048
	s_add_u32 s48, s44, 0xfffc0080
	s_addc_u32 s49, s45, -1
	s_and_b64 s[46:47], s[46:47], exec
	s_cselect_b32 s49, s27, s49
	s_cselect_b32 s48, s68, s48
	s_cselect_b32 s47, s69, s74
	s_cselect_b32 s46, s70, s71
	v_lshl_add_u64 v[154:155], s[44:45], 0, v[138:139]
	s_add_i32 m0, s55, 0xc000
	ds_read_b128 v[194:197], v150
	v_xor_b32_e32 v253, 64, v150
	ds_read_b128 v[198:201], v253
	ds_read_b128 v[202:205], v150 offset:2048
	ds_read_b128 v[206:209], v253 offset:2048
	ds_read_b128 v[210:213], v150 offset:4096
	ds_read_b128 v[214:217], v253 offset:4096
	ds_read_b128 v[218:221], v150 offset:6144
	ds_read_b128 v[222:225], v253 offset:6144
	global_load_lds_dwordx4 v[154:155], off
	v_lshl_add_u64 v[154:155], s[44:45], 0, v[136:137]
	s_add_i32 m0, s55, 0xe000
	s_nop 0
	global_load_lds_dwordx4 v[154:155], off
	s_waitcnt vmcnt(8)
	s_waitcnt lgkmcnt(0)
	s_barrier
	s_setprio 1
	s_waitcnt lgkmcnt(0)
	v_mfma_f32_16x16x32_bf16 v[124:127], v[160:163], v[194:197], 0
	v_mfma_f32_16x16x32_bf16 v[116:119], v[168:171], v[194:197], 0
	v_mfma_f32_16x16x32_bf16 v[108:111], v[160:163], v[202:205], 0
	v_mfma_f32_16x16x32_bf16 v[100:103], v[168:171], v[202:205], 0
	v_mfma_f32_16x16x32_bf16 v[92:95], v[160:163], v[210:213], 0
	v_mfma_f32_16x16x32_bf16 v[84:87], v[168:171], v[210:213], 0
	v_mfma_f32_16x16x32_bf16 v[76:79], v[160:163], v[218:221], 0
	v_mfma_f32_16x16x32_bf16 v[68:71], v[168:171], v[218:221], 0
	v_mfma_f32_16x16x32_bf16 v[124:127], v[164:167], v[198:201], v[124:127]
	v_mfma_f32_16x16x32_bf16 v[116:119], v[172:175], v[198:201], v[116:119]
	v_mfma_f32_16x16x32_bf16 v[108:111], v[164:167], v[206:209], v[108:111]
	v_mfma_f32_16x16x32_bf16 v[100:103], v[172:175], v[206:209], v[100:103]
	v_mfma_f32_16x16x32_bf16 v[92:95], v[164:167], v[214:217], v[92:95]
	v_mfma_f32_16x16x32_bf16 v[84:87], v[172:175], v[214:217], v[84:87]
	v_mfma_f32_16x16x32_bf16 v[76:79], v[164:167], v[222:225], v[76:79]
	v_mfma_f32_16x16x32_bf16 v[68:71], v[172:175], v[222:225], v[68:71]
	s_setprio 0
	s_setprio 1
	v_mfma_f32_16x16x32_bf16 v[120:123], v[176:179], v[194:197], 0
	v_mfma_f32_16x16x32_bf16 v[112:115], v[186:189], v[194:197], 0
	v_mfma_f32_16x16x32_bf16 v[104:107], v[176:179], v[202:205], 0
	v_mfma_f32_16x16x32_bf16 v[96:99], v[186:189], v[202:205], 0
	v_mfma_f32_16x16x32_bf16 v[88:91], v[176:179], v[210:213], 0
	v_mfma_f32_16x16x32_bf16 v[80:83], v[186:189], v[210:213], 0
	v_mfma_f32_16x16x32_bf16 v[72:75], v[176:179], v[218:221], 0
	v_mfma_f32_16x16x32_bf16 v[64:67], v[186:189], v[218:221], 0
	v_mfma_f32_16x16x32_bf16 v[120:123], v[180:183], v[198:201], v[120:123]
	v_mfma_f32_16x16x32_bf16 v[112:115], v[190:193], v[198:201], v[112:115]
	v_mfma_f32_16x16x32_bf16 v[104:107], v[180:183], v[206:209], v[104:107]
	v_mfma_f32_16x16x32_bf16 v[96:99], v[190:193], v[206:209], v[96:99]
	v_mfma_f32_16x16x32_bf16 v[88:91], v[180:183], v[214:217], v[88:91]
	v_mfma_f32_16x16x32_bf16 v[80:83], v[190:193], v[214:217], v[80:83]
	v_mfma_f32_16x16x32_bf16 v[72:75], v[180:183], v[222:225], v[72:75]
	v_mfma_f32_16x16x32_bf16 v[64:67], v[190:193], v[222:225], v[64:67]
	s_setprio 0
	s_barrier
	s_add_i32 s76, s64, s52
	v_lshl_add_u64 v[154:155], s[46:47], 0, v[132:133]
	s_mov_b32 m0, s76
	ds_read_b128 v[194:197], v150 offset:16384
	v_xor_b32_e32 v253, 64, v150
	ds_read_b128 v[198:201], v253 offset:16384
	ds_read_b128 v[202:205], v150 offset:18432
	ds_read_b128 v[206:209], v253 offset:18432
	ds_read_b128 v[210:213], v150 offset:20480
	ds_read_b128 v[214:217], v253 offset:20480
	ds_read_b128 v[218:221], v150 offset:22528
	ds_read_b128 v[222:225], v253 offset:22528
	global_load_lds_dwordx4 v[154:155], off
	s_add_i32 m0, s76, 0x2000
	s_add_u32 s76, s46, 0x40000
	v_lshl_add_u64 v[226:227], s[46:47], 0, v[128:129]
	s_addc_u32 s77, s47, 0
	s_add_i32 s78, s65, s52
	global_load_lds_dwordx4 v[226:227], off
	v_lshl_add_u64 v[228:229], s[76:77], 0, v[132:133]
	s_mov_b32 m0, s78
	v_lshl_add_u64 v[230:231], s[48:49], 0, v[130:131]
	global_load_lds_dwordx4 v[228:229], off
	v_lshl_add_u64 v[228:229], s[76:77], 0, v[128:129]
	s_add_i32 m0, s78, 0x2000
	s_nop 0
	global_load_lds_dwordx4 v[228:229], off
	v_lshl_add_u64 v[228:229], s[48:49], 0, v[134:135]
	s_mov_b32 m0, s55
	s_nop 0
	global_load_lds_dwordx4 v[228:229], off
	s_mov_b32 m0, s56
	s_nop 0
	global_load_lds_dwordx4 v[230:231], off
	s_waitcnt vmcnt(8)
	s_waitcnt lgkmcnt(0)
	s_barrier
	s_setprio 1
	s_waitcnt lgkmcnt(0)
	v_mfma_f32_16x16x32_bf16 v[60:63], v[160:163], v[194:197], 0
	v_mfma_f32_16x16x32_bf16 v[52:55], v[168:171], v[194:197], 0
	v_mfma_f32_16x16x32_bf16 v[44:47], v[160:163], v[202:205], 0
	v_mfma_f32_16x16x32_bf16 v[36:39], v[168:171], v[202:205], 0
	v_mfma_f32_16x16x32_bf16 v[28:31], v[160:163], v[210:213], 0
	v_mfma_f32_16x16x32_bf16 v[20:23], v[168:171], v[210:213], 0
	v_mfma_f32_16x16x32_bf16 v[12:15], v[160:163], v[218:221], 0
	v_mfma_f32_16x16x32_bf16 v[4:7], v[168:171], v[218:221], 0
	v_mfma_f32_16x16x32_bf16 v[60:63], v[164:167], v[198:201], v[60:63]
	v_mfma_f32_16x16x32_bf16 v[52:55], v[172:175], v[198:201], v[52:55]
	v_mfma_f32_16x16x32_bf16 v[44:47], v[164:167], v[206:209], v[44:47]
	v_mfma_f32_16x16x32_bf16 v[36:39], v[172:175], v[206:209], v[36:39]
	v_mfma_f32_16x16x32_bf16 v[28:31], v[164:167], v[214:217], v[28:31]
	v_mfma_f32_16x16x32_bf16 v[20:23], v[172:175], v[214:217], v[20:23]
	v_mfma_f32_16x16x32_bf16 v[12:15], v[164:167], v[222:225], v[12:15]
	v_mfma_f32_16x16x32_bf16 v[4:7], v[172:175], v[222:225], v[4:7]
	s_setprio 0
	s_setprio 1
	v_mfma_f32_16x16x32_bf16 v[56:59], v[176:179], v[194:197], 0
	v_mfma_f32_16x16x32_bf16 v[48:51], v[186:189], v[194:197], 0
	v_mfma_f32_16x16x32_bf16 v[40:43], v[176:179], v[202:205], 0
	v_mfma_f32_16x16x32_bf16 v[32:35], v[186:189], v[202:205], 0
	v_mfma_f32_16x16x32_bf16 v[24:27], v[176:179], v[210:213], 0
	v_mfma_f32_16x16x32_bf16 v[16:19], v[186:189], v[210:213], 0
	v_mfma_f32_16x16x32_bf16 v[8:11], v[176:179], v[218:221], 0
	v_mfma_f32_16x16x32_bf16 v[0:3], v[186:189], v[218:221], 0
	v_mfma_f32_16x16x32_bf16 v[56:59], v[180:183], v[198:201], v[56:59]
	v_mfma_f32_16x16x32_bf16 v[48:51], v[190:193], v[198:201], v[48:51]
	v_mfma_f32_16x16x32_bf16 v[40:43], v[180:183], v[206:209], v[40:43]
	v_mfma_f32_16x16x32_bf16 v[32:35], v[190:193], v[206:209], v[32:35]
	v_mfma_f32_16x16x32_bf16 v[24:27], v[180:183], v[214:217], v[24:27]
	v_mfma_f32_16x16x32_bf16 v[16:19], v[190:193], v[214:217], v[16:19]
	v_mfma_f32_16x16x32_bf16 v[8:11], v[180:183], v[222:225], v[8:11]
	v_mfma_f32_16x16x32_bf16 v[0:3], v[190:193], v[222:225], v[0:3]
	s_setprio 0
	s_barrier
	s_add_i32 s76, 0, 0x18000
	v_add_u32_e32 v153, s76, v147
	s_add_i32 s77, 0, 0x1c000
	ds_read_b128 v[160:163], v153
	v_xor_b32_e32 v253, 64, v153
	ds_read_b128 v[164:167], v253
	ds_read_b128 v[168:171], v153 offset:2048
	ds_read_b128 v[172:175], v253 offset:2048
	v_add_u32_e32 v153, s77, v147
	ds_read_b128 v[176:179], v153
	v_xor_b32_e32 v253, 64, v153
	ds_read_b128 v[180:183], v253
	ds_read_b128 v[186:189], v153 offset:2048
	ds_read_b128 v[190:193], v253 offset:2048
	s_add_u32 s48, s48, 0x40000
	s_addc_u32 s49, s49, 0
	s_mov_b32 m0, s57
	v_lshl_add_u64 v[232:233], s[48:49], 0, v[134:135]
	ds_read_b128 v[194:197], v150 offset:32768
	v_xor_b32_e32 v253, 64, v150
	ds_read_b128 v[198:201], v253 offset:32768
	ds_read_b128 v[202:205], v150 offset:34816
	ds_read_b128 v[206:209], v253 offset:34816
	ds_read_b128 v[210:213], v150 offset:36864
	ds_read_b128 v[214:217], v253 offset:36864
	ds_read_b128 v[218:221], v150 offset:38912
	ds_read_b128 v[222:225], v253 offset:38912
	global_load_lds_dwordx4 v[232:233], off
	v_lshl_add_u64 v[232:233], s[48:49], 0, v[130:131]
	s_mov_b32 m0, s58
	s_nop 0
	global_load_lds_dwordx4 v[232:233], off
	s_waitcnt vmcnt(8)
	s_waitcnt lgkmcnt(0)
	s_barrier
	s_setprio 1
	s_waitcnt lgkmcnt(0)
	v_mfma_f32_16x16x32_bf16 v[124:127], v[160:163], v[194:197], v[124:127]
	v_mfma_f32_16x16x32_bf16 v[124:127], v[164:167], v[198:201], v[124:127]
	v_mfma_f32_16x16x32_bf16 v[116:119], v[172:175], v[198:201], v[116:119]
	v_mfma_f32_16x16x32_bf16 v[116:119], v[168:171], v[194:197], v[116:119]
	v_mfma_f32_16x16x32_bf16 v[100:103], v[168:171], v[202:205], v[100:103]
	v_mfma_f32_16x16x32_bf16 v[100:103], v[172:175], v[206:209], v[100:103]
	v_mfma_f32_16x16x32_bf16 v[108:111], v[164:167], v[206:209], v[108:111]
	v_mfma_f32_16x16x32_bf16 v[108:111], v[160:163], v[202:205], v[108:111]
	v_mfma_f32_16x16x32_bf16 v[92:95], v[160:163], v[210:213], v[92:95]
	v_mfma_f32_16x16x32_bf16 v[92:95], v[164:167], v[214:217], v[92:95]
	v_mfma_f32_16x16x32_bf16 v[84:87], v[172:175], v[214:217], v[84:87]
	v_mfma_f32_16x16x32_bf16 v[84:87], v[168:171], v[210:213], v[84:87]
	v_mfma_f32_16x16x32_bf16 v[68:71], v[168:171], v[218:221], v[68:71]
	v_mfma_f32_16x16x32_bf16 v[68:71], v[172:175], v[222:225], v[68:71]
	v_mfma_f32_16x16x32_bf16 v[76:79], v[164:167], v[222:225], v[76:79]
	v_mfma_f32_16x16x32_bf16 v[76:79], v[160:163], v[218:221], v[76:79]
	s_setprio 0
	s_setprio 1
	v_mfma_f32_16x16x32_bf16 v[120:123], v[176:179], v[194:197], v[120:123]
	v_mfma_f32_16x16x32_bf16 v[120:123], v[180:183], v[198:201], v[120:123]
	v_mfma_f32_16x16x32_bf16 v[112:115], v[190:193], v[198:201], v[112:115]
	v_mfma_f32_16x16x32_bf16 v[112:115], v[186:189], v[194:197], v[112:115]
	v_mfma_f32_16x16x32_bf16 v[96:99], v[186:189], v[202:205], v[96:99]
	v_mfma_f32_16x16x32_bf16 v[96:99], v[190:193], v[206:209], v[96:99]
	v_mfma_f32_16x16x32_bf16 v[104:107], v[180:183], v[206:209], v[104:107]
	v_mfma_f32_16x16x32_bf16 v[104:107], v[176:179], v[202:205], v[104:107]
	v_mfma_f32_16x16x32_bf16 v[88:91], v[176:179], v[210:213], v[88:91]
	v_mfma_f32_16x16x32_bf16 v[88:91], v[180:183], v[214:217], v[88:91]
	v_mfma_f32_16x16x32_bf16 v[80:83], v[190:193], v[214:217], v[80:83]
	v_mfma_f32_16x16x32_bf16 v[80:83], v[186:189], v[210:213], v[80:83]
	v_mfma_f32_16x16x32_bf16 v[64:67], v[186:189], v[218:221], v[64:67]
	v_mfma_f32_16x16x32_bf16 v[64:67], v[190:193], v[222:225], v[64:67]
	v_mfma_f32_16x16x32_bf16 v[72:75], v[180:183], v[222:225], v[72:75]
	v_mfma_f32_16x16x32_bf16 v[72:75], v[176:179], v[218:221], v[72:75]
	s_setprio 0
	s_barrier
	s_add_i32 s48, s76, s52
	v_lshl_add_u64 v[154:155], v[154:155], 0, s[14:15]
	s_mov_b32 m0, s48
	ds_read_b128 v[194:197], v150 offset:49152
	v_xor_b32_e32 v253, 64, v150
	ds_read_b128 v[198:201], v253 offset:49152
	ds_read_b128 v[202:205], v150 offset:51200
	ds_read_b128 v[206:209], v253 offset:51200
	ds_read_b128 v[210:213], v150 offset:53248
	ds_read_b128 v[214:217], v253 offset:53248
	ds_read_b128 v[218:221], v150 offset:55296
	ds_read_b128 v[222:225], v253 offset:55296
	global_load_lds_dwordx4 v[154:155], off
	s_add_i32 m0, s48, 0x2000
	s_add_u32 s46, s46, 0x40080
	v_lshl_add_u64 v[154:155], v[226:227], 0, s[14:15]
	s_addc_u32 s47, s47, 0
	s_add_i32 s48, s77, s52
	global_load_lds_dwordx4 v[154:155], off
	v_lshl_add_u64 v[154:155], s[46:47], 0, v[132:133]
	s_mov_b32 m0, s48
	s_nop 0
	global_load_lds_dwordx4 v[154:155], off
	v_lshl_add_u64 v[154:155], s[46:47], 0, v[128:129]
	s_add_i32 m0, s48, 0x2000
	s_nop 0
	global_load_lds_dwordx4 v[154:155], off
	v_lshl_add_u64 v[154:155], v[228:229], 0, s[14:15]
	s_mov_b32 m0, s60
	s_nop 0
	global_load_lds_dwordx4 v[154:155], off
	v_lshl_add_u64 v[154:155], v[230:231], 0, s[14:15]
	s_mov_b32 m0, s61
	s_nop 0
	global_load_lds_dwordx4 v[154:155], off
	s_waitcnt vmcnt(8)
	s_waitcnt lgkmcnt(0)
	s_barrier
	s_setprio 1
	s_waitcnt lgkmcnt(0)
	v_mfma_f32_16x16x32_bf16 v[60:63], v[160:163], v[194:197], v[60:63]
	v_mfma_f32_16x16x32_bf16 v[60:63], v[164:167], v[198:201], v[60:63]
	v_mfma_f32_16x16x32_bf16 v[52:55], v[172:175], v[198:201], v[52:55]
	v_mfma_f32_16x16x32_bf16 v[52:55], v[168:171], v[194:197], v[52:55]
	v_mfma_f32_16x16x32_bf16 v[36:39], v[168:171], v[202:205], v[36:39]
	v_mfma_f32_16x16x32_bf16 v[36:39], v[172:175], v[206:209], v[36:39]
	v_mfma_f32_16x16x32_bf16 v[44:47], v[164:167], v[206:209], v[44:47]
	v_mfma_f32_16x16x32_bf16 v[44:47], v[160:163], v[202:205], v[44:47]
	v_mfma_f32_16x16x32_bf16 v[28:31], v[160:163], v[210:213], v[28:31]
	v_mfma_f32_16x16x32_bf16 v[28:31], v[164:167], v[214:217], v[28:31]
	v_mfma_f32_16x16x32_bf16 v[20:23], v[172:175], v[214:217], v[20:23]
	v_mfma_f32_16x16x32_bf16 v[20:23], v[168:171], v[210:213], v[20:23]
	v_mfma_f32_16x16x32_bf16 v[4:7], v[168:171], v[218:221], v[4:7]
	v_mfma_f32_16x16x32_bf16 v[4:7], v[172:175], v[222:225], v[4:7]
	v_mfma_f32_16x16x32_bf16 v[12:15], v[164:167], v[222:225], v[12:15]
	v_mfma_f32_16x16x32_bf16 v[12:15], v[160:163], v[218:221], v[12:15]
	s_setprio 0
	s_setprio 1
	v_mfma_f32_16x16x32_bf16 v[56:59], v[176:179], v[194:197], v[56:59]
	v_mfma_f32_16x16x32_bf16 v[56:59], v[180:183], v[198:201], v[56:59]
	v_mfma_f32_16x16x32_bf16 v[48:51], v[190:193], v[198:201], v[48:51]
	v_mfma_f32_16x16x32_bf16 v[48:51], v[186:189], v[194:197], v[48:51]
	v_mfma_f32_16x16x32_bf16 v[32:35], v[186:189], v[202:205], v[32:35]
	v_mfma_f32_16x16x32_bf16 v[32:35], v[190:193], v[206:209], v[32:35]
	v_mfma_f32_16x16x32_bf16 v[40:43], v[180:183], v[206:209], v[40:43]
	v_mfma_f32_16x16x32_bf16 v[40:43], v[176:179], v[202:205], v[40:43]
	v_mfma_f32_16x16x32_bf16 v[24:27], v[176:179], v[210:213], v[24:27]
	v_mfma_f32_16x16x32_bf16 v[24:27], v[180:183], v[214:217], v[24:27]
	v_mfma_f32_16x16x32_bf16 v[16:19], v[190:193], v[214:217], v[16:19]
	v_mfma_f32_16x16x32_bf16 v[16:19], v[186:189], v[210:213], v[16:19]
	v_mfma_f32_16x16x32_bf16 v[0:3], v[186:189], v[218:221], v[0:3]
	v_mfma_f32_16x16x32_bf16 v[0:3], v[190:193], v[222:225], v[0:3]
	v_mfma_f32_16x16x32_bf16 v[8:11], v[180:183], v[222:225], v[8:11]
	v_mfma_f32_16x16x32_bf16 v[8:11], v[176:179], v[218:221], v[8:11]
	s_setprio 0
	s_barrier
	s_add_i32 s75, s75, 2
	s_add_u32 s71, s71, 0x100
	s_addc_u32 s74, s74, 0
	s_add_u32 s44, s44, 0x100
	s_addc_u32 s45, s45, 0
	s_branch .LBB0_76
.LBB0_75:
	v_add_u32_e32 v153, s64, v147
	ds_read_b128 v[160:163], v153
	v_xor_b32_e32 v253, 64, v153
	ds_read_b128 v[164:167], v253
	ds_read_b128 v[168:171], v153 offset:2048
	ds_read_b128 v[172:175], v253 offset:2048
	v_add_u32_e32 v153, s65, v147
	ds_read_b128 v[176:179], v153
	v_xor_b32_e32 v253, 64, v153
	ds_read_b128 v[180:183], v253
	ds_read_b128 v[186:189], v153 offset:2048
	ds_read_b128 v[190:193], v253 offset:2048
	s_add_u32 s48, s44, 0xfffc0080
	s_addc_u32 s49, s45, -1
	s_and_b64 s[46:47], s[46:47], exec
	s_cselect_b32 s49, s27, s49
	s_cselect_b32 s48, s68, s48
	s_cselect_b32 s47, s69, s74
	s_cselect_b32 s46, s70, s71
	v_lshl_add_u64 v[154:155], s[44:45], 0, v[138:139]
	s_add_i32 m0, s55, 0xc000
	ds_read_b128 v[194:197], v150
	v_xor_b32_e32 v253, 64, v150
	ds_read_b128 v[198:201], v253
	ds_read_b128 v[202:205], v150 offset:2048
	ds_read_b128 v[206:209], v253 offset:2048
	ds_read_b128 v[210:213], v150 offset:4096
	ds_read_b128 v[214:217], v253 offset:4096
	ds_read_b128 v[218:221], v150 offset:6144
	ds_read_b128 v[222:225], v253 offset:6144
	global_load_lds_dwordx4 v[154:155], off
	v_lshl_add_u64 v[154:155], s[44:45], 0, v[136:137]
	s_add_i32 m0, s55, 0xe000
	s_nop 0
	global_load_lds_dwordx4 v[154:155], off
	s_waitcnt vmcnt(8)
	s_waitcnt lgkmcnt(0)
	s_barrier
	s_setprio 1
	s_waitcnt lgkmcnt(0)
	v_mfma_f32_16x16x32_bf16 v[124:127], v[160:163], v[194:197], v[124:127]
	v_mfma_f32_16x16x32_bf16 v[124:127], v[164:167], v[198:201], v[124:127]
	v_mfma_f32_16x16x32_bf16 v[116:119], v[172:175], v[198:201], v[116:119]
	v_mfma_f32_16x16x32_bf16 v[116:119], v[168:171], v[194:197], v[116:119]
	v_mfma_f32_16x16x32_bf16 v[100:103], v[168:171], v[202:205], v[100:103]
	v_mfma_f32_16x16x32_bf16 v[100:103], v[172:175], v[206:209], v[100:103]
	v_mfma_f32_16x16x32_bf16 v[108:111], v[164:167], v[206:209], v[108:111]
	v_mfma_f32_16x16x32_bf16 v[108:111], v[160:163], v[202:205], v[108:111]
	v_mfma_f32_16x16x32_bf16 v[92:95], v[160:163], v[210:213], v[92:95]
	v_mfma_f32_16x16x32_bf16 v[92:95], v[164:167], v[214:217], v[92:95]
	v_mfma_f32_16x16x32_bf16 v[84:87], v[172:175], v[214:217], v[84:87]
	v_mfma_f32_16x16x32_bf16 v[84:87], v[168:171], v[210:213], v[84:87]
	v_mfma_f32_16x16x32_bf16 v[68:71], v[168:171], v[218:221], v[68:71]
	v_mfma_f32_16x16x32_bf16 v[68:71], v[172:175], v[222:225], v[68:71]
	v_mfma_f32_16x16x32_bf16 v[76:79], v[164:167], v[222:225], v[76:79]
	v_mfma_f32_16x16x32_bf16 v[76:79], v[160:163], v[218:221], v[76:79]
	s_setprio 0
	s_setprio 1
	v_mfma_f32_16x16x32_bf16 v[120:123], v[176:179], v[194:197], v[120:123]
	v_mfma_f32_16x16x32_bf16 v[120:123], v[180:183], v[198:201], v[120:123]
	v_mfma_f32_16x16x32_bf16 v[112:115], v[190:193], v[198:201], v[112:115]
	v_mfma_f32_16x16x32_bf16 v[112:115], v[186:189], v[194:197], v[112:115]
	v_mfma_f32_16x16x32_bf16 v[96:99], v[186:189], v[202:205], v[96:99]
	v_mfma_f32_16x16x32_bf16 v[96:99], v[190:193], v[206:209], v[96:99]
	v_mfma_f32_16x16x32_bf16 v[104:107], v[180:183], v[206:209], v[104:107]
	v_mfma_f32_16x16x32_bf16 v[104:107], v[176:179], v[202:205], v[104:107]
	v_mfma_f32_16x16x32_bf16 v[88:91], v[176:179], v[210:213], v[88:91]
	v_mfma_f32_16x16x32_bf16 v[88:91], v[180:183], v[214:217], v[88:91]
	v_mfma_f32_16x16x32_bf16 v[80:83], v[190:193], v[214:217], v[80:83]
	v_mfma_f32_16x16x32_bf16 v[80:83], v[186:189], v[210:213], v[80:83]
	v_mfma_f32_16x16x32_bf16 v[64:67], v[186:189], v[218:221], v[64:67]
	v_mfma_f32_16x16x32_bf16 v[64:67], v[190:193], v[222:225], v[64:67]
	v_mfma_f32_16x16x32_bf16 v[72:75], v[180:183], v[222:225], v[72:75]
	v_mfma_f32_16x16x32_bf16 v[72:75], v[176:179], v[218:221], v[72:75]
	s_setprio 0
	s_barrier
	s_add_i32 s76, s64, s52
	v_lshl_add_u64 v[154:155], s[46:47], 0, v[132:133]
	s_mov_b32 m0, s76
	ds_read_b128 v[194:197], v150 offset:16384
	v_xor_b32_e32 v253, 64, v150
	ds_read_b128 v[198:201], v253 offset:16384
	ds_read_b128 v[202:205], v150 offset:18432
	ds_read_b128 v[206:209], v253 offset:18432
	ds_read_b128 v[210:213], v150 offset:20480
	ds_read_b128 v[214:217], v253 offset:20480
	ds_read_b128 v[218:221], v150 offset:22528
	ds_read_b128 v[222:225], v253 offset:22528
	global_load_lds_dwordx4 v[154:155], off
	s_add_i32 m0, s76, 0x2000
	s_add_u32 s76, s46, 0x40000
	v_lshl_add_u64 v[226:227], s[46:47], 0, v[128:129]
	s_addc_u32 s77, s47, 0
	s_add_i32 s78, s65, s52
	global_load_lds_dwordx4 v[226:227], off
	v_lshl_add_u64 v[228:229], s[76:77], 0, v[132:133]
	s_mov_b32 m0, s78
	v_lshl_add_u64 v[230:231], s[48:49], 0, v[130:131]
	global_load_lds_dwordx4 v[228:229], off
	v_lshl_add_u64 v[228:229], s[76:77], 0, v[128:129]
	s_add_i32 m0, s78, 0x2000
	s_nop 0
	global_load_lds_dwordx4 v[228:229], off
	v_lshl_add_u64 v[228:229], s[48:49], 0, v[134:135]
	s_mov_b32 m0, s55
	s_nop 0
	global_load_lds_dwordx4 v[228:229], off
	s_mov_b32 m0, s56
	s_nop 0
	global_load_lds_dwordx4 v[230:231], off
	s_waitcnt vmcnt(8)
	s_waitcnt lgkmcnt(0)
	s_barrier
	s_setprio 1
	s_waitcnt lgkmcnt(0)
	v_mfma_f32_16x16x32_bf16 v[60:63], v[160:163], v[194:197], v[60:63]
	v_mfma_f32_16x16x32_bf16 v[60:63], v[164:167], v[198:201], v[60:63]
	v_mfma_f32_16x16x32_bf16 v[52:55], v[172:175], v[198:201], v[52:55]
	v_mfma_f32_16x16x32_bf16 v[52:55], v[168:171], v[194:197], v[52:55]
	v_mfma_f32_16x16x32_bf16 v[36:39], v[168:171], v[202:205], v[36:39]
	v_mfma_f32_16x16x32_bf16 v[36:39], v[172:175], v[206:209], v[36:39]
	v_mfma_f32_16x16x32_bf16 v[44:47], v[164:167], v[206:209], v[44:47]
	v_mfma_f32_16x16x32_bf16 v[44:47], v[160:163], v[202:205], v[44:47]
	v_mfma_f32_16x16x32_bf16 v[28:31], v[160:163], v[210:213], v[28:31]
	v_mfma_f32_16x16x32_bf16 v[28:31], v[164:167], v[214:217], v[28:31]
	v_mfma_f32_16x16x32_bf16 v[20:23], v[172:175], v[214:217], v[20:23]
	v_mfma_f32_16x16x32_bf16 v[20:23], v[168:171], v[210:213], v[20:23]
	v_mfma_f32_16x16x32_bf16 v[4:7], v[168:171], v[218:221], v[4:7]
	v_mfma_f32_16x16x32_bf16 v[4:7], v[172:175], v[222:225], v[4:7]
	v_mfma_f32_16x16x32_bf16 v[12:15], v[164:167], v[222:225], v[12:15]
	v_mfma_f32_16x16x32_bf16 v[12:15], v[160:163], v[218:221], v[12:15]
	s_setprio 0
	s_setprio 1
	v_mfma_f32_16x16x32_bf16 v[56:59], v[176:179], v[194:197], v[56:59]
	v_mfma_f32_16x16x32_bf16 v[56:59], v[180:183], v[198:201], v[56:59]
	v_mfma_f32_16x16x32_bf16 v[48:51], v[190:193], v[198:201], v[48:51]
	v_mfma_f32_16x16x32_bf16 v[48:51], v[186:189], v[194:197], v[48:51]
	v_mfma_f32_16x16x32_bf16 v[32:35], v[186:189], v[202:205], v[32:35]
	v_mfma_f32_16x16x32_bf16 v[32:35], v[190:193], v[206:209], v[32:35]
	v_mfma_f32_16x16x32_bf16 v[40:43], v[180:183], v[206:209], v[40:43]
	v_mfma_f32_16x16x32_bf16 v[40:43], v[176:179], v[202:205], v[40:43]
	v_mfma_f32_16x16x32_bf16 v[24:27], v[176:179], v[210:213], v[24:27]
	v_mfma_f32_16x16x32_bf16 v[24:27], v[180:183], v[214:217], v[24:27]
	v_mfma_f32_16x16x32_bf16 v[16:19], v[190:193], v[214:217], v[16:19]
	v_mfma_f32_16x16x32_bf16 v[16:19], v[186:189], v[210:213], v[16:19]
	v_mfma_f32_16x16x32_bf16 v[0:3], v[186:189], v[218:221], v[0:3]
	v_mfma_f32_16x16x32_bf16 v[0:3], v[190:193], v[222:225], v[0:3]
	v_mfma_f32_16x16x32_bf16 v[8:11], v[180:183], v[222:225], v[8:11]
	v_mfma_f32_16x16x32_bf16 v[8:11], v[176:179], v[218:221], v[8:11]
	s_setprio 0
	s_barrier
	s_add_i32 s76, 0, 0x18000
	v_add_u32_e32 v153, s76, v147
	s_add_i32 s77, 0, 0x1c000
	ds_read_b128 v[160:163], v153
	v_xor_b32_e32 v253, 64, v153
	ds_read_b128 v[164:167], v253
	ds_read_b128 v[168:171], v153 offset:2048
	ds_read_b128 v[172:175], v253 offset:2048
	v_add_u32_e32 v153, s77, v147
	ds_read_b128 v[176:179], v153
	v_xor_b32_e32 v253, 64, v153
	ds_read_b128 v[180:183], v253
	ds_read_b128 v[186:189], v153 offset:2048
	ds_read_b128 v[190:193], v253 offset:2048
	s_add_u32 s48, s48, 0x40000
	s_addc_u32 s49, s49, 0
	s_mov_b32 m0, s57
	v_lshl_add_u64 v[232:233], s[48:49], 0, v[134:135]
	ds_read_b128 v[194:197], v150 offset:32768
	v_xor_b32_e32 v253, 64, v150
	ds_read_b128 v[198:201], v253 offset:32768
	ds_read_b128 v[202:205], v150 offset:34816
	ds_read_b128 v[206:209], v253 offset:34816
	ds_read_b128 v[210:213], v150 offset:36864
	ds_read_b128 v[214:217], v253 offset:36864
	ds_read_b128 v[218:221], v150 offset:38912
	ds_read_b128 v[222:225], v253 offset:38912
	global_load_lds_dwordx4 v[232:233], off
	v_lshl_add_u64 v[232:233], s[48:49], 0, v[130:131]
	s_mov_b32 m0, s58
	s_nop 0
	global_load_lds_dwordx4 v[232:233], off
	s_waitcnt vmcnt(8)
	s_waitcnt lgkmcnt(0)
	s_barrier
	s_setprio 1
	s_waitcnt lgkmcnt(0)
	v_mfma_f32_16x16x32_bf16 v[124:127], v[160:163], v[194:197], v[124:127]
	v_mfma_f32_16x16x32_bf16 v[124:127], v[164:167], v[198:201], v[124:127]
	v_mfma_f32_16x16x32_bf16 v[116:119], v[172:175], v[198:201], v[116:119]
	v_mfma_f32_16x16x32_bf16 v[116:119], v[168:171], v[194:197], v[116:119]
	v_mfma_f32_16x16x32_bf16 v[100:103], v[168:171], v[202:205], v[100:103]
	v_mfma_f32_16x16x32_bf16 v[100:103], v[172:175], v[206:209], v[100:103]
	v_mfma_f32_16x16x32_bf16 v[108:111], v[164:167], v[206:209], v[108:111]
	v_mfma_f32_16x16x32_bf16 v[108:111], v[160:163], v[202:205], v[108:111]
	v_mfma_f32_16x16x32_bf16 v[92:95], v[160:163], v[210:213], v[92:95]
	v_mfma_f32_16x16x32_bf16 v[92:95], v[164:167], v[214:217], v[92:95]
	v_mfma_f32_16x16x32_bf16 v[84:87], v[172:175], v[214:217], v[84:87]
	v_mfma_f32_16x16x32_bf16 v[84:87], v[168:171], v[210:213], v[84:87]
	v_mfma_f32_16x16x32_bf16 v[68:71], v[168:171], v[218:221], v[68:71]
	v_mfma_f32_16x16x32_bf16 v[68:71], v[172:175], v[222:225], v[68:71]
	v_mfma_f32_16x16x32_bf16 v[76:79], v[164:167], v[222:225], v[76:79]
	v_mfma_f32_16x16x32_bf16 v[76:79], v[160:163], v[218:221], v[76:79]
	s_setprio 0
	s_setprio 1
	v_mfma_f32_16x16x32_bf16 v[120:123], v[176:179], v[194:197], v[120:123]
	v_mfma_f32_16x16x32_bf16 v[120:123], v[180:183], v[198:201], v[120:123]
	v_mfma_f32_16x16x32_bf16 v[112:115], v[190:193], v[198:201], v[112:115]
	v_mfma_f32_16x16x32_bf16 v[112:115], v[186:189], v[194:197], v[112:115]
	v_mfma_f32_16x16x32_bf16 v[96:99], v[186:189], v[202:205], v[96:99]
	v_mfma_f32_16x16x32_bf16 v[96:99], v[190:193], v[206:209], v[96:99]
	v_mfma_f32_16x16x32_bf16 v[104:107], v[180:183], v[206:209], v[104:107]
	v_mfma_f32_16x16x32_bf16 v[104:107], v[176:179], v[202:205], v[104:107]
	v_mfma_f32_16x16x32_bf16 v[88:91], v[176:179], v[210:213], v[88:91]
	v_mfma_f32_16x16x32_bf16 v[88:91], v[180:183], v[214:217], v[88:91]
	v_mfma_f32_16x16x32_bf16 v[80:83], v[190:193], v[214:217], v[80:83]
	v_mfma_f32_16x16x32_bf16 v[80:83], v[186:189], v[210:213], v[80:83]
	v_mfma_f32_16x16x32_bf16 v[64:67], v[186:189], v[218:221], v[64:67]
	v_mfma_f32_16x16x32_bf16 v[64:67], v[190:193], v[222:225], v[64:67]
	v_mfma_f32_16x16x32_bf16 v[72:75], v[180:183], v[222:225], v[72:75]
	v_mfma_f32_16x16x32_bf16 v[72:75], v[176:179], v[218:221], v[72:75]
	s_setprio 0
	s_barrier
	s_add_i32 s48, s76, s52
	v_lshl_add_u64 v[154:155], v[154:155], 0, s[14:15]
	s_mov_b32 m0, s48
	ds_read_b128 v[194:197], v150 offset:49152
	v_xor_b32_e32 v253, 64, v150
	ds_read_b128 v[198:201], v253 offset:49152
	ds_read_b128 v[202:205], v150 offset:51200
	ds_read_b128 v[206:209], v253 offset:51200
	ds_read_b128 v[210:213], v150 offset:53248
	ds_read_b128 v[214:217], v253 offset:53248
	ds_read_b128 v[218:221], v150 offset:55296
	ds_read_b128 v[222:225], v253 offset:55296
	global_load_lds_dwordx4 v[154:155], off
	s_add_i32 m0, s48, 0x2000
	s_add_u32 s46, s46, 0x40080
	v_lshl_add_u64 v[154:155], v[226:227], 0, s[14:15]
	s_addc_u32 s47, s47, 0
	s_add_i32 s48, s77, s52
	global_load_lds_dwordx4 v[154:155], off
	v_lshl_add_u64 v[154:155], s[46:47], 0, v[132:133]
	s_mov_b32 m0, s48
	s_nop 0
	global_load_lds_dwordx4 v[154:155], off
	v_lshl_add_u64 v[154:155], s[46:47], 0, v[128:129]
	s_add_i32 m0, s48, 0x2000
	s_nop 0
	global_load_lds_dwordx4 v[154:155], off
	v_lshl_add_u64 v[154:155], v[228:229], 0, s[14:15]
	s_mov_b32 m0, s60
	s_nop 0
	global_load_lds_dwordx4 v[154:155], off
	v_lshl_add_u64 v[154:155], v[230:231], 0, s[14:15]
	s_mov_b32 m0, s61
	s_nop 0
	global_load_lds_dwordx4 v[154:155], off
	s_waitcnt vmcnt(8)
	s_waitcnt lgkmcnt(0)
	s_barrier
	s_setprio 1
	s_waitcnt lgkmcnt(0)
	v_mfma_f32_16x16x32_bf16 v[60:63], v[160:163], v[194:197], v[60:63]
	v_mfma_f32_16x16x32_bf16 v[60:63], v[164:167], v[198:201], v[60:63]
	v_mfma_f32_16x16x32_bf16 v[52:55], v[172:175], v[198:201], v[52:55]
	v_mfma_f32_16x16x32_bf16 v[52:55], v[168:171], v[194:197], v[52:55]
	v_mfma_f32_16x16x32_bf16 v[36:39], v[168:171], v[202:205], v[36:39]
	v_mfma_f32_16x16x32_bf16 v[36:39], v[172:175], v[206:209], v[36:39]
	v_mfma_f32_16x16x32_bf16 v[44:47], v[164:167], v[206:209], v[44:47]
	v_mfma_f32_16x16x32_bf16 v[44:47], v[160:163], v[202:205], v[44:47]
	v_mfma_f32_16x16x32_bf16 v[28:31], v[160:163], v[210:213], v[28:31]
	v_mfma_f32_16x16x32_bf16 v[28:31], v[164:167], v[214:217], v[28:31]
	v_mfma_f32_16x16x32_bf16 v[20:23], v[172:175], v[214:217], v[20:23]
	v_mfma_f32_16x16x32_bf16 v[20:23], v[168:171], v[210:213], v[20:23]
	v_mfma_f32_16x16x32_bf16 v[4:7], v[168:171], v[218:221], v[4:7]
	v_mfma_f32_16x16x32_bf16 v[4:7], v[172:175], v[222:225], v[4:7]
	v_mfma_f32_16x16x32_bf16 v[12:15], v[164:167], v[222:225], v[12:15]
	v_mfma_f32_16x16x32_bf16 v[12:15], v[160:163], v[218:221], v[12:15]
	s_setprio 0
	s_setprio 1
	v_mfma_f32_16x16x32_bf16 v[56:59], v[176:179], v[194:197], v[56:59]
	v_mfma_f32_16x16x32_bf16 v[56:59], v[180:183], v[198:201], v[56:59]
	v_mfma_f32_16x16x32_bf16 v[48:51], v[190:193], v[198:201], v[48:51]
	v_mfma_f32_16x16x32_bf16 v[48:51], v[186:189], v[194:197], v[48:51]
	v_mfma_f32_16x16x32_bf16 v[32:35], v[186:189], v[202:205], v[32:35]
	v_mfma_f32_16x16x32_bf16 v[32:35], v[190:193], v[206:209], v[32:35]
	v_mfma_f32_16x16x32_bf16 v[40:43], v[180:183], v[206:209], v[40:43]
	v_mfma_f32_16x16x32_bf16 v[40:43], v[176:179], v[202:205], v[40:43]
	v_mfma_f32_16x16x32_bf16 v[24:27], v[176:179], v[210:213], v[24:27]
	v_mfma_f32_16x16x32_bf16 v[24:27], v[180:183], v[214:217], v[24:27]
	v_mfma_f32_16x16x32_bf16 v[16:19], v[190:193], v[214:217], v[16:19]
	v_mfma_f32_16x16x32_bf16 v[16:19], v[186:189], v[210:213], v[16:19]
	v_mfma_f32_16x16x32_bf16 v[0:3], v[186:189], v[218:221], v[0:3]
	v_mfma_f32_16x16x32_bf16 v[0:3], v[190:193], v[222:225], v[0:3]
	v_mfma_f32_16x16x32_bf16 v[8:11], v[180:183], v[222:225], v[8:11]
	v_mfma_f32_16x16x32_bf16 v[8:11], v[176:179], v[218:221], v[8:11]
	s_setprio 0
	s_barrier
	s_add_i32 s75, s75, 2
	s_add_u32 s71, s71, 0x100
	s_addc_u32 s74, s74, 0
	s_add_u32 s44, s44, 0x100
	s_addc_u32 s45, s45, 0
	s_cmp_gt_u32 s75, 13
	s_cbranch_scc1 .LBB0_78

.Llast_0:
	v_add_u32_e32 v153, s64, v147
	ds_read_b128 v[160:163], v153
	v_xor_b32_e32 v253, 64, v153
	ds_read_b128 v[164:167], v253
	ds_read_b128 v[168:171], v153 offset:2048
	ds_read_b128 v[172:175], v253 offset:2048
	v_add_u32_e32 v153, s65, v147
	ds_read_b128 v[176:179], v153
	v_xor_b32_e32 v253, 64, v153
	ds_read_b128 v[180:183], v253
	ds_read_b128 v[186:189], v153 offset:2048
	ds_read_b128 v[190:193], v253 offset:2048
	s_add_u32 s48, s44, 0xfffc0080
	s_addc_u32 s49, s45, -1
	s_and_b64 s[46:47], s[46:47], exec
	s_cselect_b32 s49, s27, s49
	s_cselect_b32 s48, s68, s48
	s_cselect_b32 s47, s69, s74
	s_cselect_b32 s46, s70, s71
	v_lshl_add_u64 v[154:155], s[44:45], 0, v[138:139]
	s_add_i32 m0, s55, 0xc000
	ds_read_b128 v[194:197], v150
	v_xor_b32_e32 v253, 64, v150
	ds_read_b128 v[198:201], v253
	ds_read_b128 v[202:205], v150 offset:2048
	ds_read_b128 v[206:209], v253 offset:2048
	ds_read_b128 v[210:213], v150 offset:4096
	ds_read_b128 v[214:217], v253 offset:4096
	ds_read_b128 v[218:221], v150 offset:6144
	ds_read_b128 v[222:225], v253 offset:6144
	global_load_lds_dwordx4 v[154:155], off
	v_lshl_add_u64 v[154:155], s[44:45], 0, v[136:137]
	s_add_i32 m0, s55, 0xe000
	s_nop 0
	global_load_lds_dwordx4 v[154:155], off
	s_waitcnt vmcnt(8)
	s_waitcnt lgkmcnt(0)
	s_barrier
	s_setprio 1
	s_waitcnt lgkmcnt(0)
	v_mfma_f32_16x16x32_bf16 v[124:127], v[160:163], v[194:197], v[124:127]
	v_mfma_f32_16x16x32_bf16 v[124:127], v[164:167], v[198:201], v[124:127]
	v_mfma_f32_16x16x32_bf16 v[116:119], v[172:175], v[198:201], v[116:119]
	v_mfma_f32_16x16x32_bf16 v[116:119], v[168:171], v[194:197], v[116:119]
	v_mfma_f32_16x16x32_bf16 v[100:103], v[168:171], v[202:205], v[100:103]
	v_mfma_f32_16x16x32_bf16 v[100:103], v[172:175], v[206:209], v[100:103]
	v_mfma_f32_16x16x32_bf16 v[108:111], v[164:167], v[206:209], v[108:111]
	v_mfma_f32_16x16x32_bf16 v[108:111], v[160:163], v[202:205], v[108:111]
	v_mfma_f32_16x16x32_bf16 v[92:95], v[160:163], v[210:213], v[92:95]
	v_mfma_f32_16x16x32_bf16 v[92:95], v[164:167], v[214:217], v[92:95]
	v_mfma_f32_16x16x32_bf16 v[84:87], v[172:175], v[214:217], v[84:87]
	v_mfma_f32_16x16x32_bf16 v[84:87], v[168:171], v[210:213], v[84:87]
	v_mfma_f32_16x16x32_bf16 v[68:71], v[168:171], v[218:221], v[68:71]
	v_mfma_f32_16x16x32_bf16 v[68:71], v[172:175], v[222:225], v[68:71]
	v_mfma_f32_16x16x32_bf16 v[76:79], v[164:167], v[222:225], v[76:79]
	v_mfma_f32_16x16x32_bf16 v[76:79], v[160:163], v[218:221], v[76:79]
	s_setprio 0
	s_setprio 1
	v_mfma_f32_16x16x32_bf16 v[120:123], v[176:179], v[194:197], v[120:123]
	v_mfma_f32_16x16x32_bf16 v[120:123], v[180:183], v[198:201], v[120:123]
	v_mfma_f32_16x16x32_bf16 v[112:115], v[190:193], v[198:201], v[112:115]
	v_mfma_f32_16x16x32_bf16 v[112:115], v[186:189], v[194:197], v[112:115]
	v_mfma_f32_16x16x32_bf16 v[96:99], v[186:189], v[202:205], v[96:99]
	v_mfma_f32_16x16x32_bf16 v[96:99], v[190:193], v[206:209], v[96:99]
	v_mfma_f32_16x16x32_bf16 v[104:107], v[180:183], v[206:209], v[104:107]
	v_mfma_f32_16x16x32_bf16 v[104:107], v[176:179], v[202:205], v[104:107]
	v_mfma_f32_16x16x32_bf16 v[88:91], v[176:179], v[210:213], v[88:91]
	v_mfma_f32_16x16x32_bf16 v[88:91], v[180:183], v[214:217], v[88:91]
	v_mfma_f32_16x16x32_bf16 v[80:83], v[190:193], v[214:217], v[80:83]
	v_mfma_f32_16x16x32_bf16 v[80:83], v[186:189], v[210:213], v[80:83]
	v_mfma_f32_16x16x32_bf16 v[64:67], v[186:189], v[218:221], v[64:67]
	v_mfma_f32_16x16x32_bf16 v[64:67], v[190:193], v[222:225], v[64:67]
	v_mfma_f32_16x16x32_bf16 v[72:75], v[180:183], v[222:225], v[72:75]
	v_mfma_f32_16x16x32_bf16 v[72:75], v[176:179], v[218:221], v[72:75]
	s_setprio 0
	s_barrier
	s_add_i32 s76, s64, s52
	v_lshl_add_u64 v[154:155], s[46:47], 0, v[132:133]
	s_mov_b32 m0, s76
	ds_read_b128 v[194:197], v150 offset:16384
	v_xor_b32_e32 v253, 64, v150
	ds_read_b128 v[198:201], v253 offset:16384
	ds_read_b128 v[202:205], v150 offset:18432
	ds_read_b128 v[206:209], v253 offset:18432
	ds_read_b128 v[210:213], v150 offset:20480
	ds_read_b128 v[214:217], v253 offset:20480
	ds_read_b128 v[218:221], v150 offset:22528
	ds_read_b128 v[222:225], v253 offset:22528
	global_load_lds_dwordx4 v[154:155], off
	s_add_i32 m0, s76, 0x2000
	s_add_u32 s76, s46, 0x40000
	v_lshl_add_u64 v[226:227], s[46:47], 0, v[128:129]
	s_addc_u32 s77, s47, 0
	s_add_i32 s78, s65, s52
	global_load_lds_dwordx4 v[226:227], off
	v_lshl_add_u64 v[228:229], s[76:77], 0, v[132:133]
	s_mov_b32 m0, s78
	v_lshl_add_u64 v[230:231], s[48:49], 0, v[130:131]
	global_load_lds_dwordx4 v[228:229], off
	v_lshl_add_u64 v[228:229], s[76:77], 0, v[128:129]
	s_add_i32 m0, s78, 0x2000
	s_nop 0
	global_load_lds_dwordx4 v[228:229], off
	v_lshl_add_u64 v[228:229], s[48:49], 0, v[134:135]
	s_mov_b32 m0, s55
	s_nop 0
	global_load_lds_dwordx4 v[228:229], off
	s_mov_b32 m0, s56
	s_nop 0
	global_load_lds_dwordx4 v[230:231], off
	s_waitcnt vmcnt(8)
	s_waitcnt lgkmcnt(0)
	s_barrier
	s_setprio 1
	s_waitcnt lgkmcnt(0)
	v_mfma_f32_16x16x32_bf16 v[60:63], v[160:163], v[194:197], v[60:63]
	v_mfma_f32_16x16x32_bf16 v[60:63], v[164:167], v[198:201], v[60:63]
	v_mfma_f32_16x16x32_bf16 v[52:55], v[172:175], v[198:201], v[52:55]
	v_mfma_f32_16x16x32_bf16 v[52:55], v[168:171], v[194:197], v[52:55]
	v_mfma_f32_16x16x32_bf16 v[36:39], v[168:171], v[202:205], v[36:39]
	v_mfma_f32_16x16x32_bf16 v[36:39], v[172:175], v[206:209], v[36:39]
	v_mfma_f32_16x16x32_bf16 v[44:47], v[164:167], v[206:209], v[44:47]
	v_mfma_f32_16x16x32_bf16 v[44:47], v[160:163], v[202:205], v[44:47]
	v_mfma_f32_16x16x32_bf16 v[28:31], v[160:163], v[210:213], v[28:31]
	v_mfma_f32_16x16x32_bf16 v[28:31], v[164:167], v[214:217], v[28:31]
	v_mfma_f32_16x16x32_bf16 v[20:23], v[172:175], v[214:217], v[20:23]
	v_mfma_f32_16x16x32_bf16 v[20:23], v[168:171], v[210:213], v[20:23]
	v_mfma_f32_16x16x32_bf16 v[4:7], v[168:171], v[218:221], v[4:7]
	v_mfma_f32_16x16x32_bf16 v[4:7], v[172:175], v[222:225], v[4:7]
	v_mfma_f32_16x16x32_bf16 v[12:15], v[164:167], v[222:225], v[12:15]
	v_mfma_f32_16x16x32_bf16 v[12:15], v[160:163], v[218:221], v[12:15]
	s_setprio 0
	s_setprio 1
	v_mfma_f32_16x16x32_bf16 v[56:59], v[176:179], v[194:197], v[56:59]
	v_mfma_f32_16x16x32_bf16 v[56:59], v[180:183], v[198:201], v[56:59]
	v_mfma_f32_16x16x32_bf16 v[48:51], v[190:193], v[198:201], v[48:51]
	v_mfma_f32_16x16x32_bf16 v[48:51], v[186:189], v[194:197], v[48:51]
	v_mfma_f32_16x16x32_bf16 v[32:35], v[186:189], v[202:205], v[32:35]
	v_mfma_f32_16x16x32_bf16 v[32:35], v[190:193], v[206:209], v[32:35]
	v_mfma_f32_16x16x32_bf16 v[40:43], v[180:183], v[206:209], v[40:43]
	v_mfma_f32_16x16x32_bf16 v[40:43], v[176:179], v[202:205], v[40:43]
	v_mfma_f32_16x16x32_bf16 v[24:27], v[176:179], v[210:213], v[24:27]
	v_mfma_f32_16x16x32_bf16 v[24:27], v[180:183], v[214:217], v[24:27]
	v_mfma_f32_16x16x32_bf16 v[16:19], v[190:193], v[214:217], v[16:19]
	v_mfma_f32_16x16x32_bf16 v[16:19], v[186:189], v[210:213], v[16:19]
	v_mfma_f32_16x16x32_bf16 v[0:3], v[186:189], v[218:221], v[0:3]
	v_mfma_f32_16x16x32_bf16 v[0:3], v[190:193], v[222:225], v[0:3]
	v_mfma_f32_16x16x32_bf16 v[8:11], v[180:183], v[222:225], v[8:11]
	v_mfma_f32_16x16x32_bf16 v[8:11], v[176:179], v[218:221], v[8:11]
	s_setprio 0
	s_barrier
	s_add_i32 s76, 0, 0x18000
	v_add_u32_e32 v153, s76, v147
	s_add_i32 s77, 0, 0x1c000
	ds_read_b128 v[160:163], v153
	v_xor_b32_e32 v253, 64, v153
	ds_read_b128 v[164:167], v253
	ds_read_b128 v[168:171], v153 offset:2048
	ds_read_b128 v[172:175], v253 offset:2048
	v_add_u32_e32 v153, s77, v147
	ds_read_b128 v[176:179], v153
	v_xor_b32_e32 v253, 64, v153
	ds_read_b128 v[180:183], v253
	ds_read_b128 v[186:189], v153 offset:2048
	ds_read_b128 v[190:193], v253 offset:2048
	s_add_u32 s48, s48, 0x40000
	s_addc_u32 s49, s49, 0
	s_mov_b32 m0, s57
	v_lshl_add_u64 v[232:233], s[48:49], 0, v[134:135]
	ds_read_b128 v[194:197], v150 offset:32768
	v_xor_b32_e32 v253, 64, v150
	ds_read_b128 v[198:201], v253 offset:32768
	ds_read_b128 v[202:205], v150 offset:34816
	ds_read_b128 v[206:209], v253 offset:34816
	ds_read_b128 v[210:213], v150 offset:36864
	ds_read_b128 v[214:217], v253 offset:36864
	ds_read_b128 v[218:221], v150 offset:38912
	ds_read_b128 v[222:225], v253 offset:38912
	global_load_lds_dwordx4 v[232:233], off
	v_lshl_add_u64 v[232:233], s[48:49], 0, v[130:131]
	s_mov_b32 m0, s58
	s_nop 0
	global_load_lds_dwordx4 v[232:233], off
	s_waitcnt vmcnt(8)
	s_waitcnt lgkmcnt(0)
	s_barrier
	s_setprio 1
	s_waitcnt lgkmcnt(0)
	v_mfma_f32_16x16x32_bf16 v[124:127], v[160:163], v[194:197], v[124:127]
	v_mfma_f32_16x16x32_bf16 v[124:127], v[164:167], v[198:201], v[124:127]
	v_mfma_f32_16x16x32_bf16 v[116:119], v[172:175], v[198:201], v[116:119]
	v_mfma_f32_16x16x32_bf16 v[116:119], v[168:171], v[194:197], v[116:119]
	v_mfma_f32_16x16x32_bf16 v[100:103], v[168:171], v[202:205], v[100:103]
	v_mfma_f32_16x16x32_bf16 v[100:103], v[172:175], v[206:209], v[100:103]
	v_mfma_f32_16x16x32_bf16 v[108:111], v[164:167], v[206:209], v[108:111]
	v_mfma_f32_16x16x32_bf16 v[108:111], v[160:163], v[202:205], v[108:111]
	v_mfma_f32_16x16x32_bf16 v[92:95], v[160:163], v[210:213], v[92:95]
	v_mfma_f32_16x16x32_bf16 v[92:95], v[164:167], v[214:217], v[92:95]
	v_mfma_f32_16x16x32_bf16 v[84:87], v[172:175], v[214:217], v[84:87]
	v_mfma_f32_16x16x32_bf16 v[84:87], v[168:171], v[210:213], v[84:87]
	v_mfma_f32_16x16x32_bf16 v[68:71], v[168:171], v[218:221], v[68:71]
	v_mfma_f32_16x16x32_bf16 v[68:71], v[172:175], v[222:225], v[68:71]
	v_mfma_f32_16x16x32_bf16 v[76:79], v[164:167], v[222:225], v[76:79]
	v_mfma_f32_16x16x32_bf16 v[76:79], v[160:163], v[218:221], v[76:79]
	s_setprio 0
	s_setprio 1
	v_mfma_f32_16x16x32_bf16 v[120:123], v[176:179], v[194:197], v[120:123]
	v_mfma_f32_16x16x32_bf16 v[120:123], v[180:183], v[198:201], v[120:123]
	v_mfma_f32_16x16x32_bf16 v[112:115], v[190:193], v[198:201], v[112:115]
	v_mfma_f32_16x16x32_bf16 v[112:115], v[186:189], v[194:197], v[112:115]
	v_mfma_f32_16x16x32_bf16 v[96:99], v[186:189], v[202:205], v[96:99]
	v_mfma_f32_16x16x32_bf16 v[96:99], v[190:193], v[206:209], v[96:99]
	v_mfma_f32_16x16x32_bf16 v[104:107], v[180:183], v[206:209], v[104:107]
	v_mfma_f32_16x16x32_bf16 v[104:107], v[176:179], v[202:205], v[104:107]
	v_mfma_f32_16x16x32_bf16 v[88:91], v[176:179], v[210:213], v[88:91]
	v_mfma_f32_16x16x32_bf16 v[88:91], v[180:183], v[214:217], v[88:91]
	v_mfma_f32_16x16x32_bf16 v[80:83], v[190:193], v[214:217], v[80:83]
	v_mfma_f32_16x16x32_bf16 v[80:83], v[186:189], v[210:213], v[80:83]
	v_mfma_f32_16x16x32_bf16 v[64:67], v[186:189], v[218:221], v[64:67]
	v_mfma_f32_16x16x32_bf16 v[64:67], v[190:193], v[222:225], v[64:67]
	v_mfma_f32_16x16x32_bf16 v[72:75], v[180:183], v[222:225], v[72:75]
	v_mfma_f32_16x16x32_bf16 v[72:75], v[176:179], v[218:221], v[72:75]
	s_setprio 0
	s_barrier
	v_add_u32_e32 v234, 0x21000, v151
	ds_read_b128 v[236:239], v234
	ds_read_b128 v[240:243], v234 offset:256
	ds_read_b128 v[244:247], v234 offset:512
	ds_read_b128 v[248:251], v234 offset:768
	v_add_u32_e32 v235, s23, v146
	v_mul_u32_u24_e32 v235, 0x1600, v235
	v_lshl_or_b32 v234, s67, 7, v149
	v_lshl_add_u32 v235, v234, 1, v235
	s_add_i32 s48, s76, s52
	v_lshl_add_u64 v[154:155], v[154:155], 0, s[14:15]
	s_mov_b32 m0, s48
	ds_read_b128 v[194:197], v150 offset:49152
	v_xor_b32_e32 v253, 64, v150
	ds_read_b128 v[198:201], v253 offset:49152
	ds_read_b128 v[202:205], v150 offset:51200
	ds_read_b128 v[206:209], v253 offset:51200
	ds_read_b128 v[210:213], v150 offset:53248
	ds_read_b128 v[214:217], v253 offset:53248
	ds_read_b128 v[218:221], v150 offset:55296
	ds_read_b128 v[222:225], v253 offset:55296
	global_load_lds_dwordx4 v[154:155], off
	s_add_i32 m0, s48, 0x2000
	s_add_u32 s46, s46, 0x40080
	v_lshl_add_u64 v[154:155], v[226:227], 0, s[14:15]
	s_addc_u32 s47, s47, 0
	s_add_i32 s48, s77, s52
	global_load_lds_dwordx4 v[154:155], off
	v_lshl_add_u64 v[154:155], s[46:47], 0, v[132:133]
	s_mov_b32 m0, s48
	s_nop 0
	global_load_lds_dwordx4 v[154:155], off
	v_lshl_add_u64 v[154:155], s[46:47], 0, v[128:129]
	s_add_i32 m0, s48, 0x2000
	s_nop 0
	global_load_lds_dwordx4 v[154:155], off
	v_lshl_add_u64 v[154:155], v[228:229], 0, s[14:15]
	s_mov_b32 m0, s60
	s_nop 0
	global_load_lds_dwordx4 v[154:155], off
	v_lshl_add_u64 v[154:155], v[230:231], 0, s[14:15]
	s_mov_b32 m0, s61
	s_nop 0
	global_load_lds_dwordx4 v[154:155], off
	s_waitcnt lgkmcnt(8)
	v_add_f32_e32 v236, v236, v237
	v_add_f32_e32 v238, v238, v239
	v_add_f32_e32 v240, v240, v241
	v_add_f32_e32 v242, v242, v243
	v_add_f32_e32 v244, v244, v245
	v_add_f32_e32 v246, v246, v247
	v_add_f32_e32 v248, v248, v249
	v_add_f32_e32 v250, v250, v251
	v_add_f32_e32 v236, v236, v238
	v_add_f32_e32 v240, v240, v242
	v_add_f32_e32 v244, v244, v246
	v_add_f32_e32 v248, v248, v250
	v_fmamk_f32 v236, v236, 0x3a800000, v152
	v_fmamk_f32 v240, v240, 0x3a800000, v152
	v_fmamk_f32 v244, v244, 0x3a800000, v152
	v_fmamk_f32 v248, v248, 0x3a800000, v152
	v_rsq_f32_e32 v236, v236
	v_rsq_f32_e32 v240, v240
	v_rsq_f32_e32 v244, v244
	v_rsq_f32_e32 v248, v248
	v_mul_f32_e32 v252, 0xbfb8aa3b, v236
	v_mul_f32_e32 v254, v236, v236
	v_pk_mul_f32 v[120:121], v[124:125], v[120:121]
	v_pk_mul_f32 v[122:123], v[126:127], v[122:123]
	v_pk_mul_f32 v[112:113], v[116:117], v[112:113]
	v_pk_mul_f32 v[114:115], v[118:119], v[114:115]
	v_pk_mul_f32 v[124:125], v[124:125], v[252:253] op_sel_hi:[1,0]
	v_pk_mul_f32 v[126:127], v[126:127], v[252:253] op_sel_hi:[1,0]
	v_pk_mul_f32 v[116:117], v[116:117], v[252:253] op_sel_hi:[1,0]
	v_pk_mul_f32 v[118:119], v[118:119], v[252:253] op_sel_hi:[1,0]
	v_exp_f32_e32 v124, v124
	v_exp_f32_e32 v125, v125
	v_exp_f32_e32 v126, v126
	v_exp_f32_e32 v127, v127
	v_exp_f32_e32 v116, v116
	v_exp_f32_e32 v117, v117
	v_exp_f32_e32 v118, v118
	v_exp_f32_e32 v119, v119
	v_pk_add_f32 v[124:125], v[124:125], 1.0 op_sel_hi:[1,0]
	v_pk_add_f32 v[126:127], v[126:127], 1.0 op_sel_hi:[1,0]
	v_pk_add_f32 v[116:117], v[116:117], 1.0 op_sel_hi:[1,0]
	v_pk_add_f32 v[118:119], v[118:119], 1.0 op_sel_hi:[1,0]
	v_rcp_f32_e32 v124, v124
	v_rcp_f32_e32 v125, v125
	v_rcp_f32_e32 v126, v126
	v_rcp_f32_e32 v127, v127
	v_rcp_f32_e32 v116, v116
	v_rcp_f32_e32 v117, v117
	v_rcp_f32_e32 v118, v118
	v_rcp_f32_e32 v119, v119
	v_pk_mul_f32 v[120:121], v[120:121], v[254:255] op_sel_hi:[1,0]
	v_pk_mul_f32 v[122:123], v[122:123], v[254:255] op_sel_hi:[1,0]
	v_pk_mul_f32 v[112:113], v[112:113], v[254:255] op_sel_hi:[1,0]
	v_pk_mul_f32 v[114:115], v[114:115], v[254:255] op_sel_hi:[1,0]
	v_pk_mul_f32 v[120:121], v[120:121], v[124:125]
	v_pk_mul_f32 v[122:123], v[122:123], v[126:127]
	v_pk_mul_f32 v[112:113], v[112:113], v[116:117]
	v_pk_mul_f32 v[114:115], v[114:115], v[118:119]
	v_cvt_pk_bf16_f32 v120, v120, v121
	v_cvt_pk_bf16_f32 v121, v122, v123
	v_cvt_pk_bf16_f32 v122, v112, v113
	v_cvt_pk_bf16_f32 v123, v114, v115
	global_store_dwordx4 v235, v[120:123], s[10:11]
	v_add_u32_e32 v234, 0x16000, v235
	v_mul_f32_e32 v252, 0xbfb8aa3b, v240
	v_mul_f32_e32 v254, v240, v240
	v_pk_mul_f32 v[104:105], v[108:109], v[104:105]
	v_pk_mul_f32 v[106:107], v[110:111], v[106:107]
	v_pk_mul_f32 v[96:97], v[100:101], v[96:97]
	v_pk_mul_f32 v[98:99], v[102:103], v[98:99]
	v_pk_mul_f32 v[108:109], v[108:109], v[252:253] op_sel_hi:[1,0]
	v_pk_mul_f32 v[110:111], v[110:111], v[252:253] op_sel_hi:[1,0]
	v_pk_mul_f32 v[100:101], v[100:101], v[252:253] op_sel_hi:[1,0]
	v_pk_mul_f32 v[102:103], v[102:103], v[252:253] op_sel_hi:[1,0]
	v_exp_f32_e32 v108, v108
	v_exp_f32_e32 v109, v109
	v_exp_f32_e32 v110, v110
	v_exp_f32_e32 v111, v111
	v_exp_f32_e32 v100, v100
	v_exp_f32_e32 v101, v101
	v_exp_f32_e32 v102, v102
	v_exp_f32_e32 v103, v103
	v_pk_add_f32 v[108:109], v[108:109], 1.0 op_sel_hi:[1,0]
	v_pk_add_f32 v[110:111], v[110:111], 1.0 op_sel_hi:[1,0]
	v_pk_add_f32 v[100:101], v[100:101], 1.0 op_sel_hi:[1,0]
	v_pk_add_f32 v[102:103], v[102:103], 1.0 op_sel_hi:[1,0]
	v_rcp_f32_e32 v108, v108
	v_rcp_f32_e32 v109, v109
	v_rcp_f32_e32 v110, v110
	v_rcp_f32_e32 v111, v111
	v_rcp_f32_e32 v100, v100
	v_rcp_f32_e32 v101, v101
	v_rcp_f32_e32 v102, v102
	v_rcp_f32_e32 v103, v103
	v_pk_mul_f32 v[104:105], v[104:105], v[254:255] op_sel_hi:[1,0]
	v_pk_mul_f32 v[106:107], v[106:107], v[254:255] op_sel_hi:[1,0]
	v_pk_mul_f32 v[96:97], v[96:97], v[254:255] op_sel_hi:[1,0]
	v_pk_mul_f32 v[98:99], v[98:99], v[254:255] op_sel_hi:[1,0]
	v_pk_mul_f32 v[104:105], v[104:105], v[108:109]
	v_pk_mul_f32 v[106:107], v[106:107], v[110:111]
	v_pk_mul_f32 v[96:97], v[96:97], v[100:101]
	v_pk_mul_f32 v[98:99], v[98:99], v[102:103]
	v_cvt_pk_bf16_f32 v104, v104, v105
	v_cvt_pk_bf16_f32 v105, v106, v107
	v_cvt_pk_bf16_f32 v106, v96, v97
	v_cvt_pk_bf16_f32 v107, v98, v99
	global_store_dwordx4 v234, v[104:107], s[10:11]
	v_add_u32_e32 v235, 0x16000, v234
	v_mul_f32_e32 v252, 0xbfb8aa3b, v244
	v_mul_f32_e32 v254, v244, v244
	v_pk_mul_f32 v[88:89], v[92:93], v[88:89]
	v_pk_mul_f32 v[90:91], v[94:95], v[90:91]
	v_pk_mul_f32 v[80:81], v[84:85], v[80:81]
	v_pk_mul_f32 v[82:83], v[86:87], v[82:83]
	v_pk_mul_f32 v[92:93], v[92:93], v[252:253] op_sel_hi:[1,0]
	v_pk_mul_f32 v[94:95], v[94:95], v[252:253] op_sel_hi:[1,0]
	v_pk_mul_f32 v[84:85], v[84:85], v[252:253] op_sel_hi:[1,0]
	v_pk_mul_f32 v[86:87], v[86:87], v[252:253] op_sel_hi:[1,0]
	v_exp_f32_e32 v92, v92
	v_exp_f32_e32 v93, v93
	v_exp_f32_e32 v94, v94
	v_exp_f32_e32 v95, v95
	v_exp_f32_e32 v84, v84
	v_exp_f32_e32 v85, v85
	v_exp_f32_e32 v86, v86
	v_exp_f32_e32 v87, v87
	v_pk_add_f32 v[92:93], v[92:93], 1.0 op_sel_hi:[1,0]
	v_pk_add_f32 v[94:95], v[94:95], 1.0 op_sel_hi:[1,0]
	v_pk_add_f32 v[84:85], v[84:85], 1.0 op_sel_hi:[1,0]
	v_pk_add_f32 v[86:87], v[86:87], 1.0 op_sel_hi:[1,0]
	v_rcp_f32_e32 v92, v92
	v_rcp_f32_e32 v93, v93
	v_rcp_f32_e32 v94, v94
	v_rcp_f32_e32 v95, v95
	v_rcp_f32_e32 v84, v84
	v_rcp_f32_e32 v85, v85
	v_rcp_f32_e32 v86, v86
	v_rcp_f32_e32 v87, v87
	v_pk_mul_f32 v[88:89], v[88:89], v[254:255] op_sel_hi:[1,0]
	v_pk_mul_f32 v[90:91], v[90:91], v[254:255] op_sel_hi:[1,0]
	v_pk_mul_f32 v[80:81], v[80:81], v[254:255] op_sel_hi:[1,0]
	v_pk_mul_f32 v[82:83], v[82:83], v[254:255] op_sel_hi:[1,0]
	v_pk_mul_f32 v[88:89], v[88:89], v[92:93]
	v_pk_mul_f32 v[90:91], v[90:91], v[94:95]
	v_pk_mul_f32 v[80:81], v[80:81], v[84:85]
	v_pk_mul_f32 v[82:83], v[82:83], v[86:87]
	v_cvt_pk_bf16_f32 v88, v88, v89
	v_cvt_pk_bf16_f32 v89, v90, v91
	v_cvt_pk_bf16_f32 v90, v80, v81
	v_cvt_pk_bf16_f32 v91, v82, v83
	global_store_dwordx4 v235, v[88:91], s[10:11]
	v_add_u32_e32 v234, 0x16000, v235
	v_mul_f32_e32 v252, 0xbfb8aa3b, v248
	v_mul_f32_e32 v254, v248, v248
	v_pk_mul_f32 v[72:73], v[76:77], v[72:73]
	v_pk_mul_f32 v[74:75], v[78:79], v[74:75]
	v_pk_mul_f32 v[64:65], v[68:69], v[64:65]
	v_pk_mul_f32 v[66:67], v[70:71], v[66:67]
	v_pk_mul_f32 v[76:77], v[76:77], v[252:253] op_sel_hi:[1,0]
	v_pk_mul_f32 v[78:79], v[78:79], v[252:253] op_sel_hi:[1,0]
	v_pk_mul_f32 v[68:69], v[68:69], v[252:253] op_sel_hi:[1,0]
	v_pk_mul_f32 v[70:71], v[70:71], v[252:253] op_sel_hi:[1,0]
	v_exp_f32_e32 v76, v76
	v_exp_f32_e32 v77, v77
	v_exp_f32_e32 v78, v78
	v_exp_f32_e32 v79, v79
	v_exp_f32_e32 v68, v68
	v_exp_f32_e32 v69, v69
	v_exp_f32_e32 v70, v70
	v_exp_f32_e32 v71, v71
	v_pk_add_f32 v[76:77], v[76:77], 1.0 op_sel_hi:[1,0]
	v_pk_add_f32 v[78:79], v[78:79], 1.0 op_sel_hi:[1,0]
	v_pk_add_f32 v[68:69], v[68:69], 1.0 op_sel_hi:[1,0]
	v_pk_add_f32 v[70:71], v[70:71], 1.0 op_sel_hi:[1,0]
	v_rcp_f32_e32 v76, v76
	v_rcp_f32_e32 v77, v77
	v_rcp_f32_e32 v78, v78
	v_rcp_f32_e32 v79, v79
	v_rcp_f32_e32 v68, v68
	v_rcp_f32_e32 v69, v69
	v_rcp_f32_e32 v70, v70
	v_rcp_f32_e32 v71, v71
	v_pk_mul_f32 v[72:73], v[72:73], v[254:255] op_sel_hi:[1,0]
	v_pk_mul_f32 v[74:75], v[74:75], v[254:255] op_sel_hi:[1,0]
	v_pk_mul_f32 v[64:65], v[64:65], v[254:255] op_sel_hi:[1,0]
	v_pk_mul_f32 v[66:67], v[66:67], v[254:255] op_sel_hi:[1,0]
	v_pk_mul_f32 v[72:73], v[72:73], v[76:77]
	v_pk_mul_f32 v[74:75], v[74:75], v[78:79]
	v_pk_mul_f32 v[64:65], v[64:65], v[68:69]
	v_pk_mul_f32 v[66:67], v[66:67], v[70:71]
	v_cvt_pk_bf16_f32 v72, v72, v73
	v_cvt_pk_bf16_f32 v73, v74, v75
	v_cvt_pk_bf16_f32 v74, v64, v65
	v_cvt_pk_bf16_f32 v75, v66, v67
	global_store_dwordx4 v234, v[72:75], s[10:11]
	s_waitcnt vmcnt(12)
	s_waitcnt lgkmcnt(0)
	s_barrier
	s_setprio 1
	s_waitcnt lgkmcnt(0)
	v_mfma_f32_16x16x32_bf16 v[60:63], v[160:163], v[194:197], v[60:63]
	v_mfma_f32_16x16x32_bf16 v[60:63], v[164:167], v[198:201], v[60:63]
	v_mfma_f32_16x16x32_bf16 v[52:55], v[172:175], v[198:201], v[52:55]
	v_mfma_f32_16x16x32_bf16 v[52:55], v[168:171], v[194:197], v[52:55]
	v_mfma_f32_16x16x32_bf16 v[36:39], v[168:171], v[202:205], v[36:39]
	v_mfma_f32_16x16x32_bf16 v[36:39], v[172:175], v[206:209], v[36:39]
	v_mfma_f32_16x16x32_bf16 v[44:47], v[164:167], v[206:209], v[44:47]
	v_mfma_f32_16x16x32_bf16 v[44:47], v[160:163], v[202:205], v[44:47]
	v_mfma_f32_16x16x32_bf16 v[28:31], v[160:163], v[210:213], v[28:31]
	v_mfma_f32_16x16x32_bf16 v[28:31], v[164:167], v[214:217], v[28:31]
	v_mfma_f32_16x16x32_bf16 v[20:23], v[172:175], v[214:217], v[20:23]
	v_mfma_f32_16x16x32_bf16 v[20:23], v[168:171], v[210:213], v[20:23]
	v_mfma_f32_16x16x32_bf16 v[4:7], v[168:171], v[218:221], v[4:7]
	v_mfma_f32_16x16x32_bf16 v[4:7], v[172:175], v[222:225], v[4:7]
	v_mfma_f32_16x16x32_bf16 v[12:15], v[164:167], v[222:225], v[12:15]
	v_mfma_f32_16x16x32_bf16 v[12:15], v[160:163], v[218:221], v[12:15]
	s_setprio 0
	s_setprio 1
	v_mfma_f32_16x16x32_bf16 v[56:59], v[176:179], v[194:197], v[56:59]
	v_mfma_f32_16x16x32_bf16 v[56:59], v[180:183], v[198:201], v[56:59]
	v_mfma_f32_16x16x32_bf16 v[48:51], v[190:193], v[198:201], v[48:51]
	v_mfma_f32_16x16x32_bf16 v[48:51], v[186:189], v[194:197], v[48:51]
	v_mfma_f32_16x16x32_bf16 v[32:35], v[186:189], v[202:205], v[32:35]
	v_mfma_f32_16x16x32_bf16 v[32:35], v[190:193], v[206:209], v[32:35]
	v_mfma_f32_16x16x32_bf16 v[40:43], v[180:183], v[206:209], v[40:43]
	v_mfma_f32_16x16x32_bf16 v[40:43], v[176:179], v[202:205], v[40:43]
	v_mfma_f32_16x16x32_bf16 v[24:27], v[176:179], v[210:213], v[24:27]
	v_mfma_f32_16x16x32_bf16 v[24:27], v[180:183], v[214:217], v[24:27]
	v_mfma_f32_16x16x32_bf16 v[16:19], v[190:193], v[214:217], v[16:19]
	v_mfma_f32_16x16x32_bf16 v[16:19], v[186:189], v[210:213], v[16:19]
	v_mfma_f32_16x16x32_bf16 v[0:3], v[186:189], v[218:221], v[0:3]
	v_mfma_f32_16x16x32_bf16 v[0:3], v[190:193], v[222:225], v[0:3]
	v_mfma_f32_16x16x32_bf16 v[8:11], v[180:183], v[222:225], v[8:11]
	v_mfma_f32_16x16x32_bf16 v[8:11], v[176:179], v[218:221], v[8:11]
	s_setprio 0
	s_barrier
	s_add_i32 s75, s75, 2
	s_add_u32 s71, s71, 0x100
	s_addc_u32 s74, s74, 0
	s_add_u32 s44, s44, 0x100
	s_addc_u32 s45, s45, 0

.LBB0_158:
	s_add_u32 s81, s56, 0x100
	s_addc_u32 s82, s57, 0
	s_mov_b32 s83, -2
	s_waitcnt lgkmcnt(0)
	s_cmp_eq_u32 s70, 1
	s_cbranch_scc1 .Lfa_1
	ds_read_b128 v[128:131], v189
	v_xor_b32_e32 v253, 64, v189
	ds_read_b128 v[132:135], v253
	ds_read_b128 v[136:139], v189 offset:2048
	ds_read_b128 v[140:143], v253 offset:2048
	ds_read_b128 v[144:147], v190
	v_xor_b32_e32 v253, 64, v190
	ds_read_b128 v[148:151], v253
	ds_read_b128 v[172:175], v190 offset:2048
	ds_read_b128 v[176:179], v253 offset:2048
	s_add_u32 s56, s54, 0x100
	s_addc_u32 s57, s55, 0
	s_cmp_eq_u32 s83, 40
	s_cselect_b32 s61, s15, s57
	s_cselect_b32 s60, s14, s56
	s_cselect_b32 s59, s53, s82
	s_cselect_b32 s58, s52, s81
	v_lshl_add_u64 v[222:223], s[54:55], 0, v[166:167]
	s_add_i32 m0, s66, 0xc000
	ds_read_b128 v[180:183], v191
	v_xor_b32_e32 v253, 64, v191
	ds_read_b128 v[194:197], v253
	ds_read_b128 v[198:201], v191 offset:2048
	ds_read_b128 v[202:205], v253 offset:2048
	ds_read_b128 v[206:209], v191 offset:4096
	ds_read_b128 v[210:213], v253 offset:4096
	ds_read_b128 v[214:217], v191 offset:6144
	ds_read_b128 v[218:221], v253 offset:6144
	global_load_lds_dwordx4 v[222:223], off
	v_lshl_add_u64 v[222:223], s[54:55], 0, v[164:165]
	s_add_i32 m0, s66, 0xe000
	s_nop 0
	global_load_lds_dwordx4 v[222:223], off
	s_waitcnt vmcnt(24)
	s_waitcnt lgkmcnt(0)
	s_barrier
	s_setprio 1
	s_waitcnt lgkmcnt(0)
	v_mfma_f32_16x16x32_bf16 v[124:127], v[128:131], v[180:183], 0
	v_mfma_f32_16x16x32_bf16 v[120:123], v[136:139], v[180:183], 0
	v_mfma_f32_16x16x32_bf16 v[108:111], v[128:131], v[198:201], 0
	v_mfma_f32_16x16x32_bf16 v[104:107], v[136:139], v[198:201], 0
	v_mfma_f32_16x16x32_bf16 v[92:95], v[128:131], v[206:209], 0
	v_mfma_f32_16x16x32_bf16 v[88:91], v[136:139], v[206:209], 0
	v_mfma_f32_16x16x32_bf16 v[76:79], v[128:131], v[214:217], 0
	v_mfma_f32_16x16x32_bf16 v[72:75], v[136:139], v[214:217], 0
	v_mfma_f32_16x16x32_bf16 v[124:127], v[132:135], v[194:197], v[124:127]
	v_mfma_f32_16x16x32_bf16 v[120:123], v[140:143], v[194:197], v[120:123]
	v_mfma_f32_16x16x32_bf16 v[108:111], v[132:135], v[202:205], v[108:111]
	v_mfma_f32_16x16x32_bf16 v[104:107], v[140:143], v[202:205], v[104:107]
	v_mfma_f32_16x16x32_bf16 v[92:95], v[132:135], v[210:213], v[92:95]
	v_mfma_f32_16x16x32_bf16 v[88:91], v[140:143], v[210:213], v[88:91]
	v_mfma_f32_16x16x32_bf16 v[76:79], v[132:135], v[218:221], v[76:79]
	v_mfma_f32_16x16x32_bf16 v[72:75], v[140:143], v[218:221], v[72:75]
	s_setprio 0
	s_setprio 1
	v_mfma_f32_16x16x32_bf16 v[116:119], v[144:147], v[180:183], 0
	v_mfma_f32_16x16x32_bf16 v[112:115], v[172:175], v[180:183], 0
	v_mfma_f32_16x16x32_bf16 v[100:103], v[144:147], v[198:201], 0
	v_mfma_f32_16x16x32_bf16 v[96:99], v[172:175], v[198:201], 0
	v_mfma_f32_16x16x32_bf16 v[84:87], v[144:147], v[206:209], 0
	v_mfma_f32_16x16x32_bf16 v[80:83], v[172:175], v[206:209], 0
	v_mfma_f32_16x16x32_bf16 v[68:71], v[144:147], v[214:217], 0
	v_mfma_f32_16x16x32_bf16 v[64:67], v[172:175], v[214:217], 0
	v_mfma_f32_16x16x32_bf16 v[116:119], v[148:151], v[194:197], v[116:119]
	v_mfma_f32_16x16x32_bf16 v[112:115], v[176:179], v[194:197], v[112:115]
	v_mfma_f32_16x16x32_bf16 v[100:103], v[148:151], v[202:205], v[100:103]
	v_mfma_f32_16x16x32_bf16 v[96:99], v[176:179], v[202:205], v[96:99]
	v_mfma_f32_16x16x32_bf16 v[84:87], v[148:151], v[210:213], v[84:87]
	v_mfma_f32_16x16x32_bf16 v[80:83], v[176:179], v[210:213], v[80:83]
	v_mfma_f32_16x16x32_bf16 v[68:71], v[148:151], v[218:221], v[68:71]
	v_mfma_f32_16x16x32_bf16 v[64:67], v[176:179], v[218:221], v[64:67]
	s_setprio 0
	s_barrier
	s_add_i32 s54, s77, s65
	v_lshl_add_u64 v[222:223], s[58:59], 0, v[154:155]
	s_mov_b32 m0, s54
	ds_read_b128 v[180:183], v191 offset:16384
	v_xor_b32_e32 v253, 64, v191
	ds_read_b128 v[194:197], v253 offset:16384
	ds_read_b128 v[198:201], v191 offset:18432
	ds_read_b128 v[202:205], v253 offset:18432
	ds_read_b128 v[206:209], v191 offset:20480
	ds_read_b128 v[210:213], v253 offset:20480
	ds_read_b128 v[214:217], v191 offset:22528
	ds_read_b128 v[218:221], v253 offset:22528
	global_load_lds_dwordx4 v[222:223], off
	s_add_i32 m0, s54, 0x2000
	s_add_u32 s54, s58, 0xb0000
	v_lshl_add_u64 v[224:225], s[58:59], 0, v[162:163]
	s_addc_u32 s55, s59, 0
	s_add_i32 s84, s78, s65
	global_load_lds_dwordx4 v[224:225], off
	v_lshl_add_u64 v[226:227], s[54:55], 0, v[154:155]
	s_mov_b32 m0, s84
	v_lshl_add_u64 v[228:229], s[60:61], 0, v[160:161]
	global_load_lds_dwordx4 v[226:227], off
	v_lshl_add_u64 v[226:227], s[54:55], 0, v[162:163]
	s_add_i32 m0, s84, 0x2000
	s_nop 0
	global_load_lds_dwordx4 v[226:227], off
	v_lshl_add_u64 v[226:227], s[60:61], 0, v[152:153]
	s_mov_b32 m0, s66
	s_nop 0
	global_load_lds_dwordx4 v[226:227], off
	s_mov_b32 m0, s67
	s_nop 0
	global_load_lds_dwordx4 v[228:229], off
	s_waitcnt vmcnt(24)
	s_waitcnt lgkmcnt(0)
	s_barrier
	s_setprio 1
	s_waitcnt lgkmcnt(0)
	v_mfma_f32_16x16x32_bf16 v[60:63], v[128:131], v[180:183], 0
	v_mfma_f32_16x16x32_bf16 v[56:59], v[136:139], v[180:183], 0
	v_mfma_f32_16x16x32_bf16 v[44:47], v[128:131], v[198:201], 0
	v_mfma_f32_16x16x32_bf16 v[40:43], v[136:139], v[198:201], 0
	v_mfma_f32_16x16x32_bf16 v[28:31], v[128:131], v[206:209], 0
	v_mfma_f32_16x16x32_bf16 v[24:27], v[136:139], v[206:209], 0
	v_mfma_f32_16x16x32_bf16 v[12:15], v[128:131], v[214:217], 0
	v_mfma_f32_16x16x32_bf16 v[8:11], v[136:139], v[214:217], 0
	v_mfma_f32_16x16x32_bf16 v[60:63], v[132:135], v[194:197], v[60:63]
	v_mfma_f32_16x16x32_bf16 v[56:59], v[140:143], v[194:197], v[56:59]
	v_mfma_f32_16x16x32_bf16 v[44:47], v[132:135], v[202:205], v[44:47]
	v_mfma_f32_16x16x32_bf16 v[40:43], v[140:143], v[202:205], v[40:43]
	v_mfma_f32_16x16x32_bf16 v[28:31], v[132:135], v[210:213], v[28:31]
	v_mfma_f32_16x16x32_bf16 v[24:27], v[140:143], v[210:213], v[24:27]
	v_mfma_f32_16x16x32_bf16 v[12:15], v[132:135], v[218:221], v[12:15]
	v_mfma_f32_16x16x32_bf16 v[8:11], v[140:143], v[218:221], v[8:11]
	s_setprio 0
	s_setprio 1
	v_mfma_f32_16x16x32_bf16 v[52:55], v[144:147], v[180:183], 0
	v_mfma_f32_16x16x32_bf16 v[48:51], v[172:175], v[180:183], 0
	v_mfma_f32_16x16x32_bf16 v[36:39], v[144:147], v[198:201], 0
	v_mfma_f32_16x16x32_bf16 v[32:35], v[172:175], v[198:201], 0
	v_mfma_f32_16x16x32_bf16 v[20:23], v[144:147], v[206:209], 0
	v_mfma_f32_16x16x32_bf16 v[16:19], v[172:175], v[206:209], 0
	v_mfma_f32_16x16x32_bf16 v[4:7], v[144:147], v[214:217], 0
	v_mfma_f32_16x16x32_bf16 v[0:3], v[172:175], v[214:217], 0
	v_mfma_f32_16x16x32_bf16 v[52:55], v[148:151], v[194:197], v[52:55]
	v_mfma_f32_16x16x32_bf16 v[48:51], v[176:179], v[194:197], v[48:51]
	v_mfma_f32_16x16x32_bf16 v[36:39], v[148:151], v[202:205], v[36:39]
	v_mfma_f32_16x16x32_bf16 v[32:35], v[176:179], v[202:205], v[32:35]
	v_mfma_f32_16x16x32_bf16 v[20:23], v[148:151], v[210:213], v[20:23]
	v_mfma_f32_16x16x32_bf16 v[16:19], v[176:179], v[210:213], v[16:19]
	v_mfma_f32_16x16x32_bf16 v[4:7], v[148:151], v[218:221], v[4:7]
	v_mfma_f32_16x16x32_bf16 v[0:3], v[176:179], v[218:221], v[0:3]
	s_setprio 0
	s_barrier
	s_add_i32 s84, 0, 0x18000
	s_add_i32 s85, 0, 0x1c000
	v_add_u32_e32 v140, s84, v186
	v_add_u32_e32 v176, s85, v186
	ds_read_b128 v[128:131], v140
	v_xor_b32_e32 v253, 64, v140
	ds_read_b128 v[132:135], v253
	ds_read_b128 v[136:139], v140 offset:2048
	ds_read_b128 v[140:143], v253 offset:2048
	ds_read_b128 v[144:147], v176
	v_xor_b32_e32 v253, 64, v176
	ds_read_b128 v[148:151], v253
	ds_read_b128 v[172:175], v176 offset:2048
	ds_read_b128 v[176:179], v253 offset:2048
	s_add_u32 s54, s60, 0xb0000
	s_addc_u32 s55, s61, 0
	s_mov_b32 m0, s68
	v_lshl_add_u64 v[230:231], s[54:55], 0, v[152:153]
	ds_read_b128 v[180:183], v191 offset:32768
	v_xor_b32_e32 v253, 64, v191
	ds_read_b128 v[194:197], v253 offset:32768
	ds_read_b128 v[198:201], v191 offset:34816
	ds_read_b128 v[202:205], v253 offset:34816
	ds_read_b128 v[206:209], v191 offset:36864
	ds_read_b128 v[210:213], v253 offset:36864
	ds_read_b128 v[214:217], v191 offset:38912
	ds_read_b128 v[218:221], v253 offset:38912
	global_load_lds_dwordx4 v[230:231], off
	v_lshl_add_u64 v[230:231], s[54:55], 0, v[160:161]
	s_mov_b32 m0, s69
	s_nop 0
	global_load_lds_dwordx4 v[230:231], off
	s_waitcnt vmcnt(8)
	s_waitcnt lgkmcnt(0)
	s_barrier
	s_setprio 1
	s_waitcnt lgkmcnt(0)
	v_mfma_f32_16x16x32_bf16 v[124:127], v[128:131], v[180:183], v[124:127]
	v_mfma_f32_16x16x32_bf16 v[124:127], v[132:135], v[194:197], v[124:127]
	v_mfma_f32_16x16x32_bf16 v[120:123], v[140:143], v[194:197], v[120:123]
	v_mfma_f32_16x16x32_bf16 v[120:123], v[136:139], v[180:183], v[120:123]
	v_mfma_f32_16x16x32_bf16 v[104:107], v[136:139], v[198:201], v[104:107]
	v_mfma_f32_16x16x32_bf16 v[104:107], v[140:143], v[202:205], v[104:107]
	v_mfma_f32_16x16x32_bf16 v[108:111], v[132:135], v[202:205], v[108:111]
	v_mfma_f32_16x16x32_bf16 v[108:111], v[128:131], v[198:201], v[108:111]
	v_mfma_f32_16x16x32_bf16 v[92:95], v[128:131], v[206:209], v[92:95]
	v_mfma_f32_16x16x32_bf16 v[92:95], v[132:135], v[210:213], v[92:95]
	v_mfma_f32_16x16x32_bf16 v[88:91], v[140:143], v[210:213], v[88:91]
	v_mfma_f32_16x16x32_bf16 v[88:91], v[136:139], v[206:209], v[88:91]
	v_mfma_f32_16x16x32_bf16 v[72:75], v[136:139], v[214:217], v[72:75]
	v_mfma_f32_16x16x32_bf16 v[72:75], v[140:143], v[218:221], v[72:75]
	v_mfma_f32_16x16x32_bf16 v[76:79], v[132:135], v[218:221], v[76:79]
	v_mfma_f32_16x16x32_bf16 v[76:79], v[128:131], v[214:217], v[76:79]
	s_setprio 0
	s_setprio 1
	v_mfma_f32_16x16x32_bf16 v[116:119], v[144:147], v[180:183], v[116:119]
	v_mfma_f32_16x16x32_bf16 v[116:119], v[148:151], v[194:197], v[116:119]
	v_mfma_f32_16x16x32_bf16 v[112:115], v[176:179], v[194:197], v[112:115]
	v_mfma_f32_16x16x32_bf16 v[112:115], v[172:175], v[180:183], v[112:115]
	v_mfma_f32_16x16x32_bf16 v[96:99], v[172:175], v[198:201], v[96:99]
	v_mfma_f32_16x16x32_bf16 v[96:99], v[176:179], v[202:205], v[96:99]
	v_mfma_f32_16x16x32_bf16 v[100:103], v[148:151], v[202:205], v[100:103]
	v_mfma_f32_16x16x32_bf16 v[100:103], v[144:147], v[198:201], v[100:103]
	v_mfma_f32_16x16x32_bf16 v[84:87], v[144:147], v[206:209], v[84:87]
	v_mfma_f32_16x16x32_bf16 v[84:87], v[148:151], v[210:213], v[84:87]
	v_mfma_f32_16x16x32_bf16 v[80:83], v[176:179], v[210:213], v[80:83]
	v_mfma_f32_16x16x32_bf16 v[80:83], v[172:175], v[206:209], v[80:83]
	v_mfma_f32_16x16x32_bf16 v[64:67], v[172:175], v[214:217], v[64:67]
	v_mfma_f32_16x16x32_bf16 v[64:67], v[176:179], v[218:221], v[64:67]
	v_mfma_f32_16x16x32_bf16 v[68:71], v[148:151], v[218:221], v[68:71]
	v_mfma_f32_16x16x32_bf16 v[68:71], v[144:147], v[214:217], v[68:71]
	s_setprio 0
	s_barrier
	s_add_i32 s54, s84, s65
	v_lshl_add_u64 v[222:223], v[222:223], 0, s[28:29]
	s_mov_b32 m0, s54
	ds_read_b128 v[180:183], v191 offset:49152
	v_xor_b32_e32 v253, 64, v191
	ds_read_b128 v[194:197], v253 offset:49152
	ds_read_b128 v[198:201], v191 offset:51200
	ds_read_b128 v[202:205], v253 offset:51200
	ds_read_b128 v[206:209], v191 offset:53248
	ds_read_b128 v[210:213], v253 offset:53248
	ds_read_b128 v[214:217], v191 offset:55296
	ds_read_b128 v[218:221], v253 offset:55296
	global_load_lds_dwordx4 v[222:223], off
	s_add_i32 m0, s54, 0x2000
	s_add_u32 s54, s58, 0xb0080
	v_lshl_add_u64 v[222:223], v[224:225], 0, s[28:29]
	s_addc_u32 s55, s59, 0
	s_add_i32 s58, s85, s65
	global_load_lds_dwordx4 v[222:223], off
	v_lshl_add_u64 v[222:223], s[54:55], 0, v[154:155]
	s_mov_b32 m0, s58
	s_nop 0
	global_load_lds_dwordx4 v[222:223], off
	v_lshl_add_u64 v[222:223], s[54:55], 0, v[162:163]
	s_add_i32 m0, s58, 0x2000
	s_nop 0
	global_load_lds_dwordx4 v[222:223], off
	v_lshl_add_u64 v[222:223], v[226:227], 0, s[28:29]
	s_mov_b32 m0, s3
	s_nop 0
	global_load_lds_dwordx4 v[222:223], off
	v_lshl_add_u64 v[222:223], v[228:229], 0, s[28:29]
	s_mov_b32 m0, s71
	s_nop 0
	global_load_lds_dwordx4 v[222:223], off
	s_waitcnt vmcnt(8)
	s_waitcnt lgkmcnt(0)
	s_barrier
	s_setprio 1
	s_waitcnt lgkmcnt(0)
	v_mfma_f32_16x16x32_bf16 v[60:63], v[128:131], v[180:183], v[60:63]
	v_mfma_f32_16x16x32_bf16 v[60:63], v[132:135], v[194:197], v[60:63]
	v_mfma_f32_16x16x32_bf16 v[56:59], v[140:143], v[194:197], v[56:59]
	v_mfma_f32_16x16x32_bf16 v[56:59], v[136:139], v[180:183], v[56:59]
	v_mfma_f32_16x16x32_bf16 v[40:43], v[136:139], v[198:201], v[40:43]
	v_mfma_f32_16x16x32_bf16 v[40:43], v[140:143], v[202:205], v[40:43]
	v_mfma_f32_16x16x32_bf16 v[44:47], v[132:135], v[202:205], v[44:47]
	v_mfma_f32_16x16x32_bf16 v[44:47], v[128:131], v[198:201], v[44:47]
	v_mfma_f32_16x16x32_bf16 v[28:31], v[128:131], v[206:209], v[28:31]
	v_mfma_f32_16x16x32_bf16 v[28:31], v[132:135], v[210:213], v[28:31]
	v_mfma_f32_16x16x32_bf16 v[24:27], v[140:143], v[210:213], v[24:27]
	v_mfma_f32_16x16x32_bf16 v[24:27], v[136:139], v[206:209], v[24:27]
	v_mfma_f32_16x16x32_bf16 v[8:11], v[136:139], v[214:217], v[8:11]
	v_mfma_f32_16x16x32_bf16 v[8:11], v[140:143], v[218:221], v[8:11]
	v_mfma_f32_16x16x32_bf16 v[12:15], v[132:135], v[218:221], v[12:15]
	v_mfma_f32_16x16x32_bf16 v[12:15], v[128:131], v[214:217], v[12:15]
	s_setprio 0
	s_setprio 1
	v_mfma_f32_16x16x32_bf16 v[52:55], v[144:147], v[180:183], v[52:55]
	v_mfma_f32_16x16x32_bf16 v[52:55], v[148:151], v[194:197], v[52:55]
	v_mfma_f32_16x16x32_bf16 v[48:51], v[176:179], v[194:197], v[48:51]
	v_mfma_f32_16x16x32_bf16 v[48:51], v[172:175], v[180:183], v[48:51]
	v_mfma_f32_16x16x32_bf16 v[32:35], v[172:175], v[198:201], v[32:35]
	v_mfma_f32_16x16x32_bf16 v[32:35], v[176:179], v[202:205], v[32:35]
	v_mfma_f32_16x16x32_bf16 v[36:39], v[148:151], v[202:205], v[36:39]
	v_mfma_f32_16x16x32_bf16 v[36:39], v[144:147], v[198:201], v[36:39]
	v_mfma_f32_16x16x32_bf16 v[20:23], v[144:147], v[206:209], v[20:23]
	v_mfma_f32_16x16x32_bf16 v[20:23], v[148:151], v[210:213], v[20:23]
	v_mfma_f32_16x16x32_bf16 v[16:19], v[176:179], v[210:213], v[16:19]
	v_mfma_f32_16x16x32_bf16 v[16:19], v[172:175], v[206:209], v[16:19]
	v_mfma_f32_16x16x32_bf16 v[0:3], v[172:175], v[214:217], v[0:3]
	v_mfma_f32_16x16x32_bf16 v[0:3], v[176:179], v[218:221], v[0:3]
	v_mfma_f32_16x16x32_bf16 v[4:7], v[148:151], v[218:221], v[4:7]
	v_mfma_f32_16x16x32_bf16 v[4:7], v[144:147], v[214:217], v[4:7]
	s_setprio 0
	s_barrier
	s_add_i32 s83, s83, 2
	s_add_u32 s81, s81, 0x100
	s_addc_u32 s82, s82, 0
	s_cmp_gt_u32 s83, 41
	s_mov_b64 s[54:55], s[56:57]
	s_branch .LBB0_159
.Lfa_1:
	ds_read_b128 v[128:131], v189
	v_xor_b32_e32 v253, 64, v189
	ds_read_b128 v[132:135], v253
	ds_read_b128 v[136:139], v189 offset:2048
	ds_read_b128 v[140:143], v253 offset:2048
	ds_read_b128 v[144:147], v190
	v_xor_b32_e32 v253, 64, v190
	ds_read_b128 v[148:151], v253
	ds_read_b128 v[172:175], v190 offset:2048
	ds_read_b128 v[176:179], v253 offset:2048
	s_add_u32 s56, s54, 0x100
	s_addc_u32 s57, s55, 0
	s_cmp_eq_u32 s83, 40
	s_cselect_b32 s61, s15, s57
	s_cselect_b32 s60, s14, s56
	s_cselect_b32 s59, s53, s82
	s_cselect_b32 s58, s52, s81
	v_lshl_add_u64 v[222:223], s[54:55], 0, v[166:167]
	s_add_i32 m0, s66, 0xc000
	ds_read_b128 v[180:183], v191
	v_xor_b32_e32 v253, 64, v191
	ds_read_b128 v[194:197], v253
	ds_read_b128 v[198:201], v191 offset:2048
	ds_read_b128 v[202:205], v253 offset:2048
	ds_read_b128 v[206:209], v191 offset:4096
	ds_read_b128 v[210:213], v253 offset:4096
	ds_read_b128 v[214:217], v191 offset:6144
	ds_read_b128 v[218:221], v253 offset:6144
	global_load_lds_dwordx4 v[222:223], off
	v_lshl_add_u64 v[222:223], s[54:55], 0, v[164:165]
	s_add_i32 m0, s66, 0xe000
	s_nop 0
	global_load_lds_dwordx4 v[222:223], off
	s_waitcnt vmcnt(8)
	s_waitcnt lgkmcnt(0)
	s_barrier
	s_setprio 1
	s_waitcnt lgkmcnt(0)
	v_mfma_f32_16x16x32_bf16 v[124:127], v[128:131], v[180:183], 0
	v_mfma_f32_16x16x32_bf16 v[120:123], v[136:139], v[180:183], 0
	v_mfma_f32_16x16x32_bf16 v[108:111], v[128:131], v[198:201], 0
	v_mfma_f32_16x16x32_bf16 v[104:107], v[136:139], v[198:201], 0
	v_mfma_f32_16x16x32_bf16 v[92:95], v[128:131], v[206:209], 0
	v_mfma_f32_16x16x32_bf16 v[88:91], v[136:139], v[206:209], 0
	v_mfma_f32_16x16x32_bf16 v[76:79], v[128:131], v[214:217], 0
	v_mfma_f32_16x16x32_bf16 v[72:75], v[136:139], v[214:217], 0
	v_mfma_f32_16x16x32_bf16 v[124:127], v[132:135], v[194:197], v[124:127]
	v_mfma_f32_16x16x32_bf16 v[120:123], v[140:143], v[194:197], v[120:123]
	v_mfma_f32_16x16x32_bf16 v[108:111], v[132:135], v[202:205], v[108:111]
	v_mfma_f32_16x16x32_bf16 v[104:107], v[140:143], v[202:205], v[104:107]
	v_mfma_f32_16x16x32_bf16 v[92:95], v[132:135], v[210:213], v[92:95]
	v_mfma_f32_16x16x32_bf16 v[88:91], v[140:143], v[210:213], v[88:91]
	v_mfma_f32_16x16x32_bf16 v[76:79], v[132:135], v[218:221], v[76:79]
	v_mfma_f32_16x16x32_bf16 v[72:75], v[140:143], v[218:221], v[72:75]
	s_setprio 0
	s_setprio 1
	v_mfma_f32_16x16x32_bf16 v[116:119], v[144:147], v[180:183], 0
	v_mfma_f32_16x16x32_bf16 v[112:115], v[172:175], v[180:183], 0
	v_mfma_f32_16x16x32_bf16 v[100:103], v[144:147], v[198:201], 0
	v_mfma_f32_16x16x32_bf16 v[96:99], v[172:175], v[198:201], 0
	v_mfma_f32_16x16x32_bf16 v[84:87], v[144:147], v[206:209], 0
	v_mfma_f32_16x16x32_bf16 v[80:83], v[172:175], v[206:209], 0
	v_mfma_f32_16x16x32_bf16 v[68:71], v[144:147], v[214:217], 0
	v_mfma_f32_16x16x32_bf16 v[64:67], v[172:175], v[214:217], 0
	v_mfma_f32_16x16x32_bf16 v[116:119], v[148:151], v[194:197], v[116:119]
	v_mfma_f32_16x16x32_bf16 v[112:115], v[176:179], v[194:197], v[112:115]
	v_mfma_f32_16x16x32_bf16 v[100:103], v[148:151], v[202:205], v[100:103]
	v_mfma_f32_16x16x32_bf16 v[96:99], v[176:179], v[202:205], v[96:99]
	v_mfma_f32_16x16x32_bf16 v[84:87], v[148:151], v[210:213], v[84:87]
	v_mfma_f32_16x16x32_bf16 v[80:83], v[176:179], v[210:213], v[80:83]
	v_mfma_f32_16x16x32_bf16 v[68:71], v[148:151], v[218:221], v[68:71]
	v_mfma_f32_16x16x32_bf16 v[64:67], v[176:179], v[218:221], v[64:67]
	s_setprio 0
	s_barrier
	s_add_i32 s54, s77, s65
	v_lshl_add_u64 v[222:223], s[58:59], 0, v[154:155]
	s_mov_b32 m0, s54
	ds_read_b128 v[180:183], v191 offset:16384
	v_xor_b32_e32 v253, 64, v191
	ds_read_b128 v[194:197], v253 offset:16384
	ds_read_b128 v[198:201], v191 offset:18432
	ds_read_b128 v[202:205], v253 offset:18432
	ds_read_b128 v[206:209], v191 offset:20480
	ds_read_b128 v[210:213], v253 offset:20480
	ds_read_b128 v[214:217], v191 offset:22528
	ds_read_b128 v[218:221], v253 offset:22528
	global_load_lds_dwordx4 v[222:223], off
	s_add_i32 m0, s54, 0x2000
	s_add_u32 s54, s58, 0xb0000
	v_lshl_add_u64 v[224:225], s[58:59], 0, v[162:163]
	s_addc_u32 s55, s59, 0
	s_add_i32 s84, s78, s65
	global_load_lds_dwordx4 v[224:225], off
	v_lshl_add_u64 v[226:227], s[54:55], 0, v[154:155]
	s_mov_b32 m0, s84
	v_lshl_add_u64 v[228:229], s[60:61], 0, v[160:161]
	global_load_lds_dwordx4 v[226:227], off
	v_lshl_add_u64 v[226:227], s[54:55], 0, v[162:163]
	s_add_i32 m0, s84, 0x2000
	s_nop 0
	global_load_lds_dwordx4 v[226:227], off
	v_lshl_add_u64 v[226:227], s[60:61], 0, v[152:153]
	s_mov_b32 m0, s66
	s_nop 0
	global_load_lds_dwordx4 v[226:227], off
	s_mov_b32 m0, s67
	s_nop 0
	global_load_lds_dwordx4 v[228:229], off
	s_waitcnt vmcnt(8)
	s_waitcnt lgkmcnt(0)
	s_barrier
	s_setprio 1
	s_waitcnt lgkmcnt(0)
	v_mfma_f32_16x16x32_bf16 v[60:63], v[128:131], v[180:183], 0
	v_mfma_f32_16x16x32_bf16 v[56:59], v[136:139], v[180:183], 0
	v_mfma_f32_16x16x32_bf16 v[44:47], v[128:131], v[198:201], 0
	v_mfma_f32_16x16x32_bf16 v[40:43], v[136:139], v[198:201], 0
	v_mfma_f32_16x16x32_bf16 v[28:31], v[128:131], v[206:209], 0
	v_mfma_f32_16x16x32_bf16 v[24:27], v[136:139], v[206:209], 0
	v_mfma_f32_16x16x32_bf16 v[12:15], v[128:131], v[214:217], 0
	v_mfma_f32_16x16x32_bf16 v[8:11], v[136:139], v[214:217], 0
	v_mfma_f32_16x16x32_bf16 v[60:63], v[132:135], v[194:197], v[60:63]
	v_mfma_f32_16x16x32_bf16 v[56:59], v[140:143], v[194:197], v[56:59]
	v_mfma_f32_16x16x32_bf16 v[44:47], v[132:135], v[202:205], v[44:47]
	v_mfma_f32_16x16x32_bf16 v[40:43], v[140:143], v[202:205], v[40:43]
	v_mfma_f32_16x16x32_bf16 v[28:31], v[132:135], v[210:213], v[28:31]
	v_mfma_f32_16x16x32_bf16 v[24:27], v[140:143], v[210:213], v[24:27]
	v_mfma_f32_16x16x32_bf16 v[12:15], v[132:135], v[218:221], v[12:15]
	v_mfma_f32_16x16x32_bf16 v[8:11], v[140:143], v[218:221], v[8:11]
	s_setprio 0
	s_setprio 1
	v_mfma_f32_16x16x32_bf16 v[52:55], v[144:147], v[180:183], 0
	v_mfma_f32_16x16x32_bf16 v[48:51], v[172:175], v[180:183], 0
	v_mfma_f32_16x16x32_bf16 v[36:39], v[144:147], v[198:201], 0
	v_mfma_f32_16x16x32_bf16 v[32:35], v[172:175], v[198:201], 0
	v_mfma_f32_16x16x32_bf16 v[20:23], v[144:147], v[206:209], 0
	v_mfma_f32_16x16x32_bf16 v[16:19], v[172:175], v[206:209], 0
	v_mfma_f32_16x16x32_bf16 v[4:7], v[144:147], v[214:217], 0
	v_mfma_f32_16x16x32_bf16 v[0:3], v[172:175], v[214:217], 0
	v_mfma_f32_16x16x32_bf16 v[52:55], v[148:151], v[194:197], v[52:55]
	v_mfma_f32_16x16x32_bf16 v[48:51], v[176:179], v[194:197], v[48:51]
	v_mfma_f32_16x16x32_bf16 v[36:39], v[148:151], v[202:205], v[36:39]
	v_mfma_f32_16x16x32_bf16 v[32:35], v[176:179], v[202:205], v[32:35]
	v_mfma_f32_16x16x32_bf16 v[20:23], v[148:151], v[210:213], v[20:23]
	v_mfma_f32_16x16x32_bf16 v[16:19], v[176:179], v[210:213], v[16:19]
	v_mfma_f32_16x16x32_bf16 v[4:7], v[148:151], v[218:221], v[4:7]
	v_mfma_f32_16x16x32_bf16 v[0:3], v[176:179], v[218:221], v[0:3]
	s_setprio 0
	s_barrier
	s_add_i32 s84, 0, 0x18000
	s_add_i32 s85, 0, 0x1c000
	v_add_u32_e32 v140, s84, v186
	v_add_u32_e32 v176, s85, v186
	ds_read_b128 v[128:131], v140
	v_xor_b32_e32 v253, 64, v140
	ds_read_b128 v[132:135], v253
	ds_read_b128 v[136:139], v140 offset:2048
	ds_read_b128 v[140:143], v253 offset:2048
	ds_read_b128 v[144:147], v176
	v_xor_b32_e32 v253, 64, v176
	ds_read_b128 v[148:151], v253
	ds_read_b128 v[172:175], v176 offset:2048
	ds_read_b128 v[176:179], v253 offset:2048
	s_add_u32 s54, s60, 0xb0000
	s_addc_u32 s55, s61, 0
	s_mov_b32 m0, s68
	v_lshl_add_u64 v[230:231], s[54:55], 0, v[152:153]
	ds_read_b128 v[180:183], v191 offset:32768
	v_xor_b32_e32 v253, 64, v191
	ds_read_b128 v[194:197], v253 offset:32768
	ds_read_b128 v[198:201], v191 offset:34816
	ds_read_b128 v[202:205], v253 offset:34816
	ds_read_b128 v[206:209], v191 offset:36864
	ds_read_b128 v[210:213], v253 offset:36864
	ds_read_b128 v[214:217], v191 offset:38912
	ds_read_b128 v[218:221], v253 offset:38912
	global_load_lds_dwordx4 v[230:231], off
	v_lshl_add_u64 v[230:231], s[54:55], 0, v[160:161]
	s_mov_b32 m0, s69
	s_nop 0
	global_load_lds_dwordx4 v[230:231], off
	s_waitcnt vmcnt(8)
	s_waitcnt lgkmcnt(0)
	s_barrier
	s_setprio 1
	s_waitcnt lgkmcnt(0)
	v_mfma_f32_16x16x32_bf16 v[124:127], v[128:131], v[180:183], v[124:127]
	v_mfma_f32_16x16x32_bf16 v[124:127], v[132:135], v[194:197], v[124:127]
	v_mfma_f32_16x16x32_bf16 v[120:123], v[140:143], v[194:197], v[120:123]
	v_mfma_f32_16x16x32_bf16 v[120:123], v[136:139], v[180:183], v[120:123]
	v_mfma_f32_16x16x32_bf16 v[104:107], v[136:139], v[198:201], v[104:107]
	v_mfma_f32_16x16x32_bf16 v[104:107], v[140:143], v[202:205], v[104:107]
	v_mfma_f32_16x16x32_bf16 v[108:111], v[132:135], v[202:205], v[108:111]
	v_mfma_f32_16x16x32_bf16 v[108:111], v[128:131], v[198:201], v[108:111]
	v_mfma_f32_16x16x32_bf16 v[92:95], v[128:131], v[206:209], v[92:95]
	v_mfma_f32_16x16x32_bf16 v[92:95], v[132:135], v[210:213], v[92:95]
	v_mfma_f32_16x16x32_bf16 v[88:91], v[140:143], v[210:213], v[88:91]
	v_mfma_f32_16x16x32_bf16 v[88:91], v[136:139], v[206:209], v[88:91]
	v_mfma_f32_16x16x32_bf16 v[72:75], v[136:139], v[214:217], v[72:75]
	v_mfma_f32_16x16x32_bf16 v[72:75], v[140:143], v[218:221], v[72:75]
	v_mfma_f32_16x16x32_bf16 v[76:79], v[132:135], v[218:221], v[76:79]
	v_mfma_f32_16x16x32_bf16 v[76:79], v[128:131], v[214:217], v[76:79]
	s_setprio 0
	s_setprio 1
	v_mfma_f32_16x16x32_bf16 v[116:119], v[144:147], v[180:183], v[116:119]
	v_mfma_f32_16x16x32_bf16 v[116:119], v[148:151], v[194:197], v[116:119]
	v_mfma_f32_16x16x32_bf16 v[112:115], v[176:179], v[194:197], v[112:115]
	v_mfma_f32_16x16x32_bf16 v[112:115], v[172:175], v[180:183], v[112:115]
	v_mfma_f32_16x16x32_bf16 v[96:99], v[172:175], v[198:201], v[96:99]
	v_mfma_f32_16x16x32_bf16 v[96:99], v[176:179], v[202:205], v[96:99]
	v_mfma_f32_16x16x32_bf16 v[100:103], v[148:151], v[202:205], v[100:103]
	v_mfma_f32_16x16x32_bf16 v[100:103], v[144:147], v[198:201], v[100:103]
	v_mfma_f32_16x16x32_bf16 v[84:87], v[144:147], v[206:209], v[84:87]
	v_mfma_f32_16x16x32_bf16 v[84:87], v[148:151], v[210:213], v[84:87]
	v_mfma_f32_16x16x32_bf16 v[80:83], v[176:179], v[210:213], v[80:83]
	v_mfma_f32_16x16x32_bf16 v[80:83], v[172:175], v[206:209], v[80:83]
	v_mfma_f32_16x16x32_bf16 v[64:67], v[172:175], v[214:217], v[64:67]
	v_mfma_f32_16x16x32_bf16 v[64:67], v[176:179], v[218:221], v[64:67]
	v_mfma_f32_16x16x32_bf16 v[68:71], v[148:151], v[218:221], v[68:71]
	v_mfma_f32_16x16x32_bf16 v[68:71], v[144:147], v[214:217], v[68:71]
	s_setprio 0
	s_barrier
	s_add_i32 s54, s84, s65
	v_lshl_add_u64 v[222:223], v[222:223], 0, s[28:29]
	s_mov_b32 m0, s54
	ds_read_b128 v[180:183], v191 offset:49152
	v_xor_b32_e32 v253, 64, v191
	ds_read_b128 v[194:197], v253 offset:49152
	ds_read_b128 v[198:201], v191 offset:51200
	ds_read_b128 v[202:205], v253 offset:51200
	ds_read_b128 v[206:209], v191 offset:53248
	ds_read_b128 v[210:213], v253 offset:53248
	ds_read_b128 v[214:217], v191 offset:55296
	ds_read_b128 v[218:221], v253 offset:55296
	global_load_lds_dwordx4 v[222:223], off
	s_add_i32 m0, s54, 0x2000
	s_add_u32 s54, s58, 0xb0080
	v_lshl_add_u64 v[222:223], v[224:225], 0, s[28:29]
	s_addc_u32 s55, s59, 0
	s_add_i32 s58, s85, s65
	global_load_lds_dwordx4 v[222:223], off
	v_lshl_add_u64 v[222:223], s[54:55], 0, v[154:155]
	s_mov_b32 m0, s58
	s_nop 0
	global_load_lds_dwordx4 v[222:223], off
	v_lshl_add_u64 v[222:223], s[54:55], 0, v[162:163]
	s_add_i32 m0, s58, 0x2000
	s_nop 0
	global_load_lds_dwordx4 v[222:223], off
	v_lshl_add_u64 v[222:223], v[226:227], 0, s[28:29]
	s_mov_b32 m0, s3
	s_nop 0
	global_load_lds_dwordx4 v[222:223], off
	v_lshl_add_u64 v[222:223], v[228:229], 0, s[28:29]
	s_mov_b32 m0, s71
	s_nop 0
	global_load_lds_dwordx4 v[222:223], off
	s_waitcnt vmcnt(8)
	s_waitcnt lgkmcnt(0)
	s_barrier
	s_setprio 1
	s_waitcnt lgkmcnt(0)
	v_mfma_f32_16x16x32_bf16 v[60:63], v[128:131], v[180:183], v[60:63]
	v_mfma_f32_16x16x32_bf16 v[60:63], v[132:135], v[194:197], v[60:63]
	v_mfma_f32_16x16x32_bf16 v[56:59], v[140:143], v[194:197], v[56:59]
	v_mfma_f32_16x16x32_bf16 v[56:59], v[136:139], v[180:183], v[56:59]
	v_mfma_f32_16x16x32_bf16 v[40:43], v[136:139], v[198:201], v[40:43]
	v_mfma_f32_16x16x32_bf16 v[40:43], v[140:143], v[202:205], v[40:43]
	v_mfma_f32_16x16x32_bf16 v[44:47], v[132:135], v[202:205], v[44:47]
	v_mfma_f32_16x16x32_bf16 v[44:47], v[128:131], v[198:201], v[44:47]
	v_mfma_f32_16x16x32_bf16 v[28:31], v[128:131], v[206:209], v[28:31]
	v_mfma_f32_16x16x32_bf16 v[28:31], v[132:135], v[210:213], v[28:31]
	v_mfma_f32_16x16x32_bf16 v[24:27], v[140:143], v[210:213], v[24:27]
	v_mfma_f32_16x16x32_bf16 v[24:27], v[136:139], v[206:209], v[24:27]
	v_mfma_f32_16x16x32_bf16 v[8:11], v[136:139], v[214:217], v[8:11]
	v_mfma_f32_16x16x32_bf16 v[8:11], v[140:143], v[218:221], v[8:11]
	v_mfma_f32_16x16x32_bf16 v[12:15], v[132:135], v[218:221], v[12:15]
	v_mfma_f32_16x16x32_bf16 v[12:15], v[128:131], v[214:217], v[12:15]
	s_setprio 0
	s_setprio 1
	v_mfma_f32_16x16x32_bf16 v[52:55], v[144:147], v[180:183], v[52:55]
	v_mfma_f32_16x16x32_bf16 v[52:55], v[148:151], v[194:197], v[52:55]
	v_mfma_f32_16x16x32_bf16 v[48:51], v[176:179], v[194:197], v[48:51]
	v_mfma_f32_16x16x32_bf16 v[48:51], v[172:175], v[180:183], v[48:51]
	v_mfma_f32_16x16x32_bf16 v[32:35], v[172:175], v[198:201], v[32:35]
	v_mfma_f32_16x16x32_bf16 v[32:35], v[176:179], v[202:205], v[32:35]
	v_mfma_f32_16x16x32_bf16 v[36:39], v[148:151], v[202:205], v[36:39]
	v_mfma_f32_16x16x32_bf16 v[36:39], v[144:147], v[198:201], v[36:39]
	v_mfma_f32_16x16x32_bf16 v[20:23], v[144:147], v[206:209], v[20:23]
	v_mfma_f32_16x16x32_bf16 v[20:23], v[148:151], v[210:213], v[20:23]
	v_mfma_f32_16x16x32_bf16 v[16:19], v[176:179], v[210:213], v[16:19]
	v_mfma_f32_16x16x32_bf16 v[16:19], v[172:175], v[206:209], v[16:19]
	v_mfma_f32_16x16x32_bf16 v[0:3], v[172:175], v[214:217], v[0:3]
	v_mfma_f32_16x16x32_bf16 v[0:3], v[176:179], v[218:221], v[0:3]
	v_mfma_f32_16x16x32_bf16 v[4:7], v[148:151], v[218:221], v[4:7]
	v_mfma_f32_16x16x32_bf16 v[4:7], v[144:147], v[214:217], v[4:7]
	s_setprio 0
	s_barrier
	s_add_i32 s83, s83, 2
	s_add_u32 s81, s81, 0x100
	s_addc_u32 s82, s82, 0
	s_cmp_gt_u32 s83, 41
	s_mov_b64 s[54:55], s[56:57]
.LBB0_159:
	ds_read_b128 v[128:131], v189
	v_xor_b32_e32 v253, 64, v189
	ds_read_b128 v[132:135], v253
	ds_read_b128 v[136:139], v189 offset:2048
	ds_read_b128 v[140:143], v253 offset:2048
	ds_read_b128 v[144:147], v190
	v_xor_b32_e32 v253, 64, v190
	ds_read_b128 v[148:151], v253
	ds_read_b128 v[172:175], v190 offset:2048
	ds_read_b128 v[176:179], v253 offset:2048
	s_add_u32 s56, s54, 0x100
	s_addc_u32 s57, s55, 0
	s_cmp_eq_u32 s83, 40
	s_cselect_b32 s61, s15, s57
	s_cselect_b32 s60, s14, s56
	s_cselect_b32 s59, s53, s82
	s_cselect_b32 s58, s52, s81
	v_lshl_add_u64 v[222:223], s[54:55], 0, v[166:167]
	s_add_i32 m0, s66, 0xc000
	ds_read_b128 v[180:183], v191
	v_xor_b32_e32 v253, 64, v191
	ds_read_b128 v[194:197], v253
	ds_read_b128 v[198:201], v191 offset:2048
	ds_read_b128 v[202:205], v253 offset:2048
	ds_read_b128 v[206:209], v191 offset:4096
	ds_read_b128 v[210:213], v253 offset:4096
	ds_read_b128 v[214:217], v191 offset:6144
	ds_read_b128 v[218:221], v253 offset:6144
	global_load_lds_dwordx4 v[222:223], off
	v_lshl_add_u64 v[222:223], s[54:55], 0, v[164:165]
	s_add_i32 m0, s66, 0xe000
	s_nop 0
	global_load_lds_dwordx4 v[222:223], off
	s_waitcnt vmcnt(8)
	s_waitcnt lgkmcnt(0)
	s_barrier
	s_setprio 1
	s_waitcnt lgkmcnt(0)
	v_mfma_f32_16x16x32_bf16 v[124:127], v[128:131], v[180:183], v[124:127]
	v_mfma_f32_16x16x32_bf16 v[124:127], v[132:135], v[194:197], v[124:127]
	v_mfma_f32_16x16x32_bf16 v[120:123], v[140:143], v[194:197], v[120:123]
	v_mfma_f32_16x16x32_bf16 v[120:123], v[136:139], v[180:183], v[120:123]
	v_mfma_f32_16x16x32_bf16 v[104:107], v[136:139], v[198:201], v[104:107]
	v_mfma_f32_16x16x32_bf16 v[104:107], v[140:143], v[202:205], v[104:107]
	v_mfma_f32_16x16x32_bf16 v[108:111], v[132:135], v[202:205], v[108:111]
	v_mfma_f32_16x16x32_bf16 v[108:111], v[128:131], v[198:201], v[108:111]
	v_mfma_f32_16x16x32_bf16 v[92:95], v[128:131], v[206:209], v[92:95]
	v_mfma_f32_16x16x32_bf16 v[92:95], v[132:135], v[210:213], v[92:95]
	v_mfma_f32_16x16x32_bf16 v[88:91], v[140:143], v[210:213], v[88:91]
	v_mfma_f32_16x16x32_bf16 v[88:91], v[136:139], v[206:209], v[88:91]
	v_mfma_f32_16x16x32_bf16 v[72:75], v[136:139], v[214:217], v[72:75]
	v_mfma_f32_16x16x32_bf16 v[72:75], v[140:143], v[218:221], v[72:75]
	v_mfma_f32_16x16x32_bf16 v[76:79], v[132:135], v[218:221], v[76:79]
	v_mfma_f32_16x16x32_bf16 v[76:79], v[128:131], v[214:217], v[76:79]
	s_setprio 0
	s_setprio 1
	v_mfma_f32_16x16x32_bf16 v[116:119], v[144:147], v[180:183], v[116:119]
	v_mfma_f32_16x16x32_bf16 v[116:119], v[148:151], v[194:197], v[116:119]
	v_mfma_f32_16x16x32_bf16 v[112:115], v[176:179], v[194:197], v[112:115]
	v_mfma_f32_16x16x32_bf16 v[112:115], v[172:175], v[180:183], v[112:115]
	v_mfma_f32_16x16x32_bf16 v[96:99], v[172:175], v[198:201], v[96:99]
	v_mfma_f32_16x16x32_bf16 v[96:99], v[176:179], v[202:205], v[96:99]
	v_mfma_f32_16x16x32_bf16 v[100:103], v[148:151], v[202:205], v[100:103]
	v_mfma_f32_16x16x32_bf16 v[100:103], v[144:147], v[198:201], v[100:103]
	v_mfma_f32_16x16x32_bf16 v[84:87], v[144:147], v[206:209], v[84:87]
	v_mfma_f32_16x16x32_bf16 v[84:87], v[148:151], v[210:213], v[84:87]
	v_mfma_f32_16x16x32_bf16 v[80:83], v[176:179], v[210:213], v[80:83]
	v_mfma_f32_16x16x32_bf16 v[80:83], v[172:175], v[206:209], v[80:83]
	v_mfma_f32_16x16x32_bf16 v[64:67], v[172:175], v[214:217], v[64:67]
	v_mfma_f32_16x16x32_bf16 v[64:67], v[176:179], v[218:221], v[64:67]
	v_mfma_f32_16x16x32_bf16 v[68:71], v[148:151], v[218:221], v[68:71]
	v_mfma_f32_16x16x32_bf16 v[68:71], v[144:147], v[214:217], v[68:71]
	s_setprio 0
	s_barrier
	s_add_i32 s54, s77, s65
	v_lshl_add_u64 v[222:223], s[58:59], 0, v[154:155]
	s_mov_b32 m0, s54
	ds_read_b128 v[180:183], v191 offset:16384
	v_xor_b32_e32 v253, 64, v191
	ds_read_b128 v[194:197], v253 offset:16384
	ds_read_b128 v[198:201], v191 offset:18432
	ds_read_b128 v[202:205], v253 offset:18432
	ds_read_b128 v[206:209], v191 offset:20480
	ds_read_b128 v[210:213], v253 offset:20480
	ds_read_b128 v[214:217], v191 offset:22528
	ds_read_b128 v[218:221], v253 offset:22528
	global_load_lds_dwordx4 v[222:223], off
	s_add_i32 m0, s54, 0x2000
	s_add_u32 s54, s58, 0xb0000
	v_lshl_add_u64 v[224:225], s[58:59], 0, v[162:163]
	s_addc_u32 s55, s59, 0
	s_add_i32 s84, s78, s65
	global_load_lds_dwordx4 v[224:225], off
	v_lshl_add_u64 v[226:227], s[54:55], 0, v[154:155]
	s_mov_b32 m0, s84
	v_lshl_add_u64 v[228:229], s[60:61], 0, v[160:161]
	global_load_lds_dwordx4 v[226:227], off
	v_lshl_add_u64 v[226:227], s[54:55], 0, v[162:163]
	s_add_i32 m0, s84, 0x2000
	s_nop 0
	global_load_lds_dwordx4 v[226:227], off
	v_lshl_add_u64 v[226:227], s[60:61], 0, v[152:153]
	s_mov_b32 m0, s66
	s_nop 0
	global_load_lds_dwordx4 v[226:227], off
	s_mov_b32 m0, s67
	s_nop 0
	global_load_lds_dwordx4 v[228:229], off
	s_waitcnt vmcnt(8)
	s_waitcnt lgkmcnt(0)
	s_barrier
	s_setprio 1
	s_waitcnt lgkmcnt(0)
	v_mfma_f32_16x16x32_bf16 v[60:63], v[128:131], v[180:183], v[60:63]
	v_mfma_f32_16x16x32_bf16 v[60:63], v[132:135], v[194:197], v[60:63]
	v_mfma_f32_16x16x32_bf16 v[56:59], v[140:143], v[194:197], v[56:59]
	v_mfma_f32_16x16x32_bf16 v[56:59], v[136:139], v[180:183], v[56:59]
	v_mfma_f32_16x16x32_bf16 v[40:43], v[136:139], v[198:201], v[40:43]
	v_mfma_f32_16x16x32_bf16 v[40:43], v[140:143], v[202:205], v[40:43]
	v_mfma_f32_16x16x32_bf16 v[44:47], v[132:135], v[202:205], v[44:47]
	v_mfma_f32_16x16x32_bf16 v[44:47], v[128:131], v[198:201], v[44:47]
	v_mfma_f32_16x16x32_bf16 v[28:31], v[128:131], v[206:209], v[28:31]
	v_mfma_f32_16x16x32_bf16 v[28:31], v[132:135], v[210:213], v[28:31]
	v_mfma_f32_16x16x32_bf16 v[24:27], v[140:143], v[210:213], v[24:27]
	v_mfma_f32_16x16x32_bf16 v[24:27], v[136:139], v[206:209], v[24:27]
	v_mfma_f32_16x16x32_bf16 v[8:11], v[136:139], v[214:217], v[8:11]
	v_mfma_f32_16x16x32_bf16 v[8:11], v[140:143], v[218:221], v[8:11]
	v_mfma_f32_16x16x32_bf16 v[12:15], v[132:135], v[218:221], v[12:15]
	v_mfma_f32_16x16x32_bf16 v[12:15], v[128:131], v[214:217], v[12:15]
	s_setprio 0
	s_setprio 1
	v_mfma_f32_16x16x32_bf16 v[52:55], v[144:147], v[180:183], v[52:55]
	v_mfma_f32_16x16x32_bf16 v[52:55], v[148:151], v[194:197], v[52:55]
	v_mfma_f32_16x16x32_bf16 v[48:51], v[176:179], v[194:197], v[48:51]
	v_mfma_f32_16x16x32_bf16 v[48:51], v[172:175], v[180:183], v[48:51]
	v_mfma_f32_16x16x32_bf16 v[32:35], v[172:175], v[198:201], v[32:35]
	v_mfma_f32_16x16x32_bf16 v[32:35], v[176:179], v[202:205], v[32:35]
	v_mfma_f32_16x16x32_bf16 v[36:39], v[148:151], v[202:205], v[36:39]
	v_mfma_f32_16x16x32_bf16 v[36:39], v[144:147], v[198:201], v[36:39]
	v_mfma_f32_16x16x32_bf16 v[20:23], v[144:147], v[206:209], v[20:23]
	v_mfma_f32_16x16x32_bf16 v[20:23], v[148:151], v[210:213], v[20:23]
	v_mfma_f32_16x16x32_bf16 v[16:19], v[176:179], v[210:213], v[16:19]
	v_mfma_f32_16x16x32_bf16 v[16:19], v[172:175], v[206:209], v[16:19]
	v_mfma_f32_16x16x32_bf16 v[0:3], v[172:175], v[214:217], v[0:3]
	v_mfma_f32_16x16x32_bf16 v[0:3], v[176:179], v[218:221], v[0:3]
	v_mfma_f32_16x16x32_bf16 v[4:7], v[148:151], v[218:221], v[4:7]
	v_mfma_f32_16x16x32_bf16 v[4:7], v[144:147], v[214:217], v[4:7]
	s_setprio 0
	s_barrier
	s_add_i32 s84, 0, 0x18000
	s_add_i32 s85, 0, 0x1c000
	v_add_u32_e32 v140, s84, v186
	v_add_u32_e32 v176, s85, v186
	ds_read_b128 v[128:131], v140
	v_xor_b32_e32 v253, 64, v140
	ds_read_b128 v[132:135], v253
	ds_read_b128 v[136:139], v140 offset:2048
	ds_read_b128 v[140:143], v253 offset:2048
	ds_read_b128 v[144:147], v176
	v_xor_b32_e32 v253, 64, v176
	ds_read_b128 v[148:151], v253
	ds_read_b128 v[172:175], v176 offset:2048
	ds_read_b128 v[176:179], v253 offset:2048
	s_add_u32 s54, s60, 0xb0000
	s_addc_u32 s55, s61, 0
	s_mov_b32 m0, s68
	v_lshl_add_u64 v[230:231], s[54:55], 0, v[152:153]
	ds_read_b128 v[180:183], v191 offset:32768
	v_xor_b32_e32 v253, 64, v191
	ds_read_b128 v[194:197], v253 offset:32768
	ds_read_b128 v[198:201], v191 offset:34816
	ds_read_b128 v[202:205], v253 offset:34816
	ds_read_b128 v[206:209], v191 offset:36864
	ds_read_b128 v[210:213], v253 offset:36864
	ds_read_b128 v[214:217], v191 offset:38912
	ds_read_b128 v[218:221], v253 offset:38912
	global_load_lds_dwordx4 v[230:231], off
	v_lshl_add_u64 v[230:231], s[54:55], 0, v[160:161]
	s_mov_b32 m0, s69
	s_nop 0
	global_load_lds_dwordx4 v[230:231], off
	s_waitcnt vmcnt(8)
	s_waitcnt lgkmcnt(0)
	s_barrier
	s_setprio 1
	s_waitcnt lgkmcnt(0)
	v_mfma_f32_16x16x32_bf16 v[124:127], v[128:131], v[180:183], v[124:127]
	v_mfma_f32_16x16x32_bf16 v[124:127], v[132:135], v[194:197], v[124:127]
	v_mfma_f32_16x16x32_bf16 v[120:123], v[140:143], v[194:197], v[120:123]
	v_mfma_f32_16x16x32_bf16 v[120:123], v[136:139], v[180:183], v[120:123]
	v_mfma_f32_16x16x32_bf16 v[104:107], v[136:139], v[198:201], v[104:107]
	v_mfma_f32_16x16x32_bf16 v[104:107], v[140:143], v[202:205], v[104:107]
	v_mfma_f32_16x16x32_bf16 v[108:111], v[132:135], v[202:205], v[108:111]
	v_mfma_f32_16x16x32_bf16 v[108:111], v[128:131], v[198:201], v[108:111]
	v_mfma_f32_16x16x32_bf16 v[92:95], v[128:131], v[206:209], v[92:95]
	v_mfma_f32_16x16x32_bf16 v[92:95], v[132:135], v[210:213], v[92:95]
	v_mfma_f32_16x16x32_bf16 v[88:91], v[140:143], v[210:213], v[88:91]
	v_mfma_f32_16x16x32_bf16 v[88:91], v[136:139], v[206:209], v[88:91]
	v_mfma_f32_16x16x32_bf16 v[72:75], v[136:139], v[214:217], v[72:75]
	v_mfma_f32_16x16x32_bf16 v[72:75], v[140:143], v[218:221], v[72:75]
	v_mfma_f32_16x16x32_bf16 v[76:79], v[132:135], v[218:221], v[76:79]
	v_mfma_f32_16x16x32_bf16 v[76:79], v[128:131], v[214:217], v[76:79]
	s_setprio 0
	s_setprio 1
	v_mfma_f32_16x16x32_bf16 v[116:119], v[144:147], v[180:183], v[116:119]
	v_mfma_f32_16x16x32_bf16 v[116:119], v[148:151], v[194:197], v[116:119]
	v_mfma_f32_16x16x32_bf16 v[112:115], v[176:179], v[194:197], v[112:115]
	v_mfma_f32_16x16x32_bf16 v[112:115], v[172:175], v[180:183], v[112:115]
	v_mfma_f32_16x16x32_bf16 v[96:99], v[172:175], v[198:201], v[96:99]
	v_mfma_f32_16x16x32_bf16 v[96:99], v[176:179], v[202:205], v[96:99]
	v_mfma_f32_16x16x32_bf16 v[100:103], v[148:151], v[202:205], v[100:103]
	v_mfma_f32_16x16x32_bf16 v[100:103], v[144:147], v[198:201], v[100:103]
	v_mfma_f32_16x16x32_bf16 v[84:87], v[144:147], v[206:209], v[84:87]
	v_mfma_f32_16x16x32_bf16 v[84:87], v[148:151], v[210:213], v[84:87]
	v_mfma_f32_16x16x32_bf16 v[80:83], v[176:179], v[210:213], v[80:83]
	v_mfma_f32_16x16x32_bf16 v[80:83], v[172:175], v[206:209], v[80:83]
	v_mfma_f32_16x16x32_bf16 v[64:67], v[172:175], v[214:217], v[64:67]
	v_mfma_f32_16x16x32_bf16 v[64:67], v[176:179], v[218:221], v[64:67]
	v_mfma_f32_16x16x32_bf16 v[68:71], v[148:151], v[218:221], v[68:71]
	v_mfma_f32_16x16x32_bf16 v[68:71], v[144:147], v[214:217], v[68:71]
	s_setprio 0
	s_barrier
	s_add_i32 s54, s84, s65
	v_lshl_add_u64 v[222:223], v[222:223], 0, s[28:29]
	s_mov_b32 m0, s54
	ds_read_b128 v[180:183], v191 offset:49152
	v_xor_b32_e32 v253, 64, v191
	ds_read_b128 v[194:197], v253 offset:49152
	ds_read_b128 v[198:201], v191 offset:51200
	ds_read_b128 v[202:205], v253 offset:51200
	ds_read_b128 v[206:209], v191 offset:53248
	ds_read_b128 v[210:213], v253 offset:53248
	ds_read_b128 v[214:217], v191 offset:55296
	ds_read_b128 v[218:221], v253 offset:55296
	global_load_lds_dwordx4 v[222:223], off
	s_add_i32 m0, s54, 0x2000
	s_add_u32 s54, s58, 0xb0080
	v_lshl_add_u64 v[222:223], v[224:225], 0, s[28:29]
	s_addc_u32 s55, s59, 0
	s_add_i32 s58, s85, s65
	global_load_lds_dwordx4 v[222:223], off
	v_lshl_add_u64 v[222:223], s[54:55], 0, v[154:155]
	s_mov_b32 m0, s58
	s_nop 0
	global_load_lds_dwordx4 v[222:223], off
	v_lshl_add_u64 v[222:223], s[54:55], 0, v[162:163]
	s_add_i32 m0, s58, 0x2000
	s_nop 0
	global_load_lds_dwordx4 v[222:223], off
	v_lshl_add_u64 v[222:223], v[226:227], 0, s[28:29]
	s_mov_b32 m0, s3
	s_nop 0
	global_load_lds_dwordx4 v[222:223], off
	v_lshl_add_u64 v[222:223], v[228:229], 0, s[28:29]
	s_mov_b32 m0, s71
	s_nop 0
	global_load_lds_dwordx4 v[222:223], off
	s_waitcnt vmcnt(8)
	s_waitcnt lgkmcnt(0)
	s_barrier
	s_setprio 1
	s_waitcnt lgkmcnt(0)
	v_mfma_f32_16x16x32_bf16 v[60:63], v[128:131], v[180:183], v[60:63]
	v_mfma_f32_16x16x32_bf16 v[60:63], v[132:135], v[194:197], v[60:63]
	v_mfma_f32_16x16x32_bf16 v[56:59], v[140:143], v[194:197], v[56:59]
	v_mfma_f32_16x16x32_bf16 v[56:59], v[136:139], v[180:183], v[56:59]
	v_mfma_f32_16x16x32_bf16 v[40:43], v[136:139], v[198:201], v[40:43]
	v_mfma_f32_16x16x32_bf16 v[40:43], v[140:143], v[202:205], v[40:43]
	v_mfma_f32_16x16x32_bf16 v[44:47], v[132:135], v[202:205], v[44:47]
	v_mfma_f32_16x16x32_bf16 v[44:47], v[128:131], v[198:201], v[44:47]
	v_mfma_f32_16x16x32_bf16 v[28:31], v[128:131], v[206:209], v[28:31]
	v_mfma_f32_16x16x32_bf16 v[28:31], v[132:135], v[210:213], v[28:31]
	v_mfma_f32_16x16x32_bf16 v[24:27], v[140:143], v[210:213], v[24:27]
	v_mfma_f32_16x16x32_bf16 v[24:27], v[136:139], v[206:209], v[24:27]
	v_mfma_f32_16x16x32_bf16 v[8:11], v[136:139], v[214:217], v[8:11]
	v_mfma_f32_16x16x32_bf16 v[8:11], v[140:143], v[218:221], v[8:11]
	v_mfma_f32_16x16x32_bf16 v[12:15], v[132:135], v[218:221], v[12:15]
	v_mfma_f32_16x16x32_bf16 v[12:15], v[128:131], v[214:217], v[12:15]
	s_setprio 0
	s_setprio 1
	v_mfma_f32_16x16x32_bf16 v[52:55], v[144:147], v[180:183], v[52:55]
	v_mfma_f32_16x16x32_bf16 v[52:55], v[148:151], v[194:197], v[52:55]
	v_mfma_f32_16x16x32_bf16 v[48:51], v[176:179], v[194:197], v[48:51]
	v_mfma_f32_16x16x32_bf16 v[48:51], v[172:175], v[180:183], v[48:51]
	v_mfma_f32_16x16x32_bf16 v[32:35], v[172:175], v[198:201], v[32:35]
	v_mfma_f32_16x16x32_bf16 v[32:35], v[176:179], v[202:205], v[32:35]
	v_mfma_f32_16x16x32_bf16 v[36:39], v[148:151], v[202:205], v[36:39]
	v_mfma_f32_16x16x32_bf16 v[36:39], v[144:147], v[198:201], v[36:39]
	v_mfma_f32_16x16x32_bf16 v[20:23], v[144:147], v[206:209], v[20:23]
	v_mfma_f32_16x16x32_bf16 v[20:23], v[148:151], v[210:213], v[20:23]
	v_mfma_f32_16x16x32_bf16 v[16:19], v[176:179], v[210:213], v[16:19]
	v_mfma_f32_16x16x32_bf16 v[16:19], v[172:175], v[206:209], v[16:19]
	v_mfma_f32_16x16x32_bf16 v[0:3], v[172:175], v[214:217], v[0:3]
	v_mfma_f32_16x16x32_bf16 v[0:3], v[176:179], v[218:221], v[0:3]
	v_mfma_f32_16x16x32_bf16 v[4:7], v[148:151], v[218:221], v[4:7]
	v_mfma_f32_16x16x32_bf16 v[4:7], v[144:147], v[214:217], v[4:7]
	s_setprio 0
	s_barrier
	s_add_i32 s83, s83, 2
	s_add_u32 s81, s81, 0x100
	s_addc_u32 s82, s82, 0
	s_cmp_gt_u32 s83, 41
	s_mov_b64 s[54:55], s[56:57]
	s_cbranch_scc0 .LBB0_159
	s_and_b64 vcc, exec, s[30:31]
	s_cbranch_vccz .LBB0_162
	s_barrier

.LBB0_254:
	s_ashr_i32 s61, s60, 31
	s_lshl_b64 s[62:63], s[60:61], 19
	s_add_u32 s62, s35, s62
	s_addc_u32 s63, s47, s63
	s_and_b64 s[64:65], s[12:13], exec
	s_cselect_b32 s3, s63, s69
	s_cselect_b32 s61, s62, s68
	s_ashr_i32 s59, s58, 31
	s_lshl_b64 s[64:65], s[58:59], 19
	s_add_u32 s64, s49, s64
	s_addc_u32 s65, s70, s65
	s_and_b64 s[92:93], s[12:13], exec
	s_cselect_b32 s91, s65, s67
	s_cselect_b32 s92, s64, s66
	s_lshl_b32 s59, s14, 8
	v_add_u32_e32 v0, s59, v182
	s_add_u32 s93, s66, 0x100
	s_waitcnt lgkmcnt(0)
	v_ashrrev_i32_e32 v1, 31, v0
	s_addc_u32 s94, s67, 0
	v_lshl_add_u64 v[72:73], v[0:1], 4, s[26:27]
	s_add_u32 s14, s68, 0x40080
	s_addc_u32 s15, s69, 0
	s_mov_b32 s95, -2
	s_mov_b64 s[66:67], 0
	s_cmp_eq_u32 s90, 1
	s_cbranch_scc1 .Lfa_2
	v_add_u32_e32 v74, s83, v181
	ds_read_b128 v[88:91], v74
	v_xor_b32_e32 v253, 64, v74
	ds_read_b128 v[108:111], v253
	ds_read_b128 v[128:131], v74 offset:2048
	ds_read_b128 v[144:147], v253 offset:2048
	v_add_u32_e32 v74, s84, v181
	ds_read_b128 v[148:151], v74
	v_xor_b32_e32 v253, 64, v74
	ds_read_b128 v[152:155], v253
	ds_read_b128 v[176:179], v74 offset:2048
	ds_read_b128 v[190:193], v253 offset:2048
	s_add_u32 s68, s14, 0xfffc0080
	s_addc_u32 s69, s15, -1
	s_and_b64 s[66:67], s[66:67], exec
	s_cselect_b32 s69, s3, s69
	s_cselect_b32 s68, s61, s68
	s_cselect_b32 s67, s91, s94
	s_cselect_b32 s66, s92, s93
	v_lshl_add_u64 v[74:75], s[14:15], 0, v[170:171]
	s_add_i32 m0, s74, 0xc000
	ds_read_b128 v[194:197], v187
	v_xor_b32_e32 v253, 64, v187
	ds_read_b128 v[198:201], v253
	ds_read_b128 v[202:205], v187 offset:2048
	ds_read_b128 v[206:209], v253 offset:2048
	ds_read_b128 v[210:213], v187 offset:4096
	ds_read_b128 v[214:217], v253 offset:4096
	ds_read_b128 v[218:221], v187 offset:6144
	ds_read_b128 v[222:225], v253 offset:6144
	global_load_lds_dwordx4 v[74:75], off
	v_lshl_add_u64 v[74:75], s[14:15], 0, v[168:169]
	s_add_i32 m0, s74, 0xe000
	s_nop 0
	global_load_lds_dwordx4 v[74:75], off
	s_waitcnt vmcnt(24)
	s_waitcnt lgkmcnt(0)
	s_barrier
	s_setprio 1
	s_waitcnt lgkmcnt(0)
	v_mfma_f32_16x16x32_bf16 v[140:143], v[88:91], v[194:197], 0
	v_mfma_f32_16x16x32_bf16 v[136:139], v[128:131], v[194:197], 0
	v_mfma_f32_16x16x32_bf16 v[120:123], v[88:91], v[202:205], 0
	v_mfma_f32_16x16x32_bf16 v[116:119], v[128:131], v[202:205], 0
	v_mfma_f32_16x16x32_bf16 v[100:103], v[88:91], v[210:213], 0
	v_mfma_f32_16x16x32_bf16 v[96:99], v[128:131], v[210:213], 0
	v_mfma_f32_16x16x32_bf16 v[80:83], v[88:91], v[218:221], 0
	v_mfma_f32_16x16x32_bf16 v[74:77], v[128:131], v[218:221], 0
	v_mfma_f32_16x16x32_bf16 v[140:143], v[108:111], v[198:201], v[140:143]
	v_mfma_f32_16x16x32_bf16 v[136:139], v[144:147], v[198:201], v[136:139]
	v_mfma_f32_16x16x32_bf16 v[120:123], v[108:111], v[206:209], v[120:123]
	v_mfma_f32_16x16x32_bf16 v[116:119], v[144:147], v[206:209], v[116:119]
	v_mfma_f32_16x16x32_bf16 v[100:103], v[108:111], v[214:217], v[100:103]
	v_mfma_f32_16x16x32_bf16 v[96:99], v[144:147], v[214:217], v[96:99]
	v_mfma_f32_16x16x32_bf16 v[80:83], v[108:111], v[222:225], v[80:83]
	v_mfma_f32_16x16x32_bf16 v[74:77], v[144:147], v[222:225], v[74:77]
	s_setprio 0
	s_setprio 1
	v_mfma_f32_16x16x32_bf16 v[132:135], v[148:151], v[194:197], 0
	v_mfma_f32_16x16x32_bf16 v[124:127], v[176:179], v[194:197], 0
	v_mfma_f32_16x16x32_bf16 v[112:115], v[148:151], v[202:205], 0
	v_mfma_f32_16x16x32_bf16 v[104:107], v[176:179], v[202:205], 0
	v_mfma_f32_16x16x32_bf16 v[92:95], v[148:151], v[210:213], 0
	v_mfma_f32_16x16x32_bf16 v[84:87], v[176:179], v[210:213], 0
	v_mfma_f32_16x16x32_bf16 v[68:71], v[148:151], v[218:221], 0
	v_mfma_f32_16x16x32_bf16 v[64:67], v[176:179], v[218:221], 0
	v_mfma_f32_16x16x32_bf16 v[132:135], v[152:155], v[198:201], v[132:135]
	v_mfma_f32_16x16x32_bf16 v[124:127], v[190:193], v[198:201], v[124:127]
	v_mfma_f32_16x16x32_bf16 v[112:115], v[152:155], v[206:209], v[112:115]
	v_mfma_f32_16x16x32_bf16 v[104:107], v[190:193], v[206:209], v[104:107]
	v_mfma_f32_16x16x32_bf16 v[92:95], v[152:155], v[214:217], v[92:95]
	v_mfma_f32_16x16x32_bf16 v[84:87], v[190:193], v[214:217], v[84:87]
	v_mfma_f32_16x16x32_bf16 v[68:71], v[152:155], v[222:225], v[68:71]
	v_mfma_f32_16x16x32_bf16 v[64:67], v[190:193], v[222:225], v[64:67]
	s_setprio 0
	s_barrier
	s_add_i32 s96, s83, s71
	v_lshl_add_u64 v[226:227], s[66:67], 0, v[162:163]
	s_mov_b32 m0, s96
	ds_read_b128 v[194:197], v187 offset:16384
	v_xor_b32_e32 v253, 64, v187
	ds_read_b128 v[198:201], v253 offset:16384
	ds_read_b128 v[202:205], v187 offset:18432
	ds_read_b128 v[206:209], v253 offset:18432
	ds_read_b128 v[210:213], v187 offset:20480
	ds_read_b128 v[214:217], v253 offset:20480
	ds_read_b128 v[218:221], v187 offset:22528
	ds_read_b128 v[222:225], v253 offset:22528
	global_load_lds_dwordx4 v[226:227], off
	s_add_i32 m0, s96, 0x2000
	s_add_u32 s96, s66, 0x40000
	v_lshl_add_u64 v[228:229], s[66:67], 0, v[166:167]
	s_addc_u32 s97, s67, 0
	s_add_i32 vcc_lo, s84, s71
	global_load_lds_dwordx4 v[228:229], off
	v_lshl_add_u64 v[78:79], s[96:97], 0, v[162:163]
	s_mov_b32 m0, vcc_lo
	v_lshl_add_u64 v[230:231], s[68:69], 0, v[160:161]
	global_load_lds_dwordx4 v[78:79], off
	v_lshl_add_u64 v[78:79], s[96:97], 0, v[166:167]
	s_add_i32 m0, vcc_lo, 0x2000
	v_lshl_add_u64 v[232:233], s[68:69], 0, v[164:165]
	global_load_lds_dwordx4 v[78:79], off
	s_mov_b32 m0, s74
	s_nop 0
	global_load_lds_dwordx4 v[230:231], off
	s_mov_b32 m0, s75
	s_nop 0
	global_load_lds_dwordx4 v[232:233], off
	s_waitcnt vmcnt(24)
	s_waitcnt lgkmcnt(0)
	s_barrier
	s_setprio 1
	s_waitcnt lgkmcnt(0)
	v_mfma_f32_16x16x32_bf16 v[60:63], v[88:91], v[194:197], 0
	v_mfma_f32_16x16x32_bf16 v[56:59], v[128:131], v[194:197], 0
	v_mfma_f32_16x16x32_bf16 v[44:47], v[88:91], v[202:205], 0
	v_mfma_f32_16x16x32_bf16 v[40:43], v[128:131], v[202:205], 0
	v_mfma_f32_16x16x32_bf16 v[28:31], v[88:91], v[210:213], 0
	v_mfma_f32_16x16x32_bf16 v[24:27], v[128:131], v[210:213], 0
	v_mfma_f32_16x16x32_bf16 v[12:15], v[88:91], v[218:221], 0
	v_mfma_f32_16x16x32_bf16 v[8:11], v[128:131], v[218:221], 0
	v_mfma_f32_16x16x32_bf16 v[60:63], v[108:111], v[198:201], v[60:63]
	v_mfma_f32_16x16x32_bf16 v[56:59], v[144:147], v[198:201], v[56:59]
	v_mfma_f32_16x16x32_bf16 v[44:47], v[108:111], v[206:209], v[44:47]
	v_mfma_f32_16x16x32_bf16 v[40:43], v[144:147], v[206:209], v[40:43]
	v_mfma_f32_16x16x32_bf16 v[28:31], v[108:111], v[214:217], v[28:31]
	v_mfma_f32_16x16x32_bf16 v[24:27], v[144:147], v[214:217], v[24:27]
	v_mfma_f32_16x16x32_bf16 v[12:15], v[108:111], v[222:225], v[12:15]
	v_mfma_f32_16x16x32_bf16 v[8:11], v[144:147], v[222:225], v[8:11]
	s_setprio 0
	s_setprio 1
	v_mfma_f32_16x16x32_bf16 v[52:55], v[148:151], v[194:197], 0
	v_mfma_f32_16x16x32_bf16 v[48:51], v[176:179], v[194:197], 0
	v_mfma_f32_16x16x32_bf16 v[36:39], v[148:151], v[202:205], 0
	v_mfma_f32_16x16x32_bf16 v[32:35], v[176:179], v[202:205], 0
	v_mfma_f32_16x16x32_bf16 v[20:23], v[148:151], v[210:213], 0
	v_mfma_f32_16x16x32_bf16 v[16:19], v[176:179], v[210:213], 0
	v_mfma_f32_16x16x32_bf16 v[4:7], v[148:151], v[218:221], 0
	v_mfma_f32_16x16x32_bf16 v[0:3], v[176:179], v[218:221], 0
	v_mfma_f32_16x16x32_bf16 v[52:55], v[152:155], v[198:201], v[52:55]
	v_mfma_f32_16x16x32_bf16 v[48:51], v[190:193], v[198:201], v[48:51]
	v_mfma_f32_16x16x32_bf16 v[36:39], v[152:155], v[206:209], v[36:39]
	v_mfma_f32_16x16x32_bf16 v[32:35], v[190:193], v[206:209], v[32:35]
	v_mfma_f32_16x16x32_bf16 v[20:23], v[152:155], v[214:217], v[20:23]
	v_mfma_f32_16x16x32_bf16 v[16:19], v[190:193], v[214:217], v[16:19]
	v_mfma_f32_16x16x32_bf16 v[4:7], v[152:155], v[222:225], v[4:7]
	v_mfma_f32_16x16x32_bf16 v[0:3], v[190:193], v[222:225], v[0:3]
	s_setprio 0
	s_barrier
	s_add_i32 s96, 0, 0x18000
	v_add_u32_e32 v78, s96, v181
	s_add_i32 s97, 0, 0x1c000
	ds_read_b128 v[88:91], v78
	v_xor_b32_e32 v253, 64, v78
	ds_read_b128 v[108:111], v253
	ds_read_b128 v[128:131], v78 offset:2048
	ds_read_b128 v[144:147], v253 offset:2048
	v_add_u32_e32 v78, s97, v181
	ds_read_b128 v[148:151], v78
	v_xor_b32_e32 v253, 64, v78
	ds_read_b128 v[152:155], v253
	ds_read_b128 v[176:179], v78 offset:2048
	ds_read_b128 v[190:193], v253 offset:2048
	s_add_u32 s68, s68, 0x40000
	s_addc_u32 s69, s69, 0
	s_mov_b32 m0, s76
	v_lshl_add_u64 v[78:79], s[68:69], 0, v[160:161]
	ds_read_b128 v[194:197], v187 offset:32768
	v_xor_b32_e32 v253, 64, v187
	ds_read_b128 v[198:201], v253 offset:32768
	ds_read_b128 v[202:205], v187 offset:34816
	ds_read_b128 v[206:209], v253 offset:34816
	ds_read_b128 v[210:213], v187 offset:36864
	ds_read_b128 v[214:217], v253 offset:36864
	ds_read_b128 v[218:221], v187 offset:38912
	ds_read_b128 v[222:225], v253 offset:38912
	global_load_lds_dwordx4 v[78:79], off
	v_lshl_add_u64 v[78:79], s[68:69], 0, v[164:165]
	s_mov_b32 m0, s77
	s_nop 0
	global_load_lds_dwordx4 v[78:79], off
	s_waitcnt vmcnt(8)
	s_waitcnt lgkmcnt(0)
	s_barrier
	s_setprio 1
	s_waitcnt lgkmcnt(0)
	v_mfma_f32_16x16x32_bf16 v[140:143], v[88:91], v[194:197], v[140:143]
	v_mfma_f32_16x16x32_bf16 v[136:139], v[128:131], v[194:197], v[136:139]
	v_mfma_f32_16x16x32_bf16 v[120:123], v[88:91], v[202:205], v[120:123]
	v_mfma_f32_16x16x32_bf16 v[116:119], v[128:131], v[202:205], v[116:119]
	v_mfma_f32_16x16x32_bf16 v[100:103], v[88:91], v[210:213], v[100:103]
	v_mfma_f32_16x16x32_bf16 v[96:99], v[128:131], v[210:213], v[96:99]
	v_mfma_f32_16x16x32_bf16 v[78:81], v[88:91], v[218:221], v[80:83]
	v_mfma_f32_16x16x32_bf16 v[74:77], v[128:131], v[218:221], v[74:77]
	v_mfma_f32_16x16x32_bf16 v[140:143], v[108:111], v[198:201], v[140:143]
	v_mfma_f32_16x16x32_bf16 v[136:139], v[144:147], v[198:201], v[136:139]
	v_mfma_f32_16x16x32_bf16 v[120:123], v[108:111], v[206:209], v[120:123]
	v_mfma_f32_16x16x32_bf16 v[116:119], v[144:147], v[206:209], v[116:119]
	v_mfma_f32_16x16x32_bf16 v[100:103], v[108:111], v[214:217], v[100:103]
	v_mfma_f32_16x16x32_bf16 v[96:99], v[144:147], v[214:217], v[96:99]
	v_mfma_f32_16x16x32_bf16 v[80:83], v[108:111], v[222:225], v[78:81]
	v_mfma_f32_16x16x32_bf16 v[76:79], v[144:147], v[222:225], v[74:77]
	s_setprio 0
	s_setprio 1
	v_mfma_f32_16x16x32_bf16 v[132:135], v[148:151], v[194:197], v[132:135]
	v_mfma_f32_16x16x32_bf16 v[132:135], v[152:155], v[198:201], v[132:135]
	v_mfma_f32_16x16x32_bf16 v[124:127], v[190:193], v[198:201], v[124:127]
	v_mfma_f32_16x16x32_bf16 v[124:127], v[176:179], v[194:197], v[124:127]
	v_mfma_f32_16x16x32_bf16 v[104:107], v[176:179], v[202:205], v[104:107]
	v_mfma_f32_16x16x32_bf16 v[104:107], v[190:193], v[206:209], v[104:107]
	v_mfma_f32_16x16x32_bf16 v[112:115], v[152:155], v[206:209], v[112:115]
	v_mfma_f32_16x16x32_bf16 v[112:115], v[148:151], v[202:205], v[112:115]
	v_mfma_f32_16x16x32_bf16 v[92:95], v[148:151], v[210:213], v[92:95]
	v_mfma_f32_16x16x32_bf16 v[92:95], v[152:155], v[214:217], v[92:95]
	v_mfma_f32_16x16x32_bf16 v[84:87], v[190:193], v[214:217], v[84:87]
	v_mfma_f32_16x16x32_bf16 v[84:87], v[176:179], v[210:213], v[84:87]
	v_mfma_f32_16x16x32_bf16 v[64:67], v[176:179], v[218:221], v[64:67]
	v_mfma_f32_16x16x32_bf16 v[64:67], v[190:193], v[222:225], v[64:67]
	v_mfma_f32_16x16x32_bf16 v[68:71], v[152:155], v[222:225], v[68:71]
	v_mfma_f32_16x16x32_bf16 v[68:71], v[148:151], v[218:221], v[68:71]
	s_setprio 0
	s_barrier
	s_add_i32 s68, s96, s71
	v_lshl_add_u64 v[74:75], v[226:227], 0, s[28:29]
	s_mov_b32 m0, s68
	ds_read_b128 v[194:197], v187 offset:49152
	v_xor_b32_e32 v253, 64, v187
	ds_read_b128 v[198:201], v253 offset:49152
	ds_read_b128 v[202:205], v187 offset:51200
	ds_read_b128 v[206:209], v253 offset:51200
	ds_read_b128 v[210:213], v187 offset:53248
	ds_read_b128 v[214:217], v253 offset:53248
	ds_read_b128 v[218:221], v187 offset:55296
	ds_read_b128 v[222:225], v253 offset:55296
	global_load_lds_dwordx4 v[74:75], off
	s_add_i32 m0, s68, 0x2000
	s_add_u32 s66, s66, 0x40080
	v_lshl_add_u64 v[74:75], v[228:229], 0, s[28:29]
	s_addc_u32 s67, s67, 0
	s_add_i32 s68, s97, s71
	global_load_lds_dwordx4 v[74:75], off
	v_lshl_add_u64 v[74:75], s[66:67], 0, v[162:163]
	s_mov_b32 m0, s68
	s_nop 0
	global_load_lds_dwordx4 v[74:75], off
	v_lshl_add_u64 v[74:75], s[66:67], 0, v[166:167]
	s_add_i32 m0, s68, 0x2000
	s_nop 0
	global_load_lds_dwordx4 v[74:75], off
	v_lshl_add_u64 v[74:75], v[230:231], 0, s[28:29]
	s_mov_b32 m0, s78
	s_nop 0
	global_load_lds_dwordx4 v[74:75], off
	v_lshl_add_u64 v[74:75], v[232:233], 0, s[28:29]
	s_mov_b32 m0, s79
	s_nop 0
	global_load_lds_dwordx4 v[74:75], off
	s_waitcnt vmcnt(8)
	s_waitcnt lgkmcnt(0)
	s_barrier
	s_setprio 1
	s_waitcnt lgkmcnt(0)
	v_mfma_f32_16x16x32_bf16 v[60:63], v[88:91], v[194:197], v[60:63]
	v_mfma_f32_16x16x32_bf16 v[60:63], v[108:111], v[198:201], v[60:63]
	v_mfma_f32_16x16x32_bf16 v[56:59], v[144:147], v[198:201], v[56:59]
	v_mfma_f32_16x16x32_bf16 v[56:59], v[128:131], v[194:197], v[56:59]
	v_mfma_f32_16x16x32_bf16 v[40:43], v[128:131], v[202:205], v[40:43]
	v_mfma_f32_16x16x32_bf16 v[40:43], v[144:147], v[206:209], v[40:43]
	v_mfma_f32_16x16x32_bf16 v[44:47], v[108:111], v[206:209], v[44:47]
	v_mfma_f32_16x16x32_bf16 v[44:47], v[88:91], v[202:205], v[44:47]
	v_mfma_f32_16x16x32_bf16 v[28:31], v[88:91], v[210:213], v[28:31]
	v_mfma_f32_16x16x32_bf16 v[28:31], v[108:111], v[214:217], v[28:31]
	v_mfma_f32_16x16x32_bf16 v[24:27], v[144:147], v[214:217], v[24:27]
	v_mfma_f32_16x16x32_bf16 v[24:27], v[128:131], v[210:213], v[24:27]
	v_mfma_f32_16x16x32_bf16 v[8:11], v[128:131], v[218:221], v[8:11]
	v_mfma_f32_16x16x32_bf16 v[8:11], v[144:147], v[222:225], v[8:11]
	v_mfma_f32_16x16x32_bf16 v[12:15], v[108:111], v[222:225], v[12:15]
	v_mfma_f32_16x16x32_bf16 v[12:15], v[88:91], v[218:221], v[12:15]
	s_setprio 0
	s_setprio 1
	v_mfma_f32_16x16x32_bf16 v[52:55], v[148:151], v[194:197], v[52:55]
	v_mfma_f32_16x16x32_bf16 v[52:55], v[152:155], v[198:201], v[52:55]
	v_mfma_f32_16x16x32_bf16 v[48:51], v[190:193], v[198:201], v[48:51]
	v_mfma_f32_16x16x32_bf16 v[48:51], v[176:179], v[194:197], v[48:51]
	v_mfma_f32_16x16x32_bf16 v[32:35], v[176:179], v[202:205], v[32:35]
	v_mfma_f32_16x16x32_bf16 v[32:35], v[190:193], v[206:209], v[32:35]
	v_mfma_f32_16x16x32_bf16 v[36:39], v[152:155], v[206:209], v[36:39]
	v_mfma_f32_16x16x32_bf16 v[36:39], v[148:151], v[202:205], v[36:39]
	v_mfma_f32_16x16x32_bf16 v[20:23], v[148:151], v[210:213], v[20:23]
	v_mfma_f32_16x16x32_bf16 v[20:23], v[152:155], v[214:217], v[20:23]
	v_mfma_f32_16x16x32_bf16 v[16:19], v[190:193], v[214:217], v[16:19]
	v_mfma_f32_16x16x32_bf16 v[16:19], v[176:179], v[210:213], v[16:19]
	v_mfma_f32_16x16x32_bf16 v[0:3], v[176:179], v[218:221], v[0:3]
	v_mfma_f32_16x16x32_bf16 v[0:3], v[190:193], v[222:225], v[0:3]
	v_mfma_f32_16x16x32_bf16 v[4:7], v[152:155], v[222:225], v[4:7]
	v_mfma_f32_16x16x32_bf16 v[4:7], v[148:151], v[218:221], v[4:7]
	s_setprio 0
	s_barrier
	s_add_i32 s95, s95, 2
	s_add_u32 s93, s93, 0x100
	s_addc_u32 s94, s94, 0
	s_add_u32 s14, s14, 0x100
	s_addc_u32 s15, s15, 0
	s_branch .LBB0_256
.Lfa_2:
	v_add_u32_e32 v74, s83, v181
	ds_read_b128 v[88:91], v74
	v_xor_b32_e32 v253, 64, v74
	ds_read_b128 v[108:111], v253
	ds_read_b128 v[128:131], v74 offset:2048
	ds_read_b128 v[144:147], v253 offset:2048
	v_add_u32_e32 v74, s84, v181
	ds_read_b128 v[148:151], v74
	v_xor_b32_e32 v253, 64, v74
	ds_read_b128 v[152:155], v253
	ds_read_b128 v[176:179], v74 offset:2048
	ds_read_b128 v[190:193], v253 offset:2048
	s_add_u32 s68, s14, 0xfffc0080
	s_addc_u32 s69, s15, -1
	s_and_b64 s[66:67], s[66:67], exec
	s_cselect_b32 s69, s3, s69
	s_cselect_b32 s68, s61, s68
	s_cselect_b32 s67, s91, s94
	s_cselect_b32 s66, s92, s93
	v_lshl_add_u64 v[74:75], s[14:15], 0, v[170:171]
	s_add_i32 m0, s74, 0xc000
	ds_read_b128 v[194:197], v187
	v_xor_b32_e32 v253, 64, v187
	ds_read_b128 v[198:201], v253
	ds_read_b128 v[202:205], v187 offset:2048
	ds_read_b128 v[206:209], v253 offset:2048
	ds_read_b128 v[210:213], v187 offset:4096
	ds_read_b128 v[214:217], v253 offset:4096
	ds_read_b128 v[218:221], v187 offset:6144
	ds_read_b128 v[222:225], v253 offset:6144
	global_load_lds_dwordx4 v[74:75], off
	v_lshl_add_u64 v[74:75], s[14:15], 0, v[168:169]
	s_add_i32 m0, s74, 0xe000
	s_nop 0
	global_load_lds_dwordx4 v[74:75], off
	s_waitcnt vmcnt(8)
	s_waitcnt lgkmcnt(0)
	s_barrier
	s_setprio 1
	s_waitcnt lgkmcnt(0)
	v_mfma_f32_16x16x32_bf16 v[140:143], v[88:91], v[194:197], 0
	v_mfma_f32_16x16x32_bf16 v[136:139], v[128:131], v[194:197], 0
	v_mfma_f32_16x16x32_bf16 v[120:123], v[88:91], v[202:205], 0
	v_mfma_f32_16x16x32_bf16 v[116:119], v[128:131], v[202:205], 0
	v_mfma_f32_16x16x32_bf16 v[100:103], v[88:91], v[210:213], 0
	v_mfma_f32_16x16x32_bf16 v[96:99], v[128:131], v[210:213], 0
	v_mfma_f32_16x16x32_bf16 v[80:83], v[88:91], v[218:221], 0
	v_mfma_f32_16x16x32_bf16 v[74:77], v[128:131], v[218:221], 0
	v_mfma_f32_16x16x32_bf16 v[140:143], v[108:111], v[198:201], v[140:143]
	v_mfma_f32_16x16x32_bf16 v[136:139], v[144:147], v[198:201], v[136:139]
	v_mfma_f32_16x16x32_bf16 v[120:123], v[108:111], v[206:209], v[120:123]
	v_mfma_f32_16x16x32_bf16 v[116:119], v[144:147], v[206:209], v[116:119]
	v_mfma_f32_16x16x32_bf16 v[100:103], v[108:111], v[214:217], v[100:103]
	v_mfma_f32_16x16x32_bf16 v[96:99], v[144:147], v[214:217], v[96:99]
	v_mfma_f32_16x16x32_bf16 v[80:83], v[108:111], v[222:225], v[80:83]
	v_mfma_f32_16x16x32_bf16 v[74:77], v[144:147], v[222:225], v[74:77]
	s_setprio 0
	s_setprio 1
	v_mfma_f32_16x16x32_bf16 v[132:135], v[148:151], v[194:197], 0
	v_mfma_f32_16x16x32_bf16 v[124:127], v[176:179], v[194:197], 0
	v_mfma_f32_16x16x32_bf16 v[112:115], v[148:151], v[202:205], 0
	v_mfma_f32_16x16x32_bf16 v[104:107], v[176:179], v[202:205], 0
	v_mfma_f32_16x16x32_bf16 v[92:95], v[148:151], v[210:213], 0
	v_mfma_f32_16x16x32_bf16 v[84:87], v[176:179], v[210:213], 0
	v_mfma_f32_16x16x32_bf16 v[68:71], v[148:151], v[218:221], 0
	v_mfma_f32_16x16x32_bf16 v[64:67], v[176:179], v[218:221], 0
	v_mfma_f32_16x16x32_bf16 v[132:135], v[152:155], v[198:201], v[132:135]
	v_mfma_f32_16x16x32_bf16 v[124:127], v[190:193], v[198:201], v[124:127]
	v_mfma_f32_16x16x32_bf16 v[112:115], v[152:155], v[206:209], v[112:115]
	v_mfma_f32_16x16x32_bf16 v[104:107], v[190:193], v[206:209], v[104:107]
	v_mfma_f32_16x16x32_bf16 v[92:95], v[152:155], v[214:217], v[92:95]
	v_mfma_f32_16x16x32_bf16 v[84:87], v[190:193], v[214:217], v[84:87]
	v_mfma_f32_16x16x32_bf16 v[68:71], v[152:155], v[222:225], v[68:71]
	v_mfma_f32_16x16x32_bf16 v[64:67], v[190:193], v[222:225], v[64:67]
	s_setprio 0
	s_barrier
	s_add_i32 s96, s83, s71
	v_lshl_add_u64 v[226:227], s[66:67], 0, v[162:163]
	s_mov_b32 m0, s96
	ds_read_b128 v[194:197], v187 offset:16384
	v_xor_b32_e32 v253, 64, v187
	ds_read_b128 v[198:201], v253 offset:16384
	ds_read_b128 v[202:205], v187 offset:18432
	ds_read_b128 v[206:209], v253 offset:18432
	ds_read_b128 v[210:213], v187 offset:20480
	ds_read_b128 v[214:217], v253 offset:20480
	ds_read_b128 v[218:221], v187 offset:22528
	ds_read_b128 v[222:225], v253 offset:22528
	global_load_lds_dwordx4 v[226:227], off
	s_add_i32 m0, s96, 0x2000
	s_add_u32 s96, s66, 0x40000
	v_lshl_add_u64 v[228:229], s[66:67], 0, v[166:167]
	s_addc_u32 s97, s67, 0
	s_add_i32 vcc_lo, s84, s71
	global_load_lds_dwordx4 v[228:229], off
	v_lshl_add_u64 v[78:79], s[96:97], 0, v[162:163]
	s_mov_b32 m0, vcc_lo
	v_lshl_add_u64 v[230:231], s[68:69], 0, v[160:161]
	global_load_lds_dwordx4 v[78:79], off
	v_lshl_add_u64 v[78:79], s[96:97], 0, v[166:167]
	s_add_i32 m0, vcc_lo, 0x2000
	v_lshl_add_u64 v[232:233], s[68:69], 0, v[164:165]
	global_load_lds_dwordx4 v[78:79], off
	s_mov_b32 m0, s74
	s_nop 0
	global_load_lds_dwordx4 v[230:231], off
	s_mov_b32 m0, s75
	s_nop 0
	global_load_lds_dwordx4 v[232:233], off
	s_waitcnt vmcnt(8)
	s_waitcnt lgkmcnt(0)
	s_barrier
	s_setprio 1
	s_waitcnt lgkmcnt(0)
	v_mfma_f32_16x16x32_bf16 v[60:63], v[88:91], v[194:197], 0
	v_mfma_f32_16x16x32_bf16 v[56:59], v[128:131], v[194:197], 0
	v_mfma_f32_16x16x32_bf16 v[44:47], v[88:91], v[202:205], 0
	v_mfma_f32_16x16x32_bf16 v[40:43], v[128:131], v[202:205], 0
	v_mfma_f32_16x16x32_bf16 v[28:31], v[88:91], v[210:213], 0
	v_mfma_f32_16x16x32_bf16 v[24:27], v[128:131], v[210:213], 0
	v_mfma_f32_16x16x32_bf16 v[12:15], v[88:91], v[218:221], 0
	v_mfma_f32_16x16x32_bf16 v[8:11], v[128:131], v[218:221], 0
	v_mfma_f32_16x16x32_bf16 v[60:63], v[108:111], v[198:201], v[60:63]
	v_mfma_f32_16x16x32_bf16 v[56:59], v[144:147], v[198:201], v[56:59]
	v_mfma_f32_16x16x32_bf16 v[44:47], v[108:111], v[206:209], v[44:47]
	v_mfma_f32_16x16x32_bf16 v[40:43], v[144:147], v[206:209], v[40:43]
	v_mfma_f32_16x16x32_bf16 v[28:31], v[108:111], v[214:217], v[28:31]
	v_mfma_f32_16x16x32_bf16 v[24:27], v[144:147], v[214:217], v[24:27]
	v_mfma_f32_16x16x32_bf16 v[12:15], v[108:111], v[222:225], v[12:15]
	v_mfma_f32_16x16x32_bf16 v[8:11], v[144:147], v[222:225], v[8:11]
	s_setprio 0
	s_setprio 1
	v_mfma_f32_16x16x32_bf16 v[52:55], v[148:151], v[194:197], 0
	v_mfma_f32_16x16x32_bf16 v[48:51], v[176:179], v[194:197], 0
	v_mfma_f32_16x16x32_bf16 v[36:39], v[148:151], v[202:205], 0
	v_mfma_f32_16x16x32_bf16 v[32:35], v[176:179], v[202:205], 0
	v_mfma_f32_16x16x32_bf16 v[20:23], v[148:151], v[210:213], 0
	v_mfma_f32_16x16x32_bf16 v[16:19], v[176:179], v[210:213], 0
	v_mfma_f32_16x16x32_bf16 v[4:7], v[148:151], v[218:221], 0
	v_mfma_f32_16x16x32_bf16 v[0:3], v[176:179], v[218:221], 0
	v_mfma_f32_16x16x32_bf16 v[52:55], v[152:155], v[198:201], v[52:55]
	v_mfma_f32_16x16x32_bf16 v[48:51], v[190:193], v[198:201], v[48:51]
	v_mfma_f32_16x16x32_bf16 v[36:39], v[152:155], v[206:209], v[36:39]
	v_mfma_f32_16x16x32_bf16 v[32:35], v[190:193], v[206:209], v[32:35]
	v_mfma_f32_16x16x32_bf16 v[20:23], v[152:155], v[214:217], v[20:23]
	v_mfma_f32_16x16x32_bf16 v[16:19], v[190:193], v[214:217], v[16:19]
	v_mfma_f32_16x16x32_bf16 v[4:7], v[152:155], v[222:225], v[4:7]
	v_mfma_f32_16x16x32_bf16 v[0:3], v[190:193], v[222:225], v[0:3]
	s_setprio 0
	s_barrier
	s_add_i32 s96, 0, 0x18000
	v_add_u32_e32 v78, s96, v181
	s_add_i32 s97, 0, 0x1c000
	ds_read_b128 v[88:91], v78
	v_xor_b32_e32 v253, 64, v78
	ds_read_b128 v[108:111], v253
	ds_read_b128 v[128:131], v78 offset:2048
	ds_read_b128 v[144:147], v253 offset:2048
	v_add_u32_e32 v78, s97, v181
	ds_read_b128 v[148:151], v78
	v_xor_b32_e32 v253, 64, v78
	ds_read_b128 v[152:155], v253
	ds_read_b128 v[176:179], v78 offset:2048
	ds_read_b128 v[190:193], v253 offset:2048
	s_add_u32 s68, s68, 0x40000
	s_addc_u32 s69, s69, 0
	s_mov_b32 m0, s76
	v_lshl_add_u64 v[78:79], s[68:69], 0, v[160:161]
	ds_read_b128 v[194:197], v187 offset:32768
	v_xor_b32_e32 v253, 64, v187
	ds_read_b128 v[198:201], v253 offset:32768
	ds_read_b128 v[202:205], v187 offset:34816
	ds_read_b128 v[206:209], v253 offset:34816
	ds_read_b128 v[210:213], v187 offset:36864
	ds_read_b128 v[214:217], v253 offset:36864
	ds_read_b128 v[218:221], v187 offset:38912
	ds_read_b128 v[222:225], v253 offset:38912
	global_load_lds_dwordx4 v[78:79], off
	v_lshl_add_u64 v[78:79], s[68:69], 0, v[164:165]
	s_mov_b32 m0, s77
	s_nop 0
	global_load_lds_dwordx4 v[78:79], off
	s_waitcnt vmcnt(8)
	s_waitcnt lgkmcnt(0)
	s_barrier
	s_setprio 1
	s_waitcnt lgkmcnt(0)
	v_mfma_f32_16x16x32_bf16 v[140:143], v[88:91], v[194:197], v[140:143]
	v_mfma_f32_16x16x32_bf16 v[136:139], v[128:131], v[194:197], v[136:139]
	v_mfma_f32_16x16x32_bf16 v[120:123], v[88:91], v[202:205], v[120:123]
	v_mfma_f32_16x16x32_bf16 v[116:119], v[128:131], v[202:205], v[116:119]
	v_mfma_f32_16x16x32_bf16 v[100:103], v[88:91], v[210:213], v[100:103]
	v_mfma_f32_16x16x32_bf16 v[96:99], v[128:131], v[210:213], v[96:99]
	v_mfma_f32_16x16x32_bf16 v[78:81], v[88:91], v[218:221], v[80:83]
	v_mfma_f32_16x16x32_bf16 v[74:77], v[128:131], v[218:221], v[74:77]
	v_mfma_f32_16x16x32_bf16 v[140:143], v[108:111], v[198:201], v[140:143]
	v_mfma_f32_16x16x32_bf16 v[136:139], v[144:147], v[198:201], v[136:139]
	v_mfma_f32_16x16x32_bf16 v[120:123], v[108:111], v[206:209], v[120:123]
	v_mfma_f32_16x16x32_bf16 v[116:119], v[144:147], v[206:209], v[116:119]
	v_mfma_f32_16x16x32_bf16 v[100:103], v[108:111], v[214:217], v[100:103]
	v_mfma_f32_16x16x32_bf16 v[96:99], v[144:147], v[214:217], v[96:99]
	v_mfma_f32_16x16x32_bf16 v[80:83], v[108:111], v[222:225], v[78:81]
	v_mfma_f32_16x16x32_bf16 v[76:79], v[144:147], v[222:225], v[74:77]
	s_setprio 0
	s_setprio 1
	v_mfma_f32_16x16x32_bf16 v[132:135], v[148:151], v[194:197], v[132:135]
	v_mfma_f32_16x16x32_bf16 v[132:135], v[152:155], v[198:201], v[132:135]
	v_mfma_f32_16x16x32_bf16 v[124:127], v[190:193], v[198:201], v[124:127]
	v_mfma_f32_16x16x32_bf16 v[124:127], v[176:179], v[194:197], v[124:127]
	v_mfma_f32_16x16x32_bf16 v[104:107], v[176:179], v[202:205], v[104:107]
	v_mfma_f32_16x16x32_bf16 v[104:107], v[190:193], v[206:209], v[104:107]
	v_mfma_f32_16x16x32_bf16 v[112:115], v[152:155], v[206:209], v[112:115]
	v_mfma_f32_16x16x32_bf16 v[112:115], v[148:151], v[202:205], v[112:115]
	v_mfma_f32_16x16x32_bf16 v[92:95], v[148:151], v[210:213], v[92:95]
	v_mfma_f32_16x16x32_bf16 v[92:95], v[152:155], v[214:217], v[92:95]
	v_mfma_f32_16x16x32_bf16 v[84:87], v[190:193], v[214:217], v[84:87]
	v_mfma_f32_16x16x32_bf16 v[84:87], v[176:179], v[210:213], v[84:87]
	v_mfma_f32_16x16x32_bf16 v[64:67], v[176:179], v[218:221], v[64:67]
	v_mfma_f32_16x16x32_bf16 v[64:67], v[190:193], v[222:225], v[64:67]
	v_mfma_f32_16x16x32_bf16 v[68:71], v[152:155], v[222:225], v[68:71]
	v_mfma_f32_16x16x32_bf16 v[68:71], v[148:151], v[218:221], v[68:71]
	s_setprio 0
	s_barrier
	s_add_i32 s68, s96, s71
	v_lshl_add_u64 v[74:75], v[226:227], 0, s[28:29]
	s_mov_b32 m0, s68
	ds_read_b128 v[194:197], v187 offset:49152
	v_xor_b32_e32 v253, 64, v187
	ds_read_b128 v[198:201], v253 offset:49152
	ds_read_b128 v[202:205], v187 offset:51200
	ds_read_b128 v[206:209], v253 offset:51200
	ds_read_b128 v[210:213], v187 offset:53248
	ds_read_b128 v[214:217], v253 offset:53248
	ds_read_b128 v[218:221], v187 offset:55296
	ds_read_b128 v[222:225], v253 offset:55296
	global_load_lds_dwordx4 v[74:75], off
	s_add_i32 m0, s68, 0x2000
	s_add_u32 s66, s66, 0x40080
	v_lshl_add_u64 v[74:75], v[228:229], 0, s[28:29]
	s_addc_u32 s67, s67, 0
	s_add_i32 s68, s97, s71
	global_load_lds_dwordx4 v[74:75], off
	v_lshl_add_u64 v[74:75], s[66:67], 0, v[162:163]
	s_mov_b32 m0, s68
	s_nop 0
	global_load_lds_dwordx4 v[74:75], off
	v_lshl_add_u64 v[74:75], s[66:67], 0, v[166:167]
	s_add_i32 m0, s68, 0x2000
	s_nop 0
	global_load_lds_dwordx4 v[74:75], off
	v_lshl_add_u64 v[74:75], v[230:231], 0, s[28:29]
	s_mov_b32 m0, s78
	s_nop 0
	global_load_lds_dwordx4 v[74:75], off
	v_lshl_add_u64 v[74:75], v[232:233], 0, s[28:29]
	s_mov_b32 m0, s79
	s_nop 0
	global_load_lds_dwordx4 v[74:75], off
	s_waitcnt vmcnt(8)
	s_waitcnt lgkmcnt(0)
	s_barrier
	s_setprio 1
	s_waitcnt lgkmcnt(0)
	v_mfma_f32_16x16x32_bf16 v[60:63], v[88:91], v[194:197], v[60:63]
	v_mfma_f32_16x16x32_bf16 v[60:63], v[108:111], v[198:201], v[60:63]
	v_mfma_f32_16x16x32_bf16 v[56:59], v[144:147], v[198:201], v[56:59]
	v_mfma_f32_16x16x32_bf16 v[56:59], v[128:131], v[194:197], v[56:59]
	v_mfma_f32_16x16x32_bf16 v[40:43], v[128:131], v[202:205], v[40:43]
	v_mfma_f32_16x16x32_bf16 v[40:43], v[144:147], v[206:209], v[40:43]
	v_mfma_f32_16x16x32_bf16 v[44:47], v[108:111], v[206:209], v[44:47]
	v_mfma_f32_16x16x32_bf16 v[44:47], v[88:91], v[202:205], v[44:47]
	v_mfma_f32_16x16x32_bf16 v[28:31], v[88:91], v[210:213], v[28:31]
	v_mfma_f32_16x16x32_bf16 v[28:31], v[108:111], v[214:217], v[28:31]
	v_mfma_f32_16x16x32_bf16 v[24:27], v[144:147], v[214:217], v[24:27]
	v_mfma_f32_16x16x32_bf16 v[24:27], v[128:131], v[210:213], v[24:27]
	v_mfma_f32_16x16x32_bf16 v[8:11], v[128:131], v[218:221], v[8:11]
	v_mfma_f32_16x16x32_bf16 v[8:11], v[144:147], v[222:225], v[8:11]
	v_mfma_f32_16x16x32_bf16 v[12:15], v[108:111], v[222:225], v[12:15]
	v_mfma_f32_16x16x32_bf16 v[12:15], v[88:91], v[218:221], v[12:15]
	s_setprio 0
	s_setprio 1
	v_mfma_f32_16x16x32_bf16 v[52:55], v[148:151], v[194:197], v[52:55]
	v_mfma_f32_16x16x32_bf16 v[52:55], v[152:155], v[198:201], v[52:55]
	v_mfma_f32_16x16x32_bf16 v[48:51], v[190:193], v[198:201], v[48:51]
	v_mfma_f32_16x16x32_bf16 v[48:51], v[176:179], v[194:197], v[48:51]
	v_mfma_f32_16x16x32_bf16 v[32:35], v[176:179], v[202:205], v[32:35]
	v_mfma_f32_16x16x32_bf16 v[32:35], v[190:193], v[206:209], v[32:35]
	v_mfma_f32_16x16x32_bf16 v[36:39], v[152:155], v[206:209], v[36:39]
	v_mfma_f32_16x16x32_bf16 v[36:39], v[148:151], v[202:205], v[36:39]
	v_mfma_f32_16x16x32_bf16 v[20:23], v[148:151], v[210:213], v[20:23]
	v_mfma_f32_16x16x32_bf16 v[20:23], v[152:155], v[214:217], v[20:23]
	v_mfma_f32_16x16x32_bf16 v[16:19], v[190:193], v[214:217], v[16:19]
	v_mfma_f32_16x16x32_bf16 v[16:19], v[176:179], v[210:213], v[16:19]
	v_mfma_f32_16x16x32_bf16 v[0:3], v[176:179], v[218:221], v[0:3]
	v_mfma_f32_16x16x32_bf16 v[0:3], v[190:193], v[222:225], v[0:3]
	v_mfma_f32_16x16x32_bf16 v[4:7], v[152:155], v[222:225], v[4:7]
	v_mfma_f32_16x16x32_bf16 v[4:7], v[148:151], v[218:221], v[4:7]
	s_setprio 0
	s_barrier
	s_add_i32 s95, s95, 2
	s_add_u32 s93, s93, 0x100
	s_addc_u32 s94, s94, 0
	s_add_u32 s14, s14, 0x100
	s_addc_u32 s15, s15, 0
	s_branch .LBB0_256
.LBB0_255:
	v_add_u32_e32 v74, s83, v181
	ds_read_b128 v[88:91], v74
	v_xor_b32_e32 v253, 64, v74
	ds_read_b128 v[108:111], v253
	ds_read_b128 v[128:131], v74 offset:2048
	ds_read_b128 v[144:147], v253 offset:2048
	v_add_u32_e32 v74, s84, v181
	ds_read_b128 v[148:151], v74
	v_xor_b32_e32 v253, 64, v74
	ds_read_b128 v[152:155], v253
	ds_read_b128 v[176:179], v74 offset:2048
	ds_read_b128 v[190:193], v253 offset:2048
	s_add_u32 s68, s14, 0xfffc0080
	s_addc_u32 s69, s15, -1
	s_and_b64 s[66:67], s[66:67], exec
	s_cselect_b32 s69, s3, s69
	s_cselect_b32 s68, s61, s68
	s_cselect_b32 s67, s91, s94
	s_cselect_b32 s66, s92, s93
	v_lshl_add_u64 v[74:75], s[14:15], 0, v[170:171]
	s_add_i32 m0, s74, 0xc000
	ds_read_b128 v[194:197], v187
	v_xor_b32_e32 v253, 64, v187
	ds_read_b128 v[198:201], v253
	ds_read_b128 v[202:205], v187 offset:2048
	ds_read_b128 v[206:209], v253 offset:2048
	ds_read_b128 v[210:213], v187 offset:4096
	ds_read_b128 v[214:217], v253 offset:4096
	ds_read_b128 v[218:221], v187 offset:6144
	ds_read_b128 v[222:225], v253 offset:6144
	global_load_lds_dwordx4 v[74:75], off
	v_lshl_add_u64 v[74:75], s[14:15], 0, v[168:169]
	s_add_i32 m0, s74, 0xe000
	s_nop 0
	global_load_lds_dwordx4 v[74:75], off
	s_waitcnt vmcnt(8)
	s_waitcnt lgkmcnt(0)
	s_barrier
	s_setprio 1
	s_waitcnt lgkmcnt(0)
	v_mfma_f32_16x16x32_bf16 v[140:143], v[88:91], v[194:197], v[140:143]
	v_mfma_f32_16x16x32_bf16 v[136:139], v[128:131], v[194:197], v[136:139]
	v_mfma_f32_16x16x32_bf16 v[120:123], v[88:91], v[202:205], v[120:123]
	v_mfma_f32_16x16x32_bf16 v[116:119], v[128:131], v[202:205], v[116:119]
	v_mfma_f32_16x16x32_bf16 v[100:103], v[88:91], v[210:213], v[100:103]
	v_mfma_f32_16x16x32_bf16 v[96:99], v[128:131], v[210:213], v[96:99]
	v_mfma_f32_16x16x32_bf16 v[80:83], v[88:91], v[218:221], v[80:83]
	v_mfma_f32_16x16x32_bf16 v[74:77], v[128:131], v[218:221], v[76:79]
	v_mfma_f32_16x16x32_bf16 v[140:143], v[108:111], v[198:201], v[140:143]
	v_mfma_f32_16x16x32_bf16 v[136:139], v[144:147], v[198:201], v[136:139]
	v_mfma_f32_16x16x32_bf16 v[120:123], v[108:111], v[206:209], v[120:123]
	v_mfma_f32_16x16x32_bf16 v[116:119], v[144:147], v[206:209], v[116:119]
	v_mfma_f32_16x16x32_bf16 v[100:103], v[108:111], v[214:217], v[100:103]
	v_mfma_f32_16x16x32_bf16 v[96:99], v[144:147], v[214:217], v[96:99]
	v_mfma_f32_16x16x32_bf16 v[80:83], v[108:111], v[222:225], v[80:83]
	v_mfma_f32_16x16x32_bf16 v[74:77], v[144:147], v[222:225], v[74:77]
	s_setprio 0
	s_setprio 1
	v_mfma_f32_16x16x32_bf16 v[132:135], v[148:151], v[194:197], v[132:135]
	v_mfma_f32_16x16x32_bf16 v[132:135], v[152:155], v[198:201], v[132:135]
	v_mfma_f32_16x16x32_bf16 v[124:127], v[190:193], v[198:201], v[124:127]
	v_mfma_f32_16x16x32_bf16 v[124:127], v[176:179], v[194:197], v[124:127]
	v_mfma_f32_16x16x32_bf16 v[104:107], v[176:179], v[202:205], v[104:107]
	v_mfma_f32_16x16x32_bf16 v[104:107], v[190:193], v[206:209], v[104:107]
	v_mfma_f32_16x16x32_bf16 v[112:115], v[152:155], v[206:209], v[112:115]
	v_mfma_f32_16x16x32_bf16 v[112:115], v[148:151], v[202:205], v[112:115]
	v_mfma_f32_16x16x32_bf16 v[92:95], v[148:151], v[210:213], v[92:95]
	v_mfma_f32_16x16x32_bf16 v[92:95], v[152:155], v[214:217], v[92:95]
	v_mfma_f32_16x16x32_bf16 v[84:87], v[190:193], v[214:217], v[84:87]
	v_mfma_f32_16x16x32_bf16 v[84:87], v[176:179], v[210:213], v[84:87]
	v_mfma_f32_16x16x32_bf16 v[64:67], v[176:179], v[218:221], v[64:67]
	v_mfma_f32_16x16x32_bf16 v[64:67], v[190:193], v[222:225], v[64:67]
	v_mfma_f32_16x16x32_bf16 v[68:71], v[152:155], v[222:225], v[68:71]
	v_mfma_f32_16x16x32_bf16 v[68:71], v[148:151], v[218:221], v[68:71]
	s_setprio 0
	s_barrier
	s_add_i32 s96, s83, s71
	v_lshl_add_u64 v[226:227], s[66:67], 0, v[162:163]
	s_mov_b32 m0, s96
	ds_read_b128 v[194:197], v187 offset:16384
	v_xor_b32_e32 v253, 64, v187
	ds_read_b128 v[198:201], v253 offset:16384
	ds_read_b128 v[202:205], v187 offset:18432
	ds_read_b128 v[206:209], v253 offset:18432
	ds_read_b128 v[210:213], v187 offset:20480
	ds_read_b128 v[214:217], v253 offset:20480
	ds_read_b128 v[218:221], v187 offset:22528
	ds_read_b128 v[222:225], v253 offset:22528
	global_load_lds_dwordx4 v[226:227], off
	s_add_i32 m0, s96, 0x2000
	s_add_u32 s96, s66, 0x40000
	v_lshl_add_u64 v[228:229], s[66:67], 0, v[166:167]
	s_addc_u32 s97, s67, 0
	s_add_i32 vcc_lo, s84, s71
	global_load_lds_dwordx4 v[228:229], off
	v_lshl_add_u64 v[78:79], s[96:97], 0, v[162:163]
	s_mov_b32 m0, vcc_lo
	v_lshl_add_u64 v[230:231], s[68:69], 0, v[160:161]
	global_load_lds_dwordx4 v[78:79], off
	v_lshl_add_u64 v[78:79], s[96:97], 0, v[166:167]
	s_add_i32 m0, vcc_lo, 0x2000
	v_lshl_add_u64 v[232:233], s[68:69], 0, v[164:165]
	global_load_lds_dwordx4 v[78:79], off
	s_mov_b32 m0, s74
	s_nop 0
	global_load_lds_dwordx4 v[230:231], off
	s_mov_b32 m0, s75
	s_nop 0
	global_load_lds_dwordx4 v[232:233], off
	s_waitcnt vmcnt(8)
	s_waitcnt lgkmcnt(0)
	s_barrier
	s_setprio 1
	s_waitcnt lgkmcnt(0)
	v_mfma_f32_16x16x32_bf16 v[60:63], v[88:91], v[194:197], v[60:63]
	v_mfma_f32_16x16x32_bf16 v[60:63], v[108:111], v[198:201], v[60:63]
	v_mfma_f32_16x16x32_bf16 v[56:59], v[144:147], v[198:201], v[56:59]
	v_mfma_f32_16x16x32_bf16 v[56:59], v[128:131], v[194:197], v[56:59]
	v_mfma_f32_16x16x32_bf16 v[40:43], v[128:131], v[202:205], v[40:43]
	v_mfma_f32_16x16x32_bf16 v[40:43], v[144:147], v[206:209], v[40:43]
	v_mfma_f32_16x16x32_bf16 v[44:47], v[108:111], v[206:209], v[44:47]
	v_mfma_f32_16x16x32_bf16 v[44:47], v[88:91], v[202:205], v[44:47]
	v_mfma_f32_16x16x32_bf16 v[28:31], v[88:91], v[210:213], v[28:31]
	v_mfma_f32_16x16x32_bf16 v[28:31], v[108:111], v[214:217], v[28:31]
	v_mfma_f32_16x16x32_bf16 v[24:27], v[144:147], v[214:217], v[24:27]
	v_mfma_f32_16x16x32_bf16 v[24:27], v[128:131], v[210:213], v[24:27]
	v_mfma_f32_16x16x32_bf16 v[8:11], v[128:131], v[218:221], v[8:11]
	v_mfma_f32_16x16x32_bf16 v[8:11], v[144:147], v[222:225], v[8:11]
	v_mfma_f32_16x16x32_bf16 v[12:15], v[108:111], v[222:225], v[12:15]
	v_mfma_f32_16x16x32_bf16 v[12:15], v[88:91], v[218:221], v[12:15]
	s_setprio 0
	s_setprio 1
	v_mfma_f32_16x16x32_bf16 v[52:55], v[148:151], v[194:197], v[52:55]
	v_mfma_f32_16x16x32_bf16 v[52:55], v[152:155], v[198:201], v[52:55]
	v_mfma_f32_16x16x32_bf16 v[48:51], v[190:193], v[198:201], v[48:51]
	v_mfma_f32_16x16x32_bf16 v[48:51], v[176:179], v[194:197], v[48:51]
	v_mfma_f32_16x16x32_bf16 v[32:35], v[176:179], v[202:205], v[32:35]
	v_mfma_f32_16x16x32_bf16 v[32:35], v[190:193], v[206:209], v[32:35]
	v_mfma_f32_16x16x32_bf16 v[36:39], v[152:155], v[206:209], v[36:39]
	v_mfma_f32_16x16x32_bf16 v[36:39], v[148:151], v[202:205], v[36:39]
	v_mfma_f32_16x16x32_bf16 v[20:23], v[148:151], v[210:213], v[20:23]
	v_mfma_f32_16x16x32_bf16 v[20:23], v[152:155], v[214:217], v[20:23]
	v_mfma_f32_16x16x32_bf16 v[16:19], v[190:193], v[214:217], v[16:19]
	v_mfma_f32_16x16x32_bf16 v[16:19], v[176:179], v[210:213], v[16:19]
	v_mfma_f32_16x16x32_bf16 v[0:3], v[176:179], v[218:221], v[0:3]
	v_mfma_f32_16x16x32_bf16 v[0:3], v[190:193], v[222:225], v[0:3]
	v_mfma_f32_16x16x32_bf16 v[4:7], v[152:155], v[222:225], v[4:7]
	v_mfma_f32_16x16x32_bf16 v[4:7], v[148:151], v[218:221], v[4:7]
	s_setprio 0
	s_barrier
	s_add_i32 s96, 0, 0x18000
	v_add_u32_e32 v78, s96, v181
	s_add_i32 s97, 0, 0x1c000
	ds_read_b128 v[88:91], v78
	v_xor_b32_e32 v253, 64, v78
	ds_read_b128 v[108:111], v253
	ds_read_b128 v[128:131], v78 offset:2048
	ds_read_b128 v[144:147], v253 offset:2048
	v_add_u32_e32 v78, s97, v181
	ds_read_b128 v[148:151], v78
	v_xor_b32_e32 v253, 64, v78
	ds_read_b128 v[152:155], v253
	ds_read_b128 v[176:179], v78 offset:2048
	ds_read_b128 v[190:193], v253 offset:2048
	s_add_u32 s68, s68, 0x40000
	s_addc_u32 s69, s69, 0
	s_mov_b32 m0, s76
	v_lshl_add_u64 v[78:79], s[68:69], 0, v[160:161]
	ds_read_b128 v[194:197], v187 offset:32768
	v_xor_b32_e32 v253, 64, v187
	ds_read_b128 v[198:201], v253 offset:32768
	ds_read_b128 v[202:205], v187 offset:34816
	ds_read_b128 v[206:209], v253 offset:34816
	ds_read_b128 v[210:213], v187 offset:36864
	ds_read_b128 v[214:217], v253 offset:36864
	ds_read_b128 v[218:221], v187 offset:38912
	ds_read_b128 v[222:225], v253 offset:38912
	global_load_lds_dwordx4 v[78:79], off
	v_lshl_add_u64 v[78:79], s[68:69], 0, v[164:165]
	s_mov_b32 m0, s77
	s_nop 0
	global_load_lds_dwordx4 v[78:79], off
	s_waitcnt vmcnt(8)
	s_waitcnt lgkmcnt(0)
	s_barrier
	s_setprio 1
	s_waitcnt lgkmcnt(0)
	v_mfma_f32_16x16x32_bf16 v[140:143], v[88:91], v[194:197], v[140:143]
	v_mfma_f32_16x16x32_bf16 v[136:139], v[128:131], v[194:197], v[136:139]
	v_mfma_f32_16x16x32_bf16 v[120:123], v[88:91], v[202:205], v[120:123]
	v_mfma_f32_16x16x32_bf16 v[116:119], v[128:131], v[202:205], v[116:119]
	v_mfma_f32_16x16x32_bf16 v[100:103], v[88:91], v[210:213], v[100:103]
	v_mfma_f32_16x16x32_bf16 v[96:99], v[128:131], v[210:213], v[96:99]
	v_mfma_f32_16x16x32_bf16 v[78:81], v[88:91], v[218:221], v[80:83]
	v_mfma_f32_16x16x32_bf16 v[74:77], v[128:131], v[218:221], v[74:77]
	v_mfma_f32_16x16x32_bf16 v[140:143], v[108:111], v[198:201], v[140:143]
	v_mfma_f32_16x16x32_bf16 v[136:139], v[144:147], v[198:201], v[136:139]
	v_mfma_f32_16x16x32_bf16 v[120:123], v[108:111], v[206:209], v[120:123]
	v_mfma_f32_16x16x32_bf16 v[116:119], v[144:147], v[206:209], v[116:119]
	v_mfma_f32_16x16x32_bf16 v[100:103], v[108:111], v[214:217], v[100:103]
	v_mfma_f32_16x16x32_bf16 v[96:99], v[144:147], v[214:217], v[96:99]
	v_mfma_f32_16x16x32_bf16 v[80:83], v[108:111], v[222:225], v[78:81]
	v_mfma_f32_16x16x32_bf16 v[76:79], v[144:147], v[222:225], v[74:77]
	s_setprio 0
	s_setprio 1
	v_mfma_f32_16x16x32_bf16 v[132:135], v[148:151], v[194:197], v[132:135]
	v_mfma_f32_16x16x32_bf16 v[132:135], v[152:155], v[198:201], v[132:135]
	v_mfma_f32_16x16x32_bf16 v[124:127], v[190:193], v[198:201], v[124:127]
	v_mfma_f32_16x16x32_bf16 v[124:127], v[176:179], v[194:197], v[124:127]
	v_mfma_f32_16x16x32_bf16 v[104:107], v[176:179], v[202:205], v[104:107]
	v_mfma_f32_16x16x32_bf16 v[104:107], v[190:193], v[206:209], v[104:107]
	v_mfma_f32_16x16x32_bf16 v[112:115], v[152:155], v[206:209], v[112:115]
	v_mfma_f32_16x16x32_bf16 v[112:115], v[148:151], v[202:205], v[112:115]
	v_mfma_f32_16x16x32_bf16 v[92:95], v[148:151], v[210:213], v[92:95]
	v_mfma_f32_16x16x32_bf16 v[92:95], v[152:155], v[214:217], v[92:95]
	v_mfma_f32_16x16x32_bf16 v[84:87], v[190:193], v[214:217], v[84:87]
	v_mfma_f32_16x16x32_bf16 v[84:87], v[176:179], v[210:213], v[84:87]
	v_mfma_f32_16x16x32_bf16 v[64:67], v[176:179], v[218:221], v[64:67]
	v_mfma_f32_16x16x32_bf16 v[64:67], v[190:193], v[222:225], v[64:67]
	v_mfma_f32_16x16x32_bf16 v[68:71], v[152:155], v[222:225], v[68:71]
	v_mfma_f32_16x16x32_bf16 v[68:71], v[148:151], v[218:221], v[68:71]
	s_setprio 0
	s_barrier
	s_add_i32 s68, s96, s71
	v_lshl_add_u64 v[74:75], v[226:227], 0, s[28:29]
	s_mov_b32 m0, s68
	ds_read_b128 v[194:197], v187 offset:49152
	v_xor_b32_e32 v253, 64, v187
	ds_read_b128 v[198:201], v253 offset:49152
	ds_read_b128 v[202:205], v187 offset:51200
	ds_read_b128 v[206:209], v253 offset:51200
	ds_read_b128 v[210:213], v187 offset:53248
	ds_read_b128 v[214:217], v253 offset:53248
	ds_read_b128 v[218:221], v187 offset:55296
	ds_read_b128 v[222:225], v253 offset:55296
	global_load_lds_dwordx4 v[74:75], off
	s_add_i32 m0, s68, 0x2000
	s_add_u32 s66, s66, 0x40080
	v_lshl_add_u64 v[74:75], v[228:229], 0, s[28:29]
	s_addc_u32 s67, s67, 0
	s_add_i32 s68, s97, s71
	global_load_lds_dwordx4 v[74:75], off
	v_lshl_add_u64 v[74:75], s[66:67], 0, v[162:163]
	s_mov_b32 m0, s68
	s_nop 0
	global_load_lds_dwordx4 v[74:75], off
	v_lshl_add_u64 v[74:75], s[66:67], 0, v[166:167]
	s_add_i32 m0, s68, 0x2000
	s_nop 0
	global_load_lds_dwordx4 v[74:75], off
	v_lshl_add_u64 v[74:75], v[230:231], 0, s[28:29]
	s_mov_b32 m0, s78
	s_nop 0
	global_load_lds_dwordx4 v[74:75], off
	v_lshl_add_u64 v[74:75], v[232:233], 0, s[28:29]
	s_mov_b32 m0, s79
	s_nop 0
	global_load_lds_dwordx4 v[74:75], off
	s_waitcnt vmcnt(8)
	s_waitcnt lgkmcnt(0)
	s_barrier
	s_setprio 1
	s_waitcnt lgkmcnt(0)
	v_mfma_f32_16x16x32_bf16 v[60:63], v[88:91], v[194:197], v[60:63]
	v_mfma_f32_16x16x32_bf16 v[60:63], v[108:111], v[198:201], v[60:63]
	v_mfma_f32_16x16x32_bf16 v[56:59], v[144:147], v[198:201], v[56:59]
	v_mfma_f32_16x16x32_bf16 v[56:59], v[128:131], v[194:197], v[56:59]
	v_mfma_f32_16x16x32_bf16 v[40:43], v[128:131], v[202:205], v[40:43]
	v_mfma_f32_16x16x32_bf16 v[40:43], v[144:147], v[206:209], v[40:43]
	v_mfma_f32_16x16x32_bf16 v[44:47], v[108:111], v[206:209], v[44:47]
	v_mfma_f32_16x16x32_bf16 v[44:47], v[88:91], v[202:205], v[44:47]
	v_mfma_f32_16x16x32_bf16 v[28:31], v[88:91], v[210:213], v[28:31]
	v_mfma_f32_16x16x32_bf16 v[28:31], v[108:111], v[214:217], v[28:31]
	v_mfma_f32_16x16x32_bf16 v[24:27], v[144:147], v[214:217], v[24:27]
	v_mfma_f32_16x16x32_bf16 v[24:27], v[128:131], v[210:213], v[24:27]
	v_mfma_f32_16x16x32_bf16 v[8:11], v[128:131], v[218:221], v[8:11]
	v_mfma_f32_16x16x32_bf16 v[8:11], v[144:147], v[222:225], v[8:11]
	v_mfma_f32_16x16x32_bf16 v[12:15], v[108:111], v[222:225], v[12:15]
	v_mfma_f32_16x16x32_bf16 v[12:15], v[88:91], v[218:221], v[12:15]
	s_setprio 0
	s_setprio 1
	v_mfma_f32_16x16x32_bf16 v[52:55], v[148:151], v[194:197], v[52:55]
	v_mfma_f32_16x16x32_bf16 v[52:55], v[152:155], v[198:201], v[52:55]
	v_mfma_f32_16x16x32_bf16 v[48:51], v[190:193], v[198:201], v[48:51]
	v_mfma_f32_16x16x32_bf16 v[48:51], v[176:179], v[194:197], v[48:51]
	v_mfma_f32_16x16x32_bf16 v[32:35], v[176:179], v[202:205], v[32:35]
	v_mfma_f32_16x16x32_bf16 v[32:35], v[190:193], v[206:209], v[32:35]
	v_mfma_f32_16x16x32_bf16 v[36:39], v[152:155], v[206:209], v[36:39]
	v_mfma_f32_16x16x32_bf16 v[36:39], v[148:151], v[202:205], v[36:39]
	v_mfma_f32_16x16x32_bf16 v[20:23], v[148:151], v[210:213], v[20:23]
	v_mfma_f32_16x16x32_bf16 v[20:23], v[152:155], v[214:217], v[20:23]
	v_mfma_f32_16x16x32_bf16 v[16:19], v[190:193], v[214:217], v[16:19]
	v_mfma_f32_16x16x32_bf16 v[16:19], v[176:179], v[210:213], v[16:19]
	v_mfma_f32_16x16x32_bf16 v[0:3], v[176:179], v[218:221], v[0:3]
	v_mfma_f32_16x16x32_bf16 v[0:3], v[190:193], v[222:225], v[0:3]
	v_mfma_f32_16x16x32_bf16 v[4:7], v[152:155], v[222:225], v[4:7]
	v_mfma_f32_16x16x32_bf16 v[4:7], v[148:151], v[218:221], v[4:7]
	s_setprio 0
	s_barrier
	s_add_i32 s95, s95, 2
	s_add_u32 s93, s93, 0x100
	s_addc_u32 s94, s94, 0
	s_add_u32 s14, s14, 0x100
	s_addc_u32 s15, s15, 0
	s_cmp_gt_u32 s95, 13
	s_cbranch_scc1 .LBB0_258

.LBB0_439:
	s_ashr_i32 s53, s52, 31
	s_lshl_b64 s[54:55], s[52:53], 20
	s_add_u32 s54, s35, s54
	s_addc_u32 s55, s66, s55
	s_and_b64 s[56:57], s[12:13], exec
	s_cselect_b32 s15, s55, s63
	s_cselect_b32 s53, s54, s62
	s_ashr_i32 s51, s50, 31
	s_lshl_b64 s[56:57], s[50:51], 20
	s_add_u32 s56, s67, s56
	s_addc_u32 s57, s68, s57
	s_and_b64 s[64:65], s[12:13], exec
	s_cselect_b32 s51, s57, s61
	s_cselect_b32 s59, s56, s60
	s_add_u32 s81, s60, 0x100
	s_addc_u32 s82, s61, 0
	s_add_u32 s60, s62, 0x80080
	s_addc_u32 s61, s63, 0
	s_mov_b32 s83, -2
	s_waitcnt lgkmcnt(0)
	s_cmp_eq_u32 s74, 1
	s_cbranch_scc1 .Lfa_3
	ds_read_b128 v[128:131], v189
	v_xor_b32_e32 v253, 64, v189
	ds_read_b128 v[132:135], v253
	ds_read_b128 v[136:139], v189 offset:2048
	ds_read_b128 v[140:143], v253 offset:2048
	ds_read_b128 v[144:147], v190
	v_xor_b32_e32 v253, 64, v190
	ds_read_b128 v[148:151], v253
	ds_read_b128 v[172:175], v190 offset:2048
	ds_read_b128 v[176:179], v253 offset:2048
	s_add_u32 s62, s60, 0xfff80080
	s_addc_u32 s63, s61, -1
	s_cmp_eq_u32 s83, 28
	s_cselect_b32 s65, s15, s63
	s_cselect_b32 s64, s53, s62
	s_cselect_b32 s63, s51, s82
	s_cselect_b32 s62, s59, s81
	v_lshl_add_u64 v[222:223], s[60:61], 0, v[166:167]
	s_add_i32 m0, s70, 0xc000
	ds_read_b128 v[180:183], v191
	v_xor_b32_e32 v253, 64, v191
	ds_read_b128 v[194:197], v253
	ds_read_b128 v[198:201], v191 offset:2048
	ds_read_b128 v[202:205], v253 offset:2048
	ds_read_b128 v[206:209], v191 offset:4096
	ds_read_b128 v[210:213], v253 offset:4096
	ds_read_b128 v[214:217], v191 offset:6144
	ds_read_b128 v[218:221], v253 offset:6144
	global_load_lds_dwordx4 v[222:223], off
	v_lshl_add_u64 v[222:223], s[60:61], 0, v[164:165]
	s_add_i32 m0, s70, 0xe000
	s_nop 0
	global_load_lds_dwordx4 v[222:223], off
	s_waitcnt vmcnt(24)
	s_waitcnt lgkmcnt(0)
	s_barrier
	s_setprio 1
	s_waitcnt lgkmcnt(0)
	v_mfma_f32_16x16x32_bf16 v[124:127], v[128:131], v[180:183], 0
	v_mfma_f32_16x16x32_bf16 v[120:123], v[136:139], v[180:183], 0
	v_mfma_f32_16x16x32_bf16 v[108:111], v[128:131], v[198:201], 0
	v_mfma_f32_16x16x32_bf16 v[104:107], v[136:139], v[198:201], 0
	v_mfma_f32_16x16x32_bf16 v[92:95], v[128:131], v[206:209], 0
	v_mfma_f32_16x16x32_bf16 v[88:91], v[136:139], v[206:209], 0
	v_mfma_f32_16x16x32_bf16 v[76:79], v[128:131], v[214:217], 0
	v_mfma_f32_16x16x32_bf16 v[72:75], v[136:139], v[214:217], 0
	v_mfma_f32_16x16x32_bf16 v[124:127], v[132:135], v[194:197], v[124:127]
	v_mfma_f32_16x16x32_bf16 v[120:123], v[140:143], v[194:197], v[120:123]
	v_mfma_f32_16x16x32_bf16 v[108:111], v[132:135], v[202:205], v[108:111]
	v_mfma_f32_16x16x32_bf16 v[104:107], v[140:143], v[202:205], v[104:107]
	v_mfma_f32_16x16x32_bf16 v[92:95], v[132:135], v[210:213], v[92:95]
	v_mfma_f32_16x16x32_bf16 v[88:91], v[140:143], v[210:213], v[88:91]
	v_mfma_f32_16x16x32_bf16 v[76:79], v[132:135], v[218:221], v[76:79]
	v_mfma_f32_16x16x32_bf16 v[72:75], v[140:143], v[218:221], v[72:75]
	s_setprio 0
	s_setprio 1
	v_mfma_f32_16x16x32_bf16 v[116:119], v[144:147], v[180:183], 0
	v_mfma_f32_16x16x32_bf16 v[112:115], v[172:175], v[180:183], 0
	v_mfma_f32_16x16x32_bf16 v[100:103], v[144:147], v[198:201], 0
	v_mfma_f32_16x16x32_bf16 v[96:99], v[172:175], v[198:201], 0
	v_mfma_f32_16x16x32_bf16 v[84:87], v[144:147], v[206:209], 0
	v_mfma_f32_16x16x32_bf16 v[80:83], v[172:175], v[206:209], 0
	v_mfma_f32_16x16x32_bf16 v[68:71], v[144:147], v[214:217], 0
	v_mfma_f32_16x16x32_bf16 v[64:67], v[172:175], v[214:217], 0
	v_mfma_f32_16x16x32_bf16 v[116:119], v[148:151], v[194:197], v[116:119]
	v_mfma_f32_16x16x32_bf16 v[112:115], v[176:179], v[194:197], v[112:115]
	v_mfma_f32_16x16x32_bf16 v[100:103], v[148:151], v[202:205], v[100:103]
	v_mfma_f32_16x16x32_bf16 v[96:99], v[176:179], v[202:205], v[96:99]
	v_mfma_f32_16x16x32_bf16 v[84:87], v[148:151], v[210:213], v[84:87]
	v_mfma_f32_16x16x32_bf16 v[80:83], v[176:179], v[210:213], v[80:83]
	v_mfma_f32_16x16x32_bf16 v[68:71], v[148:151], v[218:221], v[68:71]
	v_mfma_f32_16x16x32_bf16 v[64:67], v[176:179], v[218:221], v[64:67]
	s_setprio 0
	s_barrier
	s_add_i32 s84, s79, s69
	v_lshl_add_u64 v[222:223], s[62:63], 0, v[154:155]
	s_mov_b32 m0, s84
	ds_read_b128 v[180:183], v191 offset:16384
	v_xor_b32_e32 v253, 64, v191
	ds_read_b128 v[194:197], v253 offset:16384
	ds_read_b128 v[198:201], v191 offset:18432
	ds_read_b128 v[202:205], v253 offset:18432
	ds_read_b128 v[206:209], v191 offset:20480
	ds_read_b128 v[210:213], v253 offset:20480
	ds_read_b128 v[214:217], v191 offset:22528
	ds_read_b128 v[218:221], v253 offset:22528
	global_load_lds_dwordx4 v[222:223], off
	s_add_i32 m0, s84, 0x2000
	s_add_u32 s84, s62, 0x80000
	v_lshl_add_u64 v[224:225], s[62:63], 0, v[162:163]
	s_addc_u32 s85, s63, 0
	s_add_i32 s86, s80, s69
	global_load_lds_dwordx4 v[224:225], off
	v_lshl_add_u64 v[226:227], s[84:85], 0, v[154:155]
	s_mov_b32 m0, s86
	v_lshl_add_u64 v[228:229], s[64:65], 0, v[160:161]
	global_load_lds_dwordx4 v[226:227], off
	v_lshl_add_u64 v[226:227], s[84:85], 0, v[162:163]
	s_add_i32 m0, s86, 0x2000
	s_nop 0
	global_load_lds_dwordx4 v[226:227], off
	v_lshl_add_u64 v[226:227], s[64:65], 0, v[152:153]
	s_mov_b32 m0, s70
	s_nop 0
	global_load_lds_dwordx4 v[226:227], off
	s_mov_b32 m0, s71
	s_nop 0
	global_load_lds_dwordx4 v[228:229], off
	s_waitcnt vmcnt(24)
	s_waitcnt lgkmcnt(0)
	s_barrier
	s_setprio 1
	s_waitcnt lgkmcnt(0)
	v_mfma_f32_16x16x32_bf16 v[60:63], v[128:131], v[180:183], 0
	v_mfma_f32_16x16x32_bf16 v[56:59], v[136:139], v[180:183], 0
	v_mfma_f32_16x16x32_bf16 v[44:47], v[128:131], v[198:201], 0
	v_mfma_f32_16x16x32_bf16 v[40:43], v[136:139], v[198:201], 0
	v_mfma_f32_16x16x32_bf16 v[28:31], v[128:131], v[206:209], 0
	v_mfma_f32_16x16x32_bf16 v[24:27], v[136:139], v[206:209], 0
	v_mfma_f32_16x16x32_bf16 v[12:15], v[128:131], v[214:217], 0
	v_mfma_f32_16x16x32_bf16 v[8:11], v[136:139], v[214:217], 0
	v_mfma_f32_16x16x32_bf16 v[60:63], v[132:135], v[194:197], v[60:63]
	v_mfma_f32_16x16x32_bf16 v[56:59], v[140:143], v[194:197], v[56:59]
	v_mfma_f32_16x16x32_bf16 v[44:47], v[132:135], v[202:205], v[44:47]
	v_mfma_f32_16x16x32_bf16 v[40:43], v[140:143], v[202:205], v[40:43]
	v_mfma_f32_16x16x32_bf16 v[28:31], v[132:135], v[210:213], v[28:31]
	v_mfma_f32_16x16x32_bf16 v[24:27], v[140:143], v[210:213], v[24:27]
	v_mfma_f32_16x16x32_bf16 v[12:15], v[132:135], v[218:221], v[12:15]
	v_mfma_f32_16x16x32_bf16 v[8:11], v[140:143], v[218:221], v[8:11]
	s_setprio 0
	s_setprio 1
	v_mfma_f32_16x16x32_bf16 v[52:55], v[144:147], v[180:183], 0
	v_mfma_f32_16x16x32_bf16 v[48:51], v[172:175], v[180:183], 0
	v_mfma_f32_16x16x32_bf16 v[36:39], v[144:147], v[198:201], 0
	v_mfma_f32_16x16x32_bf16 v[32:35], v[172:175], v[198:201], 0
	v_mfma_f32_16x16x32_bf16 v[20:23], v[144:147], v[206:209], 0
	v_mfma_f32_16x16x32_bf16 v[16:19], v[172:175], v[206:209], 0
	v_mfma_f32_16x16x32_bf16 v[4:7], v[144:147], v[214:217], 0
	v_mfma_f32_16x16x32_bf16 v[0:3], v[172:175], v[214:217], 0
	v_mfma_f32_16x16x32_bf16 v[52:55], v[148:151], v[194:197], v[52:55]
	v_mfma_f32_16x16x32_bf16 v[48:51], v[176:179], v[194:197], v[48:51]
	v_mfma_f32_16x16x32_bf16 v[36:39], v[148:151], v[202:205], v[36:39]
	v_mfma_f32_16x16x32_bf16 v[32:35], v[176:179], v[202:205], v[32:35]
	v_mfma_f32_16x16x32_bf16 v[20:23], v[148:151], v[210:213], v[20:23]
	v_mfma_f32_16x16x32_bf16 v[16:19], v[176:179], v[210:213], v[16:19]
	v_mfma_f32_16x16x32_bf16 v[4:7], v[148:151], v[218:221], v[4:7]
	v_mfma_f32_16x16x32_bf16 v[0:3], v[176:179], v[218:221], v[0:3]
	s_setprio 0
	s_barrier
	s_add_i32 s84, 0, 0x18000
	s_add_i32 s85, 0, 0x1c000
	v_add_u32_e32 v140, s84, v186
	v_add_u32_e32 v176, s85, v186
	ds_read_b128 v[128:131], v140
	v_xor_b32_e32 v253, 64, v140
	ds_read_b128 v[132:135], v253
	ds_read_b128 v[136:139], v140 offset:2048
	ds_read_b128 v[140:143], v253 offset:2048
	ds_read_b128 v[144:147], v176
	v_xor_b32_e32 v253, 64, v176
	ds_read_b128 v[148:151], v253
	ds_read_b128 v[172:175], v176 offset:2048
	ds_read_b128 v[176:179], v253 offset:2048
	s_add_u32 s64, s64, 0x80000
	s_addc_u32 s65, s65, 0
	s_mov_b32 m0, s72
	v_lshl_add_u64 v[230:231], s[64:65], 0, v[152:153]
	ds_read_b128 v[180:183], v191 offset:32768
	v_xor_b32_e32 v253, 64, v191
	ds_read_b128 v[194:197], v253 offset:32768
	ds_read_b128 v[198:201], v191 offset:34816
	ds_read_b128 v[202:205], v253 offset:34816
	ds_read_b128 v[206:209], v191 offset:36864
	ds_read_b128 v[210:213], v253 offset:36864
	ds_read_b128 v[214:217], v191 offset:38912
	ds_read_b128 v[218:221], v253 offset:38912
	global_load_lds_dwordx4 v[230:231], off
	v_lshl_add_u64 v[230:231], s[64:65], 0, v[160:161]
	s_mov_b32 m0, s73
	s_nop 0
	global_load_lds_dwordx4 v[230:231], off
	s_waitcnt vmcnt(8)
	s_waitcnt lgkmcnt(0)
	s_barrier
	s_setprio 1
	s_waitcnt lgkmcnt(0)
	v_mfma_f32_16x16x32_bf16 v[124:127], v[128:131], v[180:183], v[124:127]
	v_mfma_f32_16x16x32_bf16 v[124:127], v[132:135], v[194:197], v[124:127]
	v_mfma_f32_16x16x32_bf16 v[120:123], v[140:143], v[194:197], v[120:123]
	v_mfma_f32_16x16x32_bf16 v[120:123], v[136:139], v[180:183], v[120:123]
	v_mfma_f32_16x16x32_bf16 v[104:107], v[136:139], v[198:201], v[104:107]
	v_mfma_f32_16x16x32_bf16 v[104:107], v[140:143], v[202:205], v[104:107]
	v_mfma_f32_16x16x32_bf16 v[108:111], v[132:135], v[202:205], v[108:111]
	v_mfma_f32_16x16x32_bf16 v[108:111], v[128:131], v[198:201], v[108:111]
	v_mfma_f32_16x16x32_bf16 v[92:95], v[128:131], v[206:209], v[92:95]
	v_mfma_f32_16x16x32_bf16 v[92:95], v[132:135], v[210:213], v[92:95]
	v_mfma_f32_16x16x32_bf16 v[88:91], v[140:143], v[210:213], v[88:91]
	v_mfma_f32_16x16x32_bf16 v[88:91], v[136:139], v[206:209], v[88:91]
	v_mfma_f32_16x16x32_bf16 v[72:75], v[136:139], v[214:217], v[72:75]
	v_mfma_f32_16x16x32_bf16 v[72:75], v[140:143], v[218:221], v[72:75]
	v_mfma_f32_16x16x32_bf16 v[76:79], v[132:135], v[218:221], v[76:79]
	v_mfma_f32_16x16x32_bf16 v[76:79], v[128:131], v[214:217], v[76:79]
	s_setprio 0
	s_setprio 1
	v_mfma_f32_16x16x32_bf16 v[116:119], v[144:147], v[180:183], v[116:119]
	v_mfma_f32_16x16x32_bf16 v[116:119], v[148:151], v[194:197], v[116:119]
	v_mfma_f32_16x16x32_bf16 v[112:115], v[176:179], v[194:197], v[112:115]
	v_mfma_f32_16x16x32_bf16 v[112:115], v[172:175], v[180:183], v[112:115]
	v_mfma_f32_16x16x32_bf16 v[96:99], v[172:175], v[198:201], v[96:99]
	v_mfma_f32_16x16x32_bf16 v[96:99], v[176:179], v[202:205], v[96:99]
	v_mfma_f32_16x16x32_bf16 v[100:103], v[148:151], v[202:205], v[100:103]
	v_mfma_f32_16x16x32_bf16 v[100:103], v[144:147], v[198:201], v[100:103]
	v_mfma_f32_16x16x32_bf16 v[84:87], v[144:147], v[206:209], v[84:87]
	v_mfma_f32_16x16x32_bf16 v[84:87], v[148:151], v[210:213], v[84:87]
	v_mfma_f32_16x16x32_bf16 v[80:83], v[176:179], v[210:213], v[80:83]
	v_mfma_f32_16x16x32_bf16 v[80:83], v[172:175], v[206:209], v[80:83]
	v_mfma_f32_16x16x32_bf16 v[64:67], v[172:175], v[214:217], v[64:67]
	v_mfma_f32_16x16x32_bf16 v[64:67], v[176:179], v[218:221], v[64:67]
	v_mfma_f32_16x16x32_bf16 v[68:71], v[148:151], v[218:221], v[68:71]
	v_mfma_f32_16x16x32_bf16 v[68:71], v[144:147], v[214:217], v[68:71]
	s_setprio 0
	s_barrier
	s_add_i32 s64, s84, s69
	v_lshl_add_u64 v[222:223], v[222:223], 0, s[26:27]
	s_mov_b32 m0, s64
	ds_read_b128 v[180:183], v191 offset:49152
	v_xor_b32_e32 v253, 64, v191
	ds_read_b128 v[194:197], v253 offset:49152
	ds_read_b128 v[198:201], v191 offset:51200
	ds_read_b128 v[202:205], v253 offset:51200
	ds_read_b128 v[206:209], v191 offset:53248
	ds_read_b128 v[210:213], v253 offset:53248
	ds_read_b128 v[214:217], v191 offset:55296
	ds_read_b128 v[218:221], v253 offset:55296
	global_load_lds_dwordx4 v[222:223], off
	s_add_i32 m0, s64, 0x2000
	s_add_u32 s62, s62, 0x80080
	v_lshl_add_u64 v[222:223], v[224:225], 0, s[26:27]
	s_addc_u32 s63, s63, 0
	s_add_i32 s64, s85, s69
	global_load_lds_dwordx4 v[222:223], off
	v_lshl_add_u64 v[222:223], s[62:63], 0, v[154:155]
	s_mov_b32 m0, s64
	s_nop 0
	global_load_lds_dwordx4 v[222:223], off
	v_lshl_add_u64 v[222:223], s[62:63], 0, v[162:163]
	s_add_i32 m0, s64, 0x2000
	s_nop 0
	global_load_lds_dwordx4 v[222:223], off
	v_lshl_add_u64 v[222:223], v[226:227], 0, s[26:27]
	s_mov_b32 m0, s3
	s_nop 0
	global_load_lds_dwordx4 v[222:223], off
	v_lshl_add_u64 v[222:223], v[228:229], 0, s[26:27]
	s_mov_b32 m0, s75
	s_nop 0
	global_load_lds_dwordx4 v[222:223], off
	s_waitcnt vmcnt(8)
	s_waitcnt lgkmcnt(0)
	s_barrier
	s_setprio 1
	s_waitcnt lgkmcnt(0)
	v_mfma_f32_16x16x32_bf16 v[60:63], v[128:131], v[180:183], v[60:63]
	v_mfma_f32_16x16x32_bf16 v[60:63], v[132:135], v[194:197], v[60:63]
	v_mfma_f32_16x16x32_bf16 v[56:59], v[140:143], v[194:197], v[56:59]
	v_mfma_f32_16x16x32_bf16 v[56:59], v[136:139], v[180:183], v[56:59]
	v_mfma_f32_16x16x32_bf16 v[40:43], v[136:139], v[198:201], v[40:43]
	v_mfma_f32_16x16x32_bf16 v[40:43], v[140:143], v[202:205], v[40:43]
	v_mfma_f32_16x16x32_bf16 v[44:47], v[132:135], v[202:205], v[44:47]
	v_mfma_f32_16x16x32_bf16 v[44:47], v[128:131], v[198:201], v[44:47]
	v_mfma_f32_16x16x32_bf16 v[28:31], v[128:131], v[206:209], v[28:31]
	v_mfma_f32_16x16x32_bf16 v[28:31], v[132:135], v[210:213], v[28:31]
	v_mfma_f32_16x16x32_bf16 v[24:27], v[140:143], v[210:213], v[24:27]
	v_mfma_f32_16x16x32_bf16 v[24:27], v[136:139], v[206:209], v[24:27]
	v_mfma_f32_16x16x32_bf16 v[8:11], v[136:139], v[214:217], v[8:11]
	v_mfma_f32_16x16x32_bf16 v[8:11], v[140:143], v[218:221], v[8:11]
	v_mfma_f32_16x16x32_bf16 v[12:15], v[132:135], v[218:221], v[12:15]
	v_mfma_f32_16x16x32_bf16 v[12:15], v[128:131], v[214:217], v[12:15]
	s_setprio 0
	s_setprio 1
	v_mfma_f32_16x16x32_bf16 v[52:55], v[144:147], v[180:183], v[52:55]
	v_mfma_f32_16x16x32_bf16 v[52:55], v[148:151], v[194:197], v[52:55]
	v_mfma_f32_16x16x32_bf16 v[48:51], v[176:179], v[194:197], v[48:51]
	v_mfma_f32_16x16x32_bf16 v[48:51], v[172:175], v[180:183], v[48:51]
	v_mfma_f32_16x16x32_bf16 v[32:35], v[172:175], v[198:201], v[32:35]
	v_mfma_f32_16x16x32_bf16 v[32:35], v[176:179], v[202:205], v[32:35]
	v_mfma_f32_16x16x32_bf16 v[36:39], v[148:151], v[202:205], v[36:39]
	v_mfma_f32_16x16x32_bf16 v[36:39], v[144:147], v[198:201], v[36:39]
	v_mfma_f32_16x16x32_bf16 v[20:23], v[144:147], v[206:209], v[20:23]
	v_mfma_f32_16x16x32_bf16 v[20:23], v[148:151], v[210:213], v[20:23]
	v_mfma_f32_16x16x32_bf16 v[16:19], v[176:179], v[210:213], v[16:19]
	v_mfma_f32_16x16x32_bf16 v[16:19], v[172:175], v[206:209], v[16:19]
	v_mfma_f32_16x16x32_bf16 v[0:3], v[172:175], v[214:217], v[0:3]
	v_mfma_f32_16x16x32_bf16 v[0:3], v[176:179], v[218:221], v[0:3]
	v_mfma_f32_16x16x32_bf16 v[4:7], v[148:151], v[218:221], v[4:7]
	v_mfma_f32_16x16x32_bf16 v[4:7], v[144:147], v[214:217], v[4:7]
	s_setprio 0
	s_barrier
	s_add_i32 s83, s83, 2
	s_add_u32 s81, s81, 0x100
	s_addc_u32 s82, s82, 0
	s_add_u32 s60, s60, 0x100
	s_addc_u32 s61, s61, 0
	s_cmp_gt_u32 s83, 29
	s_branch .LBB0_440
.Lfa_3:
	ds_read_b128 v[128:131], v189
	v_xor_b32_e32 v253, 64, v189
	ds_read_b128 v[132:135], v253
	ds_read_b128 v[136:139], v189 offset:2048
	ds_read_b128 v[140:143], v253 offset:2048
	ds_read_b128 v[144:147], v190
	v_xor_b32_e32 v253, 64, v190
	ds_read_b128 v[148:151], v253
	ds_read_b128 v[172:175], v190 offset:2048
	ds_read_b128 v[176:179], v253 offset:2048
	s_add_u32 s62, s60, 0xfff80080
	s_addc_u32 s63, s61, -1
	s_cmp_eq_u32 s83, 28
	s_cselect_b32 s65, s15, s63
	s_cselect_b32 s64, s53, s62
	s_cselect_b32 s63, s51, s82
	s_cselect_b32 s62, s59, s81
	v_lshl_add_u64 v[222:223], s[60:61], 0, v[166:167]
	s_add_i32 m0, s70, 0xc000
	ds_read_b128 v[180:183], v191
	v_xor_b32_e32 v253, 64, v191
	ds_read_b128 v[194:197], v253
	ds_read_b128 v[198:201], v191 offset:2048
	ds_read_b128 v[202:205], v253 offset:2048
	ds_read_b128 v[206:209], v191 offset:4096
	ds_read_b128 v[210:213], v253 offset:4096
	ds_read_b128 v[214:217], v191 offset:6144
	ds_read_b128 v[218:221], v253 offset:6144
	global_load_lds_dwordx4 v[222:223], off
	v_lshl_add_u64 v[222:223], s[60:61], 0, v[164:165]
	s_add_i32 m0, s70, 0xe000
	s_nop 0
	global_load_lds_dwordx4 v[222:223], off
	s_waitcnt vmcnt(8)
	s_waitcnt lgkmcnt(0)
	s_barrier
	s_setprio 1
	s_waitcnt lgkmcnt(0)
	v_mfma_f32_16x16x32_bf16 v[124:127], v[128:131], v[180:183], 0
	v_mfma_f32_16x16x32_bf16 v[120:123], v[136:139], v[180:183], 0
	v_mfma_f32_16x16x32_bf16 v[108:111], v[128:131], v[198:201], 0
	v_mfma_f32_16x16x32_bf16 v[104:107], v[136:139], v[198:201], 0
	v_mfma_f32_16x16x32_bf16 v[92:95], v[128:131], v[206:209], 0
	v_mfma_f32_16x16x32_bf16 v[88:91], v[136:139], v[206:209], 0
	v_mfma_f32_16x16x32_bf16 v[76:79], v[128:131], v[214:217], 0
	v_mfma_f32_16x16x32_bf16 v[72:75], v[136:139], v[214:217], 0
	v_mfma_f32_16x16x32_bf16 v[124:127], v[132:135], v[194:197], v[124:127]
	v_mfma_f32_16x16x32_bf16 v[120:123], v[140:143], v[194:197], v[120:123]
	v_mfma_f32_16x16x32_bf16 v[108:111], v[132:135], v[202:205], v[108:111]
	v_mfma_f32_16x16x32_bf16 v[104:107], v[140:143], v[202:205], v[104:107]
	v_mfma_f32_16x16x32_bf16 v[92:95], v[132:135], v[210:213], v[92:95]
	v_mfma_f32_16x16x32_bf16 v[88:91], v[140:143], v[210:213], v[88:91]
	v_mfma_f32_16x16x32_bf16 v[76:79], v[132:135], v[218:221], v[76:79]
	v_mfma_f32_16x16x32_bf16 v[72:75], v[140:143], v[218:221], v[72:75]
	s_setprio 0
	s_setprio 1
	v_mfma_f32_16x16x32_bf16 v[116:119], v[144:147], v[180:183], 0
	v_mfma_f32_16x16x32_bf16 v[112:115], v[172:175], v[180:183], 0
	v_mfma_f32_16x16x32_bf16 v[100:103], v[144:147], v[198:201], 0
	v_mfma_f32_16x16x32_bf16 v[96:99], v[172:175], v[198:201], 0
	v_mfma_f32_16x16x32_bf16 v[84:87], v[144:147], v[206:209], 0
	v_mfma_f32_16x16x32_bf16 v[80:83], v[172:175], v[206:209], 0
	v_mfma_f32_16x16x32_bf16 v[68:71], v[144:147], v[214:217], 0
	v_mfma_f32_16x16x32_bf16 v[64:67], v[172:175], v[214:217], 0
	v_mfma_f32_16x16x32_bf16 v[116:119], v[148:151], v[194:197], v[116:119]
	v_mfma_f32_16x16x32_bf16 v[112:115], v[176:179], v[194:197], v[112:115]
	v_mfma_f32_16x16x32_bf16 v[100:103], v[148:151], v[202:205], v[100:103]
	v_mfma_f32_16x16x32_bf16 v[96:99], v[176:179], v[202:205], v[96:99]
	v_mfma_f32_16x16x32_bf16 v[84:87], v[148:151], v[210:213], v[84:87]
	v_mfma_f32_16x16x32_bf16 v[80:83], v[176:179], v[210:213], v[80:83]
	v_mfma_f32_16x16x32_bf16 v[68:71], v[148:151], v[218:221], v[68:71]
	v_mfma_f32_16x16x32_bf16 v[64:67], v[176:179], v[218:221], v[64:67]
	s_setprio 0
	s_barrier
	s_add_i32 s84, s79, s69
	v_lshl_add_u64 v[222:223], s[62:63], 0, v[154:155]
	s_mov_b32 m0, s84
	ds_read_b128 v[180:183], v191 offset:16384
	v_xor_b32_e32 v253, 64, v191
	ds_read_b128 v[194:197], v253 offset:16384
	ds_read_b128 v[198:201], v191 offset:18432
	ds_read_b128 v[202:205], v253 offset:18432
	ds_read_b128 v[206:209], v191 offset:20480
	ds_read_b128 v[210:213], v253 offset:20480
	ds_read_b128 v[214:217], v191 offset:22528
	ds_read_b128 v[218:221], v253 offset:22528
	global_load_lds_dwordx4 v[222:223], off
	s_add_i32 m0, s84, 0x2000
	s_add_u32 s84, s62, 0x80000
	v_lshl_add_u64 v[224:225], s[62:63], 0, v[162:163]
	s_addc_u32 s85, s63, 0
	s_add_i32 s86, s80, s69
	global_load_lds_dwordx4 v[224:225], off
	v_lshl_add_u64 v[226:227], s[84:85], 0, v[154:155]
	s_mov_b32 m0, s86
	v_lshl_add_u64 v[228:229], s[64:65], 0, v[160:161]
	global_load_lds_dwordx4 v[226:227], off
	v_lshl_add_u64 v[226:227], s[84:85], 0, v[162:163]
	s_add_i32 m0, s86, 0x2000
	s_nop 0
	global_load_lds_dwordx4 v[226:227], off
	v_lshl_add_u64 v[226:227], s[64:65], 0, v[152:153]
	s_mov_b32 m0, s70
	s_nop 0
	global_load_lds_dwordx4 v[226:227], off
	s_mov_b32 m0, s71
	s_nop 0
	global_load_lds_dwordx4 v[228:229], off
	s_waitcnt vmcnt(8)
	s_waitcnt lgkmcnt(0)
	s_barrier
	s_setprio 1
	s_waitcnt lgkmcnt(0)
	v_mfma_f32_16x16x32_bf16 v[60:63], v[128:131], v[180:183], 0
	v_mfma_f32_16x16x32_bf16 v[56:59], v[136:139], v[180:183], 0
	v_mfma_f32_16x16x32_bf16 v[44:47], v[128:131], v[198:201], 0
	v_mfma_f32_16x16x32_bf16 v[40:43], v[136:139], v[198:201], 0
	v_mfma_f32_16x16x32_bf16 v[28:31], v[128:131], v[206:209], 0
	v_mfma_f32_16x16x32_bf16 v[24:27], v[136:139], v[206:209], 0
	v_mfma_f32_16x16x32_bf16 v[12:15], v[128:131], v[214:217], 0
	v_mfma_f32_16x16x32_bf16 v[8:11], v[136:139], v[214:217], 0
	v_mfma_f32_16x16x32_bf16 v[60:63], v[132:135], v[194:197], v[60:63]
	v_mfma_f32_16x16x32_bf16 v[56:59], v[140:143], v[194:197], v[56:59]
	v_mfma_f32_16x16x32_bf16 v[44:47], v[132:135], v[202:205], v[44:47]
	v_mfma_f32_16x16x32_bf16 v[40:43], v[140:143], v[202:205], v[40:43]
	v_mfma_f32_16x16x32_bf16 v[28:31], v[132:135], v[210:213], v[28:31]
	v_mfma_f32_16x16x32_bf16 v[24:27], v[140:143], v[210:213], v[24:27]
	v_mfma_f32_16x16x32_bf16 v[12:15], v[132:135], v[218:221], v[12:15]
	v_mfma_f32_16x16x32_bf16 v[8:11], v[140:143], v[218:221], v[8:11]
	s_setprio 0
	s_setprio 1
	v_mfma_f32_16x16x32_bf16 v[52:55], v[144:147], v[180:183], 0
	v_mfma_f32_16x16x32_bf16 v[48:51], v[172:175], v[180:183], 0
	v_mfma_f32_16x16x32_bf16 v[36:39], v[144:147], v[198:201], 0
	v_mfma_f32_16x16x32_bf16 v[32:35], v[172:175], v[198:201], 0
	v_mfma_f32_16x16x32_bf16 v[20:23], v[144:147], v[206:209], 0
	v_mfma_f32_16x16x32_bf16 v[16:19], v[172:175], v[206:209], 0
	v_mfma_f32_16x16x32_bf16 v[4:7], v[144:147], v[214:217], 0
	v_mfma_f32_16x16x32_bf16 v[0:3], v[172:175], v[214:217], 0
	v_mfma_f32_16x16x32_bf16 v[52:55], v[148:151], v[194:197], v[52:55]
	v_mfma_f32_16x16x32_bf16 v[48:51], v[176:179], v[194:197], v[48:51]
	v_mfma_f32_16x16x32_bf16 v[36:39], v[148:151], v[202:205], v[36:39]
	v_mfma_f32_16x16x32_bf16 v[32:35], v[176:179], v[202:205], v[32:35]
	v_mfma_f32_16x16x32_bf16 v[20:23], v[148:151], v[210:213], v[20:23]
	v_mfma_f32_16x16x32_bf16 v[16:19], v[176:179], v[210:213], v[16:19]
	v_mfma_f32_16x16x32_bf16 v[4:7], v[148:151], v[218:221], v[4:7]
	v_mfma_f32_16x16x32_bf16 v[0:3], v[176:179], v[218:221], v[0:3]
	s_setprio 0
	s_barrier
	s_add_i32 s84, 0, 0x18000
	s_add_i32 s85, 0, 0x1c000
	v_add_u32_e32 v140, s84, v186
	v_add_u32_e32 v176, s85, v186
	ds_read_b128 v[128:131], v140
	v_xor_b32_e32 v253, 64, v140
	ds_read_b128 v[132:135], v253
	ds_read_b128 v[136:139], v140 offset:2048
	ds_read_b128 v[140:143], v253 offset:2048
	ds_read_b128 v[144:147], v176
	v_xor_b32_e32 v253, 64, v176
	ds_read_b128 v[148:151], v253
	ds_read_b128 v[172:175], v176 offset:2048
	ds_read_b128 v[176:179], v253 offset:2048
	s_add_u32 s64, s64, 0x80000
	s_addc_u32 s65, s65, 0
	s_mov_b32 m0, s72
	v_lshl_add_u64 v[230:231], s[64:65], 0, v[152:153]
	ds_read_b128 v[180:183], v191 offset:32768
	v_xor_b32_e32 v253, 64, v191
	ds_read_b128 v[194:197], v253 offset:32768
	ds_read_b128 v[198:201], v191 offset:34816
	ds_read_b128 v[202:205], v253 offset:34816
	ds_read_b128 v[206:209], v191 offset:36864
	ds_read_b128 v[210:213], v253 offset:36864
	ds_read_b128 v[214:217], v191 offset:38912
	ds_read_b128 v[218:221], v253 offset:38912
	global_load_lds_dwordx4 v[230:231], off
	v_lshl_add_u64 v[230:231], s[64:65], 0, v[160:161]
	s_mov_b32 m0, s73
	s_nop 0
	global_load_lds_dwordx4 v[230:231], off
	s_waitcnt vmcnt(8)
	s_waitcnt lgkmcnt(0)
	s_barrier
	s_setprio 1
	s_waitcnt lgkmcnt(0)
	v_mfma_f32_16x16x32_bf16 v[124:127], v[128:131], v[180:183], v[124:127]
	v_mfma_f32_16x16x32_bf16 v[124:127], v[132:135], v[194:197], v[124:127]
	v_mfma_f32_16x16x32_bf16 v[120:123], v[140:143], v[194:197], v[120:123]
	v_mfma_f32_16x16x32_bf16 v[120:123], v[136:139], v[180:183], v[120:123]
	v_mfma_f32_16x16x32_bf16 v[104:107], v[136:139], v[198:201], v[104:107]
	v_mfma_f32_16x16x32_bf16 v[104:107], v[140:143], v[202:205], v[104:107]
	v_mfma_f32_16x16x32_bf16 v[108:111], v[132:135], v[202:205], v[108:111]
	v_mfma_f32_16x16x32_bf16 v[108:111], v[128:131], v[198:201], v[108:111]
	v_mfma_f32_16x16x32_bf16 v[92:95], v[128:131], v[206:209], v[92:95]
	v_mfma_f32_16x16x32_bf16 v[92:95], v[132:135], v[210:213], v[92:95]
	v_mfma_f32_16x16x32_bf16 v[88:91], v[140:143], v[210:213], v[88:91]
	v_mfma_f32_16x16x32_bf16 v[88:91], v[136:139], v[206:209], v[88:91]
	v_mfma_f32_16x16x32_bf16 v[72:75], v[136:139], v[214:217], v[72:75]
	v_mfma_f32_16x16x32_bf16 v[72:75], v[140:143], v[218:221], v[72:75]
	v_mfma_f32_16x16x32_bf16 v[76:79], v[132:135], v[218:221], v[76:79]
	v_mfma_f32_16x16x32_bf16 v[76:79], v[128:131], v[214:217], v[76:79]
	s_setprio 0
	s_setprio 1
	v_mfma_f32_16x16x32_bf16 v[116:119], v[144:147], v[180:183], v[116:119]
	v_mfma_f32_16x16x32_bf16 v[116:119], v[148:151], v[194:197], v[116:119]
	v_mfma_f32_16x16x32_bf16 v[112:115], v[176:179], v[194:197], v[112:115]
	v_mfma_f32_16x16x32_bf16 v[112:115], v[172:175], v[180:183], v[112:115]
	v_mfma_f32_16x16x32_bf16 v[96:99], v[172:175], v[198:201], v[96:99]
	v_mfma_f32_16x16x32_bf16 v[96:99], v[176:179], v[202:205], v[96:99]
	v_mfma_f32_16x16x32_bf16 v[100:103], v[148:151], v[202:205], v[100:103]
	v_mfma_f32_16x16x32_bf16 v[100:103], v[144:147], v[198:201], v[100:103]
	v_mfma_f32_16x16x32_bf16 v[84:87], v[144:147], v[206:209], v[84:87]
	v_mfma_f32_16x16x32_bf16 v[84:87], v[148:151], v[210:213], v[84:87]
	v_mfma_f32_16x16x32_bf16 v[80:83], v[176:179], v[210:213], v[80:83]
	v_mfma_f32_16x16x32_bf16 v[80:83], v[172:175], v[206:209], v[80:83]
	v_mfma_f32_16x16x32_bf16 v[64:67], v[172:175], v[214:217], v[64:67]
	v_mfma_f32_16x16x32_bf16 v[64:67], v[176:179], v[218:221], v[64:67]
	v_mfma_f32_16x16x32_bf16 v[68:71], v[148:151], v[218:221], v[68:71]
	v_mfma_f32_16x16x32_bf16 v[68:71], v[144:147], v[214:217], v[68:71]
	s_setprio 0
	s_barrier
	s_add_i32 s64, s84, s69
	v_lshl_add_u64 v[222:223], v[222:223], 0, s[26:27]
	s_mov_b32 m0, s64
	ds_read_b128 v[180:183], v191 offset:49152
	v_xor_b32_e32 v253, 64, v191
	ds_read_b128 v[194:197], v253 offset:49152
	ds_read_b128 v[198:201], v191 offset:51200
	ds_read_b128 v[202:205], v253 offset:51200
	ds_read_b128 v[206:209], v191 offset:53248
	ds_read_b128 v[210:213], v253 offset:53248
	ds_read_b128 v[214:217], v191 offset:55296
	ds_read_b128 v[218:221], v253 offset:55296
	global_load_lds_dwordx4 v[222:223], off
	s_add_i32 m0, s64, 0x2000
	s_add_u32 s62, s62, 0x80080
	v_lshl_add_u64 v[222:223], v[224:225], 0, s[26:27]
	s_addc_u32 s63, s63, 0
	s_add_i32 s64, s85, s69
	global_load_lds_dwordx4 v[222:223], off
	v_lshl_add_u64 v[222:223], s[62:63], 0, v[154:155]
	s_mov_b32 m0, s64
	s_nop 0
	global_load_lds_dwordx4 v[222:223], off
	v_lshl_add_u64 v[222:223], s[62:63], 0, v[162:163]
	s_add_i32 m0, s64, 0x2000
	s_nop 0
	global_load_lds_dwordx4 v[222:223], off
	v_lshl_add_u64 v[222:223], v[226:227], 0, s[26:27]
	s_mov_b32 m0, s3
	s_nop 0
	global_load_lds_dwordx4 v[222:223], off
	v_lshl_add_u64 v[222:223], v[228:229], 0, s[26:27]
	s_mov_b32 m0, s75
	s_nop 0
	global_load_lds_dwordx4 v[222:223], off
	s_waitcnt vmcnt(8)
	s_waitcnt lgkmcnt(0)
	s_barrier
	s_setprio 1
	s_waitcnt lgkmcnt(0)
	v_mfma_f32_16x16x32_bf16 v[60:63], v[128:131], v[180:183], v[60:63]
	v_mfma_f32_16x16x32_bf16 v[60:63], v[132:135], v[194:197], v[60:63]
	v_mfma_f32_16x16x32_bf16 v[56:59], v[140:143], v[194:197], v[56:59]
	v_mfma_f32_16x16x32_bf16 v[56:59], v[136:139], v[180:183], v[56:59]
	v_mfma_f32_16x16x32_bf16 v[40:43], v[136:139], v[198:201], v[40:43]
	v_mfma_f32_16x16x32_bf16 v[40:43], v[140:143], v[202:205], v[40:43]
	v_mfma_f32_16x16x32_bf16 v[44:47], v[132:135], v[202:205], v[44:47]
	v_mfma_f32_16x16x32_bf16 v[44:47], v[128:131], v[198:201], v[44:47]
	v_mfma_f32_16x16x32_bf16 v[28:31], v[128:131], v[206:209], v[28:31]
	v_mfma_f32_16x16x32_bf16 v[28:31], v[132:135], v[210:213], v[28:31]
	v_mfma_f32_16x16x32_bf16 v[24:27], v[140:143], v[210:213], v[24:27]
	v_mfma_f32_16x16x32_bf16 v[24:27], v[136:139], v[206:209], v[24:27]
	v_mfma_f32_16x16x32_bf16 v[8:11], v[136:139], v[214:217], v[8:11]
	v_mfma_f32_16x16x32_bf16 v[8:11], v[140:143], v[218:221], v[8:11]
	v_mfma_f32_16x16x32_bf16 v[12:15], v[132:135], v[218:221], v[12:15]
	v_mfma_f32_16x16x32_bf16 v[12:15], v[128:131], v[214:217], v[12:15]
	s_setprio 0
	s_setprio 1
	v_mfma_f32_16x16x32_bf16 v[52:55], v[144:147], v[180:183], v[52:55]
	v_mfma_f32_16x16x32_bf16 v[52:55], v[148:151], v[194:197], v[52:55]
	v_mfma_f32_16x16x32_bf16 v[48:51], v[176:179], v[194:197], v[48:51]
	v_mfma_f32_16x16x32_bf16 v[48:51], v[172:175], v[180:183], v[48:51]
	v_mfma_f32_16x16x32_bf16 v[32:35], v[172:175], v[198:201], v[32:35]
	v_mfma_f32_16x16x32_bf16 v[32:35], v[176:179], v[202:205], v[32:35]
	v_mfma_f32_16x16x32_bf16 v[36:39], v[148:151], v[202:205], v[36:39]
	v_mfma_f32_16x16x32_bf16 v[36:39], v[144:147], v[198:201], v[36:39]
	v_mfma_f32_16x16x32_bf16 v[20:23], v[144:147], v[206:209], v[20:23]
	v_mfma_f32_16x16x32_bf16 v[20:23], v[148:151], v[210:213], v[20:23]
	v_mfma_f32_16x16x32_bf16 v[16:19], v[176:179], v[210:213], v[16:19]
	v_mfma_f32_16x16x32_bf16 v[16:19], v[172:175], v[206:209], v[16:19]
	v_mfma_f32_16x16x32_bf16 v[0:3], v[172:175], v[214:217], v[0:3]
	v_mfma_f32_16x16x32_bf16 v[0:3], v[176:179], v[218:221], v[0:3]
	v_mfma_f32_16x16x32_bf16 v[4:7], v[148:151], v[218:221], v[4:7]
	v_mfma_f32_16x16x32_bf16 v[4:7], v[144:147], v[214:217], v[4:7]
	s_setprio 0
	s_barrier
	s_add_i32 s83, s83, 2
	s_add_u32 s81, s81, 0x100
	s_addc_u32 s82, s82, 0
	s_add_u32 s60, s60, 0x100
	s_addc_u32 s61, s61, 0
	s_cmp_gt_u32 s83, 29
.LBB0_440:
	ds_read_b128 v[128:131], v189
	v_xor_b32_e32 v253, 64, v189
	ds_read_b128 v[132:135], v253
	ds_read_b128 v[136:139], v189 offset:2048
	ds_read_b128 v[140:143], v253 offset:2048
	ds_read_b128 v[144:147], v190
	v_xor_b32_e32 v253, 64, v190
	ds_read_b128 v[148:151], v253
	ds_read_b128 v[172:175], v190 offset:2048
	ds_read_b128 v[176:179], v253 offset:2048
	s_add_u32 s62, s60, 0xfff80080
	s_addc_u32 s63, s61, -1
	s_cmp_eq_u32 s83, 28
	s_cselect_b32 s65, s15, s63
	s_cselect_b32 s64, s53, s62
	s_cselect_b32 s63, s51, s82
	s_cselect_b32 s62, s59, s81
	v_lshl_add_u64 v[222:223], s[60:61], 0, v[166:167]
	s_add_i32 m0, s70, 0xc000
	ds_read_b128 v[180:183], v191
	v_xor_b32_e32 v253, 64, v191
	ds_read_b128 v[194:197], v253
	ds_read_b128 v[198:201], v191 offset:2048
	ds_read_b128 v[202:205], v253 offset:2048
	ds_read_b128 v[206:209], v191 offset:4096
	ds_read_b128 v[210:213], v253 offset:4096
	ds_read_b128 v[214:217], v191 offset:6144
	ds_read_b128 v[218:221], v253 offset:6144
	global_load_lds_dwordx4 v[222:223], off
	v_lshl_add_u64 v[222:223], s[60:61], 0, v[164:165]
	s_add_i32 m0, s70, 0xe000
	s_nop 0
	global_load_lds_dwordx4 v[222:223], off
	s_waitcnt vmcnt(8)
	s_waitcnt lgkmcnt(0)
	s_barrier
	s_setprio 1
	s_waitcnt lgkmcnt(0)
	v_mfma_f32_16x16x32_bf16 v[124:127], v[128:131], v[180:183], v[124:127]
	v_mfma_f32_16x16x32_bf16 v[124:127], v[132:135], v[194:197], v[124:127]
	v_mfma_f32_16x16x32_bf16 v[120:123], v[140:143], v[194:197], v[120:123]
	v_mfma_f32_16x16x32_bf16 v[120:123], v[136:139], v[180:183], v[120:123]
	v_mfma_f32_16x16x32_bf16 v[104:107], v[136:139], v[198:201], v[104:107]
	v_mfma_f32_16x16x32_bf16 v[104:107], v[140:143], v[202:205], v[104:107]
	v_mfma_f32_16x16x32_bf16 v[108:111], v[132:135], v[202:205], v[108:111]
	v_mfma_f32_16x16x32_bf16 v[108:111], v[128:131], v[198:201], v[108:111]
	v_mfma_f32_16x16x32_bf16 v[92:95], v[128:131], v[206:209], v[92:95]
	v_mfma_f32_16x16x32_bf16 v[92:95], v[132:135], v[210:213], v[92:95]
	v_mfma_f32_16x16x32_bf16 v[88:91], v[140:143], v[210:213], v[88:91]
	v_mfma_f32_16x16x32_bf16 v[88:91], v[136:139], v[206:209], v[88:91]
	v_mfma_f32_16x16x32_bf16 v[72:75], v[136:139], v[214:217], v[72:75]
	v_mfma_f32_16x16x32_bf16 v[72:75], v[140:143], v[218:221], v[72:75]
	v_mfma_f32_16x16x32_bf16 v[76:79], v[132:135], v[218:221], v[76:79]
	v_mfma_f32_16x16x32_bf16 v[76:79], v[128:131], v[214:217], v[76:79]
	s_setprio 0
	s_setprio 1
	v_mfma_f32_16x16x32_bf16 v[116:119], v[144:147], v[180:183], v[116:119]
	v_mfma_f32_16x16x32_bf16 v[116:119], v[148:151], v[194:197], v[116:119]
	v_mfma_f32_16x16x32_bf16 v[112:115], v[176:179], v[194:197], v[112:115]
	v_mfma_f32_16x16x32_bf16 v[112:115], v[172:175], v[180:183], v[112:115]
	v_mfma_f32_16x16x32_bf16 v[96:99], v[172:175], v[198:201], v[96:99]
	v_mfma_f32_16x16x32_bf16 v[96:99], v[176:179], v[202:205], v[96:99]
	v_mfma_f32_16x16x32_bf16 v[100:103], v[148:151], v[202:205], v[100:103]
	v_mfma_f32_16x16x32_bf16 v[100:103], v[144:147], v[198:201], v[100:103]
	v_mfma_f32_16x16x32_bf16 v[84:87], v[144:147], v[206:209], v[84:87]
	v_mfma_f32_16x16x32_bf16 v[84:87], v[148:151], v[210:213], v[84:87]
	v_mfma_f32_16x16x32_bf16 v[80:83], v[176:179], v[210:213], v[80:83]
	v_mfma_f32_16x16x32_bf16 v[80:83], v[172:175], v[206:209], v[80:83]
	v_mfma_f32_16x16x32_bf16 v[64:67], v[172:175], v[214:217], v[64:67]
	v_mfma_f32_16x16x32_bf16 v[64:67], v[176:179], v[218:221], v[64:67]
	v_mfma_f32_16x16x32_bf16 v[68:71], v[148:151], v[218:221], v[68:71]
	v_mfma_f32_16x16x32_bf16 v[68:71], v[144:147], v[214:217], v[68:71]
	s_setprio 0
	s_barrier
	s_add_i32 s84, s79, s69
	v_lshl_add_u64 v[222:223], s[62:63], 0, v[154:155]
	s_mov_b32 m0, s84
	ds_read_b128 v[180:183], v191 offset:16384
	v_xor_b32_e32 v253, 64, v191
	ds_read_b128 v[194:197], v253 offset:16384
	ds_read_b128 v[198:201], v191 offset:18432
	ds_read_b128 v[202:205], v253 offset:18432
	ds_read_b128 v[206:209], v191 offset:20480
	ds_read_b128 v[210:213], v253 offset:20480
	ds_read_b128 v[214:217], v191 offset:22528
	ds_read_b128 v[218:221], v253 offset:22528
	global_load_lds_dwordx4 v[222:223], off
	s_add_i32 m0, s84, 0x2000
	s_add_u32 s84, s62, 0x80000
	v_lshl_add_u64 v[224:225], s[62:63], 0, v[162:163]
	s_addc_u32 s85, s63, 0
	s_add_i32 s86, s80, s69
	global_load_lds_dwordx4 v[224:225], off
	v_lshl_add_u64 v[226:227], s[84:85], 0, v[154:155]
	s_mov_b32 m0, s86
	v_lshl_add_u64 v[228:229], s[64:65], 0, v[160:161]
	global_load_lds_dwordx4 v[226:227], off
	v_lshl_add_u64 v[226:227], s[84:85], 0, v[162:163]
	s_add_i32 m0, s86, 0x2000
	s_nop 0
	global_load_lds_dwordx4 v[226:227], off
	v_lshl_add_u64 v[226:227], s[64:65], 0, v[152:153]
	s_mov_b32 m0, s70
	s_nop 0
	global_load_lds_dwordx4 v[226:227], off
	s_mov_b32 m0, s71
	s_nop 0
	global_load_lds_dwordx4 v[228:229], off
	s_waitcnt vmcnt(8)
	s_waitcnt lgkmcnt(0)
	s_barrier
	s_setprio 1
	s_waitcnt lgkmcnt(0)
	v_mfma_f32_16x16x32_bf16 v[60:63], v[128:131], v[180:183], v[60:63]
	v_mfma_f32_16x16x32_bf16 v[60:63], v[132:135], v[194:197], v[60:63]
	v_mfma_f32_16x16x32_bf16 v[56:59], v[140:143], v[194:197], v[56:59]
	v_mfma_f32_16x16x32_bf16 v[56:59], v[136:139], v[180:183], v[56:59]
	v_mfma_f32_16x16x32_bf16 v[40:43], v[136:139], v[198:201], v[40:43]
	v_mfma_f32_16x16x32_bf16 v[40:43], v[140:143], v[202:205], v[40:43]
	v_mfma_f32_16x16x32_bf16 v[44:47], v[132:135], v[202:205], v[44:47]
	v_mfma_f32_16x16x32_bf16 v[44:47], v[128:131], v[198:201], v[44:47]
	v_mfma_f32_16x16x32_bf16 v[28:31], v[128:131], v[206:209], v[28:31]
	v_mfma_f32_16x16x32_bf16 v[28:31], v[132:135], v[210:213], v[28:31]
	v_mfma_f32_16x16x32_bf16 v[24:27], v[140:143], v[210:213], v[24:27]
	v_mfma_f32_16x16x32_bf16 v[24:27], v[136:139], v[206:209], v[24:27]
	v_mfma_f32_16x16x32_bf16 v[8:11], v[136:139], v[214:217], v[8:11]
	v_mfma_f32_16x16x32_bf16 v[8:11], v[140:143], v[218:221], v[8:11]
	v_mfma_f32_16x16x32_bf16 v[12:15], v[132:135], v[218:221], v[12:15]
	v_mfma_f32_16x16x32_bf16 v[12:15], v[128:131], v[214:217], v[12:15]
	s_setprio 0
	s_setprio 1
	v_mfma_f32_16x16x32_bf16 v[52:55], v[144:147], v[180:183], v[52:55]
	v_mfma_f32_16x16x32_bf16 v[52:55], v[148:151], v[194:197], v[52:55]
	v_mfma_f32_16x16x32_bf16 v[48:51], v[176:179], v[194:197], v[48:51]
	v_mfma_f32_16x16x32_bf16 v[48:51], v[172:175], v[180:183], v[48:51]
	v_mfma_f32_16x16x32_bf16 v[32:35], v[172:175], v[198:201], v[32:35]
	v_mfma_f32_16x16x32_bf16 v[32:35], v[176:179], v[202:205], v[32:35]
	v_mfma_f32_16x16x32_bf16 v[36:39], v[148:151], v[202:205], v[36:39]
	v_mfma_f32_16x16x32_bf16 v[36:39], v[144:147], v[198:201], v[36:39]
	v_mfma_f32_16x16x32_bf16 v[20:23], v[144:147], v[206:209], v[20:23]
	v_mfma_f32_16x16x32_bf16 v[20:23], v[148:151], v[210:213], v[20:23]
	v_mfma_f32_16x16x32_bf16 v[16:19], v[176:179], v[210:213], v[16:19]
	v_mfma_f32_16x16x32_bf16 v[16:19], v[172:175], v[206:209], v[16:19]
	v_mfma_f32_16x16x32_bf16 v[0:3], v[172:175], v[214:217], v[0:3]
	v_mfma_f32_16x16x32_bf16 v[0:3], v[176:179], v[218:221], v[0:3]
	v_mfma_f32_16x16x32_bf16 v[4:7], v[148:151], v[218:221], v[4:7]
	v_mfma_f32_16x16x32_bf16 v[4:7], v[144:147], v[214:217], v[4:7]
	s_setprio 0
	s_barrier
	s_add_i32 s84, 0, 0x18000
	s_add_i32 s85, 0, 0x1c000
	v_add_u32_e32 v140, s84, v186
	v_add_u32_e32 v176, s85, v186
	ds_read_b128 v[128:131], v140
	v_xor_b32_e32 v253, 64, v140
	ds_read_b128 v[132:135], v253
	ds_read_b128 v[136:139], v140 offset:2048
	ds_read_b128 v[140:143], v253 offset:2048
	ds_read_b128 v[144:147], v176
	v_xor_b32_e32 v253, 64, v176
	ds_read_b128 v[148:151], v253
	ds_read_b128 v[172:175], v176 offset:2048
	ds_read_b128 v[176:179], v253 offset:2048
	s_add_u32 s64, s64, 0x80000
	s_addc_u32 s65, s65, 0
	s_mov_b32 m0, s72
	v_lshl_add_u64 v[230:231], s[64:65], 0, v[152:153]
	ds_read_b128 v[180:183], v191 offset:32768
	v_xor_b32_e32 v253, 64, v191
	ds_read_b128 v[194:197], v253 offset:32768
	ds_read_b128 v[198:201], v191 offset:34816
	ds_read_b128 v[202:205], v253 offset:34816
	ds_read_b128 v[206:209], v191 offset:36864
	ds_read_b128 v[210:213], v253 offset:36864
	ds_read_b128 v[214:217], v191 offset:38912
	ds_read_b128 v[218:221], v253 offset:38912
	global_load_lds_dwordx4 v[230:231], off
	v_lshl_add_u64 v[230:231], s[64:65], 0, v[160:161]
	s_mov_b32 m0, s73
	s_nop 0
	global_load_lds_dwordx4 v[230:231], off
	s_waitcnt vmcnt(8)
	s_waitcnt lgkmcnt(0)
	s_barrier
	s_setprio 1
	s_waitcnt lgkmcnt(0)
	v_mfma_f32_16x16x32_bf16 v[124:127], v[128:131], v[180:183], v[124:127]
	v_mfma_f32_16x16x32_bf16 v[124:127], v[132:135], v[194:197], v[124:127]
	v_mfma_f32_16x16x32_bf16 v[120:123], v[140:143], v[194:197], v[120:123]
	v_mfma_f32_16x16x32_bf16 v[120:123], v[136:139], v[180:183], v[120:123]
	v_mfma_f32_16x16x32_bf16 v[104:107], v[136:139], v[198:201], v[104:107]
	v_mfma_f32_16x16x32_bf16 v[104:107], v[140:143], v[202:205], v[104:107]
	v_mfma_f32_16x16x32_bf16 v[108:111], v[132:135], v[202:205], v[108:111]
	v_mfma_f32_16x16x32_bf16 v[108:111], v[128:131], v[198:201], v[108:111]
	v_mfma_f32_16x16x32_bf16 v[92:95], v[128:131], v[206:209], v[92:95]
	v_mfma_f32_16x16x32_bf16 v[92:95], v[132:135], v[210:213], v[92:95]
	v_mfma_f32_16x16x32_bf16 v[88:91], v[140:143], v[210:213], v[88:91]
	v_mfma_f32_16x16x32_bf16 v[88:91], v[136:139], v[206:209], v[88:91]
	v_mfma_f32_16x16x32_bf16 v[72:75], v[136:139], v[214:217], v[72:75]
	v_mfma_f32_16x16x32_bf16 v[72:75], v[140:143], v[218:221], v[72:75]
	v_mfma_f32_16x16x32_bf16 v[76:79], v[132:135], v[218:221], v[76:79]
	v_mfma_f32_16x16x32_bf16 v[76:79], v[128:131], v[214:217], v[76:79]
	s_setprio 0
	s_setprio 1
	v_mfma_f32_16x16x32_bf16 v[116:119], v[144:147], v[180:183], v[116:119]
	v_mfma_f32_16x16x32_bf16 v[116:119], v[148:151], v[194:197], v[116:119]
	v_mfma_f32_16x16x32_bf16 v[112:115], v[176:179], v[194:197], v[112:115]
	v_mfma_f32_16x16x32_bf16 v[112:115], v[172:175], v[180:183], v[112:115]
	v_mfma_f32_16x16x32_bf16 v[96:99], v[172:175], v[198:201], v[96:99]
	v_mfma_f32_16x16x32_bf16 v[96:99], v[176:179], v[202:205], v[96:99]
	v_mfma_f32_16x16x32_bf16 v[100:103], v[148:151], v[202:205], v[100:103]
	v_mfma_f32_16x16x32_bf16 v[100:103], v[144:147], v[198:201], v[100:103]
	v_mfma_f32_16x16x32_bf16 v[84:87], v[144:147], v[206:209], v[84:87]
	v_mfma_f32_16x16x32_bf16 v[84:87], v[148:151], v[210:213], v[84:87]
	v_mfma_f32_16x16x32_bf16 v[80:83], v[176:179], v[210:213], v[80:83]
	v_mfma_f32_16x16x32_bf16 v[80:83], v[172:175], v[206:209], v[80:83]
	v_mfma_f32_16x16x32_bf16 v[64:67], v[172:175], v[214:217], v[64:67]
	v_mfma_f32_16x16x32_bf16 v[64:67], v[176:179], v[218:221], v[64:67]
	v_mfma_f32_16x16x32_bf16 v[68:71], v[148:151], v[218:221], v[68:71]
	v_mfma_f32_16x16x32_bf16 v[68:71], v[144:147], v[214:217], v[68:71]
	s_setprio 0
	s_barrier
	s_add_i32 s64, s84, s69
	v_lshl_add_u64 v[222:223], v[222:223], 0, s[26:27]
	s_mov_b32 m0, s64
	ds_read_b128 v[180:183], v191 offset:49152
	v_xor_b32_e32 v253, 64, v191
	ds_read_b128 v[194:197], v253 offset:49152
	ds_read_b128 v[198:201], v191 offset:51200
	ds_read_b128 v[202:205], v253 offset:51200
	ds_read_b128 v[206:209], v191 offset:53248
	ds_read_b128 v[210:213], v253 offset:53248
	ds_read_b128 v[214:217], v191 offset:55296
	ds_read_b128 v[218:221], v253 offset:55296
	global_load_lds_dwordx4 v[222:223], off
	s_add_i32 m0, s64, 0x2000
	s_add_u32 s62, s62, 0x80080
	v_lshl_add_u64 v[222:223], v[224:225], 0, s[26:27]
	s_addc_u32 s63, s63, 0
	s_add_i32 s64, s85, s69
	global_load_lds_dwordx4 v[222:223], off
	v_lshl_add_u64 v[222:223], s[62:63], 0, v[154:155]
	s_mov_b32 m0, s64
	s_nop 0
	global_load_lds_dwordx4 v[222:223], off
	v_lshl_add_u64 v[222:223], s[62:63], 0, v[162:163]
	s_add_i32 m0, s64, 0x2000
	s_nop 0
	global_load_lds_dwordx4 v[222:223], off
	v_lshl_add_u64 v[222:223], v[226:227], 0, s[26:27]
	s_mov_b32 m0, s3
	s_nop 0
	global_load_lds_dwordx4 v[222:223], off
	v_lshl_add_u64 v[222:223], v[228:229], 0, s[26:27]
	s_mov_b32 m0, s75
	s_nop 0
	global_load_lds_dwordx4 v[222:223], off
	s_waitcnt vmcnt(8)
	s_waitcnt lgkmcnt(0)
	s_barrier
	s_setprio 1
	s_waitcnt lgkmcnt(0)
	v_mfma_f32_16x16x32_bf16 v[60:63], v[128:131], v[180:183], v[60:63]
	v_mfma_f32_16x16x32_bf16 v[60:63], v[132:135], v[194:197], v[60:63]
	v_mfma_f32_16x16x32_bf16 v[56:59], v[140:143], v[194:197], v[56:59]
	v_mfma_f32_16x16x32_bf16 v[56:59], v[136:139], v[180:183], v[56:59]
	v_mfma_f32_16x16x32_bf16 v[40:43], v[136:139], v[198:201], v[40:43]
	v_mfma_f32_16x16x32_bf16 v[40:43], v[140:143], v[202:205], v[40:43]
	v_mfma_f32_16x16x32_bf16 v[44:47], v[132:135], v[202:205], v[44:47]
	v_mfma_f32_16x16x32_bf16 v[44:47], v[128:131], v[198:201], v[44:47]
	v_mfma_f32_16x16x32_bf16 v[28:31], v[128:131], v[206:209], v[28:31]
	v_mfma_f32_16x16x32_bf16 v[28:31], v[132:135], v[210:213], v[28:31]
	v_mfma_f32_16x16x32_bf16 v[24:27], v[140:143], v[210:213], v[24:27]
	v_mfma_f32_16x16x32_bf16 v[24:27], v[136:139], v[206:209], v[24:27]
	v_mfma_f32_16x16x32_bf16 v[8:11], v[136:139], v[214:217], v[8:11]
	v_mfma_f32_16x16x32_bf16 v[8:11], v[140:143], v[218:221], v[8:11]
	v_mfma_f32_16x16x32_bf16 v[12:15], v[132:135], v[218:221], v[12:15]
	v_mfma_f32_16x16x32_bf16 v[12:15], v[128:131], v[214:217], v[12:15]
	s_setprio 0
	s_setprio 1
	v_mfma_f32_16x16x32_bf16 v[52:55], v[144:147], v[180:183], v[52:55]
	v_mfma_f32_16x16x32_bf16 v[52:55], v[148:151], v[194:197], v[52:55]
	v_mfma_f32_16x16x32_bf16 v[48:51], v[176:179], v[194:197], v[48:51]
	v_mfma_f32_16x16x32_bf16 v[48:51], v[172:175], v[180:183], v[48:51]
	v_mfma_f32_16x16x32_bf16 v[32:35], v[172:175], v[198:201], v[32:35]
	v_mfma_f32_16x16x32_bf16 v[32:35], v[176:179], v[202:205], v[32:35]
	v_mfma_f32_16x16x32_bf16 v[36:39], v[148:151], v[202:205], v[36:39]
	v_mfma_f32_16x16x32_bf16 v[36:39], v[144:147], v[198:201], v[36:39]
	v_mfma_f32_16x16x32_bf16 v[20:23], v[144:147], v[206:209], v[20:23]
	v_mfma_f32_16x16x32_bf16 v[20:23], v[148:151], v[210:213], v[20:23]
	v_mfma_f32_16x16x32_bf16 v[16:19], v[176:179], v[210:213], v[16:19]
	v_mfma_f32_16x16x32_bf16 v[16:19], v[172:175], v[206:209], v[16:19]
	v_mfma_f32_16x16x32_bf16 v[0:3], v[172:175], v[214:217], v[0:3]
	v_mfma_f32_16x16x32_bf16 v[0:3], v[176:179], v[218:221], v[0:3]
	v_mfma_f32_16x16x32_bf16 v[4:7], v[148:151], v[218:221], v[4:7]
	v_mfma_f32_16x16x32_bf16 v[4:7], v[144:147], v[214:217], v[4:7]
	s_setprio 0
	s_barrier
	s_add_i32 s83, s83, 2
	s_add_u32 s81, s81, 0x100
	s_addc_u32 s82, s82, 0
	s_add_u32 s60, s60, 0x100
	s_addc_u32 s61, s61, 0
	s_cmp_gt_u32 s83, 29
	s_cbranch_scc0 .LBB0_440
	s_and_b64 vcc, exec, s[28:29]
	s_cbranch_vccz .LBB0_443
	s_barrier

.LBB0_525:
	s_ashr_i32 s29, s28, 31
	s_lshl_b64 s[30:31], s[28:29], 19
	s_add_u32 s30, s3, s30
	s_addc_u32 s31, s35, s31
	s_and_b64 s[44:45], s[10:11], exec
	s_cselect_b32 s29, s31, s51
	s_cselect_b32 s70, s30, s50
	s_ashr_i32 s27, s26, 31
	s_lshl_b64 s[44:45], s[26:27], 19
	s_add_u32 s44, s52, s44
	s_addc_u32 s45, s53, s45
	s_and_b64 s[72:73], s[10:11], exec
	s_cselect_b32 s71, s45, s49
	s_cselect_b32 s72, s44, s48
	s_lshl_b32 s27, s46, 8
	v_add_u32_e32 v0, s27, v148
	s_add_u32 s73, s48, 0x100
	v_ashrrev_i32_e32 v1, 31, v0
	s_addc_u32 s74, s49, 0
	v_lshl_add_u64 v[144:145], v[0:1], 4, s[16:17]
	s_add_u32 s46, s50, 0x40080
	s_addc_u32 s47, s51, 0
	s_mov_b32 s75, -2
	s_mov_b64 s[48:49], 0
	s_cmp_eq_u32 s61, 1
	s_cbranch_scc1 .Lfa_4
	v_add_u32_e32 v153, s66, v147
	ds_read_b128 v[160:163], v153
	v_xor_b32_e32 v253, 64, v153
	ds_read_b128 v[164:167], v253
	ds_read_b128 v[168:171], v153 offset:2048
	ds_read_b128 v[172:175], v253 offset:2048
	v_add_u32_e32 v153, s67, v147
	ds_read_b128 v[176:179], v153
	v_xor_b32_e32 v253, 64, v153
	ds_read_b128 v[180:183], v253
	ds_read_b128 v[186:189], v153 offset:2048
	ds_read_b128 v[190:193], v253 offset:2048
	s_add_u32 s50, s46, 0xfffc0080
	s_addc_u32 s51, s47, -1
	s_and_b64 s[48:49], s[48:49], exec
	s_cselect_b32 s51, s29, s51
	s_cselect_b32 s50, s70, s50
	s_cselect_b32 s49, s71, s74
	s_cselect_b32 s48, s72, s73
	v_lshl_add_u64 v[154:155], s[46:47], 0, v[138:139]
	s_add_i32 m0, s57, 0xc000
	ds_read_b128 v[194:197], v150
	v_xor_b32_e32 v253, 64, v150
	ds_read_b128 v[198:201], v253
	ds_read_b128 v[202:205], v150 offset:2048
	ds_read_b128 v[206:209], v253 offset:2048
	ds_read_b128 v[210:213], v150 offset:4096
	ds_read_b128 v[214:217], v253 offset:4096
	ds_read_b128 v[218:221], v150 offset:6144
	ds_read_b128 v[222:225], v253 offset:6144
	global_load_lds_dwordx4 v[154:155], off
	v_lshl_add_u64 v[154:155], s[46:47], 0, v[136:137]
	s_add_i32 m0, s57, 0xe000
	s_nop 0
	global_load_lds_dwordx4 v[154:155], off
	s_waitcnt vmcnt(16)
	s_waitcnt lgkmcnt(0)
	s_barrier
	s_setprio 1
	s_waitcnt lgkmcnt(0)
	v_mfma_f32_16x16x32_bf16 v[124:127], v[160:163], v[194:197], 0
	v_mfma_f32_16x16x32_bf16 v[116:119], v[168:171], v[194:197], 0
	v_mfma_f32_16x16x32_bf16 v[108:111], v[160:163], v[202:205], 0
	v_mfma_f32_16x16x32_bf16 v[100:103], v[168:171], v[202:205], 0
	v_mfma_f32_16x16x32_bf16 v[92:95], v[160:163], v[210:213], 0
	v_mfma_f32_16x16x32_bf16 v[84:87], v[168:171], v[210:213], 0
	v_mfma_f32_16x16x32_bf16 v[76:79], v[160:163], v[218:221], 0
	v_mfma_f32_16x16x32_bf16 v[68:71], v[168:171], v[218:221], 0
	v_mfma_f32_16x16x32_bf16 v[124:127], v[164:167], v[198:201], v[124:127]
	v_mfma_f32_16x16x32_bf16 v[116:119], v[172:175], v[198:201], v[116:119]
	v_mfma_f32_16x16x32_bf16 v[108:111], v[164:167], v[206:209], v[108:111]
	v_mfma_f32_16x16x32_bf16 v[100:103], v[172:175], v[206:209], v[100:103]
	v_mfma_f32_16x16x32_bf16 v[92:95], v[164:167], v[214:217], v[92:95]
	v_mfma_f32_16x16x32_bf16 v[84:87], v[172:175], v[214:217], v[84:87]
	v_mfma_f32_16x16x32_bf16 v[76:79], v[164:167], v[222:225], v[76:79]
	v_mfma_f32_16x16x32_bf16 v[68:71], v[172:175], v[222:225], v[68:71]
	s_setprio 0
	s_setprio 1
	v_mfma_f32_16x16x32_bf16 v[120:123], v[176:179], v[194:197], 0
	v_mfma_f32_16x16x32_bf16 v[112:115], v[186:189], v[194:197], 0
	v_mfma_f32_16x16x32_bf16 v[104:107], v[176:179], v[202:205], 0
	v_mfma_f32_16x16x32_bf16 v[96:99], v[186:189], v[202:205], 0
	v_mfma_f32_16x16x32_bf16 v[88:91], v[176:179], v[210:213], 0
	v_mfma_f32_16x16x32_bf16 v[80:83], v[186:189], v[210:213], 0
	v_mfma_f32_16x16x32_bf16 v[72:75], v[176:179], v[218:221], 0
	v_mfma_f32_16x16x32_bf16 v[64:67], v[186:189], v[218:221], 0
	v_mfma_f32_16x16x32_bf16 v[120:123], v[180:183], v[198:201], v[120:123]
	v_mfma_f32_16x16x32_bf16 v[112:115], v[190:193], v[198:201], v[112:115]
	v_mfma_f32_16x16x32_bf16 v[104:107], v[180:183], v[206:209], v[104:107]
	v_mfma_f32_16x16x32_bf16 v[96:99], v[190:193], v[206:209], v[96:99]
	v_mfma_f32_16x16x32_bf16 v[88:91], v[180:183], v[214:217], v[88:91]
	v_mfma_f32_16x16x32_bf16 v[80:83], v[190:193], v[214:217], v[80:83]
	v_mfma_f32_16x16x32_bf16 v[72:75], v[180:183], v[222:225], v[72:75]
	v_mfma_f32_16x16x32_bf16 v[64:67], v[190:193], v[222:225], v[64:67]
	s_setprio 0
	s_barrier
	s_add_i32 s76, s66, s54
	v_lshl_add_u64 v[154:155], s[48:49], 0, v[132:133]
	s_mov_b32 m0, s76
	ds_read_b128 v[194:197], v150 offset:16384
	v_xor_b32_e32 v253, 64, v150
	ds_read_b128 v[198:201], v253 offset:16384
	ds_read_b128 v[202:205], v150 offset:18432
	ds_read_b128 v[206:209], v253 offset:18432
	ds_read_b128 v[210:213], v150 offset:20480
	ds_read_b128 v[214:217], v253 offset:20480
	ds_read_b128 v[218:221], v150 offset:22528
	ds_read_b128 v[222:225], v253 offset:22528
	global_load_lds_dwordx4 v[154:155], off
	s_add_i32 m0, s76, 0x2000
	s_add_u32 s76, s48, 0x40000
	v_lshl_add_u64 v[226:227], s[48:49], 0, v[128:129]
	s_addc_u32 s77, s49, 0
	s_add_i32 s78, s67, s54
	global_load_lds_dwordx4 v[226:227], off
	v_lshl_add_u64 v[228:229], s[76:77], 0, v[132:133]
	s_mov_b32 m0, s78
	v_lshl_add_u64 v[230:231], s[50:51], 0, v[130:131]
	global_load_lds_dwordx4 v[228:229], off
	v_lshl_add_u64 v[228:229], s[76:77], 0, v[128:129]
	s_add_i32 m0, s78, 0x2000
	s_nop 0
	global_load_lds_dwordx4 v[228:229], off
	v_lshl_add_u64 v[228:229], s[50:51], 0, v[134:135]
	s_mov_b32 m0, s57
	s_nop 0
	global_load_lds_dwordx4 v[228:229], off
	s_mov_b32 m0, s58
	s_nop 0
	global_load_lds_dwordx4 v[230:231], off
	s_waitcnt vmcnt(16)
	s_waitcnt lgkmcnt(0)
	s_barrier
	s_setprio 1
	s_waitcnt lgkmcnt(0)
	v_mfma_f32_16x16x32_bf16 v[60:63], v[160:163], v[194:197], 0
	v_mfma_f32_16x16x32_bf16 v[52:55], v[168:171], v[194:197], 0
	v_mfma_f32_16x16x32_bf16 v[44:47], v[160:163], v[202:205], 0
	v_mfma_f32_16x16x32_bf16 v[36:39], v[168:171], v[202:205], 0
	v_mfma_f32_16x16x32_bf16 v[28:31], v[160:163], v[210:213], 0
	v_mfma_f32_16x16x32_bf16 v[20:23], v[168:171], v[210:213], 0
	v_mfma_f32_16x16x32_bf16 v[12:15], v[160:163], v[218:221], 0
	v_mfma_f32_16x16x32_bf16 v[4:7], v[168:171], v[218:221], 0
	v_mfma_f32_16x16x32_bf16 v[60:63], v[164:167], v[198:201], v[60:63]
	v_mfma_f32_16x16x32_bf16 v[52:55], v[172:175], v[198:201], v[52:55]
	v_mfma_f32_16x16x32_bf16 v[44:47], v[164:167], v[206:209], v[44:47]
	v_mfma_f32_16x16x32_bf16 v[36:39], v[172:175], v[206:209], v[36:39]
	v_mfma_f32_16x16x32_bf16 v[28:31], v[164:167], v[214:217], v[28:31]
	v_mfma_f32_16x16x32_bf16 v[20:23], v[172:175], v[214:217], v[20:23]
	v_mfma_f32_16x16x32_bf16 v[12:15], v[164:167], v[222:225], v[12:15]
	v_mfma_f32_16x16x32_bf16 v[4:7], v[172:175], v[222:225], v[4:7]
	s_setprio 0
	s_setprio 1
	v_mfma_f32_16x16x32_bf16 v[56:59], v[176:179], v[194:197], 0
	v_mfma_f32_16x16x32_bf16 v[48:51], v[186:189], v[194:197], 0
	v_mfma_f32_16x16x32_bf16 v[40:43], v[176:179], v[202:205], 0
	v_mfma_f32_16x16x32_bf16 v[32:35], v[186:189], v[202:205], 0
	v_mfma_f32_16x16x32_bf16 v[24:27], v[176:179], v[210:213], 0
	v_mfma_f32_16x16x32_bf16 v[16:19], v[186:189], v[210:213], 0
	v_mfma_f32_16x16x32_bf16 v[8:11], v[176:179], v[218:221], 0
	v_mfma_f32_16x16x32_bf16 v[0:3], v[186:189], v[218:221], 0
	v_mfma_f32_16x16x32_bf16 v[56:59], v[180:183], v[198:201], v[56:59]
	v_mfma_f32_16x16x32_bf16 v[48:51], v[190:193], v[198:201], v[48:51]
	v_mfma_f32_16x16x32_bf16 v[40:43], v[180:183], v[206:209], v[40:43]
	v_mfma_f32_16x16x32_bf16 v[32:35], v[190:193], v[206:209], v[32:35]
	v_mfma_f32_16x16x32_bf16 v[24:27], v[180:183], v[214:217], v[24:27]
	v_mfma_f32_16x16x32_bf16 v[16:19], v[190:193], v[214:217], v[16:19]
	v_mfma_f32_16x16x32_bf16 v[8:11], v[180:183], v[222:225], v[8:11]
	v_mfma_f32_16x16x32_bf16 v[0:3], v[190:193], v[222:225], v[0:3]
	s_setprio 0
	s_barrier
	s_add_i32 s76, 0, 0x18000
	v_add_u32_e32 v153, s76, v147
	s_add_i32 s77, 0, 0x1c000
	ds_read_b128 v[160:163], v153
	v_xor_b32_e32 v253, 64, v153
	ds_read_b128 v[164:167], v253
	ds_read_b128 v[168:171], v153 offset:2048
	ds_read_b128 v[172:175], v253 offset:2048
	v_add_u32_e32 v153, s77, v147
	ds_read_b128 v[176:179], v153
	v_xor_b32_e32 v253, 64, v153
	ds_read_b128 v[180:183], v253
	ds_read_b128 v[186:189], v153 offset:2048
	ds_read_b128 v[190:193], v253 offset:2048
	s_add_u32 s50, s50, 0x40000
	s_addc_u32 s51, s51, 0
	s_mov_b32 m0, s59
	v_lshl_add_u64 v[232:233], s[50:51], 0, v[134:135]
	ds_read_b128 v[194:197], v150 offset:32768
	v_xor_b32_e32 v253, 64, v150
	ds_read_b128 v[198:201], v253 offset:32768
	ds_read_b128 v[202:205], v150 offset:34816
	ds_read_b128 v[206:209], v253 offset:34816
	ds_read_b128 v[210:213], v150 offset:36864
	ds_read_b128 v[214:217], v253 offset:36864
	ds_read_b128 v[218:221], v150 offset:38912
	ds_read_b128 v[222:225], v253 offset:38912
	global_load_lds_dwordx4 v[232:233], off
	v_lshl_add_u64 v[232:233], s[50:51], 0, v[130:131]
	s_mov_b32 m0, s60
	s_nop 0
	global_load_lds_dwordx4 v[232:233], off
	s_waitcnt vmcnt(8)
	s_waitcnt lgkmcnt(0)
	s_barrier
	s_setprio 1
	s_waitcnt lgkmcnt(0)
	v_mfma_f32_16x16x32_bf16 v[124:127], v[160:163], v[194:197], v[124:127]
	v_mfma_f32_16x16x32_bf16 v[124:127], v[164:167], v[198:201], v[124:127]
	v_mfma_f32_16x16x32_bf16 v[116:119], v[172:175], v[198:201], v[116:119]
	v_mfma_f32_16x16x32_bf16 v[116:119], v[168:171], v[194:197], v[116:119]
	v_mfma_f32_16x16x32_bf16 v[100:103], v[168:171], v[202:205], v[100:103]
	v_mfma_f32_16x16x32_bf16 v[100:103], v[172:175], v[206:209], v[100:103]
	v_mfma_f32_16x16x32_bf16 v[108:111], v[164:167], v[206:209], v[108:111]
	v_mfma_f32_16x16x32_bf16 v[108:111], v[160:163], v[202:205], v[108:111]
	v_mfma_f32_16x16x32_bf16 v[92:95], v[160:163], v[210:213], v[92:95]
	v_mfma_f32_16x16x32_bf16 v[92:95], v[164:167], v[214:217], v[92:95]
	v_mfma_f32_16x16x32_bf16 v[84:87], v[172:175], v[214:217], v[84:87]
	v_mfma_f32_16x16x32_bf16 v[84:87], v[168:171], v[210:213], v[84:87]
	v_mfma_f32_16x16x32_bf16 v[68:71], v[168:171], v[218:221], v[68:71]
	v_mfma_f32_16x16x32_bf16 v[68:71], v[172:175], v[222:225], v[68:71]
	v_mfma_f32_16x16x32_bf16 v[76:79], v[164:167], v[222:225], v[76:79]
	v_mfma_f32_16x16x32_bf16 v[76:79], v[160:163], v[218:221], v[76:79]
	s_setprio 0
	s_setprio 1
	v_mfma_f32_16x16x32_bf16 v[120:123], v[176:179], v[194:197], v[120:123]
	v_mfma_f32_16x16x32_bf16 v[120:123], v[180:183], v[198:201], v[120:123]
	v_mfma_f32_16x16x32_bf16 v[112:115], v[190:193], v[198:201], v[112:115]
	v_mfma_f32_16x16x32_bf16 v[112:115], v[186:189], v[194:197], v[112:115]
	v_mfma_f32_16x16x32_bf16 v[96:99], v[186:189], v[202:205], v[96:99]
	v_mfma_f32_16x16x32_bf16 v[96:99], v[190:193], v[206:209], v[96:99]
	v_mfma_f32_16x16x32_bf16 v[104:107], v[180:183], v[206:209], v[104:107]
	v_mfma_f32_16x16x32_bf16 v[104:107], v[176:179], v[202:205], v[104:107]
	v_mfma_f32_16x16x32_bf16 v[88:91], v[176:179], v[210:213], v[88:91]
	v_mfma_f32_16x16x32_bf16 v[88:91], v[180:183], v[214:217], v[88:91]
	v_mfma_f32_16x16x32_bf16 v[80:83], v[190:193], v[214:217], v[80:83]
	v_mfma_f32_16x16x32_bf16 v[80:83], v[186:189], v[210:213], v[80:83]
	v_mfma_f32_16x16x32_bf16 v[64:67], v[186:189], v[218:221], v[64:67]
	v_mfma_f32_16x16x32_bf16 v[64:67], v[190:193], v[222:225], v[64:67]
	v_mfma_f32_16x16x32_bf16 v[72:75], v[180:183], v[222:225], v[72:75]
	v_mfma_f32_16x16x32_bf16 v[72:75], v[176:179], v[218:221], v[72:75]
	s_setprio 0
	s_barrier
	s_add_i32 s50, s76, s54
	v_lshl_add_u64 v[154:155], v[154:155], 0, s[20:21]
	s_mov_b32 m0, s50
	ds_read_b128 v[194:197], v150 offset:49152
	v_xor_b32_e32 v253, 64, v150
	ds_read_b128 v[198:201], v253 offset:49152
	ds_read_b128 v[202:205], v150 offset:51200
	ds_read_b128 v[206:209], v253 offset:51200
	ds_read_b128 v[210:213], v150 offset:53248
	ds_read_b128 v[214:217], v253 offset:53248
	ds_read_b128 v[218:221], v150 offset:55296
	ds_read_b128 v[222:225], v253 offset:55296
	global_load_lds_dwordx4 v[154:155], off
	s_add_i32 m0, s50, 0x2000
	s_add_u32 s48, s48, 0x40080
	v_lshl_add_u64 v[154:155], v[226:227], 0, s[20:21]
	s_addc_u32 s49, s49, 0
	s_add_i32 s50, s77, s54
	global_load_lds_dwordx4 v[154:155], off
	v_lshl_add_u64 v[154:155], s[48:49], 0, v[132:133]
	s_mov_b32 m0, s50
	s_nop 0
	global_load_lds_dwordx4 v[154:155], off
	v_lshl_add_u64 v[154:155], s[48:49], 0, v[128:129]
	s_add_i32 m0, s50, 0x2000
	s_nop 0
	global_load_lds_dwordx4 v[154:155], off
	v_lshl_add_u64 v[154:155], v[228:229], 0, s[20:21]
	s_mov_b32 m0, s62
	s_nop 0
	global_load_lds_dwordx4 v[154:155], off
	v_lshl_add_u64 v[154:155], v[230:231], 0, s[20:21]
	s_mov_b32 m0, s63
	s_nop 0
	global_load_lds_dwordx4 v[154:155], off
	s_waitcnt vmcnt(8)
	s_waitcnt lgkmcnt(0)
	s_barrier
	s_setprio 1
	s_waitcnt lgkmcnt(0)
	v_mfma_f32_16x16x32_bf16 v[60:63], v[160:163], v[194:197], v[60:63]
	v_mfma_f32_16x16x32_bf16 v[60:63], v[164:167], v[198:201], v[60:63]
	v_mfma_f32_16x16x32_bf16 v[52:55], v[172:175], v[198:201], v[52:55]
	v_mfma_f32_16x16x32_bf16 v[52:55], v[168:171], v[194:197], v[52:55]
	v_mfma_f32_16x16x32_bf16 v[36:39], v[168:171], v[202:205], v[36:39]
	v_mfma_f32_16x16x32_bf16 v[36:39], v[172:175], v[206:209], v[36:39]
	v_mfma_f32_16x16x32_bf16 v[44:47], v[164:167], v[206:209], v[44:47]
	v_mfma_f32_16x16x32_bf16 v[44:47], v[160:163], v[202:205], v[44:47]
	v_mfma_f32_16x16x32_bf16 v[28:31], v[160:163], v[210:213], v[28:31]
	v_mfma_f32_16x16x32_bf16 v[28:31], v[164:167], v[214:217], v[28:31]
	v_mfma_f32_16x16x32_bf16 v[20:23], v[172:175], v[214:217], v[20:23]
	v_mfma_f32_16x16x32_bf16 v[20:23], v[168:171], v[210:213], v[20:23]
	v_mfma_f32_16x16x32_bf16 v[4:7], v[168:171], v[218:221], v[4:7]
	v_mfma_f32_16x16x32_bf16 v[4:7], v[172:175], v[222:225], v[4:7]
	v_mfma_f32_16x16x32_bf16 v[12:15], v[164:167], v[222:225], v[12:15]
	v_mfma_f32_16x16x32_bf16 v[12:15], v[160:163], v[218:221], v[12:15]
	s_setprio 0
	s_setprio 1
	v_mfma_f32_16x16x32_bf16 v[56:59], v[176:179], v[194:197], v[56:59]
	v_mfma_f32_16x16x32_bf16 v[56:59], v[180:183], v[198:201], v[56:59]
	v_mfma_f32_16x16x32_bf16 v[48:51], v[190:193], v[198:201], v[48:51]
	v_mfma_f32_16x16x32_bf16 v[48:51], v[186:189], v[194:197], v[48:51]
	v_mfma_f32_16x16x32_bf16 v[32:35], v[186:189], v[202:205], v[32:35]
	v_mfma_f32_16x16x32_bf16 v[32:35], v[190:193], v[206:209], v[32:35]
	v_mfma_f32_16x16x32_bf16 v[40:43], v[180:183], v[206:209], v[40:43]
	v_mfma_f32_16x16x32_bf16 v[40:43], v[176:179], v[202:205], v[40:43]
	v_mfma_f32_16x16x32_bf16 v[24:27], v[176:179], v[210:213], v[24:27]
	v_mfma_f32_16x16x32_bf16 v[24:27], v[180:183], v[214:217], v[24:27]
	v_mfma_f32_16x16x32_bf16 v[16:19], v[190:193], v[214:217], v[16:19]
	v_mfma_f32_16x16x32_bf16 v[16:19], v[186:189], v[210:213], v[16:19]
	v_mfma_f32_16x16x32_bf16 v[0:3], v[186:189], v[218:221], v[0:3]
	v_mfma_f32_16x16x32_bf16 v[0:3], v[190:193], v[222:225], v[0:3]
	v_mfma_f32_16x16x32_bf16 v[8:11], v[180:183], v[222:225], v[8:11]
	v_mfma_f32_16x16x32_bf16 v[8:11], v[176:179], v[218:221], v[8:11]
	s_setprio 0
	s_barrier
	s_add_i32 s75, s75, 2
	s_add_u32 s73, s73, 0x100
	s_addc_u32 s74, s74, 0
	s_add_u32 s46, s46, 0x100
	s_addc_u32 s47, s47, 0
	s_branch .LBB0_527
.Lfa_4:
	v_add_u32_e32 v153, s66, v147
	ds_read_b128 v[160:163], v153
	v_xor_b32_e32 v253, 64, v153
	ds_read_b128 v[164:167], v253
	ds_read_b128 v[168:171], v153 offset:2048
	ds_read_b128 v[172:175], v253 offset:2048
	v_add_u32_e32 v153, s67, v147
	ds_read_b128 v[176:179], v153
	v_xor_b32_e32 v253, 64, v153
	ds_read_b128 v[180:183], v253
	ds_read_b128 v[186:189], v153 offset:2048
	ds_read_b128 v[190:193], v253 offset:2048
	s_add_u32 s50, s46, 0xfffc0080
	s_addc_u32 s51, s47, -1
	s_and_b64 s[48:49], s[48:49], exec
	s_cselect_b32 s51, s29, s51
	s_cselect_b32 s50, s70, s50
	s_cselect_b32 s49, s71, s74
	s_cselect_b32 s48, s72, s73
	v_lshl_add_u64 v[154:155], s[46:47], 0, v[138:139]
	s_add_i32 m0, s57, 0xc000
	ds_read_b128 v[194:197], v150
	v_xor_b32_e32 v253, 64, v150
	ds_read_b128 v[198:201], v253
	ds_read_b128 v[202:205], v150 offset:2048
	ds_read_b128 v[206:209], v253 offset:2048
	ds_read_b128 v[210:213], v150 offset:4096
	ds_read_b128 v[214:217], v253 offset:4096
	ds_read_b128 v[218:221], v150 offset:6144
	ds_read_b128 v[222:225], v253 offset:6144
	global_load_lds_dwordx4 v[154:155], off
	v_lshl_add_u64 v[154:155], s[46:47], 0, v[136:137]
	s_add_i32 m0, s57, 0xe000
	s_nop 0
	global_load_lds_dwordx4 v[154:155], off
	s_waitcnt vmcnt(8)
	s_waitcnt lgkmcnt(0)
	s_barrier
	s_setprio 1
	s_waitcnt lgkmcnt(0)
	v_mfma_f32_16x16x32_bf16 v[124:127], v[160:163], v[194:197], 0
	v_mfma_f32_16x16x32_bf16 v[116:119], v[168:171], v[194:197], 0
	v_mfma_f32_16x16x32_bf16 v[108:111], v[160:163], v[202:205], 0
	v_mfma_f32_16x16x32_bf16 v[100:103], v[168:171], v[202:205], 0
	v_mfma_f32_16x16x32_bf16 v[92:95], v[160:163], v[210:213], 0
	v_mfma_f32_16x16x32_bf16 v[84:87], v[168:171], v[210:213], 0
	v_mfma_f32_16x16x32_bf16 v[76:79], v[160:163], v[218:221], 0
	v_mfma_f32_16x16x32_bf16 v[68:71], v[168:171], v[218:221], 0
	v_mfma_f32_16x16x32_bf16 v[124:127], v[164:167], v[198:201], v[124:127]
	v_mfma_f32_16x16x32_bf16 v[116:119], v[172:175], v[198:201], v[116:119]
	v_mfma_f32_16x16x32_bf16 v[108:111], v[164:167], v[206:209], v[108:111]
	v_mfma_f32_16x16x32_bf16 v[100:103], v[172:175], v[206:209], v[100:103]
	v_mfma_f32_16x16x32_bf16 v[92:95], v[164:167], v[214:217], v[92:95]
	v_mfma_f32_16x16x32_bf16 v[84:87], v[172:175], v[214:217], v[84:87]
	v_mfma_f32_16x16x32_bf16 v[76:79], v[164:167], v[222:225], v[76:79]
	v_mfma_f32_16x16x32_bf16 v[68:71], v[172:175], v[222:225], v[68:71]
	s_setprio 0
	s_setprio 1
	v_mfma_f32_16x16x32_bf16 v[120:123], v[176:179], v[194:197], 0
	v_mfma_f32_16x16x32_bf16 v[112:115], v[186:189], v[194:197], 0
	v_mfma_f32_16x16x32_bf16 v[104:107], v[176:179], v[202:205], 0
	v_mfma_f32_16x16x32_bf16 v[96:99], v[186:189], v[202:205], 0
	v_mfma_f32_16x16x32_bf16 v[88:91], v[176:179], v[210:213], 0
	v_mfma_f32_16x16x32_bf16 v[80:83], v[186:189], v[210:213], 0
	v_mfma_f32_16x16x32_bf16 v[72:75], v[176:179], v[218:221], 0
	v_mfma_f32_16x16x32_bf16 v[64:67], v[186:189], v[218:221], 0
	v_mfma_f32_16x16x32_bf16 v[120:123], v[180:183], v[198:201], v[120:123]
	v_mfma_f32_16x16x32_bf16 v[112:115], v[190:193], v[198:201], v[112:115]
	v_mfma_f32_16x16x32_bf16 v[104:107], v[180:183], v[206:209], v[104:107]
	v_mfma_f32_16x16x32_bf16 v[96:99], v[190:193], v[206:209], v[96:99]
	v_mfma_f32_16x16x32_bf16 v[88:91], v[180:183], v[214:217], v[88:91]
	v_mfma_f32_16x16x32_bf16 v[80:83], v[190:193], v[214:217], v[80:83]
	v_mfma_f32_16x16x32_bf16 v[72:75], v[180:183], v[222:225], v[72:75]
	v_mfma_f32_16x16x32_bf16 v[64:67], v[190:193], v[222:225], v[64:67]
	s_setprio 0
	s_barrier
	s_add_i32 s76, s66, s54
	v_lshl_add_u64 v[154:155], s[48:49], 0, v[132:133]
	s_mov_b32 m0, s76
	ds_read_b128 v[194:197], v150 offset:16384
	v_xor_b32_e32 v253, 64, v150
	ds_read_b128 v[198:201], v253 offset:16384
	ds_read_b128 v[202:205], v150 offset:18432
	ds_read_b128 v[206:209], v253 offset:18432
	ds_read_b128 v[210:213], v150 offset:20480
	ds_read_b128 v[214:217], v253 offset:20480
	ds_read_b128 v[218:221], v150 offset:22528
	ds_read_b128 v[222:225], v253 offset:22528
	global_load_lds_dwordx4 v[154:155], off
	s_add_i32 m0, s76, 0x2000
	s_add_u32 s76, s48, 0x40000
	v_lshl_add_u64 v[226:227], s[48:49], 0, v[128:129]
	s_addc_u32 s77, s49, 0
	s_add_i32 s78, s67, s54
	global_load_lds_dwordx4 v[226:227], off
	v_lshl_add_u64 v[228:229], s[76:77], 0, v[132:133]
	s_mov_b32 m0, s78
	v_lshl_add_u64 v[230:231], s[50:51], 0, v[130:131]
	global_load_lds_dwordx4 v[228:229], off
	v_lshl_add_u64 v[228:229], s[76:77], 0, v[128:129]
	s_add_i32 m0, s78, 0x2000
	s_nop 0
	global_load_lds_dwordx4 v[228:229], off
	v_lshl_add_u64 v[228:229], s[50:51], 0, v[134:135]
	s_mov_b32 m0, s57
	s_nop 0
	global_load_lds_dwordx4 v[228:229], off
	s_mov_b32 m0, s58
	s_nop 0
	global_load_lds_dwordx4 v[230:231], off
	s_waitcnt vmcnt(8)
	s_waitcnt lgkmcnt(0)
	s_barrier
	s_setprio 1
	s_waitcnt lgkmcnt(0)
	v_mfma_f32_16x16x32_bf16 v[60:63], v[160:163], v[194:197], 0
	v_mfma_f32_16x16x32_bf16 v[52:55], v[168:171], v[194:197], 0
	v_mfma_f32_16x16x32_bf16 v[44:47], v[160:163], v[202:205], 0
	v_mfma_f32_16x16x32_bf16 v[36:39], v[168:171], v[202:205], 0
	v_mfma_f32_16x16x32_bf16 v[28:31], v[160:163], v[210:213], 0
	v_mfma_f32_16x16x32_bf16 v[20:23], v[168:171], v[210:213], 0
	v_mfma_f32_16x16x32_bf16 v[12:15], v[160:163], v[218:221], 0
	v_mfma_f32_16x16x32_bf16 v[4:7], v[168:171], v[218:221], 0
	v_mfma_f32_16x16x32_bf16 v[60:63], v[164:167], v[198:201], v[60:63]
	v_mfma_f32_16x16x32_bf16 v[52:55], v[172:175], v[198:201], v[52:55]
	v_mfma_f32_16x16x32_bf16 v[44:47], v[164:167], v[206:209], v[44:47]
	v_mfma_f32_16x16x32_bf16 v[36:39], v[172:175], v[206:209], v[36:39]
	v_mfma_f32_16x16x32_bf16 v[28:31], v[164:167], v[214:217], v[28:31]
	v_mfma_f32_16x16x32_bf16 v[20:23], v[172:175], v[214:217], v[20:23]
	v_mfma_f32_16x16x32_bf16 v[12:15], v[164:167], v[222:225], v[12:15]
	v_mfma_f32_16x16x32_bf16 v[4:7], v[172:175], v[222:225], v[4:7]
	s_setprio 0
	s_setprio 1
	v_mfma_f32_16x16x32_bf16 v[56:59], v[176:179], v[194:197], 0
	v_mfma_f32_16x16x32_bf16 v[48:51], v[186:189], v[194:197], 0
	v_mfma_f32_16x16x32_bf16 v[40:43], v[176:179], v[202:205], 0
	v_mfma_f32_16x16x32_bf16 v[32:35], v[186:189], v[202:205], 0
	v_mfma_f32_16x16x32_bf16 v[24:27], v[176:179], v[210:213], 0
	v_mfma_f32_16x16x32_bf16 v[16:19], v[186:189], v[210:213], 0
	v_mfma_f32_16x16x32_bf16 v[8:11], v[176:179], v[218:221], 0
	v_mfma_f32_16x16x32_bf16 v[0:3], v[186:189], v[218:221], 0
	v_mfma_f32_16x16x32_bf16 v[56:59], v[180:183], v[198:201], v[56:59]
	v_mfma_f32_16x16x32_bf16 v[48:51], v[190:193], v[198:201], v[48:51]
	v_mfma_f32_16x16x32_bf16 v[40:43], v[180:183], v[206:209], v[40:43]
	v_mfma_f32_16x16x32_bf16 v[32:35], v[190:193], v[206:209], v[32:35]
	v_mfma_f32_16x16x32_bf16 v[24:27], v[180:183], v[214:217], v[24:27]
	v_mfma_f32_16x16x32_bf16 v[16:19], v[190:193], v[214:217], v[16:19]
	v_mfma_f32_16x16x32_bf16 v[8:11], v[180:183], v[222:225], v[8:11]
	v_mfma_f32_16x16x32_bf16 v[0:3], v[190:193], v[222:225], v[0:3]
	s_setprio 0
	s_barrier
	s_add_i32 s76, 0, 0x18000
	v_add_u32_e32 v153, s76, v147
	s_add_i32 s77, 0, 0x1c000
	ds_read_b128 v[160:163], v153
	v_xor_b32_e32 v253, 64, v153
	ds_read_b128 v[164:167], v253
	ds_read_b128 v[168:171], v153 offset:2048
	ds_read_b128 v[172:175], v253 offset:2048
	v_add_u32_e32 v153, s77, v147
	ds_read_b128 v[176:179], v153
	v_xor_b32_e32 v253, 64, v153
	ds_read_b128 v[180:183], v253
	ds_read_b128 v[186:189], v153 offset:2048
	ds_read_b128 v[190:193], v253 offset:2048
	s_add_u32 s50, s50, 0x40000
	s_addc_u32 s51, s51, 0
	s_mov_b32 m0, s59
	v_lshl_add_u64 v[232:233], s[50:51], 0, v[134:135]
	ds_read_b128 v[194:197], v150 offset:32768
	v_xor_b32_e32 v253, 64, v150
	ds_read_b128 v[198:201], v253 offset:32768
	ds_read_b128 v[202:205], v150 offset:34816
	ds_read_b128 v[206:209], v253 offset:34816
	ds_read_b128 v[210:213], v150 offset:36864
	ds_read_b128 v[214:217], v253 offset:36864
	ds_read_b128 v[218:221], v150 offset:38912
	ds_read_b128 v[222:225], v253 offset:38912
	global_load_lds_dwordx4 v[232:233], off
	v_lshl_add_u64 v[232:233], s[50:51], 0, v[130:131]
	s_mov_b32 m0, s60
	s_nop 0
	global_load_lds_dwordx4 v[232:233], off
	s_waitcnt vmcnt(8)
	s_waitcnt lgkmcnt(0)
	s_barrier
	s_setprio 1
	s_waitcnt lgkmcnt(0)
	v_mfma_f32_16x16x32_bf16 v[124:127], v[160:163], v[194:197], v[124:127]
	v_mfma_f32_16x16x32_bf16 v[124:127], v[164:167], v[198:201], v[124:127]
	v_mfma_f32_16x16x32_bf16 v[116:119], v[172:175], v[198:201], v[116:119]
	v_mfma_f32_16x16x32_bf16 v[116:119], v[168:171], v[194:197], v[116:119]
	v_mfma_f32_16x16x32_bf16 v[100:103], v[168:171], v[202:205], v[100:103]
	v_mfma_f32_16x16x32_bf16 v[100:103], v[172:175], v[206:209], v[100:103]
	v_mfma_f32_16x16x32_bf16 v[108:111], v[164:167], v[206:209], v[108:111]
	v_mfma_f32_16x16x32_bf16 v[108:111], v[160:163], v[202:205], v[108:111]
	v_mfma_f32_16x16x32_bf16 v[92:95], v[160:163], v[210:213], v[92:95]
	v_mfma_f32_16x16x32_bf16 v[92:95], v[164:167], v[214:217], v[92:95]
	v_mfma_f32_16x16x32_bf16 v[84:87], v[172:175], v[214:217], v[84:87]
	v_mfma_f32_16x16x32_bf16 v[84:87], v[168:171], v[210:213], v[84:87]
	v_mfma_f32_16x16x32_bf16 v[68:71], v[168:171], v[218:221], v[68:71]
	v_mfma_f32_16x16x32_bf16 v[68:71], v[172:175], v[222:225], v[68:71]
	v_mfma_f32_16x16x32_bf16 v[76:79], v[164:167], v[222:225], v[76:79]
	v_mfma_f32_16x16x32_bf16 v[76:79], v[160:163], v[218:221], v[76:79]
	s_setprio 0
	s_setprio 1
	v_mfma_f32_16x16x32_bf16 v[120:123], v[176:179], v[194:197], v[120:123]
	v_mfma_f32_16x16x32_bf16 v[120:123], v[180:183], v[198:201], v[120:123]
	v_mfma_f32_16x16x32_bf16 v[112:115], v[190:193], v[198:201], v[112:115]
	v_mfma_f32_16x16x32_bf16 v[112:115], v[186:189], v[194:197], v[112:115]
	v_mfma_f32_16x16x32_bf16 v[96:99], v[186:189], v[202:205], v[96:99]
	v_mfma_f32_16x16x32_bf16 v[96:99], v[190:193], v[206:209], v[96:99]
	v_mfma_f32_16x16x32_bf16 v[104:107], v[180:183], v[206:209], v[104:107]
	v_mfma_f32_16x16x32_bf16 v[104:107], v[176:179], v[202:205], v[104:107]
	v_mfma_f32_16x16x32_bf16 v[88:91], v[176:179], v[210:213], v[88:91]
	v_mfma_f32_16x16x32_bf16 v[88:91], v[180:183], v[214:217], v[88:91]
	v_mfma_f32_16x16x32_bf16 v[80:83], v[190:193], v[214:217], v[80:83]
	v_mfma_f32_16x16x32_bf16 v[80:83], v[186:189], v[210:213], v[80:83]
	v_mfma_f32_16x16x32_bf16 v[64:67], v[186:189], v[218:221], v[64:67]
	v_mfma_f32_16x16x32_bf16 v[64:67], v[190:193], v[222:225], v[64:67]
	v_mfma_f32_16x16x32_bf16 v[72:75], v[180:183], v[222:225], v[72:75]
	v_mfma_f32_16x16x32_bf16 v[72:75], v[176:179], v[218:221], v[72:75]
	s_setprio 0
	s_barrier
	s_add_i32 s50, s76, s54
	v_lshl_add_u64 v[154:155], v[154:155], 0, s[20:21]
	s_mov_b32 m0, s50
	ds_read_b128 v[194:197], v150 offset:49152
	v_xor_b32_e32 v253, 64, v150
	ds_read_b128 v[198:201], v253 offset:49152
	ds_read_b128 v[202:205], v150 offset:51200
	ds_read_b128 v[206:209], v253 offset:51200
	ds_read_b128 v[210:213], v150 offset:53248
	ds_read_b128 v[214:217], v253 offset:53248
	ds_read_b128 v[218:221], v150 offset:55296
	ds_read_b128 v[222:225], v253 offset:55296
	global_load_lds_dwordx4 v[154:155], off
	s_add_i32 m0, s50, 0x2000
	s_add_u32 s48, s48, 0x40080
	v_lshl_add_u64 v[154:155], v[226:227], 0, s[20:21]
	s_addc_u32 s49, s49, 0
	s_add_i32 s50, s77, s54
	global_load_lds_dwordx4 v[154:155], off
	v_lshl_add_u64 v[154:155], s[48:49], 0, v[132:133]
	s_mov_b32 m0, s50
	s_nop 0
	global_load_lds_dwordx4 v[154:155], off
	v_lshl_add_u64 v[154:155], s[48:49], 0, v[128:129]
	s_add_i32 m0, s50, 0x2000
	s_nop 0
	global_load_lds_dwordx4 v[154:155], off
	v_lshl_add_u64 v[154:155], v[228:229], 0, s[20:21]
	s_mov_b32 m0, s62
	s_nop 0
	global_load_lds_dwordx4 v[154:155], off
	v_lshl_add_u64 v[154:155], v[230:231], 0, s[20:21]
	s_mov_b32 m0, s63
	s_nop 0
	global_load_lds_dwordx4 v[154:155], off
	s_waitcnt vmcnt(8)
	s_waitcnt lgkmcnt(0)
	s_barrier
	s_setprio 1
	s_waitcnt lgkmcnt(0)
	v_mfma_f32_16x16x32_bf16 v[60:63], v[160:163], v[194:197], v[60:63]
	v_mfma_f32_16x16x32_bf16 v[60:63], v[164:167], v[198:201], v[60:63]
	v_mfma_f32_16x16x32_bf16 v[52:55], v[172:175], v[198:201], v[52:55]
	v_mfma_f32_16x16x32_bf16 v[52:55], v[168:171], v[194:197], v[52:55]
	v_mfma_f32_16x16x32_bf16 v[36:39], v[168:171], v[202:205], v[36:39]
	v_mfma_f32_16x16x32_bf16 v[36:39], v[172:175], v[206:209], v[36:39]
	v_mfma_f32_16x16x32_bf16 v[44:47], v[164:167], v[206:209], v[44:47]
	v_mfma_f32_16x16x32_bf16 v[44:47], v[160:163], v[202:205], v[44:47]
	v_mfma_f32_16x16x32_bf16 v[28:31], v[160:163], v[210:213], v[28:31]
	v_mfma_f32_16x16x32_bf16 v[28:31], v[164:167], v[214:217], v[28:31]
	v_mfma_f32_16x16x32_bf16 v[20:23], v[172:175], v[214:217], v[20:23]
	v_mfma_f32_16x16x32_bf16 v[20:23], v[168:171], v[210:213], v[20:23]
	v_mfma_f32_16x16x32_bf16 v[4:7], v[168:171], v[218:221], v[4:7]
	v_mfma_f32_16x16x32_bf16 v[4:7], v[172:175], v[222:225], v[4:7]
	v_mfma_f32_16x16x32_bf16 v[12:15], v[164:167], v[222:225], v[12:15]
	v_mfma_f32_16x16x32_bf16 v[12:15], v[160:163], v[218:221], v[12:15]
	s_setprio 0
	s_setprio 1
	v_mfma_f32_16x16x32_bf16 v[56:59], v[176:179], v[194:197], v[56:59]
	v_mfma_f32_16x16x32_bf16 v[56:59], v[180:183], v[198:201], v[56:59]
	v_mfma_f32_16x16x32_bf16 v[48:51], v[190:193], v[198:201], v[48:51]
	v_mfma_f32_16x16x32_bf16 v[48:51], v[186:189], v[194:197], v[48:51]
	v_mfma_f32_16x16x32_bf16 v[32:35], v[186:189], v[202:205], v[32:35]
	v_mfma_f32_16x16x32_bf16 v[32:35], v[190:193], v[206:209], v[32:35]
	v_mfma_f32_16x16x32_bf16 v[40:43], v[180:183], v[206:209], v[40:43]
	v_mfma_f32_16x16x32_bf16 v[40:43], v[176:179], v[202:205], v[40:43]
	v_mfma_f32_16x16x32_bf16 v[24:27], v[176:179], v[210:213], v[24:27]
	v_mfma_f32_16x16x32_bf16 v[24:27], v[180:183], v[214:217], v[24:27]
	v_mfma_f32_16x16x32_bf16 v[16:19], v[190:193], v[214:217], v[16:19]
	v_mfma_f32_16x16x32_bf16 v[16:19], v[186:189], v[210:213], v[16:19]
	v_mfma_f32_16x16x32_bf16 v[0:3], v[186:189], v[218:221], v[0:3]
	v_mfma_f32_16x16x32_bf16 v[0:3], v[190:193], v[222:225], v[0:3]
	v_mfma_f32_16x16x32_bf16 v[8:11], v[180:183], v[222:225], v[8:11]
	v_mfma_f32_16x16x32_bf16 v[8:11], v[176:179], v[218:221], v[8:11]
	s_setprio 0
	s_barrier
	s_add_i32 s75, s75, 2
	s_add_u32 s73, s73, 0x100
	s_addc_u32 s74, s74, 0
	s_add_u32 s46, s46, 0x100
	s_addc_u32 s47, s47, 0
	s_branch .LBB0_527
.LBB0_526:
	v_add_u32_e32 v153, s66, v147
	ds_read_b128 v[160:163], v153
	v_xor_b32_e32 v253, 64, v153
	ds_read_b128 v[164:167], v253
	ds_read_b128 v[168:171], v153 offset:2048
	ds_read_b128 v[172:175], v253 offset:2048
	v_add_u32_e32 v153, s67, v147
	ds_read_b128 v[176:179], v153
	v_xor_b32_e32 v253, 64, v153
	ds_read_b128 v[180:183], v253
	ds_read_b128 v[186:189], v153 offset:2048
	ds_read_b128 v[190:193], v253 offset:2048
	s_add_u32 s50, s46, 0xfffc0080
	s_addc_u32 s51, s47, -1
	s_and_b64 s[48:49], s[48:49], exec
	s_cselect_b32 s51, s29, s51
	s_cselect_b32 s50, s70, s50
	s_cselect_b32 s49, s71, s74
	s_cselect_b32 s48, s72, s73
	v_lshl_add_u64 v[154:155], s[46:47], 0, v[138:139]
	s_add_i32 m0, s57, 0xc000
	ds_read_b128 v[194:197], v150
	v_xor_b32_e32 v253, 64, v150
	ds_read_b128 v[198:201], v253
	ds_read_b128 v[202:205], v150 offset:2048
	ds_read_b128 v[206:209], v253 offset:2048
	ds_read_b128 v[210:213], v150 offset:4096
	ds_read_b128 v[214:217], v253 offset:4096
	ds_read_b128 v[218:221], v150 offset:6144
	ds_read_b128 v[222:225], v253 offset:6144
	global_load_lds_dwordx4 v[154:155], off
	v_lshl_add_u64 v[154:155], s[46:47], 0, v[136:137]
	s_add_i32 m0, s57, 0xe000
	s_nop 0
	global_load_lds_dwordx4 v[154:155], off
	s_waitcnt vmcnt(8)
	s_waitcnt lgkmcnt(0)
	s_barrier
	s_setprio 1
	s_waitcnt lgkmcnt(0)
	v_mfma_f32_16x16x32_bf16 v[124:127], v[160:163], v[194:197], v[124:127]
	v_mfma_f32_16x16x32_bf16 v[124:127], v[164:167], v[198:201], v[124:127]
	v_mfma_f32_16x16x32_bf16 v[116:119], v[172:175], v[198:201], v[116:119]
	v_mfma_f32_16x16x32_bf16 v[116:119], v[168:171], v[194:197], v[116:119]
	v_mfma_f32_16x16x32_bf16 v[100:103], v[168:171], v[202:205], v[100:103]
	v_mfma_f32_16x16x32_bf16 v[100:103], v[172:175], v[206:209], v[100:103]
	v_mfma_f32_16x16x32_bf16 v[108:111], v[164:167], v[206:209], v[108:111]
	v_mfma_f32_16x16x32_bf16 v[108:111], v[160:163], v[202:205], v[108:111]
	v_mfma_f32_16x16x32_bf16 v[92:95], v[160:163], v[210:213], v[92:95]
	v_mfma_f32_16x16x32_bf16 v[92:95], v[164:167], v[214:217], v[92:95]
	v_mfma_f32_16x16x32_bf16 v[84:87], v[172:175], v[214:217], v[84:87]
	v_mfma_f32_16x16x32_bf16 v[84:87], v[168:171], v[210:213], v[84:87]
	v_mfma_f32_16x16x32_bf16 v[68:71], v[168:171], v[218:221], v[68:71]
	v_mfma_f32_16x16x32_bf16 v[68:71], v[172:175], v[222:225], v[68:71]
	v_mfma_f32_16x16x32_bf16 v[76:79], v[164:167], v[222:225], v[76:79]
	v_mfma_f32_16x16x32_bf16 v[76:79], v[160:163], v[218:221], v[76:79]
	s_setprio 0
	s_setprio 1
	v_mfma_f32_16x16x32_bf16 v[120:123], v[176:179], v[194:197], v[120:123]
	v_mfma_f32_16x16x32_bf16 v[120:123], v[180:183], v[198:201], v[120:123]
	v_mfma_f32_16x16x32_bf16 v[112:115], v[190:193], v[198:201], v[112:115]
	v_mfma_f32_16x16x32_bf16 v[112:115], v[186:189], v[194:197], v[112:115]
	v_mfma_f32_16x16x32_bf16 v[96:99], v[186:189], v[202:205], v[96:99]
	v_mfma_f32_16x16x32_bf16 v[96:99], v[190:193], v[206:209], v[96:99]
	v_mfma_f32_16x16x32_bf16 v[104:107], v[180:183], v[206:209], v[104:107]
	v_mfma_f32_16x16x32_bf16 v[104:107], v[176:179], v[202:205], v[104:107]
	v_mfma_f32_16x16x32_bf16 v[88:91], v[176:179], v[210:213], v[88:91]
	v_mfma_f32_16x16x32_bf16 v[88:91], v[180:183], v[214:217], v[88:91]
	v_mfma_f32_16x16x32_bf16 v[80:83], v[190:193], v[214:217], v[80:83]
	v_mfma_f32_16x16x32_bf16 v[80:83], v[186:189], v[210:213], v[80:83]
	v_mfma_f32_16x16x32_bf16 v[64:67], v[186:189], v[218:221], v[64:67]
	v_mfma_f32_16x16x32_bf16 v[64:67], v[190:193], v[222:225], v[64:67]
	v_mfma_f32_16x16x32_bf16 v[72:75], v[180:183], v[222:225], v[72:75]
	v_mfma_f32_16x16x32_bf16 v[72:75], v[176:179], v[218:221], v[72:75]
	s_setprio 0
	s_barrier
	s_add_i32 s76, s66, s54
	v_lshl_add_u64 v[154:155], s[48:49], 0, v[132:133]
	s_mov_b32 m0, s76
	ds_read_b128 v[194:197], v150 offset:16384
	v_xor_b32_e32 v253, 64, v150
	ds_read_b128 v[198:201], v253 offset:16384
	ds_read_b128 v[202:205], v150 offset:18432
	ds_read_b128 v[206:209], v253 offset:18432
	ds_read_b128 v[210:213], v150 offset:20480
	ds_read_b128 v[214:217], v253 offset:20480
	ds_read_b128 v[218:221], v150 offset:22528
	ds_read_b128 v[222:225], v253 offset:22528
	global_load_lds_dwordx4 v[154:155], off
	s_add_i32 m0, s76, 0x2000
	s_add_u32 s76, s48, 0x40000
	v_lshl_add_u64 v[226:227], s[48:49], 0, v[128:129]
	s_addc_u32 s77, s49, 0
	s_add_i32 s78, s67, s54
	global_load_lds_dwordx4 v[226:227], off
	v_lshl_add_u64 v[228:229], s[76:77], 0, v[132:133]
	s_mov_b32 m0, s78
	v_lshl_add_u64 v[230:231], s[50:51], 0, v[130:131]
	global_load_lds_dwordx4 v[228:229], off
	v_lshl_add_u64 v[228:229], s[76:77], 0, v[128:129]
	s_add_i32 m0, s78, 0x2000
	s_nop 0
	global_load_lds_dwordx4 v[228:229], off
	v_lshl_add_u64 v[228:229], s[50:51], 0, v[134:135]
	s_mov_b32 m0, s57
	s_nop 0
	global_load_lds_dwordx4 v[228:229], off
	s_mov_b32 m0, s58
	s_nop 0
	global_load_lds_dwordx4 v[230:231], off
	s_waitcnt vmcnt(8)
	s_waitcnt lgkmcnt(0)
	s_barrier
	s_setprio 1
	s_waitcnt lgkmcnt(0)
	v_mfma_f32_16x16x32_bf16 v[60:63], v[160:163], v[194:197], v[60:63]
	v_mfma_f32_16x16x32_bf16 v[60:63], v[164:167], v[198:201], v[60:63]
	v_mfma_f32_16x16x32_bf16 v[52:55], v[172:175], v[198:201], v[52:55]
	v_mfma_f32_16x16x32_bf16 v[52:55], v[168:171], v[194:197], v[52:55]
	v_mfma_f32_16x16x32_bf16 v[36:39], v[168:171], v[202:205], v[36:39]
	v_mfma_f32_16x16x32_bf16 v[36:39], v[172:175], v[206:209], v[36:39]
	v_mfma_f32_16x16x32_bf16 v[44:47], v[164:167], v[206:209], v[44:47]
	v_mfma_f32_16x16x32_bf16 v[44:47], v[160:163], v[202:205], v[44:47]
	v_mfma_f32_16x16x32_bf16 v[28:31], v[160:163], v[210:213], v[28:31]
	v_mfma_f32_16x16x32_bf16 v[28:31], v[164:167], v[214:217], v[28:31]
	v_mfma_f32_16x16x32_bf16 v[20:23], v[172:175], v[214:217], v[20:23]
	v_mfma_f32_16x16x32_bf16 v[20:23], v[168:171], v[210:213], v[20:23]
	v_mfma_f32_16x16x32_bf16 v[4:7], v[168:171], v[218:221], v[4:7]
	v_mfma_f32_16x16x32_bf16 v[4:7], v[172:175], v[222:225], v[4:7]
	v_mfma_f32_16x16x32_bf16 v[12:15], v[164:167], v[222:225], v[12:15]
	v_mfma_f32_16x16x32_bf16 v[12:15], v[160:163], v[218:221], v[12:15]
	s_setprio 0
	s_setprio 1
	v_mfma_f32_16x16x32_bf16 v[56:59], v[176:179], v[194:197], v[56:59]
	v_mfma_f32_16x16x32_bf16 v[56:59], v[180:183], v[198:201], v[56:59]
	v_mfma_f32_16x16x32_bf16 v[48:51], v[190:193], v[198:201], v[48:51]
	v_mfma_f32_16x16x32_bf16 v[48:51], v[186:189], v[194:197], v[48:51]
	v_mfma_f32_16x16x32_bf16 v[32:35], v[186:189], v[202:205], v[32:35]
	v_mfma_f32_16x16x32_bf16 v[32:35], v[190:193], v[206:209], v[32:35]
	v_mfma_f32_16x16x32_bf16 v[40:43], v[180:183], v[206:209], v[40:43]
	v_mfma_f32_16x16x32_bf16 v[40:43], v[176:179], v[202:205], v[40:43]
	v_mfma_f32_16x16x32_bf16 v[24:27], v[176:179], v[210:213], v[24:27]
	v_mfma_f32_16x16x32_bf16 v[24:27], v[180:183], v[214:217], v[24:27]
	v_mfma_f32_16x16x32_bf16 v[16:19], v[190:193], v[214:217], v[16:19]
	v_mfma_f32_16x16x32_bf16 v[16:19], v[186:189], v[210:213], v[16:19]
	v_mfma_f32_16x16x32_bf16 v[0:3], v[186:189], v[218:221], v[0:3]
	v_mfma_f32_16x16x32_bf16 v[0:3], v[190:193], v[222:225], v[0:3]
	v_mfma_f32_16x16x32_bf16 v[8:11], v[180:183], v[222:225], v[8:11]
	v_mfma_f32_16x16x32_bf16 v[8:11], v[176:179], v[218:221], v[8:11]
	s_setprio 0
	s_barrier
	s_add_i32 s76, 0, 0x18000
	v_add_u32_e32 v153, s76, v147
	s_add_i32 s77, 0, 0x1c000
	ds_read_b128 v[160:163], v153
	v_xor_b32_e32 v253, 64, v153
	ds_read_b128 v[164:167], v253
	ds_read_b128 v[168:171], v153 offset:2048
	ds_read_b128 v[172:175], v253 offset:2048
	v_add_u32_e32 v153, s77, v147
	ds_read_b128 v[176:179], v153
	v_xor_b32_e32 v253, 64, v153
	ds_read_b128 v[180:183], v253
	ds_read_b128 v[186:189], v153 offset:2048
	ds_read_b128 v[190:193], v253 offset:2048
	s_add_u32 s50, s50, 0x40000
	s_addc_u32 s51, s51, 0
	s_mov_b32 m0, s59
	v_lshl_add_u64 v[232:233], s[50:51], 0, v[134:135]
	ds_read_b128 v[194:197], v150 offset:32768
	v_xor_b32_e32 v253, 64, v150
	ds_read_b128 v[198:201], v253 offset:32768
	ds_read_b128 v[202:205], v150 offset:34816
	ds_read_b128 v[206:209], v253 offset:34816
	ds_read_b128 v[210:213], v150 offset:36864
	ds_read_b128 v[214:217], v253 offset:36864
	ds_read_b128 v[218:221], v150 offset:38912
	ds_read_b128 v[222:225], v253 offset:38912
	global_load_lds_dwordx4 v[232:233], off
	v_lshl_add_u64 v[232:233], s[50:51], 0, v[130:131]
	s_mov_b32 m0, s60
	s_nop 0
	global_load_lds_dwordx4 v[232:233], off
	s_waitcnt vmcnt(8)
	s_waitcnt lgkmcnt(0)
	s_barrier
	s_setprio 1
	s_waitcnt lgkmcnt(0)
	v_mfma_f32_16x16x32_bf16 v[124:127], v[160:163], v[194:197], v[124:127]
	v_mfma_f32_16x16x32_bf16 v[124:127], v[164:167], v[198:201], v[124:127]
	v_mfma_f32_16x16x32_bf16 v[116:119], v[172:175], v[198:201], v[116:119]
	v_mfma_f32_16x16x32_bf16 v[116:119], v[168:171], v[194:197], v[116:119]
	v_mfma_f32_16x16x32_bf16 v[100:103], v[168:171], v[202:205], v[100:103]
	v_mfma_f32_16x16x32_bf16 v[100:103], v[172:175], v[206:209], v[100:103]
	v_mfma_f32_16x16x32_bf16 v[108:111], v[164:167], v[206:209], v[108:111]
	v_mfma_f32_16x16x32_bf16 v[108:111], v[160:163], v[202:205], v[108:111]
	v_mfma_f32_16x16x32_bf16 v[92:95], v[160:163], v[210:213], v[92:95]
	v_mfma_f32_16x16x32_bf16 v[92:95], v[164:167], v[214:217], v[92:95]
	v_mfma_f32_16x16x32_bf16 v[84:87], v[172:175], v[214:217], v[84:87]
	v_mfma_f32_16x16x32_bf16 v[84:87], v[168:171], v[210:213], v[84:87]
	v_mfma_f32_16x16x32_bf16 v[68:71], v[168:171], v[218:221], v[68:71]
	v_mfma_f32_16x16x32_bf16 v[68:71], v[172:175], v[222:225], v[68:71]
	v_mfma_f32_16x16x32_bf16 v[76:79], v[164:167], v[222:225], v[76:79]
	v_mfma_f32_16x16x32_bf16 v[76:79], v[160:163], v[218:221], v[76:79]
	s_setprio 0
	s_setprio 1
	v_mfma_f32_16x16x32_bf16 v[120:123], v[176:179], v[194:197], v[120:123]
	v_mfma_f32_16x16x32_bf16 v[120:123], v[180:183], v[198:201], v[120:123]
	v_mfma_f32_16x16x32_bf16 v[112:115], v[190:193], v[198:201], v[112:115]
	v_mfma_f32_16x16x32_bf16 v[112:115], v[186:189], v[194:197], v[112:115]
	v_mfma_f32_16x16x32_bf16 v[96:99], v[186:189], v[202:205], v[96:99]
	v_mfma_f32_16x16x32_bf16 v[96:99], v[190:193], v[206:209], v[96:99]
	v_mfma_f32_16x16x32_bf16 v[104:107], v[180:183], v[206:209], v[104:107]
	v_mfma_f32_16x16x32_bf16 v[104:107], v[176:179], v[202:205], v[104:107]
	v_mfma_f32_16x16x32_bf16 v[88:91], v[176:179], v[210:213], v[88:91]
	v_mfma_f32_16x16x32_bf16 v[88:91], v[180:183], v[214:217], v[88:91]
	v_mfma_f32_16x16x32_bf16 v[80:83], v[190:193], v[214:217], v[80:83]
	v_mfma_f32_16x16x32_bf16 v[80:83], v[186:189], v[210:213], v[80:83]
	v_mfma_f32_16x16x32_bf16 v[64:67], v[186:189], v[218:221], v[64:67]
	v_mfma_f32_16x16x32_bf16 v[64:67], v[190:193], v[222:225], v[64:67]
	v_mfma_f32_16x16x32_bf16 v[72:75], v[180:183], v[222:225], v[72:75]
	v_mfma_f32_16x16x32_bf16 v[72:75], v[176:179], v[218:221], v[72:75]
	s_setprio 0
	s_barrier
	s_add_i32 s50, s76, s54
	v_lshl_add_u64 v[154:155], v[154:155], 0, s[20:21]
	s_mov_b32 m0, s50
	ds_read_b128 v[194:197], v150 offset:49152
	v_xor_b32_e32 v253, 64, v150
	ds_read_b128 v[198:201], v253 offset:49152
	ds_read_b128 v[202:205], v150 offset:51200
	ds_read_b128 v[206:209], v253 offset:51200
	ds_read_b128 v[210:213], v150 offset:53248
	ds_read_b128 v[214:217], v253 offset:53248
	ds_read_b128 v[218:221], v150 offset:55296
	ds_read_b128 v[222:225], v253 offset:55296
	global_load_lds_dwordx4 v[154:155], off
	s_add_i32 m0, s50, 0x2000
	s_add_u32 s48, s48, 0x40080
	v_lshl_add_u64 v[154:155], v[226:227], 0, s[20:21]
	s_addc_u32 s49, s49, 0
	s_add_i32 s50, s77, s54
	global_load_lds_dwordx4 v[154:155], off
	v_lshl_add_u64 v[154:155], s[48:49], 0, v[132:133]
	s_mov_b32 m0, s50
	s_nop 0
	global_load_lds_dwordx4 v[154:155], off
	v_lshl_add_u64 v[154:155], s[48:49], 0, v[128:129]
	s_add_i32 m0, s50, 0x2000
	s_nop 0
	global_load_lds_dwordx4 v[154:155], off
	v_lshl_add_u64 v[154:155], v[228:229], 0, s[20:21]
	s_mov_b32 m0, s62
	s_nop 0
	global_load_lds_dwordx4 v[154:155], off
	v_lshl_add_u64 v[154:155], v[230:231], 0, s[20:21]
	s_mov_b32 m0, s63
	s_nop 0
	global_load_lds_dwordx4 v[154:155], off
	s_waitcnt vmcnt(8)
	s_waitcnt lgkmcnt(0)
	s_barrier
	s_setprio 1
	s_waitcnt lgkmcnt(0)
	v_mfma_f32_16x16x32_bf16 v[60:63], v[160:163], v[194:197], v[60:63]
	v_mfma_f32_16x16x32_bf16 v[60:63], v[164:167], v[198:201], v[60:63]
	v_mfma_f32_16x16x32_bf16 v[52:55], v[172:175], v[198:201], v[52:55]
	v_mfma_f32_16x16x32_bf16 v[52:55], v[168:171], v[194:197], v[52:55]
	v_mfma_f32_16x16x32_bf16 v[36:39], v[168:171], v[202:205], v[36:39]
	v_mfma_f32_16x16x32_bf16 v[36:39], v[172:175], v[206:209], v[36:39]
	v_mfma_f32_16x16x32_bf16 v[44:47], v[164:167], v[206:209], v[44:47]
	v_mfma_f32_16x16x32_bf16 v[44:47], v[160:163], v[202:205], v[44:47]
	v_mfma_f32_16x16x32_bf16 v[28:31], v[160:163], v[210:213], v[28:31]
	v_mfma_f32_16x16x32_bf16 v[28:31], v[164:167], v[214:217], v[28:31]
	v_mfma_f32_16x16x32_bf16 v[20:23], v[172:175], v[214:217], v[20:23]
	v_mfma_f32_16x16x32_bf16 v[20:23], v[168:171], v[210:213], v[20:23]
	v_mfma_f32_16x16x32_bf16 v[4:7], v[168:171], v[218:221], v[4:7]
	v_mfma_f32_16x16x32_bf16 v[4:7], v[172:175], v[222:225], v[4:7]
	v_mfma_f32_16x16x32_bf16 v[12:15], v[164:167], v[222:225], v[12:15]
	v_mfma_f32_16x16x32_bf16 v[12:15], v[160:163], v[218:221], v[12:15]
	s_setprio 0
	s_setprio 1
	v_mfma_f32_16x16x32_bf16 v[56:59], v[176:179], v[194:197], v[56:59]
	v_mfma_f32_16x16x32_bf16 v[56:59], v[180:183], v[198:201], v[56:59]
	v_mfma_f32_16x16x32_bf16 v[48:51], v[190:193], v[198:201], v[48:51]
	v_mfma_f32_16x16x32_bf16 v[48:51], v[186:189], v[194:197], v[48:51]
	v_mfma_f32_16x16x32_bf16 v[32:35], v[186:189], v[202:205], v[32:35]
	v_mfma_f32_16x16x32_bf16 v[32:35], v[190:193], v[206:209], v[32:35]
	v_mfma_f32_16x16x32_bf16 v[40:43], v[180:183], v[206:209], v[40:43]
	v_mfma_f32_16x16x32_bf16 v[40:43], v[176:179], v[202:205], v[40:43]
	v_mfma_f32_16x16x32_bf16 v[24:27], v[176:179], v[210:213], v[24:27]
	v_mfma_f32_16x16x32_bf16 v[24:27], v[180:183], v[214:217], v[24:27]
	v_mfma_f32_16x16x32_bf16 v[16:19], v[190:193], v[214:217], v[16:19]
	v_mfma_f32_16x16x32_bf16 v[16:19], v[186:189], v[210:213], v[16:19]
	v_mfma_f32_16x16x32_bf16 v[0:3], v[186:189], v[218:221], v[0:3]
	v_mfma_f32_16x16x32_bf16 v[0:3], v[190:193], v[222:225], v[0:3]
	v_mfma_f32_16x16x32_bf16 v[8:11], v[180:183], v[222:225], v[8:11]
	v_mfma_f32_16x16x32_bf16 v[8:11], v[176:179], v[218:221], v[8:11]
	s_setprio 0
	s_barrier
	s_add_i32 s75, s75, 2
	s_add_u32 s73, s73, 0x100
	s_addc_u32 s74, s74, 0
	s_add_u32 s46, s46, 0x100
	s_addc_u32 s47, s47, 0
	s_cmp_gt_u32 s75, 13
	s_cbranch_scc1 .LBB0_529

.Llast_4:
	v_add_u32_e32 v153, s66, v147
	ds_read_b128 v[160:163], v153
	v_xor_b32_e32 v253, 64, v153
	ds_read_b128 v[164:167], v253
	ds_read_b128 v[168:171], v153 offset:2048
	ds_read_b128 v[172:175], v253 offset:2048
	v_add_u32_e32 v153, s67, v147
	ds_read_b128 v[176:179], v153
	v_xor_b32_e32 v253, 64, v153
	ds_read_b128 v[180:183], v253
	ds_read_b128 v[186:189], v153 offset:2048
	ds_read_b128 v[190:193], v253 offset:2048
	s_add_u32 s50, s46, 0xfffc0080
	s_addc_u32 s51, s47, -1
	s_and_b64 s[48:49], s[48:49], exec
	s_cselect_b32 s51, s29, s51
	s_cselect_b32 s50, s70, s50
	s_cselect_b32 s49, s71, s74
	s_cselect_b32 s48, s72, s73
	v_lshl_add_u64 v[154:155], s[46:47], 0, v[138:139]
	s_add_i32 m0, s57, 0xc000
	ds_read_b128 v[194:197], v150
	v_xor_b32_e32 v253, 64, v150
	ds_read_b128 v[198:201], v253
	ds_read_b128 v[202:205], v150 offset:2048
	ds_read_b128 v[206:209], v253 offset:2048
	ds_read_b128 v[210:213], v150 offset:4096
	ds_read_b128 v[214:217], v253 offset:4096
	ds_read_b128 v[218:221], v150 offset:6144
	ds_read_b128 v[222:225], v253 offset:6144
	global_load_lds_dwordx4 v[154:155], off
	v_lshl_add_u64 v[154:155], s[46:47], 0, v[136:137]
	s_add_i32 m0, s57, 0xe000
	s_nop 0
	global_load_lds_dwordx4 v[154:155], off
	s_waitcnt vmcnt(8)
	s_waitcnt lgkmcnt(0)
	s_barrier
	s_setprio 1
	s_waitcnt lgkmcnt(0)
	v_mfma_f32_16x16x32_bf16 v[124:127], v[160:163], v[194:197], v[124:127]
	v_mfma_f32_16x16x32_bf16 v[124:127], v[164:167], v[198:201], v[124:127]
	v_mfma_f32_16x16x32_bf16 v[116:119], v[172:175], v[198:201], v[116:119]
	v_mfma_f32_16x16x32_bf16 v[116:119], v[168:171], v[194:197], v[116:119]
	v_mfma_f32_16x16x32_bf16 v[100:103], v[168:171], v[202:205], v[100:103]
	v_mfma_f32_16x16x32_bf16 v[100:103], v[172:175], v[206:209], v[100:103]
	v_mfma_f32_16x16x32_bf16 v[108:111], v[164:167], v[206:209], v[108:111]
	v_mfma_f32_16x16x32_bf16 v[108:111], v[160:163], v[202:205], v[108:111]
	v_mfma_f32_16x16x32_bf16 v[92:95], v[160:163], v[210:213], v[92:95]
	v_mfma_f32_16x16x32_bf16 v[92:95], v[164:167], v[214:217], v[92:95]
	v_mfma_f32_16x16x32_bf16 v[84:87], v[172:175], v[214:217], v[84:87]
	v_mfma_f32_16x16x32_bf16 v[84:87], v[168:171], v[210:213], v[84:87]
	v_mfma_f32_16x16x32_bf16 v[68:71], v[168:171], v[218:221], v[68:71]
	v_mfma_f32_16x16x32_bf16 v[68:71], v[172:175], v[222:225], v[68:71]
	v_mfma_f32_16x16x32_bf16 v[76:79], v[164:167], v[222:225], v[76:79]
	v_mfma_f32_16x16x32_bf16 v[76:79], v[160:163], v[218:221], v[76:79]
	s_setprio 0
	s_setprio 1
	v_mfma_f32_16x16x32_bf16 v[120:123], v[176:179], v[194:197], v[120:123]
	v_mfma_f32_16x16x32_bf16 v[120:123], v[180:183], v[198:201], v[120:123]
	v_mfma_f32_16x16x32_bf16 v[112:115], v[190:193], v[198:201], v[112:115]
	v_mfma_f32_16x16x32_bf16 v[112:115], v[186:189], v[194:197], v[112:115]
	v_mfma_f32_16x16x32_bf16 v[96:99], v[186:189], v[202:205], v[96:99]
	v_mfma_f32_16x16x32_bf16 v[96:99], v[190:193], v[206:209], v[96:99]
	v_mfma_f32_16x16x32_bf16 v[104:107], v[180:183], v[206:209], v[104:107]
	v_mfma_f32_16x16x32_bf16 v[104:107], v[176:179], v[202:205], v[104:107]
	v_mfma_f32_16x16x32_bf16 v[88:91], v[176:179], v[210:213], v[88:91]
	v_mfma_f32_16x16x32_bf16 v[88:91], v[180:183], v[214:217], v[88:91]
	v_mfma_f32_16x16x32_bf16 v[80:83], v[190:193], v[214:217], v[80:83]
	v_mfma_f32_16x16x32_bf16 v[80:83], v[186:189], v[210:213], v[80:83]
	v_mfma_f32_16x16x32_bf16 v[64:67], v[186:189], v[218:221], v[64:67]
	v_mfma_f32_16x16x32_bf16 v[64:67], v[190:193], v[222:225], v[64:67]
	v_mfma_f32_16x16x32_bf16 v[72:75], v[180:183], v[222:225], v[72:75]
	v_mfma_f32_16x16x32_bf16 v[72:75], v[176:179], v[218:221], v[72:75]
	s_setprio 0
	s_barrier
	s_add_i32 s76, s66, s54
	v_lshl_add_u64 v[154:155], s[48:49], 0, v[132:133]
	s_mov_b32 m0, s76
	ds_read_b128 v[194:197], v150 offset:16384
	v_xor_b32_e32 v253, 64, v150
	ds_read_b128 v[198:201], v253 offset:16384
	ds_read_b128 v[202:205], v150 offset:18432
	ds_read_b128 v[206:209], v253 offset:18432
	ds_read_b128 v[210:213], v150 offset:20480
	ds_read_b128 v[214:217], v253 offset:20480
	ds_read_b128 v[218:221], v150 offset:22528
	ds_read_b128 v[222:225], v253 offset:22528
	global_load_lds_dwordx4 v[154:155], off
	s_add_i32 m0, s76, 0x2000
	s_add_u32 s76, s48, 0x40000
	v_lshl_add_u64 v[226:227], s[48:49], 0, v[128:129]
	s_addc_u32 s77, s49, 0
	s_add_i32 s78, s67, s54
	global_load_lds_dwordx4 v[226:227], off
	v_lshl_add_u64 v[228:229], s[76:77], 0, v[132:133]
	s_mov_b32 m0, s78
	v_lshl_add_u64 v[230:231], s[50:51], 0, v[130:131]
	global_load_lds_dwordx4 v[228:229], off
	v_lshl_add_u64 v[228:229], s[76:77], 0, v[128:129]
	s_add_i32 m0, s78, 0x2000
	s_nop 0
	global_load_lds_dwordx4 v[228:229], off
	v_lshl_add_u64 v[228:229], s[50:51], 0, v[134:135]
	s_mov_b32 m0, s57
	s_nop 0
	global_load_lds_dwordx4 v[228:229], off
	s_mov_b32 m0, s58
	s_nop 0
	global_load_lds_dwordx4 v[230:231], off
	s_waitcnt vmcnt(8)
	s_waitcnt lgkmcnt(0)
	s_barrier
	s_setprio 1
	s_waitcnt lgkmcnt(0)
	v_mfma_f32_16x16x32_bf16 v[60:63], v[160:163], v[194:197], v[60:63]
	v_mfma_f32_16x16x32_bf16 v[60:63], v[164:167], v[198:201], v[60:63]
	v_mfma_f32_16x16x32_bf16 v[52:55], v[172:175], v[198:201], v[52:55]
	v_mfma_f32_16x16x32_bf16 v[52:55], v[168:171], v[194:197], v[52:55]
	v_mfma_f32_16x16x32_bf16 v[36:39], v[168:171], v[202:205], v[36:39]
	v_mfma_f32_16x16x32_bf16 v[36:39], v[172:175], v[206:209], v[36:39]
	v_mfma_f32_16x16x32_bf16 v[44:47], v[164:167], v[206:209], v[44:47]
	v_mfma_f32_16x16x32_bf16 v[44:47], v[160:163], v[202:205], v[44:47]
	v_mfma_f32_16x16x32_bf16 v[28:31], v[160:163], v[210:213], v[28:31]
	v_mfma_f32_16x16x32_bf16 v[28:31], v[164:167], v[214:217], v[28:31]
	v_mfma_f32_16x16x32_bf16 v[20:23], v[172:175], v[214:217], v[20:23]
	v_mfma_f32_16x16x32_bf16 v[20:23], v[168:171], v[210:213], v[20:23]
	v_mfma_f32_16x16x32_bf16 v[4:7], v[168:171], v[218:221], v[4:7]
	v_mfma_f32_16x16x32_bf16 v[4:7], v[172:175], v[222:225], v[4:7]
	v_mfma_f32_16x16x32_bf16 v[12:15], v[164:167], v[222:225], v[12:15]
	v_mfma_f32_16x16x32_bf16 v[12:15], v[160:163], v[218:221], v[12:15]
	s_setprio 0
	s_setprio 1
	v_mfma_f32_16x16x32_bf16 v[56:59], v[176:179], v[194:197], v[56:59]
	v_mfma_f32_16x16x32_bf16 v[56:59], v[180:183], v[198:201], v[56:59]
	v_mfma_f32_16x16x32_bf16 v[48:51], v[190:193], v[198:201], v[48:51]
	v_mfma_f32_16x16x32_bf16 v[48:51], v[186:189], v[194:197], v[48:51]
	v_mfma_f32_16x16x32_bf16 v[32:35], v[186:189], v[202:205], v[32:35]
	v_mfma_f32_16x16x32_bf16 v[32:35], v[190:193], v[206:209], v[32:35]
	v_mfma_f32_16x16x32_bf16 v[40:43], v[180:183], v[206:209], v[40:43]
	v_mfma_f32_16x16x32_bf16 v[40:43], v[176:179], v[202:205], v[40:43]
	v_mfma_f32_16x16x32_bf16 v[24:27], v[176:179], v[210:213], v[24:27]
	v_mfma_f32_16x16x32_bf16 v[24:27], v[180:183], v[214:217], v[24:27]
	v_mfma_f32_16x16x32_bf16 v[16:19], v[190:193], v[214:217], v[16:19]
	v_mfma_f32_16x16x32_bf16 v[16:19], v[186:189], v[210:213], v[16:19]
	v_mfma_f32_16x16x32_bf16 v[0:3], v[186:189], v[218:221], v[0:3]
	v_mfma_f32_16x16x32_bf16 v[0:3], v[190:193], v[222:225], v[0:3]
	v_mfma_f32_16x16x32_bf16 v[8:11], v[180:183], v[222:225], v[8:11]
	v_mfma_f32_16x16x32_bf16 v[8:11], v[176:179], v[218:221], v[8:11]
	s_setprio 0
	s_barrier
	s_add_i32 s76, 0, 0x18000
	v_add_u32_e32 v153, s76, v147
	s_add_i32 s77, 0, 0x1c000
	ds_read_b128 v[160:163], v153
	v_xor_b32_e32 v253, 64, v153
	ds_read_b128 v[164:167], v253
	ds_read_b128 v[168:171], v153 offset:2048
	ds_read_b128 v[172:175], v253 offset:2048
	v_add_u32_e32 v153, s77, v147
	ds_read_b128 v[176:179], v153
	v_xor_b32_e32 v253, 64, v153
	ds_read_b128 v[180:183], v253
	ds_read_b128 v[186:189], v153 offset:2048
	ds_read_b128 v[190:193], v253 offset:2048
	s_add_u32 s50, s50, 0x40000
	s_addc_u32 s51, s51, 0
	s_mov_b32 m0, s59
	v_lshl_add_u64 v[232:233], s[50:51], 0, v[134:135]
	ds_read_b128 v[194:197], v150 offset:32768
	v_xor_b32_e32 v253, 64, v150
	ds_read_b128 v[198:201], v253 offset:32768
	ds_read_b128 v[202:205], v150 offset:34816
	ds_read_b128 v[206:209], v253 offset:34816
	ds_read_b128 v[210:213], v150 offset:36864
	ds_read_b128 v[214:217], v253 offset:36864
	ds_read_b128 v[218:221], v150 offset:38912
	ds_read_b128 v[222:225], v253 offset:38912
	global_load_lds_dwordx4 v[232:233], off
	v_lshl_add_u64 v[232:233], s[50:51], 0, v[130:131]
	s_mov_b32 m0, s60
	s_nop 0
	global_load_lds_dwordx4 v[232:233], off
	s_waitcnt vmcnt(8)
	s_waitcnt lgkmcnt(0)
	s_barrier
	s_setprio 1
	s_waitcnt lgkmcnt(0)
	v_mfma_f32_16x16x32_bf16 v[124:127], v[160:163], v[194:197], v[124:127]
	v_mfma_f32_16x16x32_bf16 v[124:127], v[164:167], v[198:201], v[124:127]
	v_mfma_f32_16x16x32_bf16 v[116:119], v[172:175], v[198:201], v[116:119]
	v_mfma_f32_16x16x32_bf16 v[116:119], v[168:171], v[194:197], v[116:119]
	v_mfma_f32_16x16x32_bf16 v[100:103], v[168:171], v[202:205], v[100:103]
	v_mfma_f32_16x16x32_bf16 v[100:103], v[172:175], v[206:209], v[100:103]
	v_mfma_f32_16x16x32_bf16 v[108:111], v[164:167], v[206:209], v[108:111]
	v_mfma_f32_16x16x32_bf16 v[108:111], v[160:163], v[202:205], v[108:111]
	v_mfma_f32_16x16x32_bf16 v[92:95], v[160:163], v[210:213], v[92:95]
	v_mfma_f32_16x16x32_bf16 v[92:95], v[164:167], v[214:217], v[92:95]
	v_mfma_f32_16x16x32_bf16 v[84:87], v[172:175], v[214:217], v[84:87]
	v_mfma_f32_16x16x32_bf16 v[84:87], v[168:171], v[210:213], v[84:87]
	v_mfma_f32_16x16x32_bf16 v[68:71], v[168:171], v[218:221], v[68:71]
	v_mfma_f32_16x16x32_bf16 v[68:71], v[172:175], v[222:225], v[68:71]
	v_mfma_f32_16x16x32_bf16 v[76:79], v[164:167], v[222:225], v[76:79]
	v_mfma_f32_16x16x32_bf16 v[76:79], v[160:163], v[218:221], v[76:79]
	s_setprio 0
	s_setprio 1
	v_mfma_f32_16x16x32_bf16 v[120:123], v[176:179], v[194:197], v[120:123]
	v_mfma_f32_16x16x32_bf16 v[120:123], v[180:183], v[198:201], v[120:123]
	v_mfma_f32_16x16x32_bf16 v[112:115], v[190:193], v[198:201], v[112:115]
	v_mfma_f32_16x16x32_bf16 v[112:115], v[186:189], v[194:197], v[112:115]
	v_mfma_f32_16x16x32_bf16 v[96:99], v[186:189], v[202:205], v[96:99]
	v_mfma_f32_16x16x32_bf16 v[96:99], v[190:193], v[206:209], v[96:99]
	v_mfma_f32_16x16x32_bf16 v[104:107], v[180:183], v[206:209], v[104:107]
	v_mfma_f32_16x16x32_bf16 v[104:107], v[176:179], v[202:205], v[104:107]
	v_mfma_f32_16x16x32_bf16 v[88:91], v[176:179], v[210:213], v[88:91]
	v_mfma_f32_16x16x32_bf16 v[88:91], v[180:183], v[214:217], v[88:91]
	v_mfma_f32_16x16x32_bf16 v[80:83], v[190:193], v[214:217], v[80:83]
	v_mfma_f32_16x16x32_bf16 v[80:83], v[186:189], v[210:213], v[80:83]
	v_mfma_f32_16x16x32_bf16 v[64:67], v[186:189], v[218:221], v[64:67]
	v_mfma_f32_16x16x32_bf16 v[64:67], v[190:193], v[222:225], v[64:67]
	v_mfma_f32_16x16x32_bf16 v[72:75], v[180:183], v[222:225], v[72:75]
	v_mfma_f32_16x16x32_bf16 v[72:75], v[176:179], v[218:221], v[72:75]
	s_setprio 0
	s_barrier
	v_add_u32_e32 v234, 0x21000, v151
	ds_read_b128 v[236:239], v234
	ds_read_b128 v[240:243], v234 offset:256
	ds_read_b128 v[244:247], v234 offset:512
	ds_read_b128 v[248:251], v234 offset:768
	v_add_u32_e32 v235, s27, v146
	v_mul_u32_u24_e32 v235, 0x1600, v235
	v_lshl_or_b32 v234, s69, 7, v149
	v_lshl_add_u32 v235, v234, 1, v235
	s_add_i32 s50, s76, s54
	v_lshl_add_u64 v[154:155], v[154:155], 0, s[20:21]
	s_mov_b32 m0, s50
	ds_read_b128 v[194:197], v150 offset:49152
	v_xor_b32_e32 v253, 64, v150
	ds_read_b128 v[198:201], v253 offset:49152
	ds_read_b128 v[202:205], v150 offset:51200
	ds_read_b128 v[206:209], v253 offset:51200
	ds_read_b128 v[210:213], v150 offset:53248
	ds_read_b128 v[214:217], v253 offset:53248
	ds_read_b128 v[218:221], v150 offset:55296
	ds_read_b128 v[222:225], v253 offset:55296
	global_load_lds_dwordx4 v[154:155], off
	s_add_i32 m0, s50, 0x2000
	s_add_u32 s48, s48, 0x40080
	v_lshl_add_u64 v[154:155], v[226:227], 0, s[20:21]
	s_addc_u32 s49, s49, 0
	s_add_i32 s50, s77, s54
	global_load_lds_dwordx4 v[154:155], off
	v_lshl_add_u64 v[154:155], s[48:49], 0, v[132:133]
	s_mov_b32 m0, s50
	s_nop 0
	global_load_lds_dwordx4 v[154:155], off
	v_lshl_add_u64 v[154:155], s[48:49], 0, v[128:129]
	s_add_i32 m0, s50, 0x2000
	s_nop 0
	global_load_lds_dwordx4 v[154:155], off
	v_lshl_add_u64 v[154:155], v[228:229], 0, s[20:21]
	s_mov_b32 m0, s62
	s_nop 0
	global_load_lds_dwordx4 v[154:155], off
	v_lshl_add_u64 v[154:155], v[230:231], 0, s[20:21]
	s_mov_b32 m0, s63
	s_nop 0
	global_load_lds_dwordx4 v[154:155], off
	s_waitcnt lgkmcnt(8)
	v_add_f32_e32 v236, v236, v237
	v_add_f32_e32 v238, v238, v239
	v_add_f32_e32 v240, v240, v241
	v_add_f32_e32 v242, v242, v243
	v_add_f32_e32 v244, v244, v245
	v_add_f32_e32 v246, v246, v247
	v_add_f32_e32 v248, v248, v249
	v_add_f32_e32 v250, v250, v251
	v_add_f32_e32 v236, v236, v238
	v_add_f32_e32 v240, v240, v242
	v_add_f32_e32 v244, v244, v246
	v_add_f32_e32 v248, v248, v250
	v_fmamk_f32 v236, v236, 0x3a800000, v152
	v_fmamk_f32 v240, v240, 0x3a800000, v152
	v_fmamk_f32 v244, v244, 0x3a800000, v152
	v_fmamk_f32 v248, v248, 0x3a800000, v152
	v_rsq_f32_e32 v236, v236
	v_rsq_f32_e32 v240, v240
	v_rsq_f32_e32 v244, v244
	v_rsq_f32_e32 v248, v248
	v_mul_f32_e32 v252, 0xbfb8aa3b, v236
	v_mul_f32_e32 v254, v236, v236
	v_pk_mul_f32 v[120:121], v[124:125], v[120:121]
	v_pk_mul_f32 v[122:123], v[126:127], v[122:123]
	v_pk_mul_f32 v[112:113], v[116:117], v[112:113]
	v_pk_mul_f32 v[114:115], v[118:119], v[114:115]
	v_pk_mul_f32 v[124:125], v[124:125], v[252:253] op_sel_hi:[1,0]
	v_pk_mul_f32 v[126:127], v[126:127], v[252:253] op_sel_hi:[1,0]
	v_pk_mul_f32 v[116:117], v[116:117], v[252:253] op_sel_hi:[1,0]
	v_pk_mul_f32 v[118:119], v[118:119], v[252:253] op_sel_hi:[1,0]
	v_exp_f32_e32 v124, v124
	v_exp_f32_e32 v125, v125
	v_exp_f32_e32 v126, v126
	v_exp_f32_e32 v127, v127
	v_exp_f32_e32 v116, v116
	v_exp_f32_e32 v117, v117
	v_exp_f32_e32 v118, v118
	v_exp_f32_e32 v119, v119
	v_pk_add_f32 v[124:125], v[124:125], 1.0 op_sel_hi:[1,0]
	v_pk_add_f32 v[126:127], v[126:127], 1.0 op_sel_hi:[1,0]
	v_pk_add_f32 v[116:117], v[116:117], 1.0 op_sel_hi:[1,0]
	v_pk_add_f32 v[118:119], v[118:119], 1.0 op_sel_hi:[1,0]
	v_rcp_f32_e32 v124, v124
	v_rcp_f32_e32 v125, v125
	v_rcp_f32_e32 v126, v126
	v_rcp_f32_e32 v127, v127
	v_rcp_f32_e32 v116, v116
	v_rcp_f32_e32 v117, v117
	v_rcp_f32_e32 v118, v118
	v_rcp_f32_e32 v119, v119
	v_pk_mul_f32 v[120:121], v[120:121], v[254:255] op_sel_hi:[1,0]
	v_pk_mul_f32 v[122:123], v[122:123], v[254:255] op_sel_hi:[1,0]
	v_pk_mul_f32 v[112:113], v[112:113], v[254:255] op_sel_hi:[1,0]
	v_pk_mul_f32 v[114:115], v[114:115], v[254:255] op_sel_hi:[1,0]
	v_pk_mul_f32 v[120:121], v[120:121], v[124:125]
	v_pk_mul_f32 v[122:123], v[122:123], v[126:127]
	v_pk_mul_f32 v[112:113], v[112:113], v[116:117]
	v_pk_mul_f32 v[114:115], v[114:115], v[118:119]
	v_cvt_pk_bf16_f32 v120, v120, v121
	v_cvt_pk_bf16_f32 v121, v122, v123
	v_cvt_pk_bf16_f32 v122, v112, v113
	v_cvt_pk_bf16_f32 v123, v114, v115
	global_store_dwordx4 v235, v[120:123], s[14:15]
	v_add_u32_e32 v234, 0x16000, v235
	v_mul_f32_e32 v252, 0xbfb8aa3b, v240
	v_mul_f32_e32 v254, v240, v240
	v_pk_mul_f32 v[104:105], v[108:109], v[104:105]
	v_pk_mul_f32 v[106:107], v[110:111], v[106:107]
	v_pk_mul_f32 v[96:97], v[100:101], v[96:97]
	v_pk_mul_f32 v[98:99], v[102:103], v[98:99]
	v_pk_mul_f32 v[108:109], v[108:109], v[252:253] op_sel_hi:[1,0]
	v_pk_mul_f32 v[110:111], v[110:111], v[252:253] op_sel_hi:[1,0]
	v_pk_mul_f32 v[100:101], v[100:101], v[252:253] op_sel_hi:[1,0]
	v_pk_mul_f32 v[102:103], v[102:103], v[252:253] op_sel_hi:[1,0]
	v_exp_f32_e32 v108, v108
	v_exp_f32_e32 v109, v109
	v_exp_f32_e32 v110, v110
	v_exp_f32_e32 v111, v111
	v_exp_f32_e32 v100, v100
	v_exp_f32_e32 v101, v101
	v_exp_f32_e32 v102, v102
	v_exp_f32_e32 v103, v103
	v_pk_add_f32 v[108:109], v[108:109], 1.0 op_sel_hi:[1,0]
	v_pk_add_f32 v[110:111], v[110:111], 1.0 op_sel_hi:[1,0]
	v_pk_add_f32 v[100:101], v[100:101], 1.0 op_sel_hi:[1,0]
	v_pk_add_f32 v[102:103], v[102:103], 1.0 op_sel_hi:[1,0]
	v_rcp_f32_e32 v108, v108
	v_rcp_f32_e32 v109, v109
	v_rcp_f32_e32 v110, v110
	v_rcp_f32_e32 v111, v111
	v_rcp_f32_e32 v100, v100
	v_rcp_f32_e32 v101, v101
	v_rcp_f32_e32 v102, v102
	v_rcp_f32_e32 v103, v103
	v_pk_mul_f32 v[104:105], v[104:105], v[254:255] op_sel_hi:[1,0]
	v_pk_mul_f32 v[106:107], v[106:107], v[254:255] op_sel_hi:[1,0]
	v_pk_mul_f32 v[96:97], v[96:97], v[254:255] op_sel_hi:[1,0]
	v_pk_mul_f32 v[98:99], v[98:99], v[254:255] op_sel_hi:[1,0]
	v_pk_mul_f32 v[104:105], v[104:105], v[108:109]
	v_pk_mul_f32 v[106:107], v[106:107], v[110:111]
	v_pk_mul_f32 v[96:97], v[96:97], v[100:101]
	v_pk_mul_f32 v[98:99], v[98:99], v[102:103]
	v_cvt_pk_bf16_f32 v104, v104, v105
	v_cvt_pk_bf16_f32 v105, v106, v107
	v_cvt_pk_bf16_f32 v106, v96, v97
	v_cvt_pk_bf16_f32 v107, v98, v99
	global_store_dwordx4 v234, v[104:107], s[14:15]
	v_add_u32_e32 v235, 0x16000, v234
	v_mul_f32_e32 v252, 0xbfb8aa3b, v244
	v_mul_f32_e32 v254, v244, v244
	v_pk_mul_f32 v[88:89], v[92:93], v[88:89]
	v_pk_mul_f32 v[90:91], v[94:95], v[90:91]
	v_pk_mul_f32 v[80:81], v[84:85], v[80:81]
	v_pk_mul_f32 v[82:83], v[86:87], v[82:83]
	v_pk_mul_f32 v[92:93], v[92:93], v[252:253] op_sel_hi:[1,0]
	v_pk_mul_f32 v[94:95], v[94:95], v[252:253] op_sel_hi:[1,0]
	v_pk_mul_f32 v[84:85], v[84:85], v[252:253] op_sel_hi:[1,0]
	v_pk_mul_f32 v[86:87], v[86:87], v[252:253] op_sel_hi:[1,0]
	v_exp_f32_e32 v92, v92
	v_exp_f32_e32 v93, v93
	v_exp_f32_e32 v94, v94
	v_exp_f32_e32 v95, v95
	v_exp_f32_e32 v84, v84
	v_exp_f32_e32 v85, v85
	v_exp_f32_e32 v86, v86
	v_exp_f32_e32 v87, v87
	v_pk_add_f32 v[92:93], v[92:93], 1.0 op_sel_hi:[1,0]
	v_pk_add_f32 v[94:95], v[94:95], 1.0 op_sel_hi:[1,0]
	v_pk_add_f32 v[84:85], v[84:85], 1.0 op_sel_hi:[1,0]
	v_pk_add_f32 v[86:87], v[86:87], 1.0 op_sel_hi:[1,0]
	v_rcp_f32_e32 v92, v92
	v_rcp_f32_e32 v93, v93
	v_rcp_f32_e32 v94, v94
	v_rcp_f32_e32 v95, v95
	v_rcp_f32_e32 v84, v84
	v_rcp_f32_e32 v85, v85
	v_rcp_f32_e32 v86, v86
	v_rcp_f32_e32 v87, v87
	v_pk_mul_f32 v[88:89], v[88:89], v[254:255] op_sel_hi:[1,0]
	v_pk_mul_f32 v[90:91], v[90:91], v[254:255] op_sel_hi:[1,0]
	v_pk_mul_f32 v[80:81], v[80:81], v[254:255] op_sel_hi:[1,0]
	v_pk_mul_f32 v[82:83], v[82:83], v[254:255] op_sel_hi:[1,0]
	v_pk_mul_f32 v[88:89], v[88:89], v[92:93]
	v_pk_mul_f32 v[90:91], v[90:91], v[94:95]
	v_pk_mul_f32 v[80:81], v[80:81], v[84:85]
	v_pk_mul_f32 v[82:83], v[82:83], v[86:87]
	v_cvt_pk_bf16_f32 v88, v88, v89
	v_cvt_pk_bf16_f32 v89, v90, v91
	v_cvt_pk_bf16_f32 v90, v80, v81
	v_cvt_pk_bf16_f32 v91, v82, v83
	global_store_dwordx4 v235, v[88:91], s[14:15]
	v_add_u32_e32 v234, 0x16000, v235
	v_mul_f32_e32 v252, 0xbfb8aa3b, v248
	v_mul_f32_e32 v254, v248, v248
	v_pk_mul_f32 v[72:73], v[76:77], v[72:73]
	v_pk_mul_f32 v[74:75], v[78:79], v[74:75]
	v_pk_mul_f32 v[64:65], v[68:69], v[64:65]
	v_pk_mul_f32 v[66:67], v[70:71], v[66:67]
	v_pk_mul_f32 v[76:77], v[76:77], v[252:253] op_sel_hi:[1,0]
	v_pk_mul_f32 v[78:79], v[78:79], v[252:253] op_sel_hi:[1,0]
	v_pk_mul_f32 v[68:69], v[68:69], v[252:253] op_sel_hi:[1,0]
	v_pk_mul_f32 v[70:71], v[70:71], v[252:253] op_sel_hi:[1,0]
	v_exp_f32_e32 v76, v76
	v_exp_f32_e32 v77, v77
	v_exp_f32_e32 v78, v78
	v_exp_f32_e32 v79, v79
	v_exp_f32_e32 v68, v68
	v_exp_f32_e32 v69, v69
	v_exp_f32_e32 v70, v70
	v_exp_f32_e32 v71, v71
	v_pk_add_f32 v[76:77], v[76:77], 1.0 op_sel_hi:[1,0]
	v_pk_add_f32 v[78:79], v[78:79], 1.0 op_sel_hi:[1,0]
	v_pk_add_f32 v[68:69], v[68:69], 1.0 op_sel_hi:[1,0]
	v_pk_add_f32 v[70:71], v[70:71], 1.0 op_sel_hi:[1,0]
	v_rcp_f32_e32 v76, v76
	v_rcp_f32_e32 v77, v77
	v_rcp_f32_e32 v78, v78
	v_rcp_f32_e32 v79, v79
	v_rcp_f32_e32 v68, v68
	v_rcp_f32_e32 v69, v69
	v_rcp_f32_e32 v70, v70
	v_rcp_f32_e32 v71, v71
	v_pk_mul_f32 v[72:73], v[72:73], v[254:255] op_sel_hi:[1,0]
	v_pk_mul_f32 v[74:75], v[74:75], v[254:255] op_sel_hi:[1,0]
	v_pk_mul_f32 v[64:65], v[64:65], v[254:255] op_sel_hi:[1,0]
	v_pk_mul_f32 v[66:67], v[66:67], v[254:255] op_sel_hi:[1,0]
	v_pk_mul_f32 v[72:73], v[72:73], v[76:77]
	v_pk_mul_f32 v[74:75], v[74:75], v[78:79]
	v_pk_mul_f32 v[64:65], v[64:65], v[68:69]
	v_pk_mul_f32 v[66:67], v[66:67], v[70:71]
	v_cvt_pk_bf16_f32 v72, v72, v73
	v_cvt_pk_bf16_f32 v73, v74, v75
	v_cvt_pk_bf16_f32 v74, v64, v65
	v_cvt_pk_bf16_f32 v75, v66, v67
	global_store_dwordx4 v234, v[72:75], s[14:15]
	s_waitcnt vmcnt(12)
	s_waitcnt lgkmcnt(0)
	s_barrier
	s_setprio 1
	s_waitcnt lgkmcnt(0)
	v_mfma_f32_16x16x32_bf16 v[60:63], v[160:163], v[194:197], v[60:63]
	v_mfma_f32_16x16x32_bf16 v[60:63], v[164:167], v[198:201], v[60:63]
	v_mfma_f32_16x16x32_bf16 v[52:55], v[172:175], v[198:201], v[52:55]
	v_mfma_f32_16x16x32_bf16 v[52:55], v[168:171], v[194:197], v[52:55]
	v_mfma_f32_16x16x32_bf16 v[36:39], v[168:171], v[202:205], v[36:39]
	v_mfma_f32_16x16x32_bf16 v[36:39], v[172:175], v[206:209], v[36:39]
	v_mfma_f32_16x16x32_bf16 v[44:47], v[164:167], v[206:209], v[44:47]
	v_mfma_f32_16x16x32_bf16 v[44:47], v[160:163], v[202:205], v[44:47]
	v_mfma_f32_16x16x32_bf16 v[28:31], v[160:163], v[210:213], v[28:31]
	v_mfma_f32_16x16x32_bf16 v[28:31], v[164:167], v[214:217], v[28:31]
	v_mfma_f32_16x16x32_bf16 v[20:23], v[172:175], v[214:217], v[20:23]
	v_mfma_f32_16x16x32_bf16 v[20:23], v[168:171], v[210:213], v[20:23]
	v_mfma_f32_16x16x32_bf16 v[4:7], v[168:171], v[218:221], v[4:7]
	v_mfma_f32_16x16x32_bf16 v[4:7], v[172:175], v[222:225], v[4:7]
	v_mfma_f32_16x16x32_bf16 v[12:15], v[164:167], v[222:225], v[12:15]
	v_mfma_f32_16x16x32_bf16 v[12:15], v[160:163], v[218:221], v[12:15]
	s_setprio 0
	s_setprio 1
	v_mfma_f32_16x16x32_bf16 v[56:59], v[176:179], v[194:197], v[56:59]
	v_mfma_f32_16x16x32_bf16 v[56:59], v[180:183], v[198:201], v[56:59]
	v_mfma_f32_16x16x32_bf16 v[48:51], v[190:193], v[198:201], v[48:51]
	v_mfma_f32_16x16x32_bf16 v[48:51], v[186:189], v[194:197], v[48:51]
	v_mfma_f32_16x16x32_bf16 v[32:35], v[186:189], v[202:205], v[32:35]
	v_mfma_f32_16x16x32_bf16 v[32:35], v[190:193], v[206:209], v[32:35]
	v_mfma_f32_16x16x32_bf16 v[40:43], v[180:183], v[206:209], v[40:43]
	v_mfma_f32_16x16x32_bf16 v[40:43], v[176:179], v[202:205], v[40:43]
	v_mfma_f32_16x16x32_bf16 v[24:27], v[176:179], v[210:213], v[24:27]
	v_mfma_f32_16x16x32_bf16 v[24:27], v[180:183], v[214:217], v[24:27]
	v_mfma_f32_16x16x32_bf16 v[16:19], v[190:193], v[214:217], v[16:19]
	v_mfma_f32_16x16x32_bf16 v[16:19], v[186:189], v[210:213], v[16:19]
	v_mfma_f32_16x16x32_bf16 v[0:3], v[186:189], v[218:221], v[0:3]
	v_mfma_f32_16x16x32_bf16 v[0:3], v[190:193], v[222:225], v[0:3]
	v_mfma_f32_16x16x32_bf16 v[8:11], v[180:183], v[222:225], v[8:11]
	v_mfma_f32_16x16x32_bf16 v[8:11], v[176:179], v[218:221], v[8:11]
	s_setprio 0
	s_barrier
	s_add_i32 s75, s75, 2
	s_add_u32 s73, s73, 0x100
	s_addc_u32 s74, s74, 0
	s_add_u32 s46, s46, 0x100
	s_addc_u32 s47, s47, 0

.LBB0_609:
	s_add_u32 s79, s56, 0x100
	s_addc_u32 s80, s57, 0
	s_mov_b32 s81, -2
	s_waitcnt lgkmcnt(0)
	s_cmp_eq_u32 s70, 1
	s_cbranch_scc1 .Lfa_5
	ds_read_b128 v[128:131], v189
	v_xor_b32_e32 v253, 64, v189
	ds_read_b128 v[132:135], v253
	ds_read_b128 v[136:139], v189 offset:2048
	ds_read_b128 v[140:143], v253 offset:2048
	ds_read_b128 v[144:147], v190
	v_xor_b32_e32 v253, 64, v190
	ds_read_b128 v[148:151], v253
	ds_read_b128 v[172:175], v190 offset:2048
	ds_read_b128 v[176:179], v253 offset:2048
	s_add_u32 s56, s54, 0x100
	s_addc_u32 s57, s55, 0
	s_cmp_eq_u32 s81, 40
	s_cselect_b32 s61, s17, s57
	s_cselect_b32 s60, s16, s56
	s_cselect_b32 s59, s53, s80
	s_cselect_b32 s58, s52, s79
	v_lshl_add_u64 v[222:223], s[54:55], 0, v[166:167]
	s_add_i32 m0, s66, 0xc000
	ds_read_b128 v[180:183], v191
	v_xor_b32_e32 v253, 64, v191
	ds_read_b128 v[194:197], v253
	ds_read_b128 v[198:201], v191 offset:2048
	ds_read_b128 v[202:205], v253 offset:2048
	ds_read_b128 v[206:209], v191 offset:4096
	ds_read_b128 v[210:213], v253 offset:4096
	ds_read_b128 v[214:217], v191 offset:6144
	ds_read_b128 v[218:221], v253 offset:6144
	global_load_lds_dwordx4 v[222:223], off
	v_lshl_add_u64 v[222:223], s[54:55], 0, v[164:165]
	s_add_i32 m0, s66, 0xe000
	s_nop 0
	global_load_lds_dwordx4 v[222:223], off
	s_waitcnt vmcnt(24)
	s_waitcnt lgkmcnt(0)
	s_barrier
	s_setprio 1
	s_waitcnt lgkmcnt(0)
	v_mfma_f32_16x16x32_bf16 v[124:127], v[128:131], v[180:183], 0
	v_mfma_f32_16x16x32_bf16 v[120:123], v[136:139], v[180:183], 0
	v_mfma_f32_16x16x32_bf16 v[108:111], v[128:131], v[198:201], 0
	v_mfma_f32_16x16x32_bf16 v[104:107], v[136:139], v[198:201], 0
	v_mfma_f32_16x16x32_bf16 v[92:95], v[128:131], v[206:209], 0
	v_mfma_f32_16x16x32_bf16 v[88:91], v[136:139], v[206:209], 0
	v_mfma_f32_16x16x32_bf16 v[76:79], v[128:131], v[214:217], 0
	v_mfma_f32_16x16x32_bf16 v[72:75], v[136:139], v[214:217], 0
	v_mfma_f32_16x16x32_bf16 v[124:127], v[132:135], v[194:197], v[124:127]
	v_mfma_f32_16x16x32_bf16 v[120:123], v[140:143], v[194:197], v[120:123]
	v_mfma_f32_16x16x32_bf16 v[108:111], v[132:135], v[202:205], v[108:111]
	v_mfma_f32_16x16x32_bf16 v[104:107], v[140:143], v[202:205], v[104:107]
	v_mfma_f32_16x16x32_bf16 v[92:95], v[132:135], v[210:213], v[92:95]
	v_mfma_f32_16x16x32_bf16 v[88:91], v[140:143], v[210:213], v[88:91]
	v_mfma_f32_16x16x32_bf16 v[76:79], v[132:135], v[218:221], v[76:79]
	v_mfma_f32_16x16x32_bf16 v[72:75], v[140:143], v[218:221], v[72:75]
	s_setprio 0
	s_setprio 1
	v_mfma_f32_16x16x32_bf16 v[116:119], v[144:147], v[180:183], 0
	v_mfma_f32_16x16x32_bf16 v[112:115], v[172:175], v[180:183], 0
	v_mfma_f32_16x16x32_bf16 v[100:103], v[144:147], v[198:201], 0
	v_mfma_f32_16x16x32_bf16 v[96:99], v[172:175], v[198:201], 0
	v_mfma_f32_16x16x32_bf16 v[84:87], v[144:147], v[206:209], 0
	v_mfma_f32_16x16x32_bf16 v[80:83], v[172:175], v[206:209], 0
	v_mfma_f32_16x16x32_bf16 v[68:71], v[144:147], v[214:217], 0
	v_mfma_f32_16x16x32_bf16 v[64:67], v[172:175], v[214:217], 0
	v_mfma_f32_16x16x32_bf16 v[116:119], v[148:151], v[194:197], v[116:119]
	v_mfma_f32_16x16x32_bf16 v[112:115], v[176:179], v[194:197], v[112:115]
	v_mfma_f32_16x16x32_bf16 v[100:103], v[148:151], v[202:205], v[100:103]
	v_mfma_f32_16x16x32_bf16 v[96:99], v[176:179], v[202:205], v[96:99]
	v_mfma_f32_16x16x32_bf16 v[84:87], v[148:151], v[210:213], v[84:87]
	v_mfma_f32_16x16x32_bf16 v[80:83], v[176:179], v[210:213], v[80:83]
	v_mfma_f32_16x16x32_bf16 v[68:71], v[148:151], v[218:221], v[68:71]
	v_mfma_f32_16x16x32_bf16 v[64:67], v[176:179], v[218:221], v[64:67]
	s_setprio 0
	s_barrier
	s_add_i32 s54, s75, s65
	v_lshl_add_u64 v[222:223], s[58:59], 0, v[154:155]
	s_mov_b32 m0, s54
	ds_read_b128 v[180:183], v191 offset:16384
	v_xor_b32_e32 v253, 64, v191
	ds_read_b128 v[194:197], v253 offset:16384
	ds_read_b128 v[198:201], v191 offset:18432
	ds_read_b128 v[202:205], v253 offset:18432
	ds_read_b128 v[206:209], v191 offset:20480
	ds_read_b128 v[210:213], v253 offset:20480
	ds_read_b128 v[214:217], v191 offset:22528
	ds_read_b128 v[218:221], v253 offset:22528
	global_load_lds_dwordx4 v[222:223], off
	s_add_i32 m0, s54, 0x2000
	s_add_u32 s54, s58, 0xb0000
	v_lshl_add_u64 v[224:225], s[58:59], 0, v[162:163]
	s_addc_u32 s55, s59, 0
	s_add_i32 s82, s76, s65
	global_load_lds_dwordx4 v[224:225], off
	v_lshl_add_u64 v[226:227], s[54:55], 0, v[154:155]
	s_mov_b32 m0, s82
	v_lshl_add_u64 v[228:229], s[60:61], 0, v[160:161]
	global_load_lds_dwordx4 v[226:227], off
	v_lshl_add_u64 v[226:227], s[54:55], 0, v[162:163]
	s_add_i32 m0, s82, 0x2000
	s_nop 0
	global_load_lds_dwordx4 v[226:227], off
	v_lshl_add_u64 v[226:227], s[60:61], 0, v[152:153]
	s_mov_b32 m0, s66
	s_nop 0
	global_load_lds_dwordx4 v[226:227], off
	s_mov_b32 m0, s67
	s_nop 0
	global_load_lds_dwordx4 v[228:229], off
	s_waitcnt vmcnt(24)
	s_waitcnt lgkmcnt(0)
	s_barrier
	s_setprio 1
	s_waitcnt lgkmcnt(0)
	v_mfma_f32_16x16x32_bf16 v[60:63], v[128:131], v[180:183], 0
	v_mfma_f32_16x16x32_bf16 v[56:59], v[136:139], v[180:183], 0
	v_mfma_f32_16x16x32_bf16 v[44:47], v[128:131], v[198:201], 0
	v_mfma_f32_16x16x32_bf16 v[40:43], v[136:139], v[198:201], 0
	v_mfma_f32_16x16x32_bf16 v[28:31], v[128:131], v[206:209], 0
	v_mfma_f32_16x16x32_bf16 v[24:27], v[136:139], v[206:209], 0
	v_mfma_f32_16x16x32_bf16 v[12:15], v[128:131], v[214:217], 0
	v_mfma_f32_16x16x32_bf16 v[8:11], v[136:139], v[214:217], 0
	v_mfma_f32_16x16x32_bf16 v[60:63], v[132:135], v[194:197], v[60:63]
	v_mfma_f32_16x16x32_bf16 v[56:59], v[140:143], v[194:197], v[56:59]
	v_mfma_f32_16x16x32_bf16 v[44:47], v[132:135], v[202:205], v[44:47]
	v_mfma_f32_16x16x32_bf16 v[40:43], v[140:143], v[202:205], v[40:43]
	v_mfma_f32_16x16x32_bf16 v[28:31], v[132:135], v[210:213], v[28:31]
	v_mfma_f32_16x16x32_bf16 v[24:27], v[140:143], v[210:213], v[24:27]
	v_mfma_f32_16x16x32_bf16 v[12:15], v[132:135], v[218:221], v[12:15]
	v_mfma_f32_16x16x32_bf16 v[8:11], v[140:143], v[218:221], v[8:11]
	s_setprio 0
	s_setprio 1
	v_mfma_f32_16x16x32_bf16 v[52:55], v[144:147], v[180:183], 0
	v_mfma_f32_16x16x32_bf16 v[48:51], v[172:175], v[180:183], 0
	v_mfma_f32_16x16x32_bf16 v[36:39], v[144:147], v[198:201], 0
	v_mfma_f32_16x16x32_bf16 v[32:35], v[172:175], v[198:201], 0
	v_mfma_f32_16x16x32_bf16 v[20:23], v[144:147], v[206:209], 0
	v_mfma_f32_16x16x32_bf16 v[16:19], v[172:175], v[206:209], 0
	v_mfma_f32_16x16x32_bf16 v[4:7], v[144:147], v[214:217], 0
	v_mfma_f32_16x16x32_bf16 v[0:3], v[172:175], v[214:217], 0
	v_mfma_f32_16x16x32_bf16 v[52:55], v[148:151], v[194:197], v[52:55]
	v_mfma_f32_16x16x32_bf16 v[48:51], v[176:179], v[194:197], v[48:51]
	v_mfma_f32_16x16x32_bf16 v[36:39], v[148:151], v[202:205], v[36:39]
	v_mfma_f32_16x16x32_bf16 v[32:35], v[176:179], v[202:205], v[32:35]
	v_mfma_f32_16x16x32_bf16 v[20:23], v[148:151], v[210:213], v[20:23]
	v_mfma_f32_16x16x32_bf16 v[16:19], v[176:179], v[210:213], v[16:19]
	v_mfma_f32_16x16x32_bf16 v[4:7], v[148:151], v[218:221], v[4:7]
	v_mfma_f32_16x16x32_bf16 v[0:3], v[176:179], v[218:221], v[0:3]
	s_setprio 0
	s_barrier
	s_add_i32 s82, 0, 0x18000
	s_add_i32 s83, 0, 0x1c000
	v_add_u32_e32 v140, s82, v186
	v_add_u32_e32 v176, s83, v186
	ds_read_b128 v[128:131], v140
	v_xor_b32_e32 v253, 64, v140
	ds_read_b128 v[132:135], v253
	ds_read_b128 v[136:139], v140 offset:2048
	ds_read_b128 v[140:143], v253 offset:2048
	ds_read_b128 v[144:147], v176
	v_xor_b32_e32 v253, 64, v176
	ds_read_b128 v[148:151], v253
	ds_read_b128 v[172:175], v176 offset:2048
	ds_read_b128 v[176:179], v253 offset:2048
	s_add_u32 s54, s60, 0xb0000
	s_addc_u32 s55, s61, 0
	s_mov_b32 m0, s68
	v_lshl_add_u64 v[230:231], s[54:55], 0, v[152:153]
	ds_read_b128 v[180:183], v191 offset:32768
	v_xor_b32_e32 v253, 64, v191
	ds_read_b128 v[194:197], v253 offset:32768
	ds_read_b128 v[198:201], v191 offset:34816
	ds_read_b128 v[202:205], v253 offset:34816
	ds_read_b128 v[206:209], v191 offset:36864
	ds_read_b128 v[210:213], v253 offset:36864
	ds_read_b128 v[214:217], v191 offset:38912
	ds_read_b128 v[218:221], v253 offset:38912
	global_load_lds_dwordx4 v[230:231], off
	v_lshl_add_u64 v[230:231], s[54:55], 0, v[160:161]
	s_mov_b32 m0, s69
	s_nop 0
	global_load_lds_dwordx4 v[230:231], off
	s_waitcnt vmcnt(8)
	s_waitcnt lgkmcnt(0)
	s_barrier
	s_setprio 1
	s_waitcnt lgkmcnt(0)
	v_mfma_f32_16x16x32_bf16 v[124:127], v[128:131], v[180:183], v[124:127]
	v_mfma_f32_16x16x32_bf16 v[124:127], v[132:135], v[194:197], v[124:127]
	v_mfma_f32_16x16x32_bf16 v[120:123], v[140:143], v[194:197], v[120:123]
	v_mfma_f32_16x16x32_bf16 v[120:123], v[136:139], v[180:183], v[120:123]
	v_mfma_f32_16x16x32_bf16 v[104:107], v[136:139], v[198:201], v[104:107]
	v_mfma_f32_16x16x32_bf16 v[104:107], v[140:143], v[202:205], v[104:107]
	v_mfma_f32_16x16x32_bf16 v[108:111], v[132:135], v[202:205], v[108:111]
	v_mfma_f32_16x16x32_bf16 v[108:111], v[128:131], v[198:201], v[108:111]
	v_mfma_f32_16x16x32_bf16 v[92:95], v[128:131], v[206:209], v[92:95]
	v_mfma_f32_16x16x32_bf16 v[92:95], v[132:135], v[210:213], v[92:95]
	v_mfma_f32_16x16x32_bf16 v[88:91], v[140:143], v[210:213], v[88:91]
	v_mfma_f32_16x16x32_bf16 v[88:91], v[136:139], v[206:209], v[88:91]
	v_mfma_f32_16x16x32_bf16 v[72:75], v[136:139], v[214:217], v[72:75]
	v_mfma_f32_16x16x32_bf16 v[72:75], v[140:143], v[218:221], v[72:75]
	v_mfma_f32_16x16x32_bf16 v[76:79], v[132:135], v[218:221], v[76:79]
	v_mfma_f32_16x16x32_bf16 v[76:79], v[128:131], v[214:217], v[76:79]
	s_setprio 0
	s_setprio 1
	v_mfma_f32_16x16x32_bf16 v[116:119], v[144:147], v[180:183], v[116:119]
	v_mfma_f32_16x16x32_bf16 v[116:119], v[148:151], v[194:197], v[116:119]
	v_mfma_f32_16x16x32_bf16 v[112:115], v[176:179], v[194:197], v[112:115]
	v_mfma_f32_16x16x32_bf16 v[112:115], v[172:175], v[180:183], v[112:115]
	v_mfma_f32_16x16x32_bf16 v[96:99], v[172:175], v[198:201], v[96:99]
	v_mfma_f32_16x16x32_bf16 v[96:99], v[176:179], v[202:205], v[96:99]
	v_mfma_f32_16x16x32_bf16 v[100:103], v[148:151], v[202:205], v[100:103]
	v_mfma_f32_16x16x32_bf16 v[100:103], v[144:147], v[198:201], v[100:103]
	v_mfma_f32_16x16x32_bf16 v[84:87], v[144:147], v[206:209], v[84:87]
	v_mfma_f32_16x16x32_bf16 v[84:87], v[148:151], v[210:213], v[84:87]
	v_mfma_f32_16x16x32_bf16 v[80:83], v[176:179], v[210:213], v[80:83]
	v_mfma_f32_16x16x32_bf16 v[80:83], v[172:175], v[206:209], v[80:83]
	v_mfma_f32_16x16x32_bf16 v[64:67], v[172:175], v[214:217], v[64:67]
	v_mfma_f32_16x16x32_bf16 v[64:67], v[176:179], v[218:221], v[64:67]
	v_mfma_f32_16x16x32_bf16 v[68:71], v[148:151], v[218:221], v[68:71]
	v_mfma_f32_16x16x32_bf16 v[68:71], v[144:147], v[214:217], v[68:71]
	s_setprio 0
	s_barrier
	s_add_i32 s54, s82, s65
	v_lshl_add_u64 v[222:223], v[222:223], 0, s[28:29]
	s_mov_b32 m0, s54
	ds_read_b128 v[180:183], v191 offset:49152
	v_xor_b32_e32 v253, 64, v191
	ds_read_b128 v[194:197], v253 offset:49152
	ds_read_b128 v[198:201], v191 offset:51200
	ds_read_b128 v[202:205], v253 offset:51200
	ds_read_b128 v[206:209], v191 offset:53248
	ds_read_b128 v[210:213], v253 offset:53248
	ds_read_b128 v[214:217], v191 offset:55296
	ds_read_b128 v[218:221], v253 offset:55296
	global_load_lds_dwordx4 v[222:223], off
	s_add_i32 m0, s54, 0x2000
	s_add_u32 s54, s58, 0xb0080
	v_lshl_add_u64 v[222:223], v[224:225], 0, s[28:29]
	s_addc_u32 s55, s59, 0
	s_add_i32 s58, s83, s65
	global_load_lds_dwordx4 v[222:223], off
	v_lshl_add_u64 v[222:223], s[54:55], 0, v[154:155]
	s_mov_b32 m0, s58
	s_nop 0
	global_load_lds_dwordx4 v[222:223], off
	v_lshl_add_u64 v[222:223], s[54:55], 0, v[162:163]
	s_add_i32 m0, s58, 0x2000
	s_nop 0
	global_load_lds_dwordx4 v[222:223], off
	v_lshl_add_u64 v[222:223], v[226:227], 0, s[28:29]
	s_mov_b32 m0, s3
	s_nop 0
	global_load_lds_dwordx4 v[222:223], off
	v_lshl_add_u64 v[222:223], v[228:229], 0, s[28:29]
	s_mov_b32 m0, s71
	s_nop 0
	global_load_lds_dwordx4 v[222:223], off
	s_waitcnt vmcnt(8)
	s_waitcnt lgkmcnt(0)
	s_barrier
	s_setprio 1
	s_waitcnt lgkmcnt(0)
	v_mfma_f32_16x16x32_bf16 v[60:63], v[128:131], v[180:183], v[60:63]
	v_mfma_f32_16x16x32_bf16 v[60:63], v[132:135], v[194:197], v[60:63]
	v_mfma_f32_16x16x32_bf16 v[56:59], v[140:143], v[194:197], v[56:59]
	v_mfma_f32_16x16x32_bf16 v[56:59], v[136:139], v[180:183], v[56:59]
	v_mfma_f32_16x16x32_bf16 v[40:43], v[136:139], v[198:201], v[40:43]
	v_mfma_f32_16x16x32_bf16 v[40:43], v[140:143], v[202:205], v[40:43]
	v_mfma_f32_16x16x32_bf16 v[44:47], v[132:135], v[202:205], v[44:47]
	v_mfma_f32_16x16x32_bf16 v[44:47], v[128:131], v[198:201], v[44:47]
	v_mfma_f32_16x16x32_bf16 v[28:31], v[128:131], v[206:209], v[28:31]
	v_mfma_f32_16x16x32_bf16 v[28:31], v[132:135], v[210:213], v[28:31]
	v_mfma_f32_16x16x32_bf16 v[24:27], v[140:143], v[210:213], v[24:27]
	v_mfma_f32_16x16x32_bf16 v[24:27], v[136:139], v[206:209], v[24:27]
	v_mfma_f32_16x16x32_bf16 v[8:11], v[136:139], v[214:217], v[8:11]
	v_mfma_f32_16x16x32_bf16 v[8:11], v[140:143], v[218:221], v[8:11]
	v_mfma_f32_16x16x32_bf16 v[12:15], v[132:135], v[218:221], v[12:15]
	v_mfma_f32_16x16x32_bf16 v[12:15], v[128:131], v[214:217], v[12:15]
	s_setprio 0
	s_setprio 1
	v_mfma_f32_16x16x32_bf16 v[52:55], v[144:147], v[180:183], v[52:55]
	v_mfma_f32_16x16x32_bf16 v[52:55], v[148:151], v[194:197], v[52:55]
	v_mfma_f32_16x16x32_bf16 v[48:51], v[176:179], v[194:197], v[48:51]
	v_mfma_f32_16x16x32_bf16 v[48:51], v[172:175], v[180:183], v[48:51]
	v_mfma_f32_16x16x32_bf16 v[32:35], v[172:175], v[198:201], v[32:35]
	v_mfma_f32_16x16x32_bf16 v[32:35], v[176:179], v[202:205], v[32:35]
	v_mfma_f32_16x16x32_bf16 v[36:39], v[148:151], v[202:205], v[36:39]
	v_mfma_f32_16x16x32_bf16 v[36:39], v[144:147], v[198:201], v[36:39]
	v_mfma_f32_16x16x32_bf16 v[20:23], v[144:147], v[206:209], v[20:23]
	v_mfma_f32_16x16x32_bf16 v[20:23], v[148:151], v[210:213], v[20:23]
	v_mfma_f32_16x16x32_bf16 v[16:19], v[176:179], v[210:213], v[16:19]
	v_mfma_f32_16x16x32_bf16 v[16:19], v[172:175], v[206:209], v[16:19]
	v_mfma_f32_16x16x32_bf16 v[0:3], v[172:175], v[214:217], v[0:3]
	v_mfma_f32_16x16x32_bf16 v[0:3], v[176:179], v[218:221], v[0:3]
	v_mfma_f32_16x16x32_bf16 v[4:7], v[148:151], v[218:221], v[4:7]
	v_mfma_f32_16x16x32_bf16 v[4:7], v[144:147], v[214:217], v[4:7]
	s_setprio 0
	s_barrier
	s_add_i32 s81, s81, 2
	s_add_u32 s79, s79, 0x100
	s_addc_u32 s80, s80, 0
	s_cmp_gt_u32 s81, 41
	s_mov_b64 s[54:55], s[56:57]
	s_branch .LBB0_610
.Lfa_5:
	ds_read_b128 v[128:131], v189
	v_xor_b32_e32 v253, 64, v189
	ds_read_b128 v[132:135], v253
	ds_read_b128 v[136:139], v189 offset:2048
	ds_read_b128 v[140:143], v253 offset:2048
	ds_read_b128 v[144:147], v190
	v_xor_b32_e32 v253, 64, v190
	ds_read_b128 v[148:151], v253
	ds_read_b128 v[172:175], v190 offset:2048
	ds_read_b128 v[176:179], v253 offset:2048
	s_add_u32 s56, s54, 0x100
	s_addc_u32 s57, s55, 0
	s_cmp_eq_u32 s81, 40
	s_cselect_b32 s61, s17, s57
	s_cselect_b32 s60, s16, s56
	s_cselect_b32 s59, s53, s80
	s_cselect_b32 s58, s52, s79
	v_lshl_add_u64 v[222:223], s[54:55], 0, v[166:167]
	s_add_i32 m0, s66, 0xc000
	ds_read_b128 v[180:183], v191
	v_xor_b32_e32 v253, 64, v191
	ds_read_b128 v[194:197], v253
	ds_read_b128 v[198:201], v191 offset:2048
	ds_read_b128 v[202:205], v253 offset:2048
	ds_read_b128 v[206:209], v191 offset:4096
	ds_read_b128 v[210:213], v253 offset:4096
	ds_read_b128 v[214:217], v191 offset:6144
	ds_read_b128 v[218:221], v253 offset:6144
	global_load_lds_dwordx4 v[222:223], off
	v_lshl_add_u64 v[222:223], s[54:55], 0, v[164:165]
	s_add_i32 m0, s66, 0xe000
	s_nop 0
	global_load_lds_dwordx4 v[222:223], off
	s_waitcnt vmcnt(8)
	s_waitcnt lgkmcnt(0)
	s_barrier
	s_setprio 1
	s_waitcnt lgkmcnt(0)
	v_mfma_f32_16x16x32_bf16 v[124:127], v[128:131], v[180:183], 0
	v_mfma_f32_16x16x32_bf16 v[120:123], v[136:139], v[180:183], 0
	v_mfma_f32_16x16x32_bf16 v[108:111], v[128:131], v[198:201], 0
	v_mfma_f32_16x16x32_bf16 v[104:107], v[136:139], v[198:201], 0
	v_mfma_f32_16x16x32_bf16 v[92:95], v[128:131], v[206:209], 0
	v_mfma_f32_16x16x32_bf16 v[88:91], v[136:139], v[206:209], 0
	v_mfma_f32_16x16x32_bf16 v[76:79], v[128:131], v[214:217], 0
	v_mfma_f32_16x16x32_bf16 v[72:75], v[136:139], v[214:217], 0
	v_mfma_f32_16x16x32_bf16 v[124:127], v[132:135], v[194:197], v[124:127]
	v_mfma_f32_16x16x32_bf16 v[120:123], v[140:143], v[194:197], v[120:123]
	v_mfma_f32_16x16x32_bf16 v[108:111], v[132:135], v[202:205], v[108:111]
	v_mfma_f32_16x16x32_bf16 v[104:107], v[140:143], v[202:205], v[104:107]
	v_mfma_f32_16x16x32_bf16 v[92:95], v[132:135], v[210:213], v[92:95]
	v_mfma_f32_16x16x32_bf16 v[88:91], v[140:143], v[210:213], v[88:91]
	v_mfma_f32_16x16x32_bf16 v[76:79], v[132:135], v[218:221], v[76:79]
	v_mfma_f32_16x16x32_bf16 v[72:75], v[140:143], v[218:221], v[72:75]
	s_setprio 0
	s_setprio 1
	v_mfma_f32_16x16x32_bf16 v[116:119], v[144:147], v[180:183], 0
	v_mfma_f32_16x16x32_bf16 v[112:115], v[172:175], v[180:183], 0
	v_mfma_f32_16x16x32_bf16 v[100:103], v[144:147], v[198:201], 0
	v_mfma_f32_16x16x32_bf16 v[96:99], v[172:175], v[198:201], 0
	v_mfma_f32_16x16x32_bf16 v[84:87], v[144:147], v[206:209], 0
	v_mfma_f32_16x16x32_bf16 v[80:83], v[172:175], v[206:209], 0
	v_mfma_f32_16x16x32_bf16 v[68:71], v[144:147], v[214:217], 0
	v_mfma_f32_16x16x32_bf16 v[64:67], v[172:175], v[214:217], 0
	v_mfma_f32_16x16x32_bf16 v[116:119], v[148:151], v[194:197], v[116:119]
	v_mfma_f32_16x16x32_bf16 v[112:115], v[176:179], v[194:197], v[112:115]
	v_mfma_f32_16x16x32_bf16 v[100:103], v[148:151], v[202:205], v[100:103]
	v_mfma_f32_16x16x32_bf16 v[96:99], v[176:179], v[202:205], v[96:99]
	v_mfma_f32_16x16x32_bf16 v[84:87], v[148:151], v[210:213], v[84:87]
	v_mfma_f32_16x16x32_bf16 v[80:83], v[176:179], v[210:213], v[80:83]
	v_mfma_f32_16x16x32_bf16 v[68:71], v[148:151], v[218:221], v[68:71]
	v_mfma_f32_16x16x32_bf16 v[64:67], v[176:179], v[218:221], v[64:67]
	s_setprio 0
	s_barrier
	s_add_i32 s54, s75, s65
	v_lshl_add_u64 v[222:223], s[58:59], 0, v[154:155]
	s_mov_b32 m0, s54
	ds_read_b128 v[180:183], v191 offset:16384
	v_xor_b32_e32 v253, 64, v191
	ds_read_b128 v[194:197], v253 offset:16384
	ds_read_b128 v[198:201], v191 offset:18432
	ds_read_b128 v[202:205], v253 offset:18432
	ds_read_b128 v[206:209], v191 offset:20480
	ds_read_b128 v[210:213], v253 offset:20480
	ds_read_b128 v[214:217], v191 offset:22528
	ds_read_b128 v[218:221], v253 offset:22528
	global_load_lds_dwordx4 v[222:223], off
	s_add_i32 m0, s54, 0x2000
	s_add_u32 s54, s58, 0xb0000
	v_lshl_add_u64 v[224:225], s[58:59], 0, v[162:163]
	s_addc_u32 s55, s59, 0
	s_add_i32 s82, s76, s65
	global_load_lds_dwordx4 v[224:225], off
	v_lshl_add_u64 v[226:227], s[54:55], 0, v[154:155]
	s_mov_b32 m0, s82
	v_lshl_add_u64 v[228:229], s[60:61], 0, v[160:161]
	global_load_lds_dwordx4 v[226:227], off
	v_lshl_add_u64 v[226:227], s[54:55], 0, v[162:163]
	s_add_i32 m0, s82, 0x2000
	s_nop 0
	global_load_lds_dwordx4 v[226:227], off
	v_lshl_add_u64 v[226:227], s[60:61], 0, v[152:153]
	s_mov_b32 m0, s66
	s_nop 0
	global_load_lds_dwordx4 v[226:227], off
	s_mov_b32 m0, s67
	s_nop 0
	global_load_lds_dwordx4 v[228:229], off
	s_waitcnt vmcnt(8)
	s_waitcnt lgkmcnt(0)
	s_barrier
	s_setprio 1
	s_waitcnt lgkmcnt(0)
	v_mfma_f32_16x16x32_bf16 v[60:63], v[128:131], v[180:183], 0
	v_mfma_f32_16x16x32_bf16 v[56:59], v[136:139], v[180:183], 0
	v_mfma_f32_16x16x32_bf16 v[44:47], v[128:131], v[198:201], 0
	v_mfma_f32_16x16x32_bf16 v[40:43], v[136:139], v[198:201], 0
	v_mfma_f32_16x16x32_bf16 v[28:31], v[128:131], v[206:209], 0
	v_mfma_f32_16x16x32_bf16 v[24:27], v[136:139], v[206:209], 0
	v_mfma_f32_16x16x32_bf16 v[12:15], v[128:131], v[214:217], 0
	v_mfma_f32_16x16x32_bf16 v[8:11], v[136:139], v[214:217], 0
	v_mfma_f32_16x16x32_bf16 v[60:63], v[132:135], v[194:197], v[60:63]
	v_mfma_f32_16x16x32_bf16 v[56:59], v[140:143], v[194:197], v[56:59]
	v_mfma_f32_16x16x32_bf16 v[44:47], v[132:135], v[202:205], v[44:47]
	v_mfma_f32_16x16x32_bf16 v[40:43], v[140:143], v[202:205], v[40:43]
	v_mfma_f32_16x16x32_bf16 v[28:31], v[132:135], v[210:213], v[28:31]
	v_mfma_f32_16x16x32_bf16 v[24:27], v[140:143], v[210:213], v[24:27]
	v_mfma_f32_16x16x32_bf16 v[12:15], v[132:135], v[218:221], v[12:15]
	v_mfma_f32_16x16x32_bf16 v[8:11], v[140:143], v[218:221], v[8:11]
	s_setprio 0
	s_setprio 1
	v_mfma_f32_16x16x32_bf16 v[52:55], v[144:147], v[180:183], 0
	v_mfma_f32_16x16x32_bf16 v[48:51], v[172:175], v[180:183], 0
	v_mfma_f32_16x16x32_bf16 v[36:39], v[144:147], v[198:201], 0
	v_mfma_f32_16x16x32_bf16 v[32:35], v[172:175], v[198:201], 0
	v_mfma_f32_16x16x32_bf16 v[20:23], v[144:147], v[206:209], 0
	v_mfma_f32_16x16x32_bf16 v[16:19], v[172:175], v[206:209], 0
	v_mfma_f32_16x16x32_bf16 v[4:7], v[144:147], v[214:217], 0
	v_mfma_f32_16x16x32_bf16 v[0:3], v[172:175], v[214:217], 0
	v_mfma_f32_16x16x32_bf16 v[52:55], v[148:151], v[194:197], v[52:55]
	v_mfma_f32_16x16x32_bf16 v[48:51], v[176:179], v[194:197], v[48:51]
	v_mfma_f32_16x16x32_bf16 v[36:39], v[148:151], v[202:205], v[36:39]
	v_mfma_f32_16x16x32_bf16 v[32:35], v[176:179], v[202:205], v[32:35]
	v_mfma_f32_16x16x32_bf16 v[20:23], v[148:151], v[210:213], v[20:23]
	v_mfma_f32_16x16x32_bf16 v[16:19], v[176:179], v[210:213], v[16:19]
	v_mfma_f32_16x16x32_bf16 v[4:7], v[148:151], v[218:221], v[4:7]
	v_mfma_f32_16x16x32_bf16 v[0:3], v[176:179], v[218:221], v[0:3]
	s_setprio 0
	s_barrier
	s_add_i32 s82, 0, 0x18000
	s_add_i32 s83, 0, 0x1c000
	v_add_u32_e32 v140, s82, v186
	v_add_u32_e32 v176, s83, v186
	ds_read_b128 v[128:131], v140
	v_xor_b32_e32 v253, 64, v140
	ds_read_b128 v[132:135], v253
	ds_read_b128 v[136:139], v140 offset:2048
	ds_read_b128 v[140:143], v253 offset:2048
	ds_read_b128 v[144:147], v176
	v_xor_b32_e32 v253, 64, v176
	ds_read_b128 v[148:151], v253
	ds_read_b128 v[172:175], v176 offset:2048
	ds_read_b128 v[176:179], v253 offset:2048
	s_add_u32 s54, s60, 0xb0000
	s_addc_u32 s55, s61, 0
	s_mov_b32 m0, s68
	v_lshl_add_u64 v[230:231], s[54:55], 0, v[152:153]
	ds_read_b128 v[180:183], v191 offset:32768
	v_xor_b32_e32 v253, 64, v191
	ds_read_b128 v[194:197], v253 offset:32768
	ds_read_b128 v[198:201], v191 offset:34816
	ds_read_b128 v[202:205], v253 offset:34816
	ds_read_b128 v[206:209], v191 offset:36864
	ds_read_b128 v[210:213], v253 offset:36864
	ds_read_b128 v[214:217], v191 offset:38912
	ds_read_b128 v[218:221], v253 offset:38912
	global_load_lds_dwordx4 v[230:231], off
	v_lshl_add_u64 v[230:231], s[54:55], 0, v[160:161]
	s_mov_b32 m0, s69
	s_nop 0
	global_load_lds_dwordx4 v[230:231], off
	s_waitcnt vmcnt(8)
	s_waitcnt lgkmcnt(0)
	s_barrier
	s_setprio 1
	s_waitcnt lgkmcnt(0)
	v_mfma_f32_16x16x32_bf16 v[124:127], v[128:131], v[180:183], v[124:127]
	v_mfma_f32_16x16x32_bf16 v[124:127], v[132:135], v[194:197], v[124:127]
	v_mfma_f32_16x16x32_bf16 v[120:123], v[140:143], v[194:197], v[120:123]
	v_mfma_f32_16x16x32_bf16 v[120:123], v[136:139], v[180:183], v[120:123]
	v_mfma_f32_16x16x32_bf16 v[104:107], v[136:139], v[198:201], v[104:107]
	v_mfma_f32_16x16x32_bf16 v[104:107], v[140:143], v[202:205], v[104:107]
	v_mfma_f32_16x16x32_bf16 v[108:111], v[132:135], v[202:205], v[108:111]
	v_mfma_f32_16x16x32_bf16 v[108:111], v[128:131], v[198:201], v[108:111]
	v_mfma_f32_16x16x32_bf16 v[92:95], v[128:131], v[206:209], v[92:95]
	v_mfma_f32_16x16x32_bf16 v[92:95], v[132:135], v[210:213], v[92:95]
	v_mfma_f32_16x16x32_bf16 v[88:91], v[140:143], v[210:213], v[88:91]
	v_mfma_f32_16x16x32_bf16 v[88:91], v[136:139], v[206:209], v[88:91]
	v_mfma_f32_16x16x32_bf16 v[72:75], v[136:139], v[214:217], v[72:75]
	v_mfma_f32_16x16x32_bf16 v[72:75], v[140:143], v[218:221], v[72:75]
	v_mfma_f32_16x16x32_bf16 v[76:79], v[132:135], v[218:221], v[76:79]
	v_mfma_f32_16x16x32_bf16 v[76:79], v[128:131], v[214:217], v[76:79]
	s_setprio 0
	s_setprio 1
	v_mfma_f32_16x16x32_bf16 v[116:119], v[144:147], v[180:183], v[116:119]
	v_mfma_f32_16x16x32_bf16 v[116:119], v[148:151], v[194:197], v[116:119]
	v_mfma_f32_16x16x32_bf16 v[112:115], v[176:179], v[194:197], v[112:115]
	v_mfma_f32_16x16x32_bf16 v[112:115], v[172:175], v[180:183], v[112:115]
	v_mfma_f32_16x16x32_bf16 v[96:99], v[172:175], v[198:201], v[96:99]
	v_mfma_f32_16x16x32_bf16 v[96:99], v[176:179], v[202:205], v[96:99]
	v_mfma_f32_16x16x32_bf16 v[100:103], v[148:151], v[202:205], v[100:103]
	v_mfma_f32_16x16x32_bf16 v[100:103], v[144:147], v[198:201], v[100:103]
	v_mfma_f32_16x16x32_bf16 v[84:87], v[144:147], v[206:209], v[84:87]
	v_mfma_f32_16x16x32_bf16 v[84:87], v[148:151], v[210:213], v[84:87]
	v_mfma_f32_16x16x32_bf16 v[80:83], v[176:179], v[210:213], v[80:83]
	v_mfma_f32_16x16x32_bf16 v[80:83], v[172:175], v[206:209], v[80:83]
	v_mfma_f32_16x16x32_bf16 v[64:67], v[172:175], v[214:217], v[64:67]
	v_mfma_f32_16x16x32_bf16 v[64:67], v[176:179], v[218:221], v[64:67]
	v_mfma_f32_16x16x32_bf16 v[68:71], v[148:151], v[218:221], v[68:71]
	v_mfma_f32_16x16x32_bf16 v[68:71], v[144:147], v[214:217], v[68:71]
	s_setprio 0
	s_barrier
	s_add_i32 s54, s82, s65
	v_lshl_add_u64 v[222:223], v[222:223], 0, s[28:29]
	s_mov_b32 m0, s54
	ds_read_b128 v[180:183], v191 offset:49152
	v_xor_b32_e32 v253, 64, v191
	ds_read_b128 v[194:197], v253 offset:49152
	ds_read_b128 v[198:201], v191 offset:51200
	ds_read_b128 v[202:205], v253 offset:51200
	ds_read_b128 v[206:209], v191 offset:53248
	ds_read_b128 v[210:213], v253 offset:53248
	ds_read_b128 v[214:217], v191 offset:55296
	ds_read_b128 v[218:221], v253 offset:55296
	global_load_lds_dwordx4 v[222:223], off
	s_add_i32 m0, s54, 0x2000
	s_add_u32 s54, s58, 0xb0080
	v_lshl_add_u64 v[222:223], v[224:225], 0, s[28:29]
	s_addc_u32 s55, s59, 0
	s_add_i32 s58, s83, s65
	global_load_lds_dwordx4 v[222:223], off
	v_lshl_add_u64 v[222:223], s[54:55], 0, v[154:155]
	s_mov_b32 m0, s58
	s_nop 0
	global_load_lds_dwordx4 v[222:223], off
	v_lshl_add_u64 v[222:223], s[54:55], 0, v[162:163]
	s_add_i32 m0, s58, 0x2000
	s_nop 0
	global_load_lds_dwordx4 v[222:223], off
	v_lshl_add_u64 v[222:223], v[226:227], 0, s[28:29]
	s_mov_b32 m0, s3
	s_nop 0
	global_load_lds_dwordx4 v[222:223], off
	v_lshl_add_u64 v[222:223], v[228:229], 0, s[28:29]
	s_mov_b32 m0, s71
	s_nop 0
	global_load_lds_dwordx4 v[222:223], off
	s_waitcnt vmcnt(8)
	s_waitcnt lgkmcnt(0)
	s_barrier
	s_setprio 1
	s_waitcnt lgkmcnt(0)
	v_mfma_f32_16x16x32_bf16 v[60:63], v[128:131], v[180:183], v[60:63]
	v_mfma_f32_16x16x32_bf16 v[60:63], v[132:135], v[194:197], v[60:63]
	v_mfma_f32_16x16x32_bf16 v[56:59], v[140:143], v[194:197], v[56:59]
	v_mfma_f32_16x16x32_bf16 v[56:59], v[136:139], v[180:183], v[56:59]
	v_mfma_f32_16x16x32_bf16 v[40:43], v[136:139], v[198:201], v[40:43]
	v_mfma_f32_16x16x32_bf16 v[40:43], v[140:143], v[202:205], v[40:43]
	v_mfma_f32_16x16x32_bf16 v[44:47], v[132:135], v[202:205], v[44:47]
	v_mfma_f32_16x16x32_bf16 v[44:47], v[128:131], v[198:201], v[44:47]
	v_mfma_f32_16x16x32_bf16 v[28:31], v[128:131], v[206:209], v[28:31]
	v_mfma_f32_16x16x32_bf16 v[28:31], v[132:135], v[210:213], v[28:31]
	v_mfma_f32_16x16x32_bf16 v[24:27], v[140:143], v[210:213], v[24:27]
	v_mfma_f32_16x16x32_bf16 v[24:27], v[136:139], v[206:209], v[24:27]
	v_mfma_f32_16x16x32_bf16 v[8:11], v[136:139], v[214:217], v[8:11]
	v_mfma_f32_16x16x32_bf16 v[8:11], v[140:143], v[218:221], v[8:11]
	v_mfma_f32_16x16x32_bf16 v[12:15], v[132:135], v[218:221], v[12:15]
	v_mfma_f32_16x16x32_bf16 v[12:15], v[128:131], v[214:217], v[12:15]
	s_setprio 0
	s_setprio 1
	v_mfma_f32_16x16x32_bf16 v[52:55], v[144:147], v[180:183], v[52:55]
	v_mfma_f32_16x16x32_bf16 v[52:55], v[148:151], v[194:197], v[52:55]
	v_mfma_f32_16x16x32_bf16 v[48:51], v[176:179], v[194:197], v[48:51]
	v_mfma_f32_16x16x32_bf16 v[48:51], v[172:175], v[180:183], v[48:51]
	v_mfma_f32_16x16x32_bf16 v[32:35], v[172:175], v[198:201], v[32:35]
	v_mfma_f32_16x16x32_bf16 v[32:35], v[176:179], v[202:205], v[32:35]
	v_mfma_f32_16x16x32_bf16 v[36:39], v[148:151], v[202:205], v[36:39]
	v_mfma_f32_16x16x32_bf16 v[36:39], v[144:147], v[198:201], v[36:39]
	v_mfma_f32_16x16x32_bf16 v[20:23], v[144:147], v[206:209], v[20:23]
	v_mfma_f32_16x16x32_bf16 v[20:23], v[148:151], v[210:213], v[20:23]
	v_mfma_f32_16x16x32_bf16 v[16:19], v[176:179], v[210:213], v[16:19]
	v_mfma_f32_16x16x32_bf16 v[16:19], v[172:175], v[206:209], v[16:19]
	v_mfma_f32_16x16x32_bf16 v[0:3], v[172:175], v[214:217], v[0:3]
	v_mfma_f32_16x16x32_bf16 v[0:3], v[176:179], v[218:221], v[0:3]
	v_mfma_f32_16x16x32_bf16 v[4:7], v[148:151], v[218:221], v[4:7]
	v_mfma_f32_16x16x32_bf16 v[4:7], v[144:147], v[214:217], v[4:7]
	s_setprio 0
	s_barrier
	s_add_i32 s81, s81, 2
	s_add_u32 s79, s79, 0x100
	s_addc_u32 s80, s80, 0
	s_cmp_gt_u32 s81, 41
	s_mov_b64 s[54:55], s[56:57]
.LBB0_610:
	ds_read_b128 v[128:131], v189
	v_xor_b32_e32 v253, 64, v189
	ds_read_b128 v[132:135], v253
	ds_read_b128 v[136:139], v189 offset:2048
	ds_read_b128 v[140:143], v253 offset:2048
	ds_read_b128 v[144:147], v190
	v_xor_b32_e32 v253, 64, v190
	ds_read_b128 v[148:151], v253
	ds_read_b128 v[172:175], v190 offset:2048
	ds_read_b128 v[176:179], v253 offset:2048
	s_add_u32 s56, s54, 0x100
	s_addc_u32 s57, s55, 0
	s_cmp_eq_u32 s81, 40
	s_cselect_b32 s61, s17, s57
	s_cselect_b32 s60, s16, s56
	s_cselect_b32 s59, s53, s80
	s_cselect_b32 s58, s52, s79
	v_lshl_add_u64 v[222:223], s[54:55], 0, v[166:167]
	s_add_i32 m0, s66, 0xc000
	ds_read_b128 v[180:183], v191
	v_xor_b32_e32 v253, 64, v191
	ds_read_b128 v[194:197], v253
	ds_read_b128 v[198:201], v191 offset:2048
	ds_read_b128 v[202:205], v253 offset:2048
	ds_read_b128 v[206:209], v191 offset:4096
	ds_read_b128 v[210:213], v253 offset:4096
	ds_read_b128 v[214:217], v191 offset:6144
	ds_read_b128 v[218:221], v253 offset:6144
	global_load_lds_dwordx4 v[222:223], off
	v_lshl_add_u64 v[222:223], s[54:55], 0, v[164:165]
	s_add_i32 m0, s66, 0xe000
	s_nop 0
	global_load_lds_dwordx4 v[222:223], off
	s_waitcnt vmcnt(8)
	s_waitcnt lgkmcnt(0)
	s_barrier
	s_setprio 1
	s_waitcnt lgkmcnt(0)
	v_mfma_f32_16x16x32_bf16 v[124:127], v[128:131], v[180:183], v[124:127]
	v_mfma_f32_16x16x32_bf16 v[124:127], v[132:135], v[194:197], v[124:127]
	v_mfma_f32_16x16x32_bf16 v[120:123], v[140:143], v[194:197], v[120:123]
	v_mfma_f32_16x16x32_bf16 v[120:123], v[136:139], v[180:183], v[120:123]
	v_mfma_f32_16x16x32_bf16 v[104:107], v[136:139], v[198:201], v[104:107]
	v_mfma_f32_16x16x32_bf16 v[104:107], v[140:143], v[202:205], v[104:107]
	v_mfma_f32_16x16x32_bf16 v[108:111], v[132:135], v[202:205], v[108:111]
	v_mfma_f32_16x16x32_bf16 v[108:111], v[128:131], v[198:201], v[108:111]
	v_mfma_f32_16x16x32_bf16 v[92:95], v[128:131], v[206:209], v[92:95]
	v_mfma_f32_16x16x32_bf16 v[92:95], v[132:135], v[210:213], v[92:95]
	v_mfma_f32_16x16x32_bf16 v[88:91], v[140:143], v[210:213], v[88:91]
	v_mfma_f32_16x16x32_bf16 v[88:91], v[136:139], v[206:209], v[88:91]
	v_mfma_f32_16x16x32_bf16 v[72:75], v[136:139], v[214:217], v[72:75]
	v_mfma_f32_16x16x32_bf16 v[72:75], v[140:143], v[218:221], v[72:75]
	v_mfma_f32_16x16x32_bf16 v[76:79], v[132:135], v[218:221], v[76:79]
	v_mfma_f32_16x16x32_bf16 v[76:79], v[128:131], v[214:217], v[76:79]
	s_setprio 0
	s_setprio 1
	v_mfma_f32_16x16x32_bf16 v[116:119], v[144:147], v[180:183], v[116:119]
	v_mfma_f32_16x16x32_bf16 v[116:119], v[148:151], v[194:197], v[116:119]
	v_mfma_f32_16x16x32_bf16 v[112:115], v[176:179], v[194:197], v[112:115]
	v_mfma_f32_16x16x32_bf16 v[112:115], v[172:175], v[180:183], v[112:115]
	v_mfma_f32_16x16x32_bf16 v[96:99], v[172:175], v[198:201], v[96:99]
	v_mfma_f32_16x16x32_bf16 v[96:99], v[176:179], v[202:205], v[96:99]
	v_mfma_f32_16x16x32_bf16 v[100:103], v[148:151], v[202:205], v[100:103]
	v_mfma_f32_16x16x32_bf16 v[100:103], v[144:147], v[198:201], v[100:103]
	v_mfma_f32_16x16x32_bf16 v[84:87], v[144:147], v[206:209], v[84:87]
	v_mfma_f32_16x16x32_bf16 v[84:87], v[148:151], v[210:213], v[84:87]
	v_mfma_f32_16x16x32_bf16 v[80:83], v[176:179], v[210:213], v[80:83]
	v_mfma_f32_16x16x32_bf16 v[80:83], v[172:175], v[206:209], v[80:83]
	v_mfma_f32_16x16x32_bf16 v[64:67], v[172:175], v[214:217], v[64:67]
	v_mfma_f32_16x16x32_bf16 v[64:67], v[176:179], v[218:221], v[64:67]
	v_mfma_f32_16x16x32_bf16 v[68:71], v[148:151], v[218:221], v[68:71]
	v_mfma_f32_16x16x32_bf16 v[68:71], v[144:147], v[214:217], v[68:71]
	s_setprio 0
	s_barrier
	s_add_i32 s54, s75, s65
	v_lshl_add_u64 v[222:223], s[58:59], 0, v[154:155]
	s_mov_b32 m0, s54
	ds_read_b128 v[180:183], v191 offset:16384
	v_xor_b32_e32 v253, 64, v191
	ds_read_b128 v[194:197], v253 offset:16384
	ds_read_b128 v[198:201], v191 offset:18432
	ds_read_b128 v[202:205], v253 offset:18432
	ds_read_b128 v[206:209], v191 offset:20480
	ds_read_b128 v[210:213], v253 offset:20480
	ds_read_b128 v[214:217], v191 offset:22528
	ds_read_b128 v[218:221], v253 offset:22528
	global_load_lds_dwordx4 v[222:223], off
	s_add_i32 m0, s54, 0x2000
	s_add_u32 s54, s58, 0xb0000
	v_lshl_add_u64 v[224:225], s[58:59], 0, v[162:163]
	s_addc_u32 s55, s59, 0
	s_add_i32 s82, s76, s65
	global_load_lds_dwordx4 v[224:225], off
	v_lshl_add_u64 v[226:227], s[54:55], 0, v[154:155]
	s_mov_b32 m0, s82
	v_lshl_add_u64 v[228:229], s[60:61], 0, v[160:161]
	global_load_lds_dwordx4 v[226:227], off
	v_lshl_add_u64 v[226:227], s[54:55], 0, v[162:163]
	s_add_i32 m0, s82, 0x2000
	s_nop 0
	global_load_lds_dwordx4 v[226:227], off
	v_lshl_add_u64 v[226:227], s[60:61], 0, v[152:153]
	s_mov_b32 m0, s66
	s_nop 0
	global_load_lds_dwordx4 v[226:227], off
	s_mov_b32 m0, s67
	s_nop 0
	global_load_lds_dwordx4 v[228:229], off
	s_waitcnt vmcnt(8)
	s_waitcnt lgkmcnt(0)
	s_barrier
	s_setprio 1
	s_waitcnt lgkmcnt(0)
	v_mfma_f32_16x16x32_bf16 v[60:63], v[128:131], v[180:183], v[60:63]
	v_mfma_f32_16x16x32_bf16 v[60:63], v[132:135], v[194:197], v[60:63]
	v_mfma_f32_16x16x32_bf16 v[56:59], v[140:143], v[194:197], v[56:59]
	v_mfma_f32_16x16x32_bf16 v[56:59], v[136:139], v[180:183], v[56:59]
	v_mfma_f32_16x16x32_bf16 v[40:43], v[136:139], v[198:201], v[40:43]
	v_mfma_f32_16x16x32_bf16 v[40:43], v[140:143], v[202:205], v[40:43]
	v_mfma_f32_16x16x32_bf16 v[44:47], v[132:135], v[202:205], v[44:47]
	v_mfma_f32_16x16x32_bf16 v[44:47], v[128:131], v[198:201], v[44:47]
	v_mfma_f32_16x16x32_bf16 v[28:31], v[128:131], v[206:209], v[28:31]
	v_mfma_f32_16x16x32_bf16 v[28:31], v[132:135], v[210:213], v[28:31]
	v_mfma_f32_16x16x32_bf16 v[24:27], v[140:143], v[210:213], v[24:27]
	v_mfma_f32_16x16x32_bf16 v[24:27], v[136:139], v[206:209], v[24:27]
	v_mfma_f32_16x16x32_bf16 v[8:11], v[136:139], v[214:217], v[8:11]
	v_mfma_f32_16x16x32_bf16 v[8:11], v[140:143], v[218:221], v[8:11]
	v_mfma_f32_16x16x32_bf16 v[12:15], v[132:135], v[218:221], v[12:15]
	v_mfma_f32_16x16x32_bf16 v[12:15], v[128:131], v[214:217], v[12:15]
	s_setprio 0
	s_setprio 1
	v_mfma_f32_16x16x32_bf16 v[52:55], v[144:147], v[180:183], v[52:55]
	v_mfma_f32_16x16x32_bf16 v[52:55], v[148:151], v[194:197], v[52:55]
	v_mfma_f32_16x16x32_bf16 v[48:51], v[176:179], v[194:197], v[48:51]
	v_mfma_f32_16x16x32_bf16 v[48:51], v[172:175], v[180:183], v[48:51]
	v_mfma_f32_16x16x32_bf16 v[32:35], v[172:175], v[198:201], v[32:35]
	v_mfma_f32_16x16x32_bf16 v[32:35], v[176:179], v[202:205], v[32:35]
	v_mfma_f32_16x16x32_bf16 v[36:39], v[148:151], v[202:205], v[36:39]
	v_mfma_f32_16x16x32_bf16 v[36:39], v[144:147], v[198:201], v[36:39]
	v_mfma_f32_16x16x32_bf16 v[20:23], v[144:147], v[206:209], v[20:23]
	v_mfma_f32_16x16x32_bf16 v[20:23], v[148:151], v[210:213], v[20:23]
	v_mfma_f32_16x16x32_bf16 v[16:19], v[176:179], v[210:213], v[16:19]
	v_mfma_f32_16x16x32_bf16 v[16:19], v[172:175], v[206:209], v[16:19]
	v_mfma_f32_16x16x32_bf16 v[0:3], v[172:175], v[214:217], v[0:3]
	v_mfma_f32_16x16x32_bf16 v[0:3], v[176:179], v[218:221], v[0:3]
	v_mfma_f32_16x16x32_bf16 v[4:7], v[148:151], v[218:221], v[4:7]
	v_mfma_f32_16x16x32_bf16 v[4:7], v[144:147], v[214:217], v[4:7]
	s_setprio 0
	s_barrier
	s_add_i32 s82, 0, 0x18000
	s_add_i32 s83, 0, 0x1c000
	v_add_u32_e32 v140, s82, v186
	v_add_u32_e32 v176, s83, v186
	ds_read_b128 v[128:131], v140
	v_xor_b32_e32 v253, 64, v140
	ds_read_b128 v[132:135], v253
	ds_read_b128 v[136:139], v140 offset:2048
	ds_read_b128 v[140:143], v253 offset:2048
	ds_read_b128 v[144:147], v176
	v_xor_b32_e32 v253, 64, v176
	ds_read_b128 v[148:151], v253
	ds_read_b128 v[172:175], v176 offset:2048
	ds_read_b128 v[176:179], v253 offset:2048
	s_add_u32 s54, s60, 0xb0000
	s_addc_u32 s55, s61, 0
	s_mov_b32 m0, s68
	v_lshl_add_u64 v[230:231], s[54:55], 0, v[152:153]
	ds_read_b128 v[180:183], v191 offset:32768
	v_xor_b32_e32 v253, 64, v191
	ds_read_b128 v[194:197], v253 offset:32768
	ds_read_b128 v[198:201], v191 offset:34816
	ds_read_b128 v[202:205], v253 offset:34816
	ds_read_b128 v[206:209], v191 offset:36864
	ds_read_b128 v[210:213], v253 offset:36864
	ds_read_b128 v[214:217], v191 offset:38912
	ds_read_b128 v[218:221], v253 offset:38912
	global_load_lds_dwordx4 v[230:231], off
	v_lshl_add_u64 v[230:231], s[54:55], 0, v[160:161]
	s_mov_b32 m0, s69
	s_nop 0
	global_load_lds_dwordx4 v[230:231], off
	s_waitcnt vmcnt(8)
	s_waitcnt lgkmcnt(0)
	s_barrier
	s_setprio 1
	s_waitcnt lgkmcnt(0)
	v_mfma_f32_16x16x32_bf16 v[124:127], v[128:131], v[180:183], v[124:127]
	v_mfma_f32_16x16x32_bf16 v[124:127], v[132:135], v[194:197], v[124:127]
	v_mfma_f32_16x16x32_bf16 v[120:123], v[140:143], v[194:197], v[120:123]
	v_mfma_f32_16x16x32_bf16 v[120:123], v[136:139], v[180:183], v[120:123]
	v_mfma_f32_16x16x32_bf16 v[104:107], v[136:139], v[198:201], v[104:107]
	v_mfma_f32_16x16x32_bf16 v[104:107], v[140:143], v[202:205], v[104:107]
	v_mfma_f32_16x16x32_bf16 v[108:111], v[132:135], v[202:205], v[108:111]
	v_mfma_f32_16x16x32_bf16 v[108:111], v[128:131], v[198:201], v[108:111]
	v_mfma_f32_16x16x32_bf16 v[92:95], v[128:131], v[206:209], v[92:95]
	v_mfma_f32_16x16x32_bf16 v[92:95], v[132:135], v[210:213], v[92:95]
	v_mfma_f32_16x16x32_bf16 v[88:91], v[140:143], v[210:213], v[88:91]
	v_mfma_f32_16x16x32_bf16 v[88:91], v[136:139], v[206:209], v[88:91]
	v_mfma_f32_16x16x32_bf16 v[72:75], v[136:139], v[214:217], v[72:75]
	v_mfma_f32_16x16x32_bf16 v[72:75], v[140:143], v[218:221], v[72:75]
	v_mfma_f32_16x16x32_bf16 v[76:79], v[132:135], v[218:221], v[76:79]
	v_mfma_f32_16x16x32_bf16 v[76:79], v[128:131], v[214:217], v[76:79]
	s_setprio 0
	s_setprio 1
	v_mfma_f32_16x16x32_bf16 v[116:119], v[144:147], v[180:183], v[116:119]
	v_mfma_f32_16x16x32_bf16 v[116:119], v[148:151], v[194:197], v[116:119]
	v_mfma_f32_16x16x32_bf16 v[112:115], v[176:179], v[194:197], v[112:115]
	v_mfma_f32_16x16x32_bf16 v[112:115], v[172:175], v[180:183], v[112:115]
	v_mfma_f32_16x16x32_bf16 v[96:99], v[172:175], v[198:201], v[96:99]
	v_mfma_f32_16x16x32_bf16 v[96:99], v[176:179], v[202:205], v[96:99]
	v_mfma_f32_16x16x32_bf16 v[100:103], v[148:151], v[202:205], v[100:103]
	v_mfma_f32_16x16x32_bf16 v[100:103], v[144:147], v[198:201], v[100:103]
	v_mfma_f32_16x16x32_bf16 v[84:87], v[144:147], v[206:209], v[84:87]
	v_mfma_f32_16x16x32_bf16 v[84:87], v[148:151], v[210:213], v[84:87]
	v_mfma_f32_16x16x32_bf16 v[80:83], v[176:179], v[210:213], v[80:83]
	v_mfma_f32_16x16x32_bf16 v[80:83], v[172:175], v[206:209], v[80:83]
	v_mfma_f32_16x16x32_bf16 v[64:67], v[172:175], v[214:217], v[64:67]
	v_mfma_f32_16x16x32_bf16 v[64:67], v[176:179], v[218:221], v[64:67]
	v_mfma_f32_16x16x32_bf16 v[68:71], v[148:151], v[218:221], v[68:71]
	v_mfma_f32_16x16x32_bf16 v[68:71], v[144:147], v[214:217], v[68:71]
	s_setprio 0
	s_barrier
	s_add_i32 s54, s82, s65
	v_lshl_add_u64 v[222:223], v[222:223], 0, s[28:29]
	s_mov_b32 m0, s54
	ds_read_b128 v[180:183], v191 offset:49152
	v_xor_b32_e32 v253, 64, v191
	ds_read_b128 v[194:197], v253 offset:49152
	ds_read_b128 v[198:201], v191 offset:51200
	ds_read_b128 v[202:205], v253 offset:51200
	ds_read_b128 v[206:209], v191 offset:53248
	ds_read_b128 v[210:213], v253 offset:53248
	ds_read_b128 v[214:217], v191 offset:55296
	ds_read_b128 v[218:221], v253 offset:55296
	global_load_lds_dwordx4 v[222:223], off
	s_add_i32 m0, s54, 0x2000
	s_add_u32 s54, s58, 0xb0080
	v_lshl_add_u64 v[222:223], v[224:225], 0, s[28:29]
	s_addc_u32 s55, s59, 0
	s_add_i32 s58, s83, s65
	global_load_lds_dwordx4 v[222:223], off
	v_lshl_add_u64 v[222:223], s[54:55], 0, v[154:155]
	s_mov_b32 m0, s58
	s_nop 0
	global_load_lds_dwordx4 v[222:223], off
	v_lshl_add_u64 v[222:223], s[54:55], 0, v[162:163]
	s_add_i32 m0, s58, 0x2000
	s_nop 0
	global_load_lds_dwordx4 v[222:223], off
	v_lshl_add_u64 v[222:223], v[226:227], 0, s[28:29]
	s_mov_b32 m0, s3
	s_nop 0
	global_load_lds_dwordx4 v[222:223], off
	v_lshl_add_u64 v[222:223], v[228:229], 0, s[28:29]
	s_mov_b32 m0, s71
	s_nop 0
	global_load_lds_dwordx4 v[222:223], off
	s_waitcnt vmcnt(8)
	s_waitcnt lgkmcnt(0)
	s_barrier
	s_setprio 1
	s_waitcnt lgkmcnt(0)
	v_mfma_f32_16x16x32_bf16 v[60:63], v[128:131], v[180:183], v[60:63]
	v_mfma_f32_16x16x32_bf16 v[60:63], v[132:135], v[194:197], v[60:63]
	v_mfma_f32_16x16x32_bf16 v[56:59], v[140:143], v[194:197], v[56:59]
	v_mfma_f32_16x16x32_bf16 v[56:59], v[136:139], v[180:183], v[56:59]
	v_mfma_f32_16x16x32_bf16 v[40:43], v[136:139], v[198:201], v[40:43]
	v_mfma_f32_16x16x32_bf16 v[40:43], v[140:143], v[202:205], v[40:43]
	v_mfma_f32_16x16x32_bf16 v[44:47], v[132:135], v[202:205], v[44:47]
	v_mfma_f32_16x16x32_bf16 v[44:47], v[128:131], v[198:201], v[44:47]
	v_mfma_f32_16x16x32_bf16 v[28:31], v[128:131], v[206:209], v[28:31]
	v_mfma_f32_16x16x32_bf16 v[28:31], v[132:135], v[210:213], v[28:31]
	v_mfma_f32_16x16x32_bf16 v[24:27], v[140:143], v[210:213], v[24:27]
	v_mfma_f32_16x16x32_bf16 v[24:27], v[136:139], v[206:209], v[24:27]
	v_mfma_f32_16x16x32_bf16 v[8:11], v[136:139], v[214:217], v[8:11]
	v_mfma_f32_16x16x32_bf16 v[8:11], v[140:143], v[218:221], v[8:11]
	v_mfma_f32_16x16x32_bf16 v[12:15], v[132:135], v[218:221], v[12:15]
	v_mfma_f32_16x16x32_bf16 v[12:15], v[128:131], v[214:217], v[12:15]
	s_setprio 0
	s_setprio 1
	v_mfma_f32_16x16x32_bf16 v[52:55], v[144:147], v[180:183], v[52:55]
	v_mfma_f32_16x16x32_bf16 v[52:55], v[148:151], v[194:197], v[52:55]
	v_mfma_f32_16x16x32_bf16 v[48:51], v[176:179], v[194:197], v[48:51]
	v_mfma_f32_16x16x32_bf16 v[48:51], v[172:175], v[180:183], v[48:51]
	v_mfma_f32_16x16x32_bf16 v[32:35], v[172:175], v[198:201], v[32:35]
	v_mfma_f32_16x16x32_bf16 v[32:35], v[176:179], v[202:205], v[32:35]
	v_mfma_f32_16x16x32_bf16 v[36:39], v[148:151], v[202:205], v[36:39]
	v_mfma_f32_16x16x32_bf16 v[36:39], v[144:147], v[198:201], v[36:39]
	v_mfma_f32_16x16x32_bf16 v[20:23], v[144:147], v[206:209], v[20:23]
	v_mfma_f32_16x16x32_bf16 v[20:23], v[148:151], v[210:213], v[20:23]
	v_mfma_f32_16x16x32_bf16 v[16:19], v[176:179], v[210:213], v[16:19]
	v_mfma_f32_16x16x32_bf16 v[16:19], v[172:175], v[206:209], v[16:19]
	v_mfma_f32_16x16x32_bf16 v[0:3], v[172:175], v[214:217], v[0:3]
	v_mfma_f32_16x16x32_bf16 v[0:3], v[176:179], v[218:221], v[0:3]
	v_mfma_f32_16x16x32_bf16 v[4:7], v[148:151], v[218:221], v[4:7]
	v_mfma_f32_16x16x32_bf16 v[4:7], v[144:147], v[214:217], v[4:7]
	s_setprio 0
	s_barrier
	s_add_i32 s81, s81, 2
	s_add_u32 s79, s79, 0x100
	s_addc_u32 s80, s80, 0
	s_cmp_gt_u32 s81, 41
	s_mov_b64 s[54:55], s[56:57]
	s_cbranch_scc0 .LBB0_610
	s_and_b64 vcc, exec, s[30:31]
	s_cbranch_vccz .LBB0_613
	s_barrier

.LBB0_873:
	s_ashr_i32 s49, s48, 31
	s_lshl_b64 s[50:51], s[48:49], 19
	s_add_u32 s50, s35, s50
	s_addc_u32 s51, s60, s51
	s_and_b64 s[52:53], s[10:11], exec
	s_cselect_b32 s49, s51, s59
	s_cselect_b32 s80, s50, s58
	s_ashr_i32 s47, s46, 31
	s_lshl_b64 s[52:53], s[46:47], 19
	s_add_u32 s52, s61, s52
	s_addc_u32 s53, s62, s53
	s_and_b64 s[82:83], s[10:11], exec
	s_cselect_b32 s81, s53, s57
	s_cselect_b32 s82, s52, s56
	s_lshl_b32 s47, s54, 8
	v_add_u32_e32 v0, s47, v151
	s_add_u32 s83, s56, 0x100
	v_ashrrev_i32_e32 v1, 31, v0
	s_addc_u32 s84, s57, 0
	v_lshl_add_u64 v[144:145], v[0:1], 4, s[20:21]
	s_add_u32 s54, s58, 0x40080
	s_addc_u32 s55, s59, 0
	s_mov_b32 s85, -2
	s_mov_b64 s[56:57], 0
	s_cmp_eq_u32 s68, 1
	s_cbranch_scc1 .Lfa_8
	v_add_u32_e32 v146, s73, v149
	ds_read_b128 v[162:165], v146
	v_xor_b32_e32 v253, 64, v146
	ds_read_b128 v[166:169], v253
	ds_read_b128 v[170:173], v146 offset:2048
	ds_read_b128 v[174:177], v253 offset:2048
	v_add_u32_e32 v146, s74, v149
	ds_read_b128 v[178:181], v146
	v_xor_b32_e32 v253, 64, v146
	ds_read_b128 v[186:189], v253
	ds_read_b128 v[190:193], v146 offset:2048
	ds_read_b128 v[194:197], v253 offset:2048
	s_add_u32 s58, s54, 0xfffc0080
	s_addc_u32 s59, s55, -1
	s_and_b64 s[56:57], s[56:57], exec
	s_cselect_b32 s59, s49, s59
	s_cselect_b32 s58, s80, s58
	s_cselect_b32 s57, s81, s84
	s_cselect_b32 s56, s82, s83
	v_lshl_add_u64 v[182:183], s[54:55], 0, v[138:139]
	s_add_i32 m0, s64, 0xc000
	ds_read_b128 v[198:201], v154
	v_xor_b32_e32 v253, 64, v154
	ds_read_b128 v[202:205], v253
	ds_read_b128 v[206:209], v154 offset:2048
	ds_read_b128 v[210:213], v253 offset:2048
	ds_read_b128 v[214:217], v154 offset:4096
	ds_read_b128 v[218:221], v253 offset:4096
	ds_read_b128 v[222:225], v154 offset:6144
	ds_read_b128 v[226:229], v253 offset:6144
	global_load_lds_dwordx4 v[182:183], off
	v_lshl_add_u64 v[182:183], s[54:55], 0, v[136:137]
	s_add_i32 m0, s64, 0xe000
	s_nop 0
	global_load_lds_dwordx4 v[182:183], off
	s_waitcnt vmcnt(24)
	s_waitcnt lgkmcnt(0)
	s_barrier
	s_setprio 1
	s_waitcnt lgkmcnt(0)
	v_mfma_f32_16x16x32_bf16 v[124:127], v[162:165], v[198:201], 0
	v_mfma_f32_16x16x32_bf16 v[120:123], v[170:173], v[198:201], 0
	v_mfma_f32_16x16x32_bf16 v[112:115], v[162:165], v[206:209], 0
	v_mfma_f32_16x16x32_bf16 v[104:107], v[170:173], v[206:209], 0
	v_mfma_f32_16x16x32_bf16 v[96:99], v[162:165], v[214:217], 0
	v_mfma_f32_16x16x32_bf16 v[88:91], v[170:173], v[214:217], 0
	v_mfma_f32_16x16x32_bf16 v[80:83], v[162:165], v[222:225], 0
	v_mfma_f32_16x16x32_bf16 v[72:75], v[170:173], v[222:225], 0
	v_mfma_f32_16x16x32_bf16 v[124:127], v[166:169], v[202:205], v[124:127]
	v_mfma_f32_16x16x32_bf16 v[120:123], v[174:177], v[202:205], v[120:123]
	v_mfma_f32_16x16x32_bf16 v[112:115], v[166:169], v[210:213], v[112:115]
	v_mfma_f32_16x16x32_bf16 v[104:107], v[174:177], v[210:213], v[104:107]
	v_mfma_f32_16x16x32_bf16 v[96:99], v[166:169], v[218:221], v[96:99]
	v_mfma_f32_16x16x32_bf16 v[88:91], v[174:177], v[218:221], v[88:91]
	v_mfma_f32_16x16x32_bf16 v[80:83], v[166:169], v[226:229], v[80:83]
	v_mfma_f32_16x16x32_bf16 v[72:75], v[174:177], v[226:229], v[72:75]
	s_setprio 0
	s_setprio 1
	v_mfma_f32_16x16x32_bf16 v[116:119], v[178:181], v[198:201], 0
	v_mfma_f32_16x16x32_bf16 v[108:111], v[190:193], v[198:201], 0
	v_mfma_f32_16x16x32_bf16 v[100:103], v[178:181], v[206:209], 0
	v_mfma_f32_16x16x32_bf16 v[92:95], v[190:193], v[206:209], 0
	v_mfma_f32_16x16x32_bf16 v[84:87], v[178:181], v[214:217], 0
	v_mfma_f32_16x16x32_bf16 v[76:79], v[190:193], v[214:217], 0
	v_mfma_f32_16x16x32_bf16 v[68:71], v[178:181], v[222:225], 0
	v_mfma_f32_16x16x32_bf16 v[64:67], v[190:193], v[222:225], 0
	v_mfma_f32_16x16x32_bf16 v[116:119], v[186:189], v[202:205], v[116:119]
	v_mfma_f32_16x16x32_bf16 v[108:111], v[194:197], v[202:205], v[108:111]
	v_mfma_f32_16x16x32_bf16 v[100:103], v[186:189], v[210:213], v[100:103]
	v_mfma_f32_16x16x32_bf16 v[92:95], v[194:197], v[210:213], v[92:95]
	v_mfma_f32_16x16x32_bf16 v[84:87], v[186:189], v[218:221], v[84:87]
	v_mfma_f32_16x16x32_bf16 v[76:79], v[194:197], v[218:221], v[76:79]
	v_mfma_f32_16x16x32_bf16 v[68:71], v[186:189], v[226:229], v[68:71]
	v_mfma_f32_16x16x32_bf16 v[64:67], v[194:197], v[226:229], v[64:67]
	s_setprio 0
	s_barrier
	s_add_i32 s86, s73, s63
	v_lshl_add_u64 v[182:183], s[56:57], 0, v[130:131]
	s_mov_b32 m0, s86
	ds_read_b128 v[198:201], v154 offset:16384
	v_xor_b32_e32 v253, 64, v154
	ds_read_b128 v[202:205], v253 offset:16384
	ds_read_b128 v[206:209], v154 offset:18432
	ds_read_b128 v[210:213], v253 offset:18432
	ds_read_b128 v[214:217], v154 offset:20480
	ds_read_b128 v[218:221], v253 offset:20480
	ds_read_b128 v[222:225], v154 offset:22528
	ds_read_b128 v[226:229], v253 offset:22528
	global_load_lds_dwordx4 v[182:183], off
	s_add_i32 m0, s86, 0x2000
	s_add_u32 s86, s56, 0x40000
	v_lshl_add_u64 v[230:231], s[56:57], 0, v[134:135]
	s_addc_u32 s87, s57, 0
	s_add_i32 s88, s74, s63
	global_load_lds_dwordx4 v[230:231], off
	v_lshl_add_u64 v[232:233], s[86:87], 0, v[130:131]
	s_mov_b32 m0, s88
	v_lshl_add_u64 v[234:235], s[58:59], 0, v[132:133]
	global_load_lds_dwordx4 v[232:233], off
	v_lshl_add_u64 v[232:233], s[86:87], 0, v[134:135]
	s_add_i32 m0, s88, 0x2000
	s_nop 0
	global_load_lds_dwordx4 v[232:233], off
	v_lshl_add_u64 v[232:233], s[58:59], 0, v[128:129]
	s_mov_b32 m0, s64
	s_nop 0
	global_load_lds_dwordx4 v[232:233], off
	s_mov_b32 m0, s65
	s_nop 0
	global_load_lds_dwordx4 v[234:235], off
	s_waitcnt vmcnt(24)
	s_waitcnt lgkmcnt(0)
	s_barrier
	s_setprio 1
	s_waitcnt lgkmcnt(0)
	v_mfma_f32_16x16x32_bf16 v[60:63], v[162:165], v[198:201], 0
	v_mfma_f32_16x16x32_bf16 v[56:59], v[170:173], v[198:201], 0
	v_mfma_f32_16x16x32_bf16 v[48:51], v[162:165], v[206:209], 0
	v_mfma_f32_16x16x32_bf16 v[40:43], v[170:173], v[206:209], 0
	v_mfma_f32_16x16x32_bf16 v[32:35], v[162:165], v[214:217], 0
	v_mfma_f32_16x16x32_bf16 v[24:27], v[170:173], v[214:217], 0
	v_mfma_f32_16x16x32_bf16 v[16:19], v[162:165], v[222:225], 0
	v_mfma_f32_16x16x32_bf16 v[8:11], v[170:173], v[222:225], 0
	v_mfma_f32_16x16x32_bf16 v[60:63], v[166:169], v[202:205], v[60:63]
	v_mfma_f32_16x16x32_bf16 v[56:59], v[174:177], v[202:205], v[56:59]
	v_mfma_f32_16x16x32_bf16 v[48:51], v[166:169], v[210:213], v[48:51]
	v_mfma_f32_16x16x32_bf16 v[40:43], v[174:177], v[210:213], v[40:43]
	v_mfma_f32_16x16x32_bf16 v[32:35], v[166:169], v[218:221], v[32:35]
	v_mfma_f32_16x16x32_bf16 v[24:27], v[174:177], v[218:221], v[24:27]
	v_mfma_f32_16x16x32_bf16 v[16:19], v[166:169], v[226:229], v[16:19]
	v_mfma_f32_16x16x32_bf16 v[8:11], v[174:177], v[226:229], v[8:11]
	s_setprio 0
	s_setprio 1
	v_mfma_f32_16x16x32_bf16 v[52:55], v[178:181], v[198:201], 0
	v_mfma_f32_16x16x32_bf16 v[44:47], v[190:193], v[198:201], 0
	v_mfma_f32_16x16x32_bf16 v[36:39], v[178:181], v[206:209], 0
	v_mfma_f32_16x16x32_bf16 v[28:31], v[190:193], v[206:209], 0
	v_mfma_f32_16x16x32_bf16 v[20:23], v[178:181], v[214:217], 0
	v_mfma_f32_16x16x32_bf16 v[12:15], v[190:193], v[214:217], 0
	v_mfma_f32_16x16x32_bf16 v[4:7], v[178:181], v[222:225], 0
	v_mfma_f32_16x16x32_bf16 v[0:3], v[190:193], v[222:225], 0
	v_mfma_f32_16x16x32_bf16 v[52:55], v[186:189], v[202:205], v[52:55]
	v_mfma_f32_16x16x32_bf16 v[44:47], v[194:197], v[202:205], v[44:47]
	v_mfma_f32_16x16x32_bf16 v[36:39], v[186:189], v[210:213], v[36:39]
	v_mfma_f32_16x16x32_bf16 v[28:31], v[194:197], v[210:213], v[28:31]
	v_mfma_f32_16x16x32_bf16 v[20:23], v[186:189], v[218:221], v[20:23]
	v_mfma_f32_16x16x32_bf16 v[12:15], v[194:197], v[218:221], v[12:15]
	v_mfma_f32_16x16x32_bf16 v[4:7], v[186:189], v[226:229], v[4:7]
	v_mfma_f32_16x16x32_bf16 v[0:3], v[194:197], v[226:229], v[0:3]
	s_setprio 0
	s_barrier
	s_add_i32 s86, 0, 0x18000
	v_add_u32_e32 v146, s86, v149
	s_add_i32 s87, 0, 0x1c000
	ds_read_b128 v[162:165], v146
	v_xor_b32_e32 v253, 64, v146
	ds_read_b128 v[166:169], v253
	ds_read_b128 v[170:173], v146 offset:2048
	ds_read_b128 v[174:177], v253 offset:2048
	v_add_u32_e32 v146, s87, v149
	ds_read_b128 v[178:181], v146
	v_xor_b32_e32 v253, 64, v146
	ds_read_b128 v[186:189], v253
	ds_read_b128 v[190:193], v146 offset:2048
	ds_read_b128 v[194:197], v253 offset:2048
	s_add_u32 s58, s58, 0x40000
	s_addc_u32 s59, s59, 0
	s_mov_b32 m0, s66
	v_lshl_add_u64 v[236:237], s[58:59], 0, v[128:129]
	ds_read_b128 v[198:201], v154 offset:32768
	v_xor_b32_e32 v253, 64, v154
	ds_read_b128 v[202:205], v253 offset:32768
	ds_read_b128 v[206:209], v154 offset:34816
	ds_read_b128 v[210:213], v253 offset:34816
	ds_read_b128 v[214:217], v154 offset:36864
	ds_read_b128 v[218:221], v253 offset:36864
	ds_read_b128 v[222:225], v154 offset:38912
	ds_read_b128 v[226:229], v253 offset:38912
	global_load_lds_dwordx4 v[236:237], off
	v_lshl_add_u64 v[236:237], s[58:59], 0, v[132:133]
	s_mov_b32 m0, s67
	s_nop 0
	global_load_lds_dwordx4 v[236:237], off
	s_waitcnt vmcnt(8)
	s_waitcnt lgkmcnt(0)
	s_barrier
	s_setprio 1
	s_waitcnt lgkmcnt(0)
	v_mfma_f32_16x16x32_bf16 v[124:127], v[162:165], v[198:201], v[124:127]
	v_mfma_f32_16x16x32_bf16 v[124:127], v[166:169], v[202:205], v[124:127]
	v_mfma_f32_16x16x32_bf16 v[120:123], v[174:177], v[202:205], v[120:123]
	v_mfma_f32_16x16x32_bf16 v[120:123], v[170:173], v[198:201], v[120:123]
	v_mfma_f32_16x16x32_bf16 v[104:107], v[170:173], v[206:209], v[104:107]
	v_mfma_f32_16x16x32_bf16 v[104:107], v[174:177], v[210:213], v[104:107]
	v_mfma_f32_16x16x32_bf16 v[112:115], v[166:169], v[210:213], v[112:115]
	v_mfma_f32_16x16x32_bf16 v[112:115], v[162:165], v[206:209], v[112:115]
	v_mfma_f32_16x16x32_bf16 v[96:99], v[162:165], v[214:217], v[96:99]
	v_mfma_f32_16x16x32_bf16 v[96:99], v[166:169], v[218:221], v[96:99]
	v_mfma_f32_16x16x32_bf16 v[88:91], v[174:177], v[218:221], v[88:91]
	v_mfma_f32_16x16x32_bf16 v[88:91], v[170:173], v[214:217], v[88:91]
	v_mfma_f32_16x16x32_bf16 v[72:75], v[170:173], v[222:225], v[72:75]
	v_mfma_f32_16x16x32_bf16 v[72:75], v[174:177], v[226:229], v[72:75]
	v_mfma_f32_16x16x32_bf16 v[80:83], v[166:169], v[226:229], v[80:83]
	v_mfma_f32_16x16x32_bf16 v[80:83], v[162:165], v[222:225], v[80:83]
	s_setprio 0
	s_setprio 1
	v_mfma_f32_16x16x32_bf16 v[116:119], v[178:181], v[198:201], v[116:119]
	v_mfma_f32_16x16x32_bf16 v[116:119], v[186:189], v[202:205], v[116:119]
	v_mfma_f32_16x16x32_bf16 v[108:111], v[194:197], v[202:205], v[108:111]
	v_mfma_f32_16x16x32_bf16 v[108:111], v[190:193], v[198:201], v[108:111]
	v_mfma_f32_16x16x32_bf16 v[92:95], v[190:193], v[206:209], v[92:95]
	v_mfma_f32_16x16x32_bf16 v[92:95], v[194:197], v[210:213], v[92:95]
	v_mfma_f32_16x16x32_bf16 v[100:103], v[186:189], v[210:213], v[100:103]
	v_mfma_f32_16x16x32_bf16 v[100:103], v[178:181], v[206:209], v[100:103]
	v_mfma_f32_16x16x32_bf16 v[84:87], v[178:181], v[214:217], v[84:87]
	v_mfma_f32_16x16x32_bf16 v[84:87], v[186:189], v[218:221], v[84:87]
	v_mfma_f32_16x16x32_bf16 v[76:79], v[194:197], v[218:221], v[76:79]
	v_mfma_f32_16x16x32_bf16 v[76:79], v[190:193], v[214:217], v[76:79]
	v_mfma_f32_16x16x32_bf16 v[64:67], v[190:193], v[222:225], v[64:67]
	v_mfma_f32_16x16x32_bf16 v[64:67], v[194:197], v[226:229], v[64:67]
	v_mfma_f32_16x16x32_bf16 v[68:71], v[186:189], v[226:229], v[68:71]
	v_mfma_f32_16x16x32_bf16 v[68:71], v[178:181], v[222:225], v[68:71]
	s_setprio 0
	s_barrier
	s_add_i32 s58, s86, s63
	v_lshl_add_u64 v[182:183], v[182:183], 0, s[22:23]
	s_mov_b32 m0, s58
	ds_read_b128 v[198:201], v154 offset:49152
	v_xor_b32_e32 v253, 64, v154
	ds_read_b128 v[202:205], v253 offset:49152
	ds_read_b128 v[206:209], v154 offset:51200
	ds_read_b128 v[210:213], v253 offset:51200
	ds_read_b128 v[214:217], v154 offset:53248
	ds_read_b128 v[218:221], v253 offset:53248
	ds_read_b128 v[222:225], v154 offset:55296
	ds_read_b128 v[226:229], v253 offset:55296
	global_load_lds_dwordx4 v[182:183], off
	s_add_i32 m0, s58, 0x2000
	s_add_u32 s56, s56, 0x40080
	v_lshl_add_u64 v[182:183], v[230:231], 0, s[22:23]
	s_addc_u32 s57, s57, 0
	s_add_i32 s58, s87, s63
	global_load_lds_dwordx4 v[182:183], off
	v_lshl_add_u64 v[182:183], s[56:57], 0, v[130:131]
	s_mov_b32 m0, s58
	s_nop 0
	global_load_lds_dwordx4 v[182:183], off
	v_lshl_add_u64 v[182:183], s[56:57], 0, v[134:135]
	s_add_i32 m0, s58, 0x2000
	s_nop 0
	global_load_lds_dwordx4 v[182:183], off
	v_lshl_add_u64 v[182:183], v[232:233], 0, s[22:23]
	s_mov_b32 m0, s69
	s_nop 0
	global_load_lds_dwordx4 v[182:183], off
	v_lshl_add_u64 v[182:183], v[234:235], 0, s[22:23]
	s_mov_b32 m0, s70
	s_nop 0
	global_load_lds_dwordx4 v[182:183], off
	s_waitcnt vmcnt(8)
	s_waitcnt lgkmcnt(0)
	s_barrier
	s_setprio 1
	s_waitcnt lgkmcnt(0)
	v_mfma_f32_16x16x32_bf16 v[60:63], v[162:165], v[198:201], v[60:63]
	v_mfma_f32_16x16x32_bf16 v[60:63], v[166:169], v[202:205], v[60:63]
	v_mfma_f32_16x16x32_bf16 v[56:59], v[174:177], v[202:205], v[56:59]
	v_mfma_f32_16x16x32_bf16 v[56:59], v[170:173], v[198:201], v[56:59]
	v_mfma_f32_16x16x32_bf16 v[40:43], v[170:173], v[206:209], v[40:43]
	v_mfma_f32_16x16x32_bf16 v[40:43], v[174:177], v[210:213], v[40:43]
	v_mfma_f32_16x16x32_bf16 v[48:51], v[166:169], v[210:213], v[48:51]
	v_mfma_f32_16x16x32_bf16 v[48:51], v[162:165], v[206:209], v[48:51]
	v_mfma_f32_16x16x32_bf16 v[32:35], v[162:165], v[214:217], v[32:35]
	v_mfma_f32_16x16x32_bf16 v[32:35], v[166:169], v[218:221], v[32:35]
	v_mfma_f32_16x16x32_bf16 v[24:27], v[174:177], v[218:221], v[24:27]
	v_mfma_f32_16x16x32_bf16 v[24:27], v[170:173], v[214:217], v[24:27]
	v_mfma_f32_16x16x32_bf16 v[8:11], v[170:173], v[222:225], v[8:11]
	v_mfma_f32_16x16x32_bf16 v[8:11], v[174:177], v[226:229], v[8:11]
	v_mfma_f32_16x16x32_bf16 v[16:19], v[166:169], v[226:229], v[16:19]
	v_mfma_f32_16x16x32_bf16 v[16:19], v[162:165], v[222:225], v[16:19]
	s_setprio 0
	s_setprio 1
	v_mfma_f32_16x16x32_bf16 v[52:55], v[178:181], v[198:201], v[52:55]
	v_mfma_f32_16x16x32_bf16 v[52:55], v[186:189], v[202:205], v[52:55]
	v_mfma_f32_16x16x32_bf16 v[44:47], v[194:197], v[202:205], v[44:47]
	v_mfma_f32_16x16x32_bf16 v[44:47], v[190:193], v[198:201], v[44:47]
	v_mfma_f32_16x16x32_bf16 v[28:31], v[190:193], v[206:209], v[28:31]
	v_mfma_f32_16x16x32_bf16 v[28:31], v[194:197], v[210:213], v[28:31]
	v_mfma_f32_16x16x32_bf16 v[36:39], v[186:189], v[210:213], v[36:39]
	v_mfma_f32_16x16x32_bf16 v[36:39], v[178:181], v[206:209], v[36:39]
	v_mfma_f32_16x16x32_bf16 v[20:23], v[178:181], v[214:217], v[20:23]
	v_mfma_f32_16x16x32_bf16 v[20:23], v[186:189], v[218:221], v[20:23]
	v_mfma_f32_16x16x32_bf16 v[12:15], v[194:197], v[218:221], v[12:15]
	v_mfma_f32_16x16x32_bf16 v[12:15], v[190:193], v[214:217], v[12:15]
	v_mfma_f32_16x16x32_bf16 v[0:3], v[190:193], v[222:225], v[0:3]
	v_mfma_f32_16x16x32_bf16 v[0:3], v[194:197], v[226:229], v[0:3]
	v_mfma_f32_16x16x32_bf16 v[4:7], v[186:189], v[226:229], v[4:7]
	v_mfma_f32_16x16x32_bf16 v[4:7], v[178:181], v[222:225], v[4:7]
	s_setprio 0
	s_barrier
	s_add_i32 s85, s85, 2
	s_add_u32 s83, s83, 0x100
	s_addc_u32 s84, s84, 0
	s_add_u32 s54, s54, 0x100
	s_addc_u32 s55, s55, 0
	s_branch .LBB0_875
.Lfa_8:
	v_add_u32_e32 v146, s73, v149
	ds_read_b128 v[162:165], v146
	v_xor_b32_e32 v253, 64, v146
	ds_read_b128 v[166:169], v253
	ds_read_b128 v[170:173], v146 offset:2048
	ds_read_b128 v[174:177], v253 offset:2048
	v_add_u32_e32 v146, s74, v149
	ds_read_b128 v[178:181], v146
	v_xor_b32_e32 v253, 64, v146
	ds_read_b128 v[186:189], v253
	ds_read_b128 v[190:193], v146 offset:2048
	ds_read_b128 v[194:197], v253 offset:2048
	s_add_u32 s58, s54, 0xfffc0080
	s_addc_u32 s59, s55, -1
	s_and_b64 s[56:57], s[56:57], exec
	s_cselect_b32 s59, s49, s59
	s_cselect_b32 s58, s80, s58
	s_cselect_b32 s57, s81, s84
	s_cselect_b32 s56, s82, s83
	v_lshl_add_u64 v[182:183], s[54:55], 0, v[138:139]
	s_add_i32 m0, s64, 0xc000
	ds_read_b128 v[198:201], v154
	v_xor_b32_e32 v253, 64, v154
	ds_read_b128 v[202:205], v253
	ds_read_b128 v[206:209], v154 offset:2048
	ds_read_b128 v[210:213], v253 offset:2048
	ds_read_b128 v[214:217], v154 offset:4096
	ds_read_b128 v[218:221], v253 offset:4096
	ds_read_b128 v[222:225], v154 offset:6144
	ds_read_b128 v[226:229], v253 offset:6144
	global_load_lds_dwordx4 v[182:183], off
	v_lshl_add_u64 v[182:183], s[54:55], 0, v[136:137]
	s_add_i32 m0, s64, 0xe000
	s_nop 0
	global_load_lds_dwordx4 v[182:183], off
	s_waitcnt vmcnt(8)
	s_waitcnt lgkmcnt(0)
	s_barrier
	s_setprio 1
	s_waitcnt lgkmcnt(0)
	v_mfma_f32_16x16x32_bf16 v[124:127], v[162:165], v[198:201], 0
	v_mfma_f32_16x16x32_bf16 v[120:123], v[170:173], v[198:201], 0
	v_mfma_f32_16x16x32_bf16 v[112:115], v[162:165], v[206:209], 0
	v_mfma_f32_16x16x32_bf16 v[104:107], v[170:173], v[206:209], 0
	v_mfma_f32_16x16x32_bf16 v[96:99], v[162:165], v[214:217], 0
	v_mfma_f32_16x16x32_bf16 v[88:91], v[170:173], v[214:217], 0
	v_mfma_f32_16x16x32_bf16 v[80:83], v[162:165], v[222:225], 0
	v_mfma_f32_16x16x32_bf16 v[72:75], v[170:173], v[222:225], 0
	v_mfma_f32_16x16x32_bf16 v[124:127], v[166:169], v[202:205], v[124:127]
	v_mfma_f32_16x16x32_bf16 v[120:123], v[174:177], v[202:205], v[120:123]
	v_mfma_f32_16x16x32_bf16 v[112:115], v[166:169], v[210:213], v[112:115]
	v_mfma_f32_16x16x32_bf16 v[104:107], v[174:177], v[210:213], v[104:107]
	v_mfma_f32_16x16x32_bf16 v[96:99], v[166:169], v[218:221], v[96:99]
	v_mfma_f32_16x16x32_bf16 v[88:91], v[174:177], v[218:221], v[88:91]
	v_mfma_f32_16x16x32_bf16 v[80:83], v[166:169], v[226:229], v[80:83]
	v_mfma_f32_16x16x32_bf16 v[72:75], v[174:177], v[226:229], v[72:75]
	s_setprio 0
	s_setprio 1
	v_mfma_f32_16x16x32_bf16 v[116:119], v[178:181], v[198:201], 0
	v_mfma_f32_16x16x32_bf16 v[108:111], v[190:193], v[198:201], 0
	v_mfma_f32_16x16x32_bf16 v[100:103], v[178:181], v[206:209], 0
	v_mfma_f32_16x16x32_bf16 v[92:95], v[190:193], v[206:209], 0
	v_mfma_f32_16x16x32_bf16 v[84:87], v[178:181], v[214:217], 0
	v_mfma_f32_16x16x32_bf16 v[76:79], v[190:193], v[214:217], 0
	v_mfma_f32_16x16x32_bf16 v[68:71], v[178:181], v[222:225], 0
	v_mfma_f32_16x16x32_bf16 v[64:67], v[190:193], v[222:225], 0
	v_mfma_f32_16x16x32_bf16 v[116:119], v[186:189], v[202:205], v[116:119]
	v_mfma_f32_16x16x32_bf16 v[108:111], v[194:197], v[202:205], v[108:111]
	v_mfma_f32_16x16x32_bf16 v[100:103], v[186:189], v[210:213], v[100:103]
	v_mfma_f32_16x16x32_bf16 v[92:95], v[194:197], v[210:213], v[92:95]
	v_mfma_f32_16x16x32_bf16 v[84:87], v[186:189], v[218:221], v[84:87]
	v_mfma_f32_16x16x32_bf16 v[76:79], v[194:197], v[218:221], v[76:79]
	v_mfma_f32_16x16x32_bf16 v[68:71], v[186:189], v[226:229], v[68:71]
	v_mfma_f32_16x16x32_bf16 v[64:67], v[194:197], v[226:229], v[64:67]
	s_setprio 0
	s_barrier
	s_add_i32 s86, s73, s63
	v_lshl_add_u64 v[182:183], s[56:57], 0, v[130:131]
	s_mov_b32 m0, s86
	ds_read_b128 v[198:201], v154 offset:16384
	v_xor_b32_e32 v253, 64, v154
	ds_read_b128 v[202:205], v253 offset:16384
	ds_read_b128 v[206:209], v154 offset:18432
	ds_read_b128 v[210:213], v253 offset:18432
	ds_read_b128 v[214:217], v154 offset:20480
	ds_read_b128 v[218:221], v253 offset:20480
	ds_read_b128 v[222:225], v154 offset:22528
	ds_read_b128 v[226:229], v253 offset:22528
	global_load_lds_dwordx4 v[182:183], off
	s_add_i32 m0, s86, 0x2000
	s_add_u32 s86, s56, 0x40000
	v_lshl_add_u64 v[230:231], s[56:57], 0, v[134:135]
	s_addc_u32 s87, s57, 0
	s_add_i32 s88, s74, s63
	global_load_lds_dwordx4 v[230:231], off
	v_lshl_add_u64 v[232:233], s[86:87], 0, v[130:131]
	s_mov_b32 m0, s88
	v_lshl_add_u64 v[234:235], s[58:59], 0, v[132:133]
	global_load_lds_dwordx4 v[232:233], off
	v_lshl_add_u64 v[232:233], s[86:87], 0, v[134:135]
	s_add_i32 m0, s88, 0x2000
	s_nop 0
	global_load_lds_dwordx4 v[232:233], off
	v_lshl_add_u64 v[232:233], s[58:59], 0, v[128:129]
	s_mov_b32 m0, s64
	s_nop 0
	global_load_lds_dwordx4 v[232:233], off
	s_mov_b32 m0, s65
	s_nop 0
	global_load_lds_dwordx4 v[234:235], off
	s_waitcnt vmcnt(8)
	s_waitcnt lgkmcnt(0)
	s_barrier
	s_setprio 1
	s_waitcnt lgkmcnt(0)
	v_mfma_f32_16x16x32_bf16 v[60:63], v[162:165], v[198:201], 0
	v_mfma_f32_16x16x32_bf16 v[56:59], v[170:173], v[198:201], 0
	v_mfma_f32_16x16x32_bf16 v[48:51], v[162:165], v[206:209], 0
	v_mfma_f32_16x16x32_bf16 v[40:43], v[170:173], v[206:209], 0
	v_mfma_f32_16x16x32_bf16 v[32:35], v[162:165], v[214:217], 0
	v_mfma_f32_16x16x32_bf16 v[24:27], v[170:173], v[214:217], 0
	v_mfma_f32_16x16x32_bf16 v[16:19], v[162:165], v[222:225], 0
	v_mfma_f32_16x16x32_bf16 v[8:11], v[170:173], v[222:225], 0
	v_mfma_f32_16x16x32_bf16 v[60:63], v[166:169], v[202:205], v[60:63]
	v_mfma_f32_16x16x32_bf16 v[56:59], v[174:177], v[202:205], v[56:59]
	v_mfma_f32_16x16x32_bf16 v[48:51], v[166:169], v[210:213], v[48:51]
	v_mfma_f32_16x16x32_bf16 v[40:43], v[174:177], v[210:213], v[40:43]
	v_mfma_f32_16x16x32_bf16 v[32:35], v[166:169], v[218:221], v[32:35]
	v_mfma_f32_16x16x32_bf16 v[24:27], v[174:177], v[218:221], v[24:27]
	v_mfma_f32_16x16x32_bf16 v[16:19], v[166:169], v[226:229], v[16:19]
	v_mfma_f32_16x16x32_bf16 v[8:11], v[174:177], v[226:229], v[8:11]
	s_setprio 0
	s_setprio 1
	v_mfma_f32_16x16x32_bf16 v[52:55], v[178:181], v[198:201], 0
	v_mfma_f32_16x16x32_bf16 v[44:47], v[190:193], v[198:201], 0
	v_mfma_f32_16x16x32_bf16 v[36:39], v[178:181], v[206:209], 0
	v_mfma_f32_16x16x32_bf16 v[28:31], v[190:193], v[206:209], 0
	v_mfma_f32_16x16x32_bf16 v[20:23], v[178:181], v[214:217], 0
	v_mfma_f32_16x16x32_bf16 v[12:15], v[190:193], v[214:217], 0
	v_mfma_f32_16x16x32_bf16 v[4:7], v[178:181], v[222:225], 0
	v_mfma_f32_16x16x32_bf16 v[0:3], v[190:193], v[222:225], 0
	v_mfma_f32_16x16x32_bf16 v[52:55], v[186:189], v[202:205], v[52:55]
	v_mfma_f32_16x16x32_bf16 v[44:47], v[194:197], v[202:205], v[44:47]
	v_mfma_f32_16x16x32_bf16 v[36:39], v[186:189], v[210:213], v[36:39]
	v_mfma_f32_16x16x32_bf16 v[28:31], v[194:197], v[210:213], v[28:31]
	v_mfma_f32_16x16x32_bf16 v[20:23], v[186:189], v[218:221], v[20:23]
	v_mfma_f32_16x16x32_bf16 v[12:15], v[194:197], v[218:221], v[12:15]
	v_mfma_f32_16x16x32_bf16 v[4:7], v[186:189], v[226:229], v[4:7]
	v_mfma_f32_16x16x32_bf16 v[0:3], v[194:197], v[226:229], v[0:3]
	s_setprio 0
	s_barrier
	s_add_i32 s86, 0, 0x18000
	v_add_u32_e32 v146, s86, v149
	s_add_i32 s87, 0, 0x1c000
	ds_read_b128 v[162:165], v146
	v_xor_b32_e32 v253, 64, v146
	ds_read_b128 v[166:169], v253
	ds_read_b128 v[170:173], v146 offset:2048
	ds_read_b128 v[174:177], v253 offset:2048
	v_add_u32_e32 v146, s87, v149
	ds_read_b128 v[178:181], v146
	v_xor_b32_e32 v253, 64, v146
	ds_read_b128 v[186:189], v253
	ds_read_b128 v[190:193], v146 offset:2048
	ds_read_b128 v[194:197], v253 offset:2048
	s_add_u32 s58, s58, 0x40000
	s_addc_u32 s59, s59, 0
	s_mov_b32 m0, s66
	v_lshl_add_u64 v[236:237], s[58:59], 0, v[128:129]
	ds_read_b128 v[198:201], v154 offset:32768
	v_xor_b32_e32 v253, 64, v154
	ds_read_b128 v[202:205], v253 offset:32768
	ds_read_b128 v[206:209], v154 offset:34816
	ds_read_b128 v[210:213], v253 offset:34816
	ds_read_b128 v[214:217], v154 offset:36864
	ds_read_b128 v[218:221], v253 offset:36864
	ds_read_b128 v[222:225], v154 offset:38912
	ds_read_b128 v[226:229], v253 offset:38912
	global_load_lds_dwordx4 v[236:237], off
	v_lshl_add_u64 v[236:237], s[58:59], 0, v[132:133]
	s_mov_b32 m0, s67
	s_nop 0
	global_load_lds_dwordx4 v[236:237], off
	s_waitcnt vmcnt(8)
	s_waitcnt lgkmcnt(0)
	s_barrier
	s_setprio 1
	s_waitcnt lgkmcnt(0)
	v_mfma_f32_16x16x32_bf16 v[124:127], v[162:165], v[198:201], v[124:127]
	v_mfma_f32_16x16x32_bf16 v[124:127], v[166:169], v[202:205], v[124:127]
	v_mfma_f32_16x16x32_bf16 v[120:123], v[174:177], v[202:205], v[120:123]
	v_mfma_f32_16x16x32_bf16 v[120:123], v[170:173], v[198:201], v[120:123]
	v_mfma_f32_16x16x32_bf16 v[104:107], v[170:173], v[206:209], v[104:107]
	v_mfma_f32_16x16x32_bf16 v[104:107], v[174:177], v[210:213], v[104:107]
	v_mfma_f32_16x16x32_bf16 v[112:115], v[166:169], v[210:213], v[112:115]
	v_mfma_f32_16x16x32_bf16 v[112:115], v[162:165], v[206:209], v[112:115]
	v_mfma_f32_16x16x32_bf16 v[96:99], v[162:165], v[214:217], v[96:99]
	v_mfma_f32_16x16x32_bf16 v[96:99], v[166:169], v[218:221], v[96:99]
	v_mfma_f32_16x16x32_bf16 v[88:91], v[174:177], v[218:221], v[88:91]
	v_mfma_f32_16x16x32_bf16 v[88:91], v[170:173], v[214:217], v[88:91]
	v_mfma_f32_16x16x32_bf16 v[72:75], v[170:173], v[222:225], v[72:75]
	v_mfma_f32_16x16x32_bf16 v[72:75], v[174:177], v[226:229], v[72:75]
	v_mfma_f32_16x16x32_bf16 v[80:83], v[166:169], v[226:229], v[80:83]
	v_mfma_f32_16x16x32_bf16 v[80:83], v[162:165], v[222:225], v[80:83]
	s_setprio 0
	s_setprio 1
	v_mfma_f32_16x16x32_bf16 v[116:119], v[178:181], v[198:201], v[116:119]
	v_mfma_f32_16x16x32_bf16 v[116:119], v[186:189], v[202:205], v[116:119]
	v_mfma_f32_16x16x32_bf16 v[108:111], v[194:197], v[202:205], v[108:111]
	v_mfma_f32_16x16x32_bf16 v[108:111], v[190:193], v[198:201], v[108:111]
	v_mfma_f32_16x16x32_bf16 v[92:95], v[190:193], v[206:209], v[92:95]
	v_mfma_f32_16x16x32_bf16 v[92:95], v[194:197], v[210:213], v[92:95]
	v_mfma_f32_16x16x32_bf16 v[100:103], v[186:189], v[210:213], v[100:103]
	v_mfma_f32_16x16x32_bf16 v[100:103], v[178:181], v[206:209], v[100:103]
	v_mfma_f32_16x16x32_bf16 v[84:87], v[178:181], v[214:217], v[84:87]
	v_mfma_f32_16x16x32_bf16 v[84:87], v[186:189], v[218:221], v[84:87]
	v_mfma_f32_16x16x32_bf16 v[76:79], v[194:197], v[218:221], v[76:79]
	v_mfma_f32_16x16x32_bf16 v[76:79], v[190:193], v[214:217], v[76:79]
	v_mfma_f32_16x16x32_bf16 v[64:67], v[190:193], v[222:225], v[64:67]
	v_mfma_f32_16x16x32_bf16 v[64:67], v[194:197], v[226:229], v[64:67]
	v_mfma_f32_16x16x32_bf16 v[68:71], v[186:189], v[226:229], v[68:71]
	v_mfma_f32_16x16x32_bf16 v[68:71], v[178:181], v[222:225], v[68:71]
	s_setprio 0
	s_barrier
	s_add_i32 s58, s86, s63
	v_lshl_add_u64 v[182:183], v[182:183], 0, s[22:23]
	s_mov_b32 m0, s58
	ds_read_b128 v[198:201], v154 offset:49152
	v_xor_b32_e32 v253, 64, v154
	ds_read_b128 v[202:205], v253 offset:49152
	ds_read_b128 v[206:209], v154 offset:51200
	ds_read_b128 v[210:213], v253 offset:51200
	ds_read_b128 v[214:217], v154 offset:53248
	ds_read_b128 v[218:221], v253 offset:53248
	ds_read_b128 v[222:225], v154 offset:55296
	ds_read_b128 v[226:229], v253 offset:55296
	global_load_lds_dwordx4 v[182:183], off
	s_add_i32 m0, s58, 0x2000
	s_add_u32 s56, s56, 0x40080
	v_lshl_add_u64 v[182:183], v[230:231], 0, s[22:23]
	s_addc_u32 s57, s57, 0
	s_add_i32 s58, s87, s63
	global_load_lds_dwordx4 v[182:183], off
	v_lshl_add_u64 v[182:183], s[56:57], 0, v[130:131]
	s_mov_b32 m0, s58
	s_nop 0
	global_load_lds_dwordx4 v[182:183], off
	v_lshl_add_u64 v[182:183], s[56:57], 0, v[134:135]
	s_add_i32 m0, s58, 0x2000
	s_nop 0
	global_load_lds_dwordx4 v[182:183], off
	v_lshl_add_u64 v[182:183], v[232:233], 0, s[22:23]
	s_mov_b32 m0, s69
	s_nop 0
	global_load_lds_dwordx4 v[182:183], off
	v_lshl_add_u64 v[182:183], v[234:235], 0, s[22:23]
	s_mov_b32 m0, s70
	s_nop 0
	global_load_lds_dwordx4 v[182:183], off
	s_waitcnt vmcnt(8)
	s_waitcnt lgkmcnt(0)
	s_barrier
	s_setprio 1
	s_waitcnt lgkmcnt(0)
	v_mfma_f32_16x16x32_bf16 v[60:63], v[162:165], v[198:201], v[60:63]
	v_mfma_f32_16x16x32_bf16 v[60:63], v[166:169], v[202:205], v[60:63]
	v_mfma_f32_16x16x32_bf16 v[56:59], v[174:177], v[202:205], v[56:59]
	v_mfma_f32_16x16x32_bf16 v[56:59], v[170:173], v[198:201], v[56:59]
	v_mfma_f32_16x16x32_bf16 v[40:43], v[170:173], v[206:209], v[40:43]
	v_mfma_f32_16x16x32_bf16 v[40:43], v[174:177], v[210:213], v[40:43]
	v_mfma_f32_16x16x32_bf16 v[48:51], v[166:169], v[210:213], v[48:51]
	v_mfma_f32_16x16x32_bf16 v[48:51], v[162:165], v[206:209], v[48:51]
	v_mfma_f32_16x16x32_bf16 v[32:35], v[162:165], v[214:217], v[32:35]
	v_mfma_f32_16x16x32_bf16 v[32:35], v[166:169], v[218:221], v[32:35]
	v_mfma_f32_16x16x32_bf16 v[24:27], v[174:177], v[218:221], v[24:27]
	v_mfma_f32_16x16x32_bf16 v[24:27], v[170:173], v[214:217], v[24:27]
	v_mfma_f32_16x16x32_bf16 v[8:11], v[170:173], v[222:225], v[8:11]
	v_mfma_f32_16x16x32_bf16 v[8:11], v[174:177], v[226:229], v[8:11]
	v_mfma_f32_16x16x32_bf16 v[16:19], v[166:169], v[226:229], v[16:19]
	v_mfma_f32_16x16x32_bf16 v[16:19], v[162:165], v[222:225], v[16:19]
	s_setprio 0
	s_setprio 1
	v_mfma_f32_16x16x32_bf16 v[52:55], v[178:181], v[198:201], v[52:55]
	v_mfma_f32_16x16x32_bf16 v[52:55], v[186:189], v[202:205], v[52:55]
	v_mfma_f32_16x16x32_bf16 v[44:47], v[194:197], v[202:205], v[44:47]
	v_mfma_f32_16x16x32_bf16 v[44:47], v[190:193], v[198:201], v[44:47]
	v_mfma_f32_16x16x32_bf16 v[28:31], v[190:193], v[206:209], v[28:31]
	v_mfma_f32_16x16x32_bf16 v[28:31], v[194:197], v[210:213], v[28:31]
	v_mfma_f32_16x16x32_bf16 v[36:39], v[186:189], v[210:213], v[36:39]
	v_mfma_f32_16x16x32_bf16 v[36:39], v[178:181], v[206:209], v[36:39]
	v_mfma_f32_16x16x32_bf16 v[20:23], v[178:181], v[214:217], v[20:23]
	v_mfma_f32_16x16x32_bf16 v[20:23], v[186:189], v[218:221], v[20:23]
	v_mfma_f32_16x16x32_bf16 v[12:15], v[194:197], v[218:221], v[12:15]
	v_mfma_f32_16x16x32_bf16 v[12:15], v[190:193], v[214:217], v[12:15]
	v_mfma_f32_16x16x32_bf16 v[0:3], v[190:193], v[222:225], v[0:3]
	v_mfma_f32_16x16x32_bf16 v[0:3], v[194:197], v[226:229], v[0:3]
	v_mfma_f32_16x16x32_bf16 v[4:7], v[186:189], v[226:229], v[4:7]
	v_mfma_f32_16x16x32_bf16 v[4:7], v[178:181], v[222:225], v[4:7]
	s_setprio 0
	s_barrier
	s_add_i32 s85, s85, 2
	s_add_u32 s83, s83, 0x100
	s_addc_u32 s84, s84, 0
	s_add_u32 s54, s54, 0x100
	s_addc_u32 s55, s55, 0
	s_branch .LBB0_875
.LBB0_874:
	v_add_u32_e32 v146, s73, v149
	ds_read_b128 v[162:165], v146
	v_xor_b32_e32 v253, 64, v146
	ds_read_b128 v[166:169], v253
	ds_read_b128 v[170:173], v146 offset:2048
	ds_read_b128 v[174:177], v253 offset:2048
	v_add_u32_e32 v146, s74, v149
	ds_read_b128 v[178:181], v146
	v_xor_b32_e32 v253, 64, v146
	ds_read_b128 v[186:189], v253
	ds_read_b128 v[190:193], v146 offset:2048
	ds_read_b128 v[194:197], v253 offset:2048
	s_add_u32 s58, s54, 0xfffc0080
	s_addc_u32 s59, s55, -1
	s_and_b64 s[56:57], s[56:57], exec
	s_cselect_b32 s59, s49, s59
	s_cselect_b32 s58, s80, s58
	s_cselect_b32 s57, s81, s84
	s_cselect_b32 s56, s82, s83
	v_lshl_add_u64 v[182:183], s[54:55], 0, v[138:139]
	s_add_i32 m0, s64, 0xc000
	ds_read_b128 v[198:201], v154
	v_xor_b32_e32 v253, 64, v154
	ds_read_b128 v[202:205], v253
	ds_read_b128 v[206:209], v154 offset:2048
	ds_read_b128 v[210:213], v253 offset:2048
	ds_read_b128 v[214:217], v154 offset:4096
	ds_read_b128 v[218:221], v253 offset:4096
	ds_read_b128 v[222:225], v154 offset:6144
	ds_read_b128 v[226:229], v253 offset:6144
	global_load_lds_dwordx4 v[182:183], off
	v_lshl_add_u64 v[182:183], s[54:55], 0, v[136:137]
	s_add_i32 m0, s64, 0xe000
	s_nop 0
	global_load_lds_dwordx4 v[182:183], off
	s_waitcnt vmcnt(8)
	s_waitcnt lgkmcnt(0)
	s_barrier
	s_setprio 1
	s_waitcnt lgkmcnt(0)
	v_mfma_f32_16x16x32_bf16 v[124:127], v[162:165], v[198:201], v[124:127]
	v_mfma_f32_16x16x32_bf16 v[124:127], v[166:169], v[202:205], v[124:127]
	v_mfma_f32_16x16x32_bf16 v[120:123], v[174:177], v[202:205], v[120:123]
	v_mfma_f32_16x16x32_bf16 v[120:123], v[170:173], v[198:201], v[120:123]
	v_mfma_f32_16x16x32_bf16 v[104:107], v[170:173], v[206:209], v[104:107]
	v_mfma_f32_16x16x32_bf16 v[104:107], v[174:177], v[210:213], v[104:107]
	v_mfma_f32_16x16x32_bf16 v[112:115], v[166:169], v[210:213], v[112:115]
	v_mfma_f32_16x16x32_bf16 v[112:115], v[162:165], v[206:209], v[112:115]
	v_mfma_f32_16x16x32_bf16 v[96:99], v[162:165], v[214:217], v[96:99]
	v_mfma_f32_16x16x32_bf16 v[96:99], v[166:169], v[218:221], v[96:99]
	v_mfma_f32_16x16x32_bf16 v[88:91], v[174:177], v[218:221], v[88:91]
	v_mfma_f32_16x16x32_bf16 v[88:91], v[170:173], v[214:217], v[88:91]
	v_mfma_f32_16x16x32_bf16 v[72:75], v[170:173], v[222:225], v[72:75]
	v_mfma_f32_16x16x32_bf16 v[72:75], v[174:177], v[226:229], v[72:75]
	v_mfma_f32_16x16x32_bf16 v[80:83], v[166:169], v[226:229], v[80:83]
	v_mfma_f32_16x16x32_bf16 v[80:83], v[162:165], v[222:225], v[80:83]
	s_setprio 0
	s_setprio 1
	v_mfma_f32_16x16x32_bf16 v[116:119], v[178:181], v[198:201], v[116:119]
	v_mfma_f32_16x16x32_bf16 v[116:119], v[186:189], v[202:205], v[116:119]
	v_mfma_f32_16x16x32_bf16 v[108:111], v[194:197], v[202:205], v[108:111]
	v_mfma_f32_16x16x32_bf16 v[108:111], v[190:193], v[198:201], v[108:111]
	v_mfma_f32_16x16x32_bf16 v[92:95], v[190:193], v[206:209], v[92:95]
	v_mfma_f32_16x16x32_bf16 v[92:95], v[194:197], v[210:213], v[92:95]
	v_mfma_f32_16x16x32_bf16 v[100:103], v[186:189], v[210:213], v[100:103]
	v_mfma_f32_16x16x32_bf16 v[100:103], v[178:181], v[206:209], v[100:103]
	v_mfma_f32_16x16x32_bf16 v[84:87], v[178:181], v[214:217], v[84:87]
	v_mfma_f32_16x16x32_bf16 v[84:87], v[186:189], v[218:221], v[84:87]
	v_mfma_f32_16x16x32_bf16 v[76:79], v[194:197], v[218:221], v[76:79]
	v_mfma_f32_16x16x32_bf16 v[76:79], v[190:193], v[214:217], v[76:79]
	v_mfma_f32_16x16x32_bf16 v[64:67], v[190:193], v[222:225], v[64:67]
	v_mfma_f32_16x16x32_bf16 v[64:67], v[194:197], v[226:229], v[64:67]
	v_mfma_f32_16x16x32_bf16 v[68:71], v[186:189], v[226:229], v[68:71]
	v_mfma_f32_16x16x32_bf16 v[68:71], v[178:181], v[222:225], v[68:71]
	s_setprio 0
	s_barrier
	s_add_i32 s86, s73, s63
	v_lshl_add_u64 v[182:183], s[56:57], 0, v[130:131]
	s_mov_b32 m0, s86
	ds_read_b128 v[198:201], v154 offset:16384
	v_xor_b32_e32 v253, 64, v154
	ds_read_b128 v[202:205], v253 offset:16384
	ds_read_b128 v[206:209], v154 offset:18432
	ds_read_b128 v[210:213], v253 offset:18432
	ds_read_b128 v[214:217], v154 offset:20480
	ds_read_b128 v[218:221], v253 offset:20480
	ds_read_b128 v[222:225], v154 offset:22528
	ds_read_b128 v[226:229], v253 offset:22528
	global_load_lds_dwordx4 v[182:183], off
	s_add_i32 m0, s86, 0x2000
	s_add_u32 s86, s56, 0x40000
	v_lshl_add_u64 v[230:231], s[56:57], 0, v[134:135]
	s_addc_u32 s87, s57, 0
	s_add_i32 s88, s74, s63
	global_load_lds_dwordx4 v[230:231], off
	v_lshl_add_u64 v[232:233], s[86:87], 0, v[130:131]
	s_mov_b32 m0, s88
	v_lshl_add_u64 v[234:235], s[58:59], 0, v[132:133]
	global_load_lds_dwordx4 v[232:233], off
	v_lshl_add_u64 v[232:233], s[86:87], 0, v[134:135]
	s_add_i32 m0, s88, 0x2000
	s_nop 0
	global_load_lds_dwordx4 v[232:233], off
	v_lshl_add_u64 v[232:233], s[58:59], 0, v[128:129]
	s_mov_b32 m0, s64
	s_nop 0
	global_load_lds_dwordx4 v[232:233], off
	s_mov_b32 m0, s65
	s_nop 0
	global_load_lds_dwordx4 v[234:235], off
	s_waitcnt vmcnt(8)
	s_waitcnt lgkmcnt(0)
	s_barrier
	s_setprio 1
	s_waitcnt lgkmcnt(0)
	v_mfma_f32_16x16x32_bf16 v[60:63], v[162:165], v[198:201], v[60:63]
	v_mfma_f32_16x16x32_bf16 v[60:63], v[166:169], v[202:205], v[60:63]
	v_mfma_f32_16x16x32_bf16 v[56:59], v[174:177], v[202:205], v[56:59]
	v_mfma_f32_16x16x32_bf16 v[56:59], v[170:173], v[198:201], v[56:59]
	v_mfma_f32_16x16x32_bf16 v[40:43], v[170:173], v[206:209], v[40:43]
	v_mfma_f32_16x16x32_bf16 v[40:43], v[174:177], v[210:213], v[40:43]
	v_mfma_f32_16x16x32_bf16 v[48:51], v[166:169], v[210:213], v[48:51]
	v_mfma_f32_16x16x32_bf16 v[48:51], v[162:165], v[206:209], v[48:51]
	v_mfma_f32_16x16x32_bf16 v[32:35], v[162:165], v[214:217], v[32:35]
	v_mfma_f32_16x16x32_bf16 v[32:35], v[166:169], v[218:221], v[32:35]
	v_mfma_f32_16x16x32_bf16 v[24:27], v[174:177], v[218:221], v[24:27]
	v_mfma_f32_16x16x32_bf16 v[24:27], v[170:173], v[214:217], v[24:27]
	v_mfma_f32_16x16x32_bf16 v[8:11], v[170:173], v[222:225], v[8:11]
	v_mfma_f32_16x16x32_bf16 v[8:11], v[174:177], v[226:229], v[8:11]
	v_mfma_f32_16x16x32_bf16 v[16:19], v[166:169], v[226:229], v[16:19]
	v_mfma_f32_16x16x32_bf16 v[16:19], v[162:165], v[222:225], v[16:19]
	s_setprio 0
	s_setprio 1
	v_mfma_f32_16x16x32_bf16 v[52:55], v[178:181], v[198:201], v[52:55]
	v_mfma_f32_16x16x32_bf16 v[52:55], v[186:189], v[202:205], v[52:55]
	v_mfma_f32_16x16x32_bf16 v[44:47], v[194:197], v[202:205], v[44:47]
	v_mfma_f32_16x16x32_bf16 v[44:47], v[190:193], v[198:201], v[44:47]
	v_mfma_f32_16x16x32_bf16 v[28:31], v[190:193], v[206:209], v[28:31]
	v_mfma_f32_16x16x32_bf16 v[28:31], v[194:197], v[210:213], v[28:31]
	v_mfma_f32_16x16x32_bf16 v[36:39], v[186:189], v[210:213], v[36:39]
	v_mfma_f32_16x16x32_bf16 v[36:39], v[178:181], v[206:209], v[36:39]
	v_mfma_f32_16x16x32_bf16 v[20:23], v[178:181], v[214:217], v[20:23]
	v_mfma_f32_16x16x32_bf16 v[20:23], v[186:189], v[218:221], v[20:23]
	v_mfma_f32_16x16x32_bf16 v[12:15], v[194:197], v[218:221], v[12:15]
	v_mfma_f32_16x16x32_bf16 v[12:15], v[190:193], v[214:217], v[12:15]
	v_mfma_f32_16x16x32_bf16 v[0:3], v[190:193], v[222:225], v[0:3]
	v_mfma_f32_16x16x32_bf16 v[0:3], v[194:197], v[226:229], v[0:3]
	v_mfma_f32_16x16x32_bf16 v[4:7], v[186:189], v[226:229], v[4:7]
	v_mfma_f32_16x16x32_bf16 v[4:7], v[178:181], v[222:225], v[4:7]
	s_setprio 0
	s_barrier
	s_add_i32 s86, 0, 0x18000
	v_add_u32_e32 v146, s86, v149
	s_add_i32 s87, 0, 0x1c000
	ds_read_b128 v[162:165], v146
	v_xor_b32_e32 v253, 64, v146
	ds_read_b128 v[166:169], v253
	ds_read_b128 v[170:173], v146 offset:2048
	ds_read_b128 v[174:177], v253 offset:2048
	v_add_u32_e32 v146, s87, v149
	ds_read_b128 v[178:181], v146
	v_xor_b32_e32 v253, 64, v146
	ds_read_b128 v[186:189], v253
	ds_read_b128 v[190:193], v146 offset:2048
	ds_read_b128 v[194:197], v253 offset:2048
	s_add_u32 s58, s58, 0x40000
	s_addc_u32 s59, s59, 0
	s_mov_b32 m0, s66
	v_lshl_add_u64 v[236:237], s[58:59], 0, v[128:129]
	ds_read_b128 v[198:201], v154 offset:32768
	v_xor_b32_e32 v253, 64, v154
	ds_read_b128 v[202:205], v253 offset:32768
	ds_read_b128 v[206:209], v154 offset:34816
	ds_read_b128 v[210:213], v253 offset:34816
	ds_read_b128 v[214:217], v154 offset:36864
	ds_read_b128 v[218:221], v253 offset:36864
	ds_read_b128 v[222:225], v154 offset:38912
	ds_read_b128 v[226:229], v253 offset:38912
	global_load_lds_dwordx4 v[236:237], off
	v_lshl_add_u64 v[236:237], s[58:59], 0, v[132:133]
	s_mov_b32 m0, s67
	s_nop 0
	global_load_lds_dwordx4 v[236:237], off
	s_waitcnt vmcnt(8)
	s_waitcnt lgkmcnt(0)
	s_barrier
	s_setprio 1
	s_waitcnt lgkmcnt(0)
	v_mfma_f32_16x16x32_bf16 v[124:127], v[162:165], v[198:201], v[124:127]
	v_mfma_f32_16x16x32_bf16 v[124:127], v[166:169], v[202:205], v[124:127]
	v_mfma_f32_16x16x32_bf16 v[120:123], v[174:177], v[202:205], v[120:123]
	v_mfma_f32_16x16x32_bf16 v[120:123], v[170:173], v[198:201], v[120:123]
	v_mfma_f32_16x16x32_bf16 v[104:107], v[170:173], v[206:209], v[104:107]
	v_mfma_f32_16x16x32_bf16 v[104:107], v[174:177], v[210:213], v[104:107]
	v_mfma_f32_16x16x32_bf16 v[112:115], v[166:169], v[210:213], v[112:115]
	v_mfma_f32_16x16x32_bf16 v[112:115], v[162:165], v[206:209], v[112:115]
	v_mfma_f32_16x16x32_bf16 v[96:99], v[162:165], v[214:217], v[96:99]
	v_mfma_f32_16x16x32_bf16 v[96:99], v[166:169], v[218:221], v[96:99]
	v_mfma_f32_16x16x32_bf16 v[88:91], v[174:177], v[218:221], v[88:91]
	v_mfma_f32_16x16x32_bf16 v[88:91], v[170:173], v[214:217], v[88:91]
	v_mfma_f32_16x16x32_bf16 v[72:75], v[170:173], v[222:225], v[72:75]
	v_mfma_f32_16x16x32_bf16 v[72:75], v[174:177], v[226:229], v[72:75]
	v_mfma_f32_16x16x32_bf16 v[80:83], v[166:169], v[226:229], v[80:83]
	v_mfma_f32_16x16x32_bf16 v[80:83], v[162:165], v[222:225], v[80:83]
	s_setprio 0
	s_setprio 1
	v_mfma_f32_16x16x32_bf16 v[116:119], v[178:181], v[198:201], v[116:119]
	v_mfma_f32_16x16x32_bf16 v[116:119], v[186:189], v[202:205], v[116:119]
	v_mfma_f32_16x16x32_bf16 v[108:111], v[194:197], v[202:205], v[108:111]
	v_mfma_f32_16x16x32_bf16 v[108:111], v[190:193], v[198:201], v[108:111]
	v_mfma_f32_16x16x32_bf16 v[92:95], v[190:193], v[206:209], v[92:95]
	v_mfma_f32_16x16x32_bf16 v[92:95], v[194:197], v[210:213], v[92:95]
	v_mfma_f32_16x16x32_bf16 v[100:103], v[186:189], v[210:213], v[100:103]
	v_mfma_f32_16x16x32_bf16 v[100:103], v[178:181], v[206:209], v[100:103]
	v_mfma_f32_16x16x32_bf16 v[84:87], v[178:181], v[214:217], v[84:87]
	v_mfma_f32_16x16x32_bf16 v[84:87], v[186:189], v[218:221], v[84:87]
	v_mfma_f32_16x16x32_bf16 v[76:79], v[194:197], v[218:221], v[76:79]
	v_mfma_f32_16x16x32_bf16 v[76:79], v[190:193], v[214:217], v[76:79]
	v_mfma_f32_16x16x32_bf16 v[64:67], v[190:193], v[222:225], v[64:67]
	v_mfma_f32_16x16x32_bf16 v[64:67], v[194:197], v[226:229], v[64:67]
	v_mfma_f32_16x16x32_bf16 v[68:71], v[186:189], v[226:229], v[68:71]
	v_mfma_f32_16x16x32_bf16 v[68:71], v[178:181], v[222:225], v[68:71]
	s_setprio 0
	s_barrier
	s_add_i32 s58, s86, s63
	v_lshl_add_u64 v[182:183], v[182:183], 0, s[22:23]
	s_mov_b32 m0, s58
	ds_read_b128 v[198:201], v154 offset:49152
	v_xor_b32_e32 v253, 64, v154
	ds_read_b128 v[202:205], v253 offset:49152
	ds_read_b128 v[206:209], v154 offset:51200
	ds_read_b128 v[210:213], v253 offset:51200
	ds_read_b128 v[214:217], v154 offset:53248
	ds_read_b128 v[218:221], v253 offset:53248
	ds_read_b128 v[222:225], v154 offset:55296
	ds_read_b128 v[226:229], v253 offset:55296
	global_load_lds_dwordx4 v[182:183], off
	s_add_i32 m0, s58, 0x2000
	s_add_u32 s56, s56, 0x40080
	v_lshl_add_u64 v[182:183], v[230:231], 0, s[22:23]
	s_addc_u32 s57, s57, 0
	s_add_i32 s58, s87, s63
	global_load_lds_dwordx4 v[182:183], off
	v_lshl_add_u64 v[182:183], s[56:57], 0, v[130:131]
	s_mov_b32 m0, s58
	s_nop 0
	global_load_lds_dwordx4 v[182:183], off
	v_lshl_add_u64 v[182:183], s[56:57], 0, v[134:135]
	s_add_i32 m0, s58, 0x2000
	s_nop 0
	global_load_lds_dwordx4 v[182:183], off
	v_lshl_add_u64 v[182:183], v[232:233], 0, s[22:23]
	s_mov_b32 m0, s69
	s_nop 0
	global_load_lds_dwordx4 v[182:183], off
	v_lshl_add_u64 v[182:183], v[234:235], 0, s[22:23]
	s_mov_b32 m0, s70
	s_nop 0
	global_load_lds_dwordx4 v[182:183], off
	s_waitcnt vmcnt(8)
	s_waitcnt lgkmcnt(0)
	s_barrier
	s_setprio 1
	s_waitcnt lgkmcnt(0)
	v_mfma_f32_16x16x32_bf16 v[60:63], v[162:165], v[198:201], v[60:63]
	v_mfma_f32_16x16x32_bf16 v[60:63], v[166:169], v[202:205], v[60:63]
	v_mfma_f32_16x16x32_bf16 v[56:59], v[174:177], v[202:205], v[56:59]
	v_mfma_f32_16x16x32_bf16 v[56:59], v[170:173], v[198:201], v[56:59]
	v_mfma_f32_16x16x32_bf16 v[40:43], v[170:173], v[206:209], v[40:43]
	v_mfma_f32_16x16x32_bf16 v[40:43], v[174:177], v[210:213], v[40:43]
	v_mfma_f32_16x16x32_bf16 v[48:51], v[166:169], v[210:213], v[48:51]
	v_mfma_f32_16x16x32_bf16 v[48:51], v[162:165], v[206:209], v[48:51]
	v_mfma_f32_16x16x32_bf16 v[32:35], v[162:165], v[214:217], v[32:35]
	v_mfma_f32_16x16x32_bf16 v[32:35], v[166:169], v[218:221], v[32:35]
	v_mfma_f32_16x16x32_bf16 v[24:27], v[174:177], v[218:221], v[24:27]
	v_mfma_f32_16x16x32_bf16 v[24:27], v[170:173], v[214:217], v[24:27]
	v_mfma_f32_16x16x32_bf16 v[8:11], v[170:173], v[222:225], v[8:11]
	v_mfma_f32_16x16x32_bf16 v[8:11], v[174:177], v[226:229], v[8:11]
	v_mfma_f32_16x16x32_bf16 v[16:19], v[166:169], v[226:229], v[16:19]
	v_mfma_f32_16x16x32_bf16 v[16:19], v[162:165], v[222:225], v[16:19]
	s_setprio 0
	s_setprio 1
	v_mfma_f32_16x16x32_bf16 v[52:55], v[178:181], v[198:201], v[52:55]
	v_mfma_f32_16x16x32_bf16 v[52:55], v[186:189], v[202:205], v[52:55]
	v_mfma_f32_16x16x32_bf16 v[44:47], v[194:197], v[202:205], v[44:47]
	v_mfma_f32_16x16x32_bf16 v[44:47], v[190:193], v[198:201], v[44:47]
	v_mfma_f32_16x16x32_bf16 v[28:31], v[190:193], v[206:209], v[28:31]
	v_mfma_f32_16x16x32_bf16 v[28:31], v[194:197], v[210:213], v[28:31]
	v_mfma_f32_16x16x32_bf16 v[36:39], v[186:189], v[210:213], v[36:39]
	v_mfma_f32_16x16x32_bf16 v[36:39], v[178:181], v[206:209], v[36:39]
	v_mfma_f32_16x16x32_bf16 v[20:23], v[178:181], v[214:217], v[20:23]
	v_mfma_f32_16x16x32_bf16 v[20:23], v[186:189], v[218:221], v[20:23]
	v_mfma_f32_16x16x32_bf16 v[12:15], v[194:197], v[218:221], v[12:15]
	v_mfma_f32_16x16x32_bf16 v[12:15], v[190:193], v[214:217], v[12:15]
	v_mfma_f32_16x16x32_bf16 v[0:3], v[190:193], v[222:225], v[0:3]
	v_mfma_f32_16x16x32_bf16 v[0:3], v[194:197], v[226:229], v[0:3]
	v_mfma_f32_16x16x32_bf16 v[4:7], v[186:189], v[226:229], v[4:7]
	v_mfma_f32_16x16x32_bf16 v[4:7], v[178:181], v[222:225], v[4:7]
	s_setprio 0
	s_barrier
	s_add_i32 s85, s85, 2
	s_add_u32 s83, s83, 0x100
	s_addc_u32 s84, s84, 0
	s_add_u32 s54, s54, 0x100
	s_addc_u32 s55, s55, 0
	s_cmp_gt_u32 s85, 13
	s_cbranch_scc1 .LBB0_877

.LBB0_1010:
	s_ashr_i32 s51, s50, 31
	s_lshl_b64 s[52:53], s[50:51], 19
	s_add_u32 s52, s33, s52
	s_addc_u32 s53, s35, s53
	s_and_b64 s[54:55], s[12:13], exec
	s_cselect_b32 s15, s53, s61
	s_cselect_b32 s51, s52, s60
	s_ashr_i32 s49, s48, 31
	s_lshl_b64 s[54:55], s[48:49], 19
	s_add_u32 s54, s64, s54
	s_addc_u32 s55, s65, s55
	s_and_b64 s[62:63], s[12:13], exec
	s_cselect_b32 s49, s55, s59
	s_cselect_b32 s57, s54, s58
	s_add_u32 s78, s58, 0x100
	s_addc_u32 s79, s59, 0
	s_add_u32 s58, s60, 0x40080
	s_addc_u32 s59, s61, 0
	s_mov_b32 s80, -2
	s_waitcnt lgkmcnt(0)
	s_cmp_eq_u32 s71, 1
	s_cbranch_scc1 .Lfa_9
	ds_read_b128 v[128:131], v188
	v_xor_b32_e32 v253, 64, v188
	ds_read_b128 v[132:135], v253
	ds_read_b128 v[136:139], v188 offset:2048
	ds_read_b128 v[140:143], v253 offset:2048
	ds_read_b128 v[144:147], v189
	v_xor_b32_e32 v253, 64, v189
	ds_read_b128 v[148:151], v253
	ds_read_b128 v[172:175], v189 offset:2048
	ds_read_b128 v[176:179], v253 offset:2048
	s_add_u32 s60, s58, 0xfffc0080
	s_addc_u32 s61, s59, -1
	s_cmp_eq_u32 s80, 12
	s_cselect_b32 s63, s15, s61
	s_cselect_b32 s62, s51, s60
	s_cselect_b32 s61, s49, s79
	s_cselect_b32 s60, s57, s78
	v_lshl_add_u64 v[220:221], s[58:59], 0, v[166:167]
	s_add_i32 m0, s67, 0xc000
	ds_read_b128 v[180:183], v190
	v_xor_b32_e32 v253, 64, v190
	ds_read_b128 v[192:195], v253
	ds_read_b128 v[196:199], v190 offset:2048
	ds_read_b128 v[200:203], v253 offset:2048
	ds_read_b128 v[204:207], v190 offset:4096
	ds_read_b128 v[208:211], v253 offset:4096
	ds_read_b128 v[212:215], v190 offset:6144
	ds_read_b128 v[216:219], v253 offset:6144
	global_load_lds_dwordx4 v[220:221], off
	v_lshl_add_u64 v[220:221], s[58:59], 0, v[164:165]
	s_add_i32 m0, s67, 0xe000
	s_nop 0
	global_load_lds_dwordx4 v[220:221], off
	s_waitcnt vmcnt(24)
	s_waitcnt lgkmcnt(0)
	s_barrier
	s_setprio 1
	s_waitcnt lgkmcnt(0)
	v_mfma_f32_16x16x32_bf16 v[124:127], v[128:131], v[180:183], 0
	v_mfma_f32_16x16x32_bf16 v[120:123], v[136:139], v[180:183], 0
	v_mfma_f32_16x16x32_bf16 v[108:111], v[128:131], v[196:199], 0
	v_mfma_f32_16x16x32_bf16 v[104:107], v[136:139], v[196:199], 0
	v_mfma_f32_16x16x32_bf16 v[92:95], v[128:131], v[204:207], 0
	v_mfma_f32_16x16x32_bf16 v[88:91], v[136:139], v[204:207], 0
	v_mfma_f32_16x16x32_bf16 v[76:79], v[128:131], v[212:215], 0
	v_mfma_f32_16x16x32_bf16 v[72:75], v[136:139], v[212:215], 0
	v_mfma_f32_16x16x32_bf16 v[124:127], v[132:135], v[192:195], v[124:127]
	v_mfma_f32_16x16x32_bf16 v[120:123], v[140:143], v[192:195], v[120:123]
	v_mfma_f32_16x16x32_bf16 v[108:111], v[132:135], v[200:203], v[108:111]
	v_mfma_f32_16x16x32_bf16 v[104:107], v[140:143], v[200:203], v[104:107]
	v_mfma_f32_16x16x32_bf16 v[92:95], v[132:135], v[208:211], v[92:95]
	v_mfma_f32_16x16x32_bf16 v[88:91], v[140:143], v[208:211], v[88:91]
	v_mfma_f32_16x16x32_bf16 v[76:79], v[132:135], v[216:219], v[76:79]
	v_mfma_f32_16x16x32_bf16 v[72:75], v[140:143], v[216:219], v[72:75]
	s_setprio 0
	s_setprio 1
	v_mfma_f32_16x16x32_bf16 v[116:119], v[144:147], v[180:183], 0
	v_mfma_f32_16x16x32_bf16 v[112:115], v[172:175], v[180:183], 0
	v_mfma_f32_16x16x32_bf16 v[100:103], v[144:147], v[196:199], 0
	v_mfma_f32_16x16x32_bf16 v[96:99], v[172:175], v[196:199], 0
	v_mfma_f32_16x16x32_bf16 v[84:87], v[144:147], v[204:207], 0
	v_mfma_f32_16x16x32_bf16 v[80:83], v[172:175], v[204:207], 0
	v_mfma_f32_16x16x32_bf16 v[68:71], v[144:147], v[212:215], 0
	v_mfma_f32_16x16x32_bf16 v[64:67], v[172:175], v[212:215], 0
	v_mfma_f32_16x16x32_bf16 v[116:119], v[148:151], v[192:195], v[116:119]
	v_mfma_f32_16x16x32_bf16 v[112:115], v[176:179], v[192:195], v[112:115]
	v_mfma_f32_16x16x32_bf16 v[100:103], v[148:151], v[200:203], v[100:103]
	v_mfma_f32_16x16x32_bf16 v[96:99], v[176:179], v[200:203], v[96:99]
	v_mfma_f32_16x16x32_bf16 v[84:87], v[148:151], v[208:211], v[84:87]
	v_mfma_f32_16x16x32_bf16 v[80:83], v[176:179], v[208:211], v[80:83]
	v_mfma_f32_16x16x32_bf16 v[68:71], v[148:151], v[216:219], v[68:71]
	v_mfma_f32_16x16x32_bf16 v[64:67], v[176:179], v[216:219], v[64:67]
	s_setprio 0
	s_barrier
	s_add_i32 s81, s76, s66
	v_lshl_add_u64 v[220:221], s[60:61], 0, v[154:155]
	s_mov_b32 m0, s81
	ds_read_b128 v[180:183], v190 offset:16384
	v_xor_b32_e32 v253, 64, v190
	ds_read_b128 v[192:195], v253 offset:16384
	ds_read_b128 v[196:199], v190 offset:18432
	ds_read_b128 v[200:203], v253 offset:18432
	ds_read_b128 v[204:207], v190 offset:20480
	ds_read_b128 v[208:211], v253 offset:20480
	ds_read_b128 v[212:215], v190 offset:22528
	ds_read_b128 v[216:219], v253 offset:22528
	global_load_lds_dwordx4 v[220:221], off
	s_add_i32 m0, s81, 0x2000
	s_add_u32 s82, s60, 0x40000
	v_lshl_add_u64 v[222:223], s[60:61], 0, v[162:163]
	s_addc_u32 s83, s61, 0
	s_add_i32 s81, s77, s66
	global_load_lds_dwordx4 v[222:223], off
	v_lshl_add_u64 v[224:225], s[82:83], 0, v[154:155]
	s_mov_b32 m0, s81
	v_lshl_add_u64 v[226:227], s[62:63], 0, v[160:161]
	global_load_lds_dwordx4 v[224:225], off
	v_lshl_add_u64 v[224:225], s[82:83], 0, v[162:163]
	s_add_i32 m0, s81, 0x2000
	s_nop 0
	global_load_lds_dwordx4 v[224:225], off
	v_lshl_add_u64 v[224:225], s[62:63], 0, v[152:153]
	s_mov_b32 m0, s67
	s_nop 0
	global_load_lds_dwordx4 v[224:225], off
	s_mov_b32 m0, s68
	s_nop 0
	global_load_lds_dwordx4 v[226:227], off
	s_waitcnt vmcnt(24)
	s_waitcnt lgkmcnt(0)
	s_barrier
	s_setprio 1
	s_waitcnt lgkmcnt(0)
	v_mfma_f32_16x16x32_bf16 v[60:63], v[128:131], v[180:183], 0
	v_mfma_f32_16x16x32_bf16 v[56:59], v[136:139], v[180:183], 0
	v_mfma_f32_16x16x32_bf16 v[44:47], v[128:131], v[196:199], 0
	v_mfma_f32_16x16x32_bf16 v[40:43], v[136:139], v[196:199], 0
	v_mfma_f32_16x16x32_bf16 v[28:31], v[128:131], v[204:207], 0
	v_mfma_f32_16x16x32_bf16 v[24:27], v[136:139], v[204:207], 0
	v_mfma_f32_16x16x32_bf16 v[12:15], v[128:131], v[212:215], 0
	v_mfma_f32_16x16x32_bf16 v[8:11], v[136:139], v[212:215], 0
	v_mfma_f32_16x16x32_bf16 v[60:63], v[132:135], v[192:195], v[60:63]
	v_mfma_f32_16x16x32_bf16 v[56:59], v[140:143], v[192:195], v[56:59]
	v_mfma_f32_16x16x32_bf16 v[44:47], v[132:135], v[200:203], v[44:47]
	v_mfma_f32_16x16x32_bf16 v[40:43], v[140:143], v[200:203], v[40:43]
	v_mfma_f32_16x16x32_bf16 v[28:31], v[132:135], v[208:211], v[28:31]
	v_mfma_f32_16x16x32_bf16 v[24:27], v[140:143], v[208:211], v[24:27]
	v_mfma_f32_16x16x32_bf16 v[12:15], v[132:135], v[216:219], v[12:15]
	v_mfma_f32_16x16x32_bf16 v[8:11], v[140:143], v[216:219], v[8:11]
	s_setprio 0
	s_setprio 1
	v_mfma_f32_16x16x32_bf16 v[52:55], v[144:147], v[180:183], 0
	v_mfma_f32_16x16x32_bf16 v[48:51], v[172:175], v[180:183], 0
	v_mfma_f32_16x16x32_bf16 v[36:39], v[144:147], v[196:199], 0
	v_mfma_f32_16x16x32_bf16 v[32:35], v[172:175], v[196:199], 0
	v_mfma_f32_16x16x32_bf16 v[20:23], v[144:147], v[204:207], 0
	v_mfma_f32_16x16x32_bf16 v[16:19], v[172:175], v[204:207], 0
	v_mfma_f32_16x16x32_bf16 v[4:7], v[144:147], v[212:215], 0
	v_mfma_f32_16x16x32_bf16 v[0:3], v[172:175], v[212:215], 0
	v_mfma_f32_16x16x32_bf16 v[52:55], v[148:151], v[192:195], v[52:55]
	v_mfma_f32_16x16x32_bf16 v[48:51], v[176:179], v[192:195], v[48:51]
	v_mfma_f32_16x16x32_bf16 v[36:39], v[148:151], v[200:203], v[36:39]
	v_mfma_f32_16x16x32_bf16 v[32:35], v[176:179], v[200:203], v[32:35]
	v_mfma_f32_16x16x32_bf16 v[20:23], v[148:151], v[208:211], v[20:23]
	v_mfma_f32_16x16x32_bf16 v[16:19], v[176:179], v[208:211], v[16:19]
	v_mfma_f32_16x16x32_bf16 v[4:7], v[148:151], v[216:219], v[4:7]
	v_mfma_f32_16x16x32_bf16 v[0:3], v[176:179], v[216:219], v[0:3]
	s_setprio 0
	s_barrier
	s_add_i32 s81, 0, 0x18000
	s_add_i32 s82, 0, 0x1c000
	v_add_u32_e32 v140, s81, v185
	v_add_u32_e32 v176, s82, v185
	ds_read_b128 v[128:131], v140
	v_xor_b32_e32 v253, 64, v140
	ds_read_b128 v[132:135], v253
	ds_read_b128 v[136:139], v140 offset:2048
	ds_read_b128 v[140:143], v253 offset:2048
	ds_read_b128 v[144:147], v176
	v_xor_b32_e32 v253, 64, v176
	ds_read_b128 v[148:151], v253
	ds_read_b128 v[172:175], v176 offset:2048
	ds_read_b128 v[176:179], v253 offset:2048
	s_add_u32 s62, s62, 0x40000
	s_addc_u32 s63, s63, 0
	s_mov_b32 m0, s69
	v_lshl_add_u64 v[228:229], s[62:63], 0, v[152:153]
	ds_read_b128 v[180:183], v190 offset:32768
	v_xor_b32_e32 v253, 64, v190
	ds_read_b128 v[192:195], v253 offset:32768
	ds_read_b128 v[196:199], v190 offset:34816
	ds_read_b128 v[200:203], v253 offset:34816
	ds_read_b128 v[204:207], v190 offset:36864
	ds_read_b128 v[208:211], v253 offset:36864
	ds_read_b128 v[212:215], v190 offset:38912
	ds_read_b128 v[216:219], v253 offset:38912
	global_load_lds_dwordx4 v[228:229], off
	v_lshl_add_u64 v[228:229], s[62:63], 0, v[160:161]
	s_mov_b32 m0, s70
	s_nop 0
	global_load_lds_dwordx4 v[228:229], off
	s_waitcnt vmcnt(8)
	s_waitcnt lgkmcnt(0)
	s_barrier
	s_setprio 1
	s_waitcnt lgkmcnt(0)
	v_mfma_f32_16x16x32_bf16 v[124:127], v[128:131], v[180:183], v[124:127]
	v_mfma_f32_16x16x32_bf16 v[124:127], v[132:135], v[192:195], v[124:127]
	v_mfma_f32_16x16x32_bf16 v[120:123], v[140:143], v[192:195], v[120:123]
	v_mfma_f32_16x16x32_bf16 v[120:123], v[136:139], v[180:183], v[120:123]
	v_mfma_f32_16x16x32_bf16 v[104:107], v[136:139], v[196:199], v[104:107]
	v_mfma_f32_16x16x32_bf16 v[104:107], v[140:143], v[200:203], v[104:107]
	v_mfma_f32_16x16x32_bf16 v[108:111], v[132:135], v[200:203], v[108:111]
	v_mfma_f32_16x16x32_bf16 v[108:111], v[128:131], v[196:199], v[108:111]
	v_mfma_f32_16x16x32_bf16 v[92:95], v[128:131], v[204:207], v[92:95]
	v_mfma_f32_16x16x32_bf16 v[92:95], v[132:135], v[208:211], v[92:95]
	v_mfma_f32_16x16x32_bf16 v[88:91], v[140:143], v[208:211], v[88:91]
	v_mfma_f32_16x16x32_bf16 v[88:91], v[136:139], v[204:207], v[88:91]
	v_mfma_f32_16x16x32_bf16 v[72:75], v[136:139], v[212:215], v[72:75]
	v_mfma_f32_16x16x32_bf16 v[72:75], v[140:143], v[216:219], v[72:75]
	v_mfma_f32_16x16x32_bf16 v[76:79], v[132:135], v[216:219], v[76:79]
	v_mfma_f32_16x16x32_bf16 v[76:79], v[128:131], v[212:215], v[76:79]
	s_setprio 0
	s_setprio 1
	v_mfma_f32_16x16x32_bf16 v[116:119], v[144:147], v[180:183], v[116:119]
	v_mfma_f32_16x16x32_bf16 v[116:119], v[148:151], v[192:195], v[116:119]
	v_mfma_f32_16x16x32_bf16 v[112:115], v[176:179], v[192:195], v[112:115]
	v_mfma_f32_16x16x32_bf16 v[112:115], v[172:175], v[180:183], v[112:115]
	v_mfma_f32_16x16x32_bf16 v[96:99], v[172:175], v[196:199], v[96:99]
	v_mfma_f32_16x16x32_bf16 v[96:99], v[176:179], v[200:203], v[96:99]
	v_mfma_f32_16x16x32_bf16 v[100:103], v[148:151], v[200:203], v[100:103]
	v_mfma_f32_16x16x32_bf16 v[100:103], v[144:147], v[196:199], v[100:103]
	v_mfma_f32_16x16x32_bf16 v[84:87], v[144:147], v[204:207], v[84:87]
	v_mfma_f32_16x16x32_bf16 v[84:87], v[148:151], v[208:211], v[84:87]
	v_mfma_f32_16x16x32_bf16 v[80:83], v[176:179], v[208:211], v[80:83]
	v_mfma_f32_16x16x32_bf16 v[80:83], v[172:175], v[204:207], v[80:83]
	v_mfma_f32_16x16x32_bf16 v[64:67], v[172:175], v[212:215], v[64:67]
	v_mfma_f32_16x16x32_bf16 v[64:67], v[176:179], v[216:219], v[64:67]
	v_mfma_f32_16x16x32_bf16 v[68:71], v[148:151], v[216:219], v[68:71]
	v_mfma_f32_16x16x32_bf16 v[68:71], v[144:147], v[212:215], v[68:71]
	s_setprio 0
	s_barrier
	s_add_i32 s62, s81, s66
	v_lshl_add_u64 v[220:221], v[220:221], 0, s[26:27]
	s_mov_b32 m0, s62
	ds_read_b128 v[180:183], v190 offset:49152
	v_xor_b32_e32 v253, 64, v190
	ds_read_b128 v[192:195], v253 offset:49152
	ds_read_b128 v[196:199], v190 offset:51200
	ds_read_b128 v[200:203], v253 offset:51200
	ds_read_b128 v[204:207], v190 offset:53248
	ds_read_b128 v[208:211], v253 offset:53248
	ds_read_b128 v[212:215], v190 offset:55296
	ds_read_b128 v[216:219], v253 offset:55296
	global_load_lds_dwordx4 v[220:221], off
	s_add_i32 m0, s62, 0x2000
	s_add_u32 s60, s60, 0x40080
	v_lshl_add_u64 v[220:221], v[222:223], 0, s[26:27]
	s_addc_u32 s61, s61, 0
	s_add_i32 s62, s82, s66
	global_load_lds_dwordx4 v[220:221], off
	v_lshl_add_u64 v[220:221], s[60:61], 0, v[154:155]
	s_mov_b32 m0, s62
	s_nop 0
	global_load_lds_dwordx4 v[220:221], off
	v_lshl_add_u64 v[220:221], s[60:61], 0, v[162:163]
	s_add_i32 m0, s62, 0x2000
	s_nop 0
	global_load_lds_dwordx4 v[220:221], off
	v_lshl_add_u64 v[220:221], v[224:225], 0, s[26:27]
	s_mov_b32 m0, s3
	s_nop 0
	global_load_lds_dwordx4 v[220:221], off
	v_lshl_add_u64 v[220:221], v[226:227], 0, s[26:27]
	s_mov_b32 m0, s72
	s_nop 0
	global_load_lds_dwordx4 v[220:221], off
	s_waitcnt vmcnt(8)
	s_waitcnt lgkmcnt(0)
	s_barrier
	s_setprio 1
	s_waitcnt lgkmcnt(0)
	v_mfma_f32_16x16x32_bf16 v[60:63], v[128:131], v[180:183], v[60:63]
	v_mfma_f32_16x16x32_bf16 v[60:63], v[132:135], v[192:195], v[60:63]
	v_mfma_f32_16x16x32_bf16 v[56:59], v[140:143], v[192:195], v[56:59]
	v_mfma_f32_16x16x32_bf16 v[56:59], v[136:139], v[180:183], v[56:59]
	v_mfma_f32_16x16x32_bf16 v[40:43], v[136:139], v[196:199], v[40:43]
	v_mfma_f32_16x16x32_bf16 v[40:43], v[140:143], v[200:203], v[40:43]
	v_mfma_f32_16x16x32_bf16 v[44:47], v[132:135], v[200:203], v[44:47]
	v_mfma_f32_16x16x32_bf16 v[44:47], v[128:131], v[196:199], v[44:47]
	v_mfma_f32_16x16x32_bf16 v[28:31], v[128:131], v[204:207], v[28:31]
	v_mfma_f32_16x16x32_bf16 v[28:31], v[132:135], v[208:211], v[28:31]
	v_mfma_f32_16x16x32_bf16 v[24:27], v[140:143], v[208:211], v[24:27]
	v_mfma_f32_16x16x32_bf16 v[24:27], v[136:139], v[204:207], v[24:27]
	v_mfma_f32_16x16x32_bf16 v[8:11], v[136:139], v[212:215], v[8:11]
	v_mfma_f32_16x16x32_bf16 v[8:11], v[140:143], v[216:219], v[8:11]
	v_mfma_f32_16x16x32_bf16 v[12:15], v[132:135], v[216:219], v[12:15]
	v_mfma_f32_16x16x32_bf16 v[12:15], v[128:131], v[212:215], v[12:15]
	s_setprio 0
	s_setprio 1
	v_mfma_f32_16x16x32_bf16 v[52:55], v[144:147], v[180:183], v[52:55]
	v_mfma_f32_16x16x32_bf16 v[52:55], v[148:151], v[192:195], v[52:55]
	v_mfma_f32_16x16x32_bf16 v[48:51], v[176:179], v[192:195], v[48:51]
	v_mfma_f32_16x16x32_bf16 v[48:51], v[172:175], v[180:183], v[48:51]
	v_mfma_f32_16x16x32_bf16 v[32:35], v[172:175], v[196:199], v[32:35]
	v_mfma_f32_16x16x32_bf16 v[32:35], v[176:179], v[200:203], v[32:35]
	v_mfma_f32_16x16x32_bf16 v[36:39], v[148:151], v[200:203], v[36:39]
	v_mfma_f32_16x16x32_bf16 v[36:39], v[144:147], v[196:199], v[36:39]
	v_mfma_f32_16x16x32_bf16 v[20:23], v[144:147], v[204:207], v[20:23]
	v_mfma_f32_16x16x32_bf16 v[20:23], v[148:151], v[208:211], v[20:23]
	v_mfma_f32_16x16x32_bf16 v[16:19], v[176:179], v[208:211], v[16:19]
	v_mfma_f32_16x16x32_bf16 v[16:19], v[172:175], v[204:207], v[16:19]
	v_mfma_f32_16x16x32_bf16 v[0:3], v[172:175], v[212:215], v[0:3]
	v_mfma_f32_16x16x32_bf16 v[0:3], v[176:179], v[216:219], v[0:3]
	v_mfma_f32_16x16x32_bf16 v[4:7], v[148:151], v[216:219], v[4:7]
	v_mfma_f32_16x16x32_bf16 v[4:7], v[144:147], v[212:215], v[4:7]
	s_setprio 0
	s_barrier
	s_add_i32 s80, s80, 2
	s_add_u32 s78, s78, 0x100
	s_addc_u32 s79, s79, 0
	s_add_u32 s58, s58, 0x100
	s_addc_u32 s59, s59, 0
	s_cmp_gt_u32 s80, 13
	s_branch .LBB0_1011
.Lfa_9:
	ds_read_b128 v[128:131], v188
	v_xor_b32_e32 v253, 64, v188
	ds_read_b128 v[132:135], v253
	ds_read_b128 v[136:139], v188 offset:2048
	ds_read_b128 v[140:143], v253 offset:2048
	ds_read_b128 v[144:147], v189
	v_xor_b32_e32 v253, 64, v189
	ds_read_b128 v[148:151], v253
	ds_read_b128 v[172:175], v189 offset:2048
	ds_read_b128 v[176:179], v253 offset:2048
	s_add_u32 s60, s58, 0xfffc0080
	s_addc_u32 s61, s59, -1
	s_cmp_eq_u32 s80, 12
	s_cselect_b32 s63, s15, s61
	s_cselect_b32 s62, s51, s60
	s_cselect_b32 s61, s49, s79
	s_cselect_b32 s60, s57, s78
	v_lshl_add_u64 v[220:221], s[58:59], 0, v[166:167]
	s_add_i32 m0, s67, 0xc000
	ds_read_b128 v[180:183], v190
	v_xor_b32_e32 v253, 64, v190
	ds_read_b128 v[192:195], v253
	ds_read_b128 v[196:199], v190 offset:2048
	ds_read_b128 v[200:203], v253 offset:2048
	ds_read_b128 v[204:207], v190 offset:4096
	ds_read_b128 v[208:211], v253 offset:4096
	ds_read_b128 v[212:215], v190 offset:6144
	ds_read_b128 v[216:219], v253 offset:6144
	global_load_lds_dwordx4 v[220:221], off
	v_lshl_add_u64 v[220:221], s[58:59], 0, v[164:165]
	s_add_i32 m0, s67, 0xe000
	s_nop 0
	global_load_lds_dwordx4 v[220:221], off
	s_waitcnt vmcnt(8)
	s_waitcnt lgkmcnt(0)
	s_barrier
	s_setprio 1
	s_waitcnt lgkmcnt(0)
	v_mfma_f32_16x16x32_bf16 v[124:127], v[128:131], v[180:183], 0
	v_mfma_f32_16x16x32_bf16 v[120:123], v[136:139], v[180:183], 0
	v_mfma_f32_16x16x32_bf16 v[108:111], v[128:131], v[196:199], 0
	v_mfma_f32_16x16x32_bf16 v[104:107], v[136:139], v[196:199], 0
	v_mfma_f32_16x16x32_bf16 v[92:95], v[128:131], v[204:207], 0
	v_mfma_f32_16x16x32_bf16 v[88:91], v[136:139], v[204:207], 0
	v_mfma_f32_16x16x32_bf16 v[76:79], v[128:131], v[212:215], 0
	v_mfma_f32_16x16x32_bf16 v[72:75], v[136:139], v[212:215], 0
	v_mfma_f32_16x16x32_bf16 v[124:127], v[132:135], v[192:195], v[124:127]
	v_mfma_f32_16x16x32_bf16 v[120:123], v[140:143], v[192:195], v[120:123]
	v_mfma_f32_16x16x32_bf16 v[108:111], v[132:135], v[200:203], v[108:111]
	v_mfma_f32_16x16x32_bf16 v[104:107], v[140:143], v[200:203], v[104:107]
	v_mfma_f32_16x16x32_bf16 v[92:95], v[132:135], v[208:211], v[92:95]
	v_mfma_f32_16x16x32_bf16 v[88:91], v[140:143], v[208:211], v[88:91]
	v_mfma_f32_16x16x32_bf16 v[76:79], v[132:135], v[216:219], v[76:79]
	v_mfma_f32_16x16x32_bf16 v[72:75], v[140:143], v[216:219], v[72:75]
	s_setprio 0
	s_setprio 1
	v_mfma_f32_16x16x32_bf16 v[116:119], v[144:147], v[180:183], 0
	v_mfma_f32_16x16x32_bf16 v[112:115], v[172:175], v[180:183], 0
	v_mfma_f32_16x16x32_bf16 v[100:103], v[144:147], v[196:199], 0
	v_mfma_f32_16x16x32_bf16 v[96:99], v[172:175], v[196:199], 0
	v_mfma_f32_16x16x32_bf16 v[84:87], v[144:147], v[204:207], 0
	v_mfma_f32_16x16x32_bf16 v[80:83], v[172:175], v[204:207], 0
	v_mfma_f32_16x16x32_bf16 v[68:71], v[144:147], v[212:215], 0
	v_mfma_f32_16x16x32_bf16 v[64:67], v[172:175], v[212:215], 0
	v_mfma_f32_16x16x32_bf16 v[116:119], v[148:151], v[192:195], v[116:119]
	v_mfma_f32_16x16x32_bf16 v[112:115], v[176:179], v[192:195], v[112:115]
	v_mfma_f32_16x16x32_bf16 v[100:103], v[148:151], v[200:203], v[100:103]
	v_mfma_f32_16x16x32_bf16 v[96:99], v[176:179], v[200:203], v[96:99]
	v_mfma_f32_16x16x32_bf16 v[84:87], v[148:151], v[208:211], v[84:87]
	v_mfma_f32_16x16x32_bf16 v[80:83], v[176:179], v[208:211], v[80:83]
	v_mfma_f32_16x16x32_bf16 v[68:71], v[148:151], v[216:219], v[68:71]
	v_mfma_f32_16x16x32_bf16 v[64:67], v[176:179], v[216:219], v[64:67]
	s_setprio 0
	s_barrier
	s_add_i32 s81, s76, s66
	v_lshl_add_u64 v[220:221], s[60:61], 0, v[154:155]
	s_mov_b32 m0, s81
	ds_read_b128 v[180:183], v190 offset:16384
	v_xor_b32_e32 v253, 64, v190
	ds_read_b128 v[192:195], v253 offset:16384
	ds_read_b128 v[196:199], v190 offset:18432
	ds_read_b128 v[200:203], v253 offset:18432
	ds_read_b128 v[204:207], v190 offset:20480
	ds_read_b128 v[208:211], v253 offset:20480
	ds_read_b128 v[212:215], v190 offset:22528
	ds_read_b128 v[216:219], v253 offset:22528
	global_load_lds_dwordx4 v[220:221], off
	s_add_i32 m0, s81, 0x2000
	s_add_u32 s82, s60, 0x40000
	v_lshl_add_u64 v[222:223], s[60:61], 0, v[162:163]
	s_addc_u32 s83, s61, 0
	s_add_i32 s81, s77, s66
	global_load_lds_dwordx4 v[222:223], off
	v_lshl_add_u64 v[224:225], s[82:83], 0, v[154:155]
	s_mov_b32 m0, s81
	v_lshl_add_u64 v[226:227], s[62:63], 0, v[160:161]
	global_load_lds_dwordx4 v[224:225], off
	v_lshl_add_u64 v[224:225], s[82:83], 0, v[162:163]
	s_add_i32 m0, s81, 0x2000
	s_nop 0
	global_load_lds_dwordx4 v[224:225], off
	v_lshl_add_u64 v[224:225], s[62:63], 0, v[152:153]
	s_mov_b32 m0, s67
	s_nop 0
	global_load_lds_dwordx4 v[224:225], off
	s_mov_b32 m0, s68
	s_nop 0
	global_load_lds_dwordx4 v[226:227], off
	s_waitcnt vmcnt(8)
	s_waitcnt lgkmcnt(0)
	s_barrier
	s_setprio 1
	s_waitcnt lgkmcnt(0)
	v_mfma_f32_16x16x32_bf16 v[60:63], v[128:131], v[180:183], 0
	v_mfma_f32_16x16x32_bf16 v[56:59], v[136:139], v[180:183], 0
	v_mfma_f32_16x16x32_bf16 v[44:47], v[128:131], v[196:199], 0
	v_mfma_f32_16x16x32_bf16 v[40:43], v[136:139], v[196:199], 0
	v_mfma_f32_16x16x32_bf16 v[28:31], v[128:131], v[204:207], 0
	v_mfma_f32_16x16x32_bf16 v[24:27], v[136:139], v[204:207], 0
	v_mfma_f32_16x16x32_bf16 v[12:15], v[128:131], v[212:215], 0
	v_mfma_f32_16x16x32_bf16 v[8:11], v[136:139], v[212:215], 0
	v_mfma_f32_16x16x32_bf16 v[60:63], v[132:135], v[192:195], v[60:63]
	v_mfma_f32_16x16x32_bf16 v[56:59], v[140:143], v[192:195], v[56:59]
	v_mfma_f32_16x16x32_bf16 v[44:47], v[132:135], v[200:203], v[44:47]
	v_mfma_f32_16x16x32_bf16 v[40:43], v[140:143], v[200:203], v[40:43]
	v_mfma_f32_16x16x32_bf16 v[28:31], v[132:135], v[208:211], v[28:31]
	v_mfma_f32_16x16x32_bf16 v[24:27], v[140:143], v[208:211], v[24:27]
	v_mfma_f32_16x16x32_bf16 v[12:15], v[132:135], v[216:219], v[12:15]
	v_mfma_f32_16x16x32_bf16 v[8:11], v[140:143], v[216:219], v[8:11]
	s_setprio 0
	s_setprio 1
	v_mfma_f32_16x16x32_bf16 v[52:55], v[144:147], v[180:183], 0
	v_mfma_f32_16x16x32_bf16 v[48:51], v[172:175], v[180:183], 0
	v_mfma_f32_16x16x32_bf16 v[36:39], v[144:147], v[196:199], 0
	v_mfma_f32_16x16x32_bf16 v[32:35], v[172:175], v[196:199], 0
	v_mfma_f32_16x16x32_bf16 v[20:23], v[144:147], v[204:207], 0
	v_mfma_f32_16x16x32_bf16 v[16:19], v[172:175], v[204:207], 0
	v_mfma_f32_16x16x32_bf16 v[4:7], v[144:147], v[212:215], 0
	v_mfma_f32_16x16x32_bf16 v[0:3], v[172:175], v[212:215], 0
	v_mfma_f32_16x16x32_bf16 v[52:55], v[148:151], v[192:195], v[52:55]
	v_mfma_f32_16x16x32_bf16 v[48:51], v[176:179], v[192:195], v[48:51]
	v_mfma_f32_16x16x32_bf16 v[36:39], v[148:151], v[200:203], v[36:39]
	v_mfma_f32_16x16x32_bf16 v[32:35], v[176:179], v[200:203], v[32:35]
	v_mfma_f32_16x16x32_bf16 v[20:23], v[148:151], v[208:211], v[20:23]
	v_mfma_f32_16x16x32_bf16 v[16:19], v[176:179], v[208:211], v[16:19]
	v_mfma_f32_16x16x32_bf16 v[4:7], v[148:151], v[216:219], v[4:7]
	v_mfma_f32_16x16x32_bf16 v[0:3], v[176:179], v[216:219], v[0:3]
	s_setprio 0
	s_barrier
	s_add_i32 s81, 0, 0x18000
	s_add_i32 s82, 0, 0x1c000
	v_add_u32_e32 v140, s81, v185
	v_add_u32_e32 v176, s82, v185
	ds_read_b128 v[128:131], v140
	v_xor_b32_e32 v253, 64, v140
	ds_read_b128 v[132:135], v253
	ds_read_b128 v[136:139], v140 offset:2048
	ds_read_b128 v[140:143], v253 offset:2048
	ds_read_b128 v[144:147], v176
	v_xor_b32_e32 v253, 64, v176
	ds_read_b128 v[148:151], v253
	ds_read_b128 v[172:175], v176 offset:2048
	ds_read_b128 v[176:179], v253 offset:2048
	s_add_u32 s62, s62, 0x40000
	s_addc_u32 s63, s63, 0
	s_mov_b32 m0, s69
	v_lshl_add_u64 v[228:229], s[62:63], 0, v[152:153]
	ds_read_b128 v[180:183], v190 offset:32768
	v_xor_b32_e32 v253, 64, v190
	ds_read_b128 v[192:195], v253 offset:32768
	ds_read_b128 v[196:199], v190 offset:34816
	ds_read_b128 v[200:203], v253 offset:34816
	ds_read_b128 v[204:207], v190 offset:36864
	ds_read_b128 v[208:211], v253 offset:36864
	ds_read_b128 v[212:215], v190 offset:38912
	ds_read_b128 v[216:219], v253 offset:38912
	global_load_lds_dwordx4 v[228:229], off
	v_lshl_add_u64 v[228:229], s[62:63], 0, v[160:161]
	s_mov_b32 m0, s70
	s_nop 0
	global_load_lds_dwordx4 v[228:229], off
	s_waitcnt vmcnt(8)
	s_waitcnt lgkmcnt(0)
	s_barrier
	s_setprio 1
	s_waitcnt lgkmcnt(0)
	v_mfma_f32_16x16x32_bf16 v[124:127], v[128:131], v[180:183], v[124:127]
	v_mfma_f32_16x16x32_bf16 v[124:127], v[132:135], v[192:195], v[124:127]
	v_mfma_f32_16x16x32_bf16 v[120:123], v[140:143], v[192:195], v[120:123]
	v_mfma_f32_16x16x32_bf16 v[120:123], v[136:139], v[180:183], v[120:123]
	v_mfma_f32_16x16x32_bf16 v[104:107], v[136:139], v[196:199], v[104:107]
	v_mfma_f32_16x16x32_bf16 v[104:107], v[140:143], v[200:203], v[104:107]
	v_mfma_f32_16x16x32_bf16 v[108:111], v[132:135], v[200:203], v[108:111]
	v_mfma_f32_16x16x32_bf16 v[108:111], v[128:131], v[196:199], v[108:111]
	v_mfma_f32_16x16x32_bf16 v[92:95], v[128:131], v[204:207], v[92:95]
	v_mfma_f32_16x16x32_bf16 v[92:95], v[132:135], v[208:211], v[92:95]
	v_mfma_f32_16x16x32_bf16 v[88:91], v[140:143], v[208:211], v[88:91]
	v_mfma_f32_16x16x32_bf16 v[88:91], v[136:139], v[204:207], v[88:91]
	v_mfma_f32_16x16x32_bf16 v[72:75], v[136:139], v[212:215], v[72:75]
	v_mfma_f32_16x16x32_bf16 v[72:75], v[140:143], v[216:219], v[72:75]
	v_mfma_f32_16x16x32_bf16 v[76:79], v[132:135], v[216:219], v[76:79]
	v_mfma_f32_16x16x32_bf16 v[76:79], v[128:131], v[212:215], v[76:79]
	s_setprio 0
	s_setprio 1
	v_mfma_f32_16x16x32_bf16 v[116:119], v[144:147], v[180:183], v[116:119]
	v_mfma_f32_16x16x32_bf16 v[116:119], v[148:151], v[192:195], v[116:119]
	v_mfma_f32_16x16x32_bf16 v[112:115], v[176:179], v[192:195], v[112:115]
	v_mfma_f32_16x16x32_bf16 v[112:115], v[172:175], v[180:183], v[112:115]
	v_mfma_f32_16x16x32_bf16 v[96:99], v[172:175], v[196:199], v[96:99]
	v_mfma_f32_16x16x32_bf16 v[96:99], v[176:179], v[200:203], v[96:99]
	v_mfma_f32_16x16x32_bf16 v[100:103], v[148:151], v[200:203], v[100:103]
	v_mfma_f32_16x16x32_bf16 v[100:103], v[144:147], v[196:199], v[100:103]
	v_mfma_f32_16x16x32_bf16 v[84:87], v[144:147], v[204:207], v[84:87]
	v_mfma_f32_16x16x32_bf16 v[84:87], v[148:151], v[208:211], v[84:87]
	v_mfma_f32_16x16x32_bf16 v[80:83], v[176:179], v[208:211], v[80:83]
	v_mfma_f32_16x16x32_bf16 v[80:83], v[172:175], v[204:207], v[80:83]
	v_mfma_f32_16x16x32_bf16 v[64:67], v[172:175], v[212:215], v[64:67]
	v_mfma_f32_16x16x32_bf16 v[64:67], v[176:179], v[216:219], v[64:67]
	v_mfma_f32_16x16x32_bf16 v[68:71], v[148:151], v[216:219], v[68:71]
	v_mfma_f32_16x16x32_bf16 v[68:71], v[144:147], v[212:215], v[68:71]
	s_setprio 0
	s_barrier
	s_add_i32 s62, s81, s66
	v_lshl_add_u64 v[220:221], v[220:221], 0, s[26:27]
	s_mov_b32 m0, s62
	ds_read_b128 v[180:183], v190 offset:49152
	v_xor_b32_e32 v253, 64, v190
	ds_read_b128 v[192:195], v253 offset:49152
	ds_read_b128 v[196:199], v190 offset:51200
	ds_read_b128 v[200:203], v253 offset:51200
	ds_read_b128 v[204:207], v190 offset:53248
	ds_read_b128 v[208:211], v253 offset:53248
	ds_read_b128 v[212:215], v190 offset:55296
	ds_read_b128 v[216:219], v253 offset:55296
	global_load_lds_dwordx4 v[220:221], off
	s_add_i32 m0, s62, 0x2000
	s_add_u32 s60, s60, 0x40080
	v_lshl_add_u64 v[220:221], v[222:223], 0, s[26:27]
	s_addc_u32 s61, s61, 0
	s_add_i32 s62, s82, s66
	global_load_lds_dwordx4 v[220:221], off
	v_lshl_add_u64 v[220:221], s[60:61], 0, v[154:155]
	s_mov_b32 m0, s62
	s_nop 0
	global_load_lds_dwordx4 v[220:221], off
	v_lshl_add_u64 v[220:221], s[60:61], 0, v[162:163]
	s_add_i32 m0, s62, 0x2000
	s_nop 0
	global_load_lds_dwordx4 v[220:221], off
	v_lshl_add_u64 v[220:221], v[224:225], 0, s[26:27]
	s_mov_b32 m0, s3
	s_nop 0
	global_load_lds_dwordx4 v[220:221], off
	v_lshl_add_u64 v[220:221], v[226:227], 0, s[26:27]
	s_mov_b32 m0, s72
	s_nop 0
	global_load_lds_dwordx4 v[220:221], off
	s_waitcnt vmcnt(8)
	s_waitcnt lgkmcnt(0)
	s_barrier
	s_setprio 1
	s_waitcnt lgkmcnt(0)
	v_mfma_f32_16x16x32_bf16 v[60:63], v[128:131], v[180:183], v[60:63]
	v_mfma_f32_16x16x32_bf16 v[60:63], v[132:135], v[192:195], v[60:63]
	v_mfma_f32_16x16x32_bf16 v[56:59], v[140:143], v[192:195], v[56:59]
	v_mfma_f32_16x16x32_bf16 v[56:59], v[136:139], v[180:183], v[56:59]
	v_mfma_f32_16x16x32_bf16 v[40:43], v[136:139], v[196:199], v[40:43]
	v_mfma_f32_16x16x32_bf16 v[40:43], v[140:143], v[200:203], v[40:43]
	v_mfma_f32_16x16x32_bf16 v[44:47], v[132:135], v[200:203], v[44:47]
	v_mfma_f32_16x16x32_bf16 v[44:47], v[128:131], v[196:199], v[44:47]
	v_mfma_f32_16x16x32_bf16 v[28:31], v[128:131], v[204:207], v[28:31]
	v_mfma_f32_16x16x32_bf16 v[28:31], v[132:135], v[208:211], v[28:31]
	v_mfma_f32_16x16x32_bf16 v[24:27], v[140:143], v[208:211], v[24:27]
	v_mfma_f32_16x16x32_bf16 v[24:27], v[136:139], v[204:207], v[24:27]
	v_mfma_f32_16x16x32_bf16 v[8:11], v[136:139], v[212:215], v[8:11]
	v_mfma_f32_16x16x32_bf16 v[8:11], v[140:143], v[216:219], v[8:11]
	v_mfma_f32_16x16x32_bf16 v[12:15], v[132:135], v[216:219], v[12:15]
	v_mfma_f32_16x16x32_bf16 v[12:15], v[128:131], v[212:215], v[12:15]
	s_setprio 0
	s_setprio 1
	v_mfma_f32_16x16x32_bf16 v[52:55], v[144:147], v[180:183], v[52:55]
	v_mfma_f32_16x16x32_bf16 v[52:55], v[148:151], v[192:195], v[52:55]
	v_mfma_f32_16x16x32_bf16 v[48:51], v[176:179], v[192:195], v[48:51]
	v_mfma_f32_16x16x32_bf16 v[48:51], v[172:175], v[180:183], v[48:51]
	v_mfma_f32_16x16x32_bf16 v[32:35], v[172:175], v[196:199], v[32:35]
	v_mfma_f32_16x16x32_bf16 v[32:35], v[176:179], v[200:203], v[32:35]
	v_mfma_f32_16x16x32_bf16 v[36:39], v[148:151], v[200:203], v[36:39]
	v_mfma_f32_16x16x32_bf16 v[36:39], v[144:147], v[196:199], v[36:39]
	v_mfma_f32_16x16x32_bf16 v[20:23], v[144:147], v[204:207], v[20:23]
	v_mfma_f32_16x16x32_bf16 v[20:23], v[148:151], v[208:211], v[20:23]
	v_mfma_f32_16x16x32_bf16 v[16:19], v[176:179], v[208:211], v[16:19]
	v_mfma_f32_16x16x32_bf16 v[16:19], v[172:175], v[204:207], v[16:19]
	v_mfma_f32_16x16x32_bf16 v[0:3], v[172:175], v[212:215], v[0:3]
	v_mfma_f32_16x16x32_bf16 v[0:3], v[176:179], v[216:219], v[0:3]
	v_mfma_f32_16x16x32_bf16 v[4:7], v[148:151], v[216:219], v[4:7]
	v_mfma_f32_16x16x32_bf16 v[4:7], v[144:147], v[212:215], v[4:7]
	s_setprio 0
	s_barrier
	s_add_i32 s80, s80, 2
	s_add_u32 s78, s78, 0x100
	s_addc_u32 s79, s79, 0
	s_add_u32 s58, s58, 0x100
	s_addc_u32 s59, s59, 0
	s_cmp_gt_u32 s80, 13
.LBB0_1011:
	ds_read_b128 v[128:131], v188
	v_xor_b32_e32 v253, 64, v188
	ds_read_b128 v[132:135], v253
	ds_read_b128 v[136:139], v188 offset:2048
	ds_read_b128 v[140:143], v253 offset:2048
	ds_read_b128 v[144:147], v189
	v_xor_b32_e32 v253, 64, v189
	ds_read_b128 v[148:151], v253
	ds_read_b128 v[172:175], v189 offset:2048
	ds_read_b128 v[176:179], v253 offset:2048
	s_add_u32 s60, s58, 0xfffc0080
	s_addc_u32 s61, s59, -1
	s_cmp_eq_u32 s80, 12
	s_cselect_b32 s63, s15, s61
	s_cselect_b32 s62, s51, s60
	s_cselect_b32 s61, s49, s79
	s_cselect_b32 s60, s57, s78
	v_lshl_add_u64 v[220:221], s[58:59], 0, v[166:167]
	s_add_i32 m0, s67, 0xc000
	ds_read_b128 v[180:183], v190
	v_xor_b32_e32 v253, 64, v190
	ds_read_b128 v[192:195], v253
	ds_read_b128 v[196:199], v190 offset:2048
	ds_read_b128 v[200:203], v253 offset:2048
	ds_read_b128 v[204:207], v190 offset:4096
	ds_read_b128 v[208:211], v253 offset:4096
	ds_read_b128 v[212:215], v190 offset:6144
	ds_read_b128 v[216:219], v253 offset:6144
	global_load_lds_dwordx4 v[220:221], off
	v_lshl_add_u64 v[220:221], s[58:59], 0, v[164:165]
	s_add_i32 m0, s67, 0xe000
	s_nop 0
	global_load_lds_dwordx4 v[220:221], off
	s_waitcnt vmcnt(8)
	s_waitcnt lgkmcnt(0)
	s_barrier
	s_setprio 1
	s_waitcnt lgkmcnt(0)
	v_mfma_f32_16x16x32_bf16 v[124:127], v[128:131], v[180:183], v[124:127]
	v_mfma_f32_16x16x32_bf16 v[124:127], v[132:135], v[192:195], v[124:127]
	v_mfma_f32_16x16x32_bf16 v[120:123], v[140:143], v[192:195], v[120:123]
	v_mfma_f32_16x16x32_bf16 v[120:123], v[136:139], v[180:183], v[120:123]
	v_mfma_f32_16x16x32_bf16 v[104:107], v[136:139], v[196:199], v[104:107]
	v_mfma_f32_16x16x32_bf16 v[104:107], v[140:143], v[200:203], v[104:107]
	v_mfma_f32_16x16x32_bf16 v[108:111], v[132:135], v[200:203], v[108:111]
	v_mfma_f32_16x16x32_bf16 v[108:111], v[128:131], v[196:199], v[108:111]
	v_mfma_f32_16x16x32_bf16 v[92:95], v[128:131], v[204:207], v[92:95]
	v_mfma_f32_16x16x32_bf16 v[92:95], v[132:135], v[208:211], v[92:95]
	v_mfma_f32_16x16x32_bf16 v[88:91], v[140:143], v[208:211], v[88:91]
	v_mfma_f32_16x16x32_bf16 v[88:91], v[136:139], v[204:207], v[88:91]
	v_mfma_f32_16x16x32_bf16 v[72:75], v[136:139], v[212:215], v[72:75]
	v_mfma_f32_16x16x32_bf16 v[72:75], v[140:143], v[216:219], v[72:75]
	v_mfma_f32_16x16x32_bf16 v[76:79], v[132:135], v[216:219], v[76:79]
	v_mfma_f32_16x16x32_bf16 v[76:79], v[128:131], v[212:215], v[76:79]
	s_setprio 0
	s_setprio 1
	v_mfma_f32_16x16x32_bf16 v[116:119], v[144:147], v[180:183], v[116:119]
	v_mfma_f32_16x16x32_bf16 v[116:119], v[148:151], v[192:195], v[116:119]
	v_mfma_f32_16x16x32_bf16 v[112:115], v[176:179], v[192:195], v[112:115]
	v_mfma_f32_16x16x32_bf16 v[112:115], v[172:175], v[180:183], v[112:115]
	v_mfma_f32_16x16x32_bf16 v[96:99], v[172:175], v[196:199], v[96:99]
	v_mfma_f32_16x16x32_bf16 v[96:99], v[176:179], v[200:203], v[96:99]
	v_mfma_f32_16x16x32_bf16 v[100:103], v[148:151], v[200:203], v[100:103]
	v_mfma_f32_16x16x32_bf16 v[100:103], v[144:147], v[196:199], v[100:103]
	v_mfma_f32_16x16x32_bf16 v[84:87], v[144:147], v[204:207], v[84:87]
	v_mfma_f32_16x16x32_bf16 v[84:87], v[148:151], v[208:211], v[84:87]
	v_mfma_f32_16x16x32_bf16 v[80:83], v[176:179], v[208:211], v[80:83]
	v_mfma_f32_16x16x32_bf16 v[80:83], v[172:175], v[204:207], v[80:83]
	v_mfma_f32_16x16x32_bf16 v[64:67], v[172:175], v[212:215], v[64:67]
	v_mfma_f32_16x16x32_bf16 v[64:67], v[176:179], v[216:219], v[64:67]
	v_mfma_f32_16x16x32_bf16 v[68:71], v[148:151], v[216:219], v[68:71]
	v_mfma_f32_16x16x32_bf16 v[68:71], v[144:147], v[212:215], v[68:71]
	s_setprio 0
	s_barrier
	s_add_i32 s81, s76, s66
	v_lshl_add_u64 v[220:221], s[60:61], 0, v[154:155]
	s_mov_b32 m0, s81
	ds_read_b128 v[180:183], v190 offset:16384
	v_xor_b32_e32 v253, 64, v190
	ds_read_b128 v[192:195], v253 offset:16384
	ds_read_b128 v[196:199], v190 offset:18432
	ds_read_b128 v[200:203], v253 offset:18432
	ds_read_b128 v[204:207], v190 offset:20480
	ds_read_b128 v[208:211], v253 offset:20480
	ds_read_b128 v[212:215], v190 offset:22528
	ds_read_b128 v[216:219], v253 offset:22528
	global_load_lds_dwordx4 v[220:221], off
	s_add_i32 m0, s81, 0x2000
	s_add_u32 s82, s60, 0x40000
	v_lshl_add_u64 v[222:223], s[60:61], 0, v[162:163]
	s_addc_u32 s83, s61, 0
	s_add_i32 s81, s77, s66
	global_load_lds_dwordx4 v[222:223], off
	v_lshl_add_u64 v[224:225], s[82:83], 0, v[154:155]
	s_mov_b32 m0, s81
	v_lshl_add_u64 v[226:227], s[62:63], 0, v[160:161]
	global_load_lds_dwordx4 v[224:225], off
	v_lshl_add_u64 v[224:225], s[82:83], 0, v[162:163]
	s_add_i32 m0, s81, 0x2000
	s_nop 0
	global_load_lds_dwordx4 v[224:225], off
	v_lshl_add_u64 v[224:225], s[62:63], 0, v[152:153]
	s_mov_b32 m0, s67
	s_nop 0
	global_load_lds_dwordx4 v[224:225], off
	s_mov_b32 m0, s68
	s_nop 0
	global_load_lds_dwordx4 v[226:227], off
	s_waitcnt vmcnt(8)
	s_waitcnt lgkmcnt(0)
	s_barrier
	s_setprio 1
	s_waitcnt lgkmcnt(0)
	v_mfma_f32_16x16x32_bf16 v[60:63], v[128:131], v[180:183], v[60:63]
	v_mfma_f32_16x16x32_bf16 v[60:63], v[132:135], v[192:195], v[60:63]
	v_mfma_f32_16x16x32_bf16 v[56:59], v[140:143], v[192:195], v[56:59]
	v_mfma_f32_16x16x32_bf16 v[56:59], v[136:139], v[180:183], v[56:59]
	v_mfma_f32_16x16x32_bf16 v[40:43], v[136:139], v[196:199], v[40:43]
	v_mfma_f32_16x16x32_bf16 v[40:43], v[140:143], v[200:203], v[40:43]
	v_mfma_f32_16x16x32_bf16 v[44:47], v[132:135], v[200:203], v[44:47]
	v_mfma_f32_16x16x32_bf16 v[44:47], v[128:131], v[196:199], v[44:47]
	v_mfma_f32_16x16x32_bf16 v[28:31], v[128:131], v[204:207], v[28:31]
	v_mfma_f32_16x16x32_bf16 v[28:31], v[132:135], v[208:211], v[28:31]
	v_mfma_f32_16x16x32_bf16 v[24:27], v[140:143], v[208:211], v[24:27]
	v_mfma_f32_16x16x32_bf16 v[24:27], v[136:139], v[204:207], v[24:27]
	v_mfma_f32_16x16x32_bf16 v[8:11], v[136:139], v[212:215], v[8:11]
	v_mfma_f32_16x16x32_bf16 v[8:11], v[140:143], v[216:219], v[8:11]
	v_mfma_f32_16x16x32_bf16 v[12:15], v[132:135], v[216:219], v[12:15]
	v_mfma_f32_16x16x32_bf16 v[12:15], v[128:131], v[212:215], v[12:15]
	s_setprio 0
	s_setprio 1
	v_mfma_f32_16x16x32_bf16 v[52:55], v[144:147], v[180:183], v[52:55]
	v_mfma_f32_16x16x32_bf16 v[52:55], v[148:151], v[192:195], v[52:55]
	v_mfma_f32_16x16x32_bf16 v[48:51], v[176:179], v[192:195], v[48:51]
	v_mfma_f32_16x16x32_bf16 v[48:51], v[172:175], v[180:183], v[48:51]
	v_mfma_f32_16x16x32_bf16 v[32:35], v[172:175], v[196:199], v[32:35]
	v_mfma_f32_16x16x32_bf16 v[32:35], v[176:179], v[200:203], v[32:35]
	v_mfma_f32_16x16x32_bf16 v[36:39], v[148:151], v[200:203], v[36:39]
	v_mfma_f32_16x16x32_bf16 v[36:39], v[144:147], v[196:199], v[36:39]
	v_mfma_f32_16x16x32_bf16 v[20:23], v[144:147], v[204:207], v[20:23]
	v_mfma_f32_16x16x32_bf16 v[20:23], v[148:151], v[208:211], v[20:23]
	v_mfma_f32_16x16x32_bf16 v[16:19], v[176:179], v[208:211], v[16:19]
	v_mfma_f32_16x16x32_bf16 v[16:19], v[172:175], v[204:207], v[16:19]
	v_mfma_f32_16x16x32_bf16 v[0:3], v[172:175], v[212:215], v[0:3]
	v_mfma_f32_16x16x32_bf16 v[0:3], v[176:179], v[216:219], v[0:3]
	v_mfma_f32_16x16x32_bf16 v[4:7], v[148:151], v[216:219], v[4:7]
	v_mfma_f32_16x16x32_bf16 v[4:7], v[144:147], v[212:215], v[4:7]
	s_setprio 0
	s_barrier
	s_add_i32 s81, 0, 0x18000
	s_add_i32 s82, 0, 0x1c000
	v_add_u32_e32 v140, s81, v185
	v_add_u32_e32 v176, s82, v185
	ds_read_b128 v[128:131], v140
	v_xor_b32_e32 v253, 64, v140
	ds_read_b128 v[132:135], v253
	ds_read_b128 v[136:139], v140 offset:2048
	ds_read_b128 v[140:143], v253 offset:2048
	ds_read_b128 v[144:147], v176
	v_xor_b32_e32 v253, 64, v176
	ds_read_b128 v[148:151], v253
	ds_read_b128 v[172:175], v176 offset:2048
	ds_read_b128 v[176:179], v253 offset:2048
	s_add_u32 s62, s62, 0x40000
	s_addc_u32 s63, s63, 0
	s_mov_b32 m0, s69
	v_lshl_add_u64 v[228:229], s[62:63], 0, v[152:153]
	ds_read_b128 v[180:183], v190 offset:32768
	v_xor_b32_e32 v253, 64, v190
	ds_read_b128 v[192:195], v253 offset:32768
	ds_read_b128 v[196:199], v190 offset:34816
	ds_read_b128 v[200:203], v253 offset:34816
	ds_read_b128 v[204:207], v190 offset:36864
	ds_read_b128 v[208:211], v253 offset:36864
	ds_read_b128 v[212:215], v190 offset:38912
	ds_read_b128 v[216:219], v253 offset:38912
	global_load_lds_dwordx4 v[228:229], off
	v_lshl_add_u64 v[228:229], s[62:63], 0, v[160:161]
	s_mov_b32 m0, s70
	s_nop 0
	global_load_lds_dwordx4 v[228:229], off
	s_waitcnt vmcnt(8)
	s_waitcnt lgkmcnt(0)
	s_barrier
	s_setprio 1
	s_waitcnt lgkmcnt(0)
	v_mfma_f32_16x16x32_bf16 v[124:127], v[128:131], v[180:183], v[124:127]
	v_mfma_f32_16x16x32_bf16 v[124:127], v[132:135], v[192:195], v[124:127]
	v_mfma_f32_16x16x32_bf16 v[120:123], v[140:143], v[192:195], v[120:123]
	v_mfma_f32_16x16x32_bf16 v[120:123], v[136:139], v[180:183], v[120:123]
	v_mfma_f32_16x16x32_bf16 v[104:107], v[136:139], v[196:199], v[104:107]
	v_mfma_f32_16x16x32_bf16 v[104:107], v[140:143], v[200:203], v[104:107]
	v_mfma_f32_16x16x32_bf16 v[108:111], v[132:135], v[200:203], v[108:111]
	v_mfma_f32_16x16x32_bf16 v[108:111], v[128:131], v[196:199], v[108:111]
	v_mfma_f32_16x16x32_bf16 v[92:95], v[128:131], v[204:207], v[92:95]
	v_mfma_f32_16x16x32_bf16 v[92:95], v[132:135], v[208:211], v[92:95]
	v_mfma_f32_16x16x32_bf16 v[88:91], v[140:143], v[208:211], v[88:91]
	v_mfma_f32_16x16x32_bf16 v[88:91], v[136:139], v[204:207], v[88:91]
	v_mfma_f32_16x16x32_bf16 v[72:75], v[136:139], v[212:215], v[72:75]
	v_mfma_f32_16x16x32_bf16 v[72:75], v[140:143], v[216:219], v[72:75]
	v_mfma_f32_16x16x32_bf16 v[76:79], v[132:135], v[216:219], v[76:79]
	v_mfma_f32_16x16x32_bf16 v[76:79], v[128:131], v[212:215], v[76:79]
	s_setprio 0
	s_setprio 1
	v_mfma_f32_16x16x32_bf16 v[116:119], v[144:147], v[180:183], v[116:119]
	v_mfma_f32_16x16x32_bf16 v[116:119], v[148:151], v[192:195], v[116:119]
	v_mfma_f32_16x16x32_bf16 v[112:115], v[176:179], v[192:195], v[112:115]
	v_mfma_f32_16x16x32_bf16 v[112:115], v[172:175], v[180:183], v[112:115]
	v_mfma_f32_16x16x32_bf16 v[96:99], v[172:175], v[196:199], v[96:99]
	v_mfma_f32_16x16x32_bf16 v[96:99], v[176:179], v[200:203], v[96:99]
	v_mfma_f32_16x16x32_bf16 v[100:103], v[148:151], v[200:203], v[100:103]
	v_mfma_f32_16x16x32_bf16 v[100:103], v[144:147], v[196:199], v[100:103]
	v_mfma_f32_16x16x32_bf16 v[84:87], v[144:147], v[204:207], v[84:87]
	v_mfma_f32_16x16x32_bf16 v[84:87], v[148:151], v[208:211], v[84:87]
	v_mfma_f32_16x16x32_bf16 v[80:83], v[176:179], v[208:211], v[80:83]
	v_mfma_f32_16x16x32_bf16 v[80:83], v[172:175], v[204:207], v[80:83]
	v_mfma_f32_16x16x32_bf16 v[64:67], v[172:175], v[212:215], v[64:67]
	v_mfma_f32_16x16x32_bf16 v[64:67], v[176:179], v[216:219], v[64:67]
	v_mfma_f32_16x16x32_bf16 v[68:71], v[148:151], v[216:219], v[68:71]
	v_mfma_f32_16x16x32_bf16 v[68:71], v[144:147], v[212:215], v[68:71]
	s_setprio 0
	s_barrier
	s_add_i32 s62, s81, s66
	v_lshl_add_u64 v[220:221], v[220:221], 0, s[26:27]
	s_mov_b32 m0, s62
	ds_read_b128 v[180:183], v190 offset:49152
	v_xor_b32_e32 v253, 64, v190
	ds_read_b128 v[192:195], v253 offset:49152
	ds_read_b128 v[196:199], v190 offset:51200
	ds_read_b128 v[200:203], v253 offset:51200
	ds_read_b128 v[204:207], v190 offset:53248
	ds_read_b128 v[208:211], v253 offset:53248
	ds_read_b128 v[212:215], v190 offset:55296
	ds_read_b128 v[216:219], v253 offset:55296
	global_load_lds_dwordx4 v[220:221], off
	s_add_i32 m0, s62, 0x2000
	s_add_u32 s60, s60, 0x40080
	v_lshl_add_u64 v[220:221], v[222:223], 0, s[26:27]
	s_addc_u32 s61, s61, 0
	s_add_i32 s62, s82, s66
	global_load_lds_dwordx4 v[220:221], off
	v_lshl_add_u64 v[220:221], s[60:61], 0, v[154:155]
	s_mov_b32 m0, s62
	s_nop 0
	global_load_lds_dwordx4 v[220:221], off
	v_lshl_add_u64 v[220:221], s[60:61], 0, v[162:163]
	s_add_i32 m0, s62, 0x2000
	s_nop 0
	global_load_lds_dwordx4 v[220:221], off
	v_lshl_add_u64 v[220:221], v[224:225], 0, s[26:27]
	s_mov_b32 m0, s3
	s_nop 0
	global_load_lds_dwordx4 v[220:221], off
	v_lshl_add_u64 v[220:221], v[226:227], 0, s[26:27]
	s_mov_b32 m0, s72
	s_nop 0
	global_load_lds_dwordx4 v[220:221], off
	s_waitcnt vmcnt(8)
	s_waitcnt lgkmcnt(0)
	s_barrier
	s_setprio 1
	s_waitcnt lgkmcnt(0)
	v_mfma_f32_16x16x32_bf16 v[60:63], v[128:131], v[180:183], v[60:63]
	v_mfma_f32_16x16x32_bf16 v[60:63], v[132:135], v[192:195], v[60:63]
	v_mfma_f32_16x16x32_bf16 v[56:59], v[140:143], v[192:195], v[56:59]
	v_mfma_f32_16x16x32_bf16 v[56:59], v[136:139], v[180:183], v[56:59]
	v_mfma_f32_16x16x32_bf16 v[40:43], v[136:139], v[196:199], v[40:43]
	v_mfma_f32_16x16x32_bf16 v[40:43], v[140:143], v[200:203], v[40:43]
	v_mfma_f32_16x16x32_bf16 v[44:47], v[132:135], v[200:203], v[44:47]
	v_mfma_f32_16x16x32_bf16 v[44:47], v[128:131], v[196:199], v[44:47]
	v_mfma_f32_16x16x32_bf16 v[28:31], v[128:131], v[204:207], v[28:31]
	v_mfma_f32_16x16x32_bf16 v[28:31], v[132:135], v[208:211], v[28:31]
	v_mfma_f32_16x16x32_bf16 v[24:27], v[140:143], v[208:211], v[24:27]
	v_mfma_f32_16x16x32_bf16 v[24:27], v[136:139], v[204:207], v[24:27]
	v_mfma_f32_16x16x32_bf16 v[8:11], v[136:139], v[212:215], v[8:11]
	v_mfma_f32_16x16x32_bf16 v[8:11], v[140:143], v[216:219], v[8:11]
	v_mfma_f32_16x16x32_bf16 v[12:15], v[132:135], v[216:219], v[12:15]
	v_mfma_f32_16x16x32_bf16 v[12:15], v[128:131], v[212:215], v[12:15]
	s_setprio 0
	s_setprio 1
	v_mfma_f32_16x16x32_bf16 v[52:55], v[144:147], v[180:183], v[52:55]
	v_mfma_f32_16x16x32_bf16 v[52:55], v[148:151], v[192:195], v[52:55]
	v_mfma_f32_16x16x32_bf16 v[48:51], v[176:179], v[192:195], v[48:51]
	v_mfma_f32_16x16x32_bf16 v[48:51], v[172:175], v[180:183], v[48:51]
	v_mfma_f32_16x16x32_bf16 v[32:35], v[172:175], v[196:199], v[32:35]
	v_mfma_f32_16x16x32_bf16 v[32:35], v[176:179], v[200:203], v[32:35]
	v_mfma_f32_16x16x32_bf16 v[36:39], v[148:151], v[200:203], v[36:39]
	v_mfma_f32_16x16x32_bf16 v[36:39], v[144:147], v[196:199], v[36:39]
	v_mfma_f32_16x16x32_bf16 v[20:23], v[144:147], v[204:207], v[20:23]
	v_mfma_f32_16x16x32_bf16 v[20:23], v[148:151], v[208:211], v[20:23]
	v_mfma_f32_16x16x32_bf16 v[16:19], v[176:179], v[208:211], v[16:19]
	v_mfma_f32_16x16x32_bf16 v[16:19], v[172:175], v[204:207], v[16:19]
	v_mfma_f32_16x16x32_bf16 v[0:3], v[172:175], v[212:215], v[0:3]
	v_mfma_f32_16x16x32_bf16 v[0:3], v[176:179], v[216:219], v[0:3]
	v_mfma_f32_16x16x32_bf16 v[4:7], v[148:151], v[216:219], v[4:7]
	v_mfma_f32_16x16x32_bf16 v[4:7], v[144:147], v[212:215], v[4:7]
	s_setprio 0
	s_barrier
	s_add_i32 s80, s80, 2
	s_add_u32 s78, s78, 0x100
	s_addc_u32 s79, s79, 0
	s_add_u32 s58, s58, 0x100
	s_addc_u32 s59, s59, 0
	s_cmp_gt_u32 s80, 13
	s_cbranch_scc0 .LBB0_1011
	s_and_b64 vcc, exec, s[28:29]
	s_cbranch_vccz .LBB0_1014
	s_barrier

.LBB0_1096:
	s_ashr_i32 s25, s24, 31
	s_lshl_b64 s[26:27], s[24:25], 19
	s_add_u32 s26, s3, s26
	s_addc_u32 s27, s33, s27
	s_and_b64 s[28:29], s[6:7], exec
	s_cselect_b32 s25, s27, s47
	s_cselect_b32 s65, s26, s46
	s_ashr_i32 s23, s22, 31
	s_lshl_b64 s[28:29], s[22:23], 19
	s_add_u32 s28, s35, s28
	s_addc_u32 s29, s48, s29
	s_and_b64 s[66:67], s[6:7], exec
	s_cselect_b32 s66, s29, s45
	s_cselect_b32 s67, s28, s44
	s_lshl_b32 s23, s30, 8
	v_add_u32_e32 v0, s23, v148
	s_add_u32 s68, s44, 0x100
	v_ashrrev_i32_e32 v1, 31, v0
	s_addc_u32 s69, s45, 0
	v_lshl_add_u64 v[144:145], v[0:1], 4, s[12:13]
	s_add_u32 s30, s46, 0x40080
	s_addc_u32 s31, s47, 0
	s_mov_b32 s70, -2
	s_mov_b64 s[44:45], 0
	s_cmp_eq_u32 s56, 1
	s_cbranch_scc1 .Lfa_10
	v_add_u32_e32 v153, s61, v147
	ds_read_b128 v[160:163], v153
	v_xor_b32_e32 v253, 64, v153
	ds_read_b128 v[164:167], v253
	ds_read_b128 v[168:171], v153 offset:2048
	ds_read_b128 v[172:175], v253 offset:2048
	v_add_u32_e32 v153, s62, v147
	ds_read_b128 v[176:179], v153
	v_xor_b32_e32 v253, 64, v153
	ds_read_b128 v[180:183], v253
	ds_read_b128 v[184:187], v153 offset:2048
	ds_read_b128 v[188:191], v253 offset:2048
	s_add_u32 s46, s30, 0xfffc0080
	s_addc_u32 s47, s31, -1
	s_and_b64 s[44:45], s[44:45], exec
	s_cselect_b32 s47, s25, s47
	s_cselect_b32 s46, s65, s46
	s_cselect_b32 s45, s66, s69
	s_cselect_b32 s44, s67, s68
	v_lshl_add_u64 v[154:155], s[30:31], 0, v[138:139]
	s_add_i32 m0, s52, 0xc000
	ds_read_b128 v[192:195], v150
	v_xor_b32_e32 v253, 64, v150
	ds_read_b128 v[196:199], v253
	ds_read_b128 v[200:203], v150 offset:2048
	ds_read_b128 v[204:207], v253 offset:2048
	ds_read_b128 v[208:211], v150 offset:4096
	ds_read_b128 v[212:215], v253 offset:4096
	ds_read_b128 v[216:219], v150 offset:6144
	ds_read_b128 v[220:223], v253 offset:6144
	global_load_lds_dwordx4 v[154:155], off
	v_lshl_add_u64 v[154:155], s[30:31], 0, v[136:137]
	s_add_i32 m0, s52, 0xe000
	s_nop 0
	global_load_lds_dwordx4 v[154:155], off
	s_waitcnt vmcnt(16)
	s_waitcnt lgkmcnt(0)
	s_barrier
	s_setprio 1
	s_waitcnt lgkmcnt(0)
	v_mfma_f32_16x16x32_bf16 v[124:127], v[160:163], v[192:195], 0
	v_mfma_f32_16x16x32_bf16 v[116:119], v[168:171], v[192:195], 0
	v_mfma_f32_16x16x32_bf16 v[108:111], v[160:163], v[200:203], 0
	v_mfma_f32_16x16x32_bf16 v[100:103], v[168:171], v[200:203], 0
	v_mfma_f32_16x16x32_bf16 v[92:95], v[160:163], v[208:211], 0
	v_mfma_f32_16x16x32_bf16 v[84:87], v[168:171], v[208:211], 0
	v_mfma_f32_16x16x32_bf16 v[76:79], v[160:163], v[216:219], 0
	v_mfma_f32_16x16x32_bf16 v[68:71], v[168:171], v[216:219], 0
	v_mfma_f32_16x16x32_bf16 v[124:127], v[164:167], v[196:199], v[124:127]
	v_mfma_f32_16x16x32_bf16 v[116:119], v[172:175], v[196:199], v[116:119]
	v_mfma_f32_16x16x32_bf16 v[108:111], v[164:167], v[204:207], v[108:111]
	v_mfma_f32_16x16x32_bf16 v[100:103], v[172:175], v[204:207], v[100:103]
	v_mfma_f32_16x16x32_bf16 v[92:95], v[164:167], v[212:215], v[92:95]
	v_mfma_f32_16x16x32_bf16 v[84:87], v[172:175], v[212:215], v[84:87]
	v_mfma_f32_16x16x32_bf16 v[76:79], v[164:167], v[220:223], v[76:79]
	v_mfma_f32_16x16x32_bf16 v[68:71], v[172:175], v[220:223], v[68:71]
	s_setprio 0
	s_setprio 1
	v_mfma_f32_16x16x32_bf16 v[120:123], v[176:179], v[192:195], 0
	v_mfma_f32_16x16x32_bf16 v[112:115], v[184:187], v[192:195], 0
	v_mfma_f32_16x16x32_bf16 v[104:107], v[176:179], v[200:203], 0
	v_mfma_f32_16x16x32_bf16 v[96:99], v[184:187], v[200:203], 0
	v_mfma_f32_16x16x32_bf16 v[88:91], v[176:179], v[208:211], 0
	v_mfma_f32_16x16x32_bf16 v[80:83], v[184:187], v[208:211], 0
	v_mfma_f32_16x16x32_bf16 v[72:75], v[176:179], v[216:219], 0
	v_mfma_f32_16x16x32_bf16 v[64:67], v[184:187], v[216:219], 0
	v_mfma_f32_16x16x32_bf16 v[120:123], v[180:183], v[196:199], v[120:123]
	v_mfma_f32_16x16x32_bf16 v[112:115], v[188:191], v[196:199], v[112:115]
	v_mfma_f32_16x16x32_bf16 v[104:107], v[180:183], v[204:207], v[104:107]
	v_mfma_f32_16x16x32_bf16 v[96:99], v[188:191], v[204:207], v[96:99]
	v_mfma_f32_16x16x32_bf16 v[88:91], v[180:183], v[212:215], v[88:91]
	v_mfma_f32_16x16x32_bf16 v[80:83], v[188:191], v[212:215], v[80:83]
	v_mfma_f32_16x16x32_bf16 v[72:75], v[180:183], v[220:223], v[72:75]
	v_mfma_f32_16x16x32_bf16 v[64:67], v[188:191], v[220:223], v[64:67]
	s_setprio 0
	s_barrier
	s_add_i32 s71, s61, s49
	v_lshl_add_u64 v[154:155], s[44:45], 0, v[132:133]
	s_mov_b32 m0, s71
	ds_read_b128 v[192:195], v150 offset:16384
	v_xor_b32_e32 v253, 64, v150
	ds_read_b128 v[196:199], v253 offset:16384
	ds_read_b128 v[200:203], v150 offset:18432
	ds_read_b128 v[204:207], v253 offset:18432
	ds_read_b128 v[208:211], v150 offset:20480
	ds_read_b128 v[212:215], v253 offset:20480
	ds_read_b128 v[216:219], v150 offset:22528
	ds_read_b128 v[220:223], v253 offset:22528
	global_load_lds_dwordx4 v[154:155], off
	s_add_i32 m0, s71, 0x2000
	s_add_u32 s72, s44, 0x40000
	v_lshl_add_u64 v[224:225], s[44:45], 0, v[128:129]
	s_addc_u32 s73, s45, 0
	s_add_i32 s71, s62, s49
	global_load_lds_dwordx4 v[224:225], off
	v_lshl_add_u64 v[226:227], s[72:73], 0, v[132:133]
	s_mov_b32 m0, s71
	v_lshl_add_u64 v[228:229], s[46:47], 0, v[130:131]
	global_load_lds_dwordx4 v[226:227], off
	v_lshl_add_u64 v[226:227], s[72:73], 0, v[128:129]
	s_add_i32 m0, s71, 0x2000
	s_nop 0
	global_load_lds_dwordx4 v[226:227], off
	v_lshl_add_u64 v[226:227], s[46:47], 0, v[134:135]
	s_mov_b32 m0, s52
	s_nop 0
	global_load_lds_dwordx4 v[226:227], off
	s_mov_b32 m0, s53
	s_nop 0
	global_load_lds_dwordx4 v[228:229], off
	s_waitcnt vmcnt(16)
	s_waitcnt lgkmcnt(0)
	s_barrier
	s_setprio 1
	s_waitcnt lgkmcnt(0)
	v_mfma_f32_16x16x32_bf16 v[60:63], v[160:163], v[192:195], 0
	v_mfma_f32_16x16x32_bf16 v[52:55], v[168:171], v[192:195], 0
	v_mfma_f32_16x16x32_bf16 v[44:47], v[160:163], v[200:203], 0
	v_mfma_f32_16x16x32_bf16 v[36:39], v[168:171], v[200:203], 0
	v_mfma_f32_16x16x32_bf16 v[28:31], v[160:163], v[208:211], 0
	v_mfma_f32_16x16x32_bf16 v[20:23], v[168:171], v[208:211], 0
	v_mfma_f32_16x16x32_bf16 v[12:15], v[160:163], v[216:219], 0
	v_mfma_f32_16x16x32_bf16 v[4:7], v[168:171], v[216:219], 0
	v_mfma_f32_16x16x32_bf16 v[60:63], v[164:167], v[196:199], v[60:63]
	v_mfma_f32_16x16x32_bf16 v[52:55], v[172:175], v[196:199], v[52:55]
	v_mfma_f32_16x16x32_bf16 v[44:47], v[164:167], v[204:207], v[44:47]
	v_mfma_f32_16x16x32_bf16 v[36:39], v[172:175], v[204:207], v[36:39]
	v_mfma_f32_16x16x32_bf16 v[28:31], v[164:167], v[212:215], v[28:31]
	v_mfma_f32_16x16x32_bf16 v[20:23], v[172:175], v[212:215], v[20:23]
	v_mfma_f32_16x16x32_bf16 v[12:15], v[164:167], v[220:223], v[12:15]
	v_mfma_f32_16x16x32_bf16 v[4:7], v[172:175], v[220:223], v[4:7]
	s_setprio 0
	s_setprio 1
	v_mfma_f32_16x16x32_bf16 v[56:59], v[176:179], v[192:195], 0
	v_mfma_f32_16x16x32_bf16 v[48:51], v[184:187], v[192:195], 0
	v_mfma_f32_16x16x32_bf16 v[40:43], v[176:179], v[200:203], 0
	v_mfma_f32_16x16x32_bf16 v[32:35], v[184:187], v[200:203], 0
	v_mfma_f32_16x16x32_bf16 v[24:27], v[176:179], v[208:211], 0
	v_mfma_f32_16x16x32_bf16 v[16:19], v[184:187], v[208:211], 0
	v_mfma_f32_16x16x32_bf16 v[8:11], v[176:179], v[216:219], 0
	v_mfma_f32_16x16x32_bf16 v[0:3], v[184:187], v[216:219], 0
	v_mfma_f32_16x16x32_bf16 v[56:59], v[180:183], v[196:199], v[56:59]
	v_mfma_f32_16x16x32_bf16 v[48:51], v[188:191], v[196:199], v[48:51]
	v_mfma_f32_16x16x32_bf16 v[40:43], v[180:183], v[204:207], v[40:43]
	v_mfma_f32_16x16x32_bf16 v[32:35], v[188:191], v[204:207], v[32:35]
	v_mfma_f32_16x16x32_bf16 v[24:27], v[180:183], v[212:215], v[24:27]
	v_mfma_f32_16x16x32_bf16 v[16:19], v[188:191], v[212:215], v[16:19]
	v_mfma_f32_16x16x32_bf16 v[8:11], v[180:183], v[220:223], v[8:11]
	v_mfma_f32_16x16x32_bf16 v[0:3], v[188:191], v[220:223], v[0:3]
	s_setprio 0
	s_barrier
	s_add_i32 s71, 0, 0x18000
	v_add_u32_e32 v153, s71, v147
	s_add_i32 s72, 0, 0x1c000
	ds_read_b128 v[160:163], v153
	v_xor_b32_e32 v253, 64, v153
	ds_read_b128 v[164:167], v253
	ds_read_b128 v[168:171], v153 offset:2048
	ds_read_b128 v[172:175], v253 offset:2048
	v_add_u32_e32 v153, s72, v147
	ds_read_b128 v[176:179], v153
	v_xor_b32_e32 v253, 64, v153
	ds_read_b128 v[180:183], v253
	ds_read_b128 v[184:187], v153 offset:2048
	ds_read_b128 v[188:191], v253 offset:2048
	s_add_u32 s46, s46, 0x40000
	s_addc_u32 s47, s47, 0
	s_mov_b32 m0, s54
	v_lshl_add_u64 v[230:231], s[46:47], 0, v[134:135]
	ds_read_b128 v[192:195], v150 offset:32768
	v_xor_b32_e32 v253, 64, v150
	ds_read_b128 v[196:199], v253 offset:32768
	ds_read_b128 v[200:203], v150 offset:34816
	ds_read_b128 v[204:207], v253 offset:34816
	ds_read_b128 v[208:211], v150 offset:36864
	ds_read_b128 v[212:215], v253 offset:36864
	ds_read_b128 v[216:219], v150 offset:38912
	ds_read_b128 v[220:223], v253 offset:38912
	global_load_lds_dwordx4 v[230:231], off
	v_lshl_add_u64 v[230:231], s[46:47], 0, v[130:131]
	s_mov_b32 m0, s55
	s_nop 0
	global_load_lds_dwordx4 v[230:231], off
	s_waitcnt vmcnt(8)
	s_waitcnt lgkmcnt(0)
	s_barrier
	s_setprio 1
	s_waitcnt lgkmcnt(0)
	v_mfma_f32_16x16x32_bf16 v[124:127], v[160:163], v[192:195], v[124:127]
	v_mfma_f32_16x16x32_bf16 v[124:127], v[164:167], v[196:199], v[124:127]
	v_mfma_f32_16x16x32_bf16 v[116:119], v[172:175], v[196:199], v[116:119]
	v_mfma_f32_16x16x32_bf16 v[116:119], v[168:171], v[192:195], v[116:119]
	v_mfma_f32_16x16x32_bf16 v[100:103], v[168:171], v[200:203], v[100:103]
	v_mfma_f32_16x16x32_bf16 v[100:103], v[172:175], v[204:207], v[100:103]
	v_mfma_f32_16x16x32_bf16 v[108:111], v[164:167], v[204:207], v[108:111]
	v_mfma_f32_16x16x32_bf16 v[108:111], v[160:163], v[200:203], v[108:111]
	v_mfma_f32_16x16x32_bf16 v[92:95], v[160:163], v[208:211], v[92:95]
	v_mfma_f32_16x16x32_bf16 v[92:95], v[164:167], v[212:215], v[92:95]
	v_mfma_f32_16x16x32_bf16 v[84:87], v[172:175], v[212:215], v[84:87]
	v_mfma_f32_16x16x32_bf16 v[84:87], v[168:171], v[208:211], v[84:87]
	v_mfma_f32_16x16x32_bf16 v[68:71], v[168:171], v[216:219], v[68:71]
	v_mfma_f32_16x16x32_bf16 v[68:71], v[172:175], v[220:223], v[68:71]
	v_mfma_f32_16x16x32_bf16 v[76:79], v[164:167], v[220:223], v[76:79]
	v_mfma_f32_16x16x32_bf16 v[76:79], v[160:163], v[216:219], v[76:79]
	s_setprio 0
	s_setprio 1
	v_mfma_f32_16x16x32_bf16 v[120:123], v[176:179], v[192:195], v[120:123]
	v_mfma_f32_16x16x32_bf16 v[120:123], v[180:183], v[196:199], v[120:123]
	v_mfma_f32_16x16x32_bf16 v[112:115], v[188:191], v[196:199], v[112:115]
	v_mfma_f32_16x16x32_bf16 v[112:115], v[184:187], v[192:195], v[112:115]
	v_mfma_f32_16x16x32_bf16 v[96:99], v[184:187], v[200:203], v[96:99]
	v_mfma_f32_16x16x32_bf16 v[96:99], v[188:191], v[204:207], v[96:99]
	v_mfma_f32_16x16x32_bf16 v[104:107], v[180:183], v[204:207], v[104:107]
	v_mfma_f32_16x16x32_bf16 v[104:107], v[176:179], v[200:203], v[104:107]
	v_mfma_f32_16x16x32_bf16 v[88:91], v[176:179], v[208:211], v[88:91]
	v_mfma_f32_16x16x32_bf16 v[88:91], v[180:183], v[212:215], v[88:91]
	v_mfma_f32_16x16x32_bf16 v[80:83], v[188:191], v[212:215], v[80:83]
	v_mfma_f32_16x16x32_bf16 v[80:83], v[184:187], v[208:211], v[80:83]
	v_mfma_f32_16x16x32_bf16 v[64:67], v[184:187], v[216:219], v[64:67]
	v_mfma_f32_16x16x32_bf16 v[64:67], v[188:191], v[220:223], v[64:67]
	v_mfma_f32_16x16x32_bf16 v[72:75], v[180:183], v[220:223], v[72:75]
	v_mfma_f32_16x16x32_bf16 v[72:75], v[176:179], v[216:219], v[72:75]
	s_setprio 0
	s_barrier
	s_add_i32 s46, s71, s49
	v_lshl_add_u64 v[154:155], v[154:155], 0, s[14:15]
	s_mov_b32 m0, s46
	ds_read_b128 v[192:195], v150 offset:49152
	v_xor_b32_e32 v253, 64, v150
	ds_read_b128 v[196:199], v253 offset:49152
	ds_read_b128 v[200:203], v150 offset:51200
	ds_read_b128 v[204:207], v253 offset:51200
	ds_read_b128 v[208:211], v150 offset:53248
	ds_read_b128 v[212:215], v253 offset:53248
	ds_read_b128 v[216:219], v150 offset:55296
	ds_read_b128 v[220:223], v253 offset:55296
	global_load_lds_dwordx4 v[154:155], off
	s_add_i32 m0, s46, 0x2000
	s_add_u32 s44, s44, 0x40080
	v_lshl_add_u64 v[154:155], v[224:225], 0, s[14:15]
	s_addc_u32 s45, s45, 0
	s_add_i32 s46, s72, s49
	global_load_lds_dwordx4 v[154:155], off
	v_lshl_add_u64 v[154:155], s[44:45], 0, v[132:133]
	s_mov_b32 m0, s46
	s_nop 0
	global_load_lds_dwordx4 v[154:155], off
	v_lshl_add_u64 v[154:155], s[44:45], 0, v[128:129]
	s_add_i32 m0, s46, 0x2000
	s_nop 0
	global_load_lds_dwordx4 v[154:155], off
	v_lshl_add_u64 v[154:155], v[226:227], 0, s[14:15]
	s_mov_b32 m0, s57
	s_nop 0
	global_load_lds_dwordx4 v[154:155], off
	v_lshl_add_u64 v[154:155], v[228:229], 0, s[14:15]
	s_mov_b32 m0, s58
	s_nop 0
	global_load_lds_dwordx4 v[154:155], off
	s_waitcnt vmcnt(8)
	s_waitcnt lgkmcnt(0)
	s_barrier
	s_setprio 1
	s_waitcnt lgkmcnt(0)
	v_mfma_f32_16x16x32_bf16 v[60:63], v[160:163], v[192:195], v[60:63]
	v_mfma_f32_16x16x32_bf16 v[60:63], v[164:167], v[196:199], v[60:63]
	v_mfma_f32_16x16x32_bf16 v[52:55], v[172:175], v[196:199], v[52:55]
	v_mfma_f32_16x16x32_bf16 v[52:55], v[168:171], v[192:195], v[52:55]
	v_mfma_f32_16x16x32_bf16 v[36:39], v[168:171], v[200:203], v[36:39]
	v_mfma_f32_16x16x32_bf16 v[36:39], v[172:175], v[204:207], v[36:39]
	v_mfma_f32_16x16x32_bf16 v[44:47], v[164:167], v[204:207], v[44:47]
	v_mfma_f32_16x16x32_bf16 v[44:47], v[160:163], v[200:203], v[44:47]
	v_mfma_f32_16x16x32_bf16 v[28:31], v[160:163], v[208:211], v[28:31]
	v_mfma_f32_16x16x32_bf16 v[28:31], v[164:167], v[212:215], v[28:31]
	v_mfma_f32_16x16x32_bf16 v[20:23], v[172:175], v[212:215], v[20:23]
	v_mfma_f32_16x16x32_bf16 v[20:23], v[168:171], v[208:211], v[20:23]
	v_mfma_f32_16x16x32_bf16 v[4:7], v[168:171], v[216:219], v[4:7]
	v_mfma_f32_16x16x32_bf16 v[4:7], v[172:175], v[220:223], v[4:7]
	v_mfma_f32_16x16x32_bf16 v[12:15], v[164:167], v[220:223], v[12:15]
	v_mfma_f32_16x16x32_bf16 v[12:15], v[160:163], v[216:219], v[12:15]
	s_setprio 0
	s_setprio 1
	v_mfma_f32_16x16x32_bf16 v[56:59], v[176:179], v[192:195], v[56:59]
	v_mfma_f32_16x16x32_bf16 v[56:59], v[180:183], v[196:199], v[56:59]
	v_mfma_f32_16x16x32_bf16 v[48:51], v[188:191], v[196:199], v[48:51]
	v_mfma_f32_16x16x32_bf16 v[48:51], v[184:187], v[192:195], v[48:51]
	v_mfma_f32_16x16x32_bf16 v[32:35], v[184:187], v[200:203], v[32:35]
	v_mfma_f32_16x16x32_bf16 v[32:35], v[188:191], v[204:207], v[32:35]
	v_mfma_f32_16x16x32_bf16 v[40:43], v[180:183], v[204:207], v[40:43]
	v_mfma_f32_16x16x32_bf16 v[40:43], v[176:179], v[200:203], v[40:43]
	v_mfma_f32_16x16x32_bf16 v[24:27], v[176:179], v[208:211], v[24:27]
	v_mfma_f32_16x16x32_bf16 v[24:27], v[180:183], v[212:215], v[24:27]
	v_mfma_f32_16x16x32_bf16 v[16:19], v[188:191], v[212:215], v[16:19]
	v_mfma_f32_16x16x32_bf16 v[16:19], v[184:187], v[208:211], v[16:19]
	v_mfma_f32_16x16x32_bf16 v[0:3], v[184:187], v[216:219], v[0:3]
	v_mfma_f32_16x16x32_bf16 v[0:3], v[188:191], v[220:223], v[0:3]
	v_mfma_f32_16x16x32_bf16 v[8:11], v[180:183], v[220:223], v[8:11]
	v_mfma_f32_16x16x32_bf16 v[8:11], v[176:179], v[216:219], v[8:11]
	s_setprio 0
	s_barrier
	s_add_i32 s70, s70, 2
	s_add_u32 s68, s68, 0x100
	s_addc_u32 s69, s69, 0
	s_add_u32 s30, s30, 0x100
	s_addc_u32 s31, s31, 0
	s_branch .LBB0_1098
.Lfa_10:
	v_add_u32_e32 v153, s61, v147
	ds_read_b128 v[160:163], v153
	v_xor_b32_e32 v253, 64, v153
	ds_read_b128 v[164:167], v253
	ds_read_b128 v[168:171], v153 offset:2048
	ds_read_b128 v[172:175], v253 offset:2048
	v_add_u32_e32 v153, s62, v147
	ds_read_b128 v[176:179], v153
	v_xor_b32_e32 v253, 64, v153
	ds_read_b128 v[180:183], v253
	ds_read_b128 v[184:187], v153 offset:2048
	ds_read_b128 v[188:191], v253 offset:2048
	s_add_u32 s46, s30, 0xfffc0080
	s_addc_u32 s47, s31, -1
	s_and_b64 s[44:45], s[44:45], exec
	s_cselect_b32 s47, s25, s47
	s_cselect_b32 s46, s65, s46
	s_cselect_b32 s45, s66, s69
	s_cselect_b32 s44, s67, s68
	v_lshl_add_u64 v[154:155], s[30:31], 0, v[138:139]
	s_add_i32 m0, s52, 0xc000
	ds_read_b128 v[192:195], v150
	v_xor_b32_e32 v253, 64, v150
	ds_read_b128 v[196:199], v253
	ds_read_b128 v[200:203], v150 offset:2048
	ds_read_b128 v[204:207], v253 offset:2048
	ds_read_b128 v[208:211], v150 offset:4096
	ds_read_b128 v[212:215], v253 offset:4096
	ds_read_b128 v[216:219], v150 offset:6144
	ds_read_b128 v[220:223], v253 offset:6144
	global_load_lds_dwordx4 v[154:155], off
	v_lshl_add_u64 v[154:155], s[30:31], 0, v[136:137]
	s_add_i32 m0, s52, 0xe000
	s_nop 0
	global_load_lds_dwordx4 v[154:155], off
	s_waitcnt vmcnt(8)
	s_waitcnt lgkmcnt(0)
	s_barrier
	s_setprio 1
	s_waitcnt lgkmcnt(0)
	v_mfma_f32_16x16x32_bf16 v[124:127], v[160:163], v[192:195], 0
	v_mfma_f32_16x16x32_bf16 v[116:119], v[168:171], v[192:195], 0
	v_mfma_f32_16x16x32_bf16 v[108:111], v[160:163], v[200:203], 0
	v_mfma_f32_16x16x32_bf16 v[100:103], v[168:171], v[200:203], 0
	v_mfma_f32_16x16x32_bf16 v[92:95], v[160:163], v[208:211], 0
	v_mfma_f32_16x16x32_bf16 v[84:87], v[168:171], v[208:211], 0
	v_mfma_f32_16x16x32_bf16 v[76:79], v[160:163], v[216:219], 0
	v_mfma_f32_16x16x32_bf16 v[68:71], v[168:171], v[216:219], 0
	v_mfma_f32_16x16x32_bf16 v[124:127], v[164:167], v[196:199], v[124:127]
	v_mfma_f32_16x16x32_bf16 v[116:119], v[172:175], v[196:199], v[116:119]
	v_mfma_f32_16x16x32_bf16 v[108:111], v[164:167], v[204:207], v[108:111]
	v_mfma_f32_16x16x32_bf16 v[100:103], v[172:175], v[204:207], v[100:103]
	v_mfma_f32_16x16x32_bf16 v[92:95], v[164:167], v[212:215], v[92:95]
	v_mfma_f32_16x16x32_bf16 v[84:87], v[172:175], v[212:215], v[84:87]
	v_mfma_f32_16x16x32_bf16 v[76:79], v[164:167], v[220:223], v[76:79]
	v_mfma_f32_16x16x32_bf16 v[68:71], v[172:175], v[220:223], v[68:71]
	s_setprio 0
	s_setprio 1
	v_mfma_f32_16x16x32_bf16 v[120:123], v[176:179], v[192:195], 0
	v_mfma_f32_16x16x32_bf16 v[112:115], v[184:187], v[192:195], 0
	v_mfma_f32_16x16x32_bf16 v[104:107], v[176:179], v[200:203], 0
	v_mfma_f32_16x16x32_bf16 v[96:99], v[184:187], v[200:203], 0
	v_mfma_f32_16x16x32_bf16 v[88:91], v[176:179], v[208:211], 0
	v_mfma_f32_16x16x32_bf16 v[80:83], v[184:187], v[208:211], 0
	v_mfma_f32_16x16x32_bf16 v[72:75], v[176:179], v[216:219], 0
	v_mfma_f32_16x16x32_bf16 v[64:67], v[184:187], v[216:219], 0
	v_mfma_f32_16x16x32_bf16 v[120:123], v[180:183], v[196:199], v[120:123]
	v_mfma_f32_16x16x32_bf16 v[112:115], v[188:191], v[196:199], v[112:115]
	v_mfma_f32_16x16x32_bf16 v[104:107], v[180:183], v[204:207], v[104:107]
	v_mfma_f32_16x16x32_bf16 v[96:99], v[188:191], v[204:207], v[96:99]
	v_mfma_f32_16x16x32_bf16 v[88:91], v[180:183], v[212:215], v[88:91]
	v_mfma_f32_16x16x32_bf16 v[80:83], v[188:191], v[212:215], v[80:83]
	v_mfma_f32_16x16x32_bf16 v[72:75], v[180:183], v[220:223], v[72:75]
	v_mfma_f32_16x16x32_bf16 v[64:67], v[188:191], v[220:223], v[64:67]
	s_setprio 0
	s_barrier
	s_add_i32 s71, s61, s49
	v_lshl_add_u64 v[154:155], s[44:45], 0, v[132:133]
	s_mov_b32 m0, s71
	ds_read_b128 v[192:195], v150 offset:16384
	v_xor_b32_e32 v253, 64, v150
	ds_read_b128 v[196:199], v253 offset:16384
	ds_read_b128 v[200:203], v150 offset:18432
	ds_read_b128 v[204:207], v253 offset:18432
	ds_read_b128 v[208:211], v150 offset:20480
	ds_read_b128 v[212:215], v253 offset:20480
	ds_read_b128 v[216:219], v150 offset:22528
	ds_read_b128 v[220:223], v253 offset:22528
	global_load_lds_dwordx4 v[154:155], off
	s_add_i32 m0, s71, 0x2000
	s_add_u32 s72, s44, 0x40000
	v_lshl_add_u64 v[224:225], s[44:45], 0, v[128:129]
	s_addc_u32 s73, s45, 0
	s_add_i32 s71, s62, s49
	global_load_lds_dwordx4 v[224:225], off
	v_lshl_add_u64 v[226:227], s[72:73], 0, v[132:133]
	s_mov_b32 m0, s71
	v_lshl_add_u64 v[228:229], s[46:47], 0, v[130:131]
	global_load_lds_dwordx4 v[226:227], off
	v_lshl_add_u64 v[226:227], s[72:73], 0, v[128:129]
	s_add_i32 m0, s71, 0x2000
	s_nop 0
	global_load_lds_dwordx4 v[226:227], off
	v_lshl_add_u64 v[226:227], s[46:47], 0, v[134:135]
	s_mov_b32 m0, s52
	s_nop 0
	global_load_lds_dwordx4 v[226:227], off
	s_mov_b32 m0, s53
	s_nop 0
	global_load_lds_dwordx4 v[228:229], off
	s_waitcnt vmcnt(8)
	s_waitcnt lgkmcnt(0)
	s_barrier
	s_setprio 1
	s_waitcnt lgkmcnt(0)
	v_mfma_f32_16x16x32_bf16 v[60:63], v[160:163], v[192:195], 0
	v_mfma_f32_16x16x32_bf16 v[52:55], v[168:171], v[192:195], 0
	v_mfma_f32_16x16x32_bf16 v[44:47], v[160:163], v[200:203], 0
	v_mfma_f32_16x16x32_bf16 v[36:39], v[168:171], v[200:203], 0
	v_mfma_f32_16x16x32_bf16 v[28:31], v[160:163], v[208:211], 0
	v_mfma_f32_16x16x32_bf16 v[20:23], v[168:171], v[208:211], 0
	v_mfma_f32_16x16x32_bf16 v[12:15], v[160:163], v[216:219], 0
	v_mfma_f32_16x16x32_bf16 v[4:7], v[168:171], v[216:219], 0
	v_mfma_f32_16x16x32_bf16 v[60:63], v[164:167], v[196:199], v[60:63]
	v_mfma_f32_16x16x32_bf16 v[52:55], v[172:175], v[196:199], v[52:55]
	v_mfma_f32_16x16x32_bf16 v[44:47], v[164:167], v[204:207], v[44:47]
	v_mfma_f32_16x16x32_bf16 v[36:39], v[172:175], v[204:207], v[36:39]
	v_mfma_f32_16x16x32_bf16 v[28:31], v[164:167], v[212:215], v[28:31]
	v_mfma_f32_16x16x32_bf16 v[20:23], v[172:175], v[212:215], v[20:23]
	v_mfma_f32_16x16x32_bf16 v[12:15], v[164:167], v[220:223], v[12:15]
	v_mfma_f32_16x16x32_bf16 v[4:7], v[172:175], v[220:223], v[4:7]
	s_setprio 0
	s_setprio 1
	v_mfma_f32_16x16x32_bf16 v[56:59], v[176:179], v[192:195], 0
	v_mfma_f32_16x16x32_bf16 v[48:51], v[184:187], v[192:195], 0
	v_mfma_f32_16x16x32_bf16 v[40:43], v[176:179], v[200:203], 0
	v_mfma_f32_16x16x32_bf16 v[32:35], v[184:187], v[200:203], 0
	v_mfma_f32_16x16x32_bf16 v[24:27], v[176:179], v[208:211], 0
	v_mfma_f32_16x16x32_bf16 v[16:19], v[184:187], v[208:211], 0
	v_mfma_f32_16x16x32_bf16 v[8:11], v[176:179], v[216:219], 0
	v_mfma_f32_16x16x32_bf16 v[0:3], v[184:187], v[216:219], 0
	v_mfma_f32_16x16x32_bf16 v[56:59], v[180:183], v[196:199], v[56:59]
	v_mfma_f32_16x16x32_bf16 v[48:51], v[188:191], v[196:199], v[48:51]
	v_mfma_f32_16x16x32_bf16 v[40:43], v[180:183], v[204:207], v[40:43]
	v_mfma_f32_16x16x32_bf16 v[32:35], v[188:191], v[204:207], v[32:35]
	v_mfma_f32_16x16x32_bf16 v[24:27], v[180:183], v[212:215], v[24:27]
	v_mfma_f32_16x16x32_bf16 v[16:19], v[188:191], v[212:215], v[16:19]
	v_mfma_f32_16x16x32_bf16 v[8:11], v[180:183], v[220:223], v[8:11]
	v_mfma_f32_16x16x32_bf16 v[0:3], v[188:191], v[220:223], v[0:3]
	s_setprio 0
	s_barrier
	s_add_i32 s71, 0, 0x18000
	v_add_u32_e32 v153, s71, v147
	s_add_i32 s72, 0, 0x1c000
	ds_read_b128 v[160:163], v153
	v_xor_b32_e32 v253, 64, v153
	ds_read_b128 v[164:167], v253
	ds_read_b128 v[168:171], v153 offset:2048
	ds_read_b128 v[172:175], v253 offset:2048
	v_add_u32_e32 v153, s72, v147
	ds_read_b128 v[176:179], v153
	v_xor_b32_e32 v253, 64, v153
	ds_read_b128 v[180:183], v253
	ds_read_b128 v[184:187], v153 offset:2048
	ds_read_b128 v[188:191], v253 offset:2048
	s_add_u32 s46, s46, 0x40000
	s_addc_u32 s47, s47, 0
	s_mov_b32 m0, s54
	v_lshl_add_u64 v[230:231], s[46:47], 0, v[134:135]
	ds_read_b128 v[192:195], v150 offset:32768
	v_xor_b32_e32 v253, 64, v150
	ds_read_b128 v[196:199], v253 offset:32768
	ds_read_b128 v[200:203], v150 offset:34816
	ds_read_b128 v[204:207], v253 offset:34816
	ds_read_b128 v[208:211], v150 offset:36864
	ds_read_b128 v[212:215], v253 offset:36864
	ds_read_b128 v[216:219], v150 offset:38912
	ds_read_b128 v[220:223], v253 offset:38912
	global_load_lds_dwordx4 v[230:231], off
	v_lshl_add_u64 v[230:231], s[46:47], 0, v[130:131]
	s_mov_b32 m0, s55
	s_nop 0
	global_load_lds_dwordx4 v[230:231], off
	s_waitcnt vmcnt(8)
	s_waitcnt lgkmcnt(0)
	s_barrier
	s_setprio 1
	s_waitcnt lgkmcnt(0)
	v_mfma_f32_16x16x32_bf16 v[124:127], v[160:163], v[192:195], v[124:127]
	v_mfma_f32_16x16x32_bf16 v[124:127], v[164:167], v[196:199], v[124:127]
	v_mfma_f32_16x16x32_bf16 v[116:119], v[172:175], v[196:199], v[116:119]
	v_mfma_f32_16x16x32_bf16 v[116:119], v[168:171], v[192:195], v[116:119]
	v_mfma_f32_16x16x32_bf16 v[100:103], v[168:171], v[200:203], v[100:103]
	v_mfma_f32_16x16x32_bf16 v[100:103], v[172:175], v[204:207], v[100:103]
	v_mfma_f32_16x16x32_bf16 v[108:111], v[164:167], v[204:207], v[108:111]
	v_mfma_f32_16x16x32_bf16 v[108:111], v[160:163], v[200:203], v[108:111]
	v_mfma_f32_16x16x32_bf16 v[92:95], v[160:163], v[208:211], v[92:95]
	v_mfma_f32_16x16x32_bf16 v[92:95], v[164:167], v[212:215], v[92:95]
	v_mfma_f32_16x16x32_bf16 v[84:87], v[172:175], v[212:215], v[84:87]
	v_mfma_f32_16x16x32_bf16 v[84:87], v[168:171], v[208:211], v[84:87]
	v_mfma_f32_16x16x32_bf16 v[68:71], v[168:171], v[216:219], v[68:71]
	v_mfma_f32_16x16x32_bf16 v[68:71], v[172:175], v[220:223], v[68:71]
	v_mfma_f32_16x16x32_bf16 v[76:79], v[164:167], v[220:223], v[76:79]
	v_mfma_f32_16x16x32_bf16 v[76:79], v[160:163], v[216:219], v[76:79]
	s_setprio 0
	s_setprio 1
	v_mfma_f32_16x16x32_bf16 v[120:123], v[176:179], v[192:195], v[120:123]
	v_mfma_f32_16x16x32_bf16 v[120:123], v[180:183], v[196:199], v[120:123]
	v_mfma_f32_16x16x32_bf16 v[112:115], v[188:191], v[196:199], v[112:115]
	v_mfma_f32_16x16x32_bf16 v[112:115], v[184:187], v[192:195], v[112:115]
	v_mfma_f32_16x16x32_bf16 v[96:99], v[184:187], v[200:203], v[96:99]
	v_mfma_f32_16x16x32_bf16 v[96:99], v[188:191], v[204:207], v[96:99]
	v_mfma_f32_16x16x32_bf16 v[104:107], v[180:183], v[204:207], v[104:107]
	v_mfma_f32_16x16x32_bf16 v[104:107], v[176:179], v[200:203], v[104:107]
	v_mfma_f32_16x16x32_bf16 v[88:91], v[176:179], v[208:211], v[88:91]
	v_mfma_f32_16x16x32_bf16 v[88:91], v[180:183], v[212:215], v[88:91]
	v_mfma_f32_16x16x32_bf16 v[80:83], v[188:191], v[212:215], v[80:83]
	v_mfma_f32_16x16x32_bf16 v[80:83], v[184:187], v[208:211], v[80:83]
	v_mfma_f32_16x16x32_bf16 v[64:67], v[184:187], v[216:219], v[64:67]
	v_mfma_f32_16x16x32_bf16 v[64:67], v[188:191], v[220:223], v[64:67]
	v_mfma_f32_16x16x32_bf16 v[72:75], v[180:183], v[220:223], v[72:75]
	v_mfma_f32_16x16x32_bf16 v[72:75], v[176:179], v[216:219], v[72:75]
	s_setprio 0
	s_barrier
	s_add_i32 s46, s71, s49
	v_lshl_add_u64 v[154:155], v[154:155], 0, s[14:15]
	s_mov_b32 m0, s46
	ds_read_b128 v[192:195], v150 offset:49152
	v_xor_b32_e32 v253, 64, v150
	ds_read_b128 v[196:199], v253 offset:49152
	ds_read_b128 v[200:203], v150 offset:51200
	ds_read_b128 v[204:207], v253 offset:51200
	ds_read_b128 v[208:211], v150 offset:53248
	ds_read_b128 v[212:215], v253 offset:53248
	ds_read_b128 v[216:219], v150 offset:55296
	ds_read_b128 v[220:223], v253 offset:55296
	global_load_lds_dwordx4 v[154:155], off
	s_add_i32 m0, s46, 0x2000
	s_add_u32 s44, s44, 0x40080
	v_lshl_add_u64 v[154:155], v[224:225], 0, s[14:15]
	s_addc_u32 s45, s45, 0
	s_add_i32 s46, s72, s49
	global_load_lds_dwordx4 v[154:155], off
	v_lshl_add_u64 v[154:155], s[44:45], 0, v[132:133]
	s_mov_b32 m0, s46
	s_nop 0
	global_load_lds_dwordx4 v[154:155], off
	v_lshl_add_u64 v[154:155], s[44:45], 0, v[128:129]
	s_add_i32 m0, s46, 0x2000
	s_nop 0
	global_load_lds_dwordx4 v[154:155], off
	v_lshl_add_u64 v[154:155], v[226:227], 0, s[14:15]
	s_mov_b32 m0, s57
	s_nop 0
	global_load_lds_dwordx4 v[154:155], off
	v_lshl_add_u64 v[154:155], v[228:229], 0, s[14:15]
	s_mov_b32 m0, s58
	s_nop 0
	global_load_lds_dwordx4 v[154:155], off
	s_waitcnt vmcnt(8)
	s_waitcnt lgkmcnt(0)
	s_barrier
	s_setprio 1
	s_waitcnt lgkmcnt(0)
	v_mfma_f32_16x16x32_bf16 v[60:63], v[160:163], v[192:195], v[60:63]
	v_mfma_f32_16x16x32_bf16 v[60:63], v[164:167], v[196:199], v[60:63]
	v_mfma_f32_16x16x32_bf16 v[52:55], v[172:175], v[196:199], v[52:55]
	v_mfma_f32_16x16x32_bf16 v[52:55], v[168:171], v[192:195], v[52:55]
	v_mfma_f32_16x16x32_bf16 v[36:39], v[168:171], v[200:203], v[36:39]
	v_mfma_f32_16x16x32_bf16 v[36:39], v[172:175], v[204:207], v[36:39]
	v_mfma_f32_16x16x32_bf16 v[44:47], v[164:167], v[204:207], v[44:47]
	v_mfma_f32_16x16x32_bf16 v[44:47], v[160:163], v[200:203], v[44:47]
	v_mfma_f32_16x16x32_bf16 v[28:31], v[160:163], v[208:211], v[28:31]
	v_mfma_f32_16x16x32_bf16 v[28:31], v[164:167], v[212:215], v[28:31]
	v_mfma_f32_16x16x32_bf16 v[20:23], v[172:175], v[212:215], v[20:23]
	v_mfma_f32_16x16x32_bf16 v[20:23], v[168:171], v[208:211], v[20:23]
	v_mfma_f32_16x16x32_bf16 v[4:7], v[168:171], v[216:219], v[4:7]
	v_mfma_f32_16x16x32_bf16 v[4:7], v[172:175], v[220:223], v[4:7]
	v_mfma_f32_16x16x32_bf16 v[12:15], v[164:167], v[220:223], v[12:15]
	v_mfma_f32_16x16x32_bf16 v[12:15], v[160:163], v[216:219], v[12:15]
	s_setprio 0
	s_setprio 1
	v_mfma_f32_16x16x32_bf16 v[56:59], v[176:179], v[192:195], v[56:59]
	v_mfma_f32_16x16x32_bf16 v[56:59], v[180:183], v[196:199], v[56:59]
	v_mfma_f32_16x16x32_bf16 v[48:51], v[188:191], v[196:199], v[48:51]
	v_mfma_f32_16x16x32_bf16 v[48:51], v[184:187], v[192:195], v[48:51]
	v_mfma_f32_16x16x32_bf16 v[32:35], v[184:187], v[200:203], v[32:35]
	v_mfma_f32_16x16x32_bf16 v[32:35], v[188:191], v[204:207], v[32:35]
	v_mfma_f32_16x16x32_bf16 v[40:43], v[180:183], v[204:207], v[40:43]
	v_mfma_f32_16x16x32_bf16 v[40:43], v[176:179], v[200:203], v[40:43]
	v_mfma_f32_16x16x32_bf16 v[24:27], v[176:179], v[208:211], v[24:27]
	v_mfma_f32_16x16x32_bf16 v[24:27], v[180:183], v[212:215], v[24:27]
	v_mfma_f32_16x16x32_bf16 v[16:19], v[188:191], v[212:215], v[16:19]
	v_mfma_f32_16x16x32_bf16 v[16:19], v[184:187], v[208:211], v[16:19]
	v_mfma_f32_16x16x32_bf16 v[0:3], v[184:187], v[216:219], v[0:3]
	v_mfma_f32_16x16x32_bf16 v[0:3], v[188:191], v[220:223], v[0:3]
	v_mfma_f32_16x16x32_bf16 v[8:11], v[180:183], v[220:223], v[8:11]
	v_mfma_f32_16x16x32_bf16 v[8:11], v[176:179], v[216:219], v[8:11]
	s_setprio 0
	s_barrier
	s_add_i32 s70, s70, 2
	s_add_u32 s68, s68, 0x100
	s_addc_u32 s69, s69, 0
	s_add_u32 s30, s30, 0x100
	s_addc_u32 s31, s31, 0
	s_branch .LBB0_1098
.LBB0_1097:
	v_add_u32_e32 v153, s61, v147
	ds_read_b128 v[160:163], v153
	v_xor_b32_e32 v253, 64, v153
	ds_read_b128 v[164:167], v253
	ds_read_b128 v[168:171], v153 offset:2048
	ds_read_b128 v[172:175], v253 offset:2048
	v_add_u32_e32 v153, s62, v147
	ds_read_b128 v[176:179], v153
	v_xor_b32_e32 v253, 64, v153
	ds_read_b128 v[180:183], v253
	ds_read_b128 v[184:187], v153 offset:2048
	ds_read_b128 v[188:191], v253 offset:2048
	s_add_u32 s46, s30, 0xfffc0080
	s_addc_u32 s47, s31, -1
	s_and_b64 s[44:45], s[44:45], exec
	s_cselect_b32 s47, s25, s47
	s_cselect_b32 s46, s65, s46
	s_cselect_b32 s45, s66, s69
	s_cselect_b32 s44, s67, s68
	v_lshl_add_u64 v[154:155], s[30:31], 0, v[138:139]
	s_add_i32 m0, s52, 0xc000
	ds_read_b128 v[192:195], v150
	v_xor_b32_e32 v253, 64, v150
	ds_read_b128 v[196:199], v253
	ds_read_b128 v[200:203], v150 offset:2048
	ds_read_b128 v[204:207], v253 offset:2048
	ds_read_b128 v[208:211], v150 offset:4096
	ds_read_b128 v[212:215], v253 offset:4096
	ds_read_b128 v[216:219], v150 offset:6144
	ds_read_b128 v[220:223], v253 offset:6144
	global_load_lds_dwordx4 v[154:155], off
	v_lshl_add_u64 v[154:155], s[30:31], 0, v[136:137]
	s_add_i32 m0, s52, 0xe000
	s_nop 0
	global_load_lds_dwordx4 v[154:155], off
	s_waitcnt vmcnt(8)
	s_waitcnt lgkmcnt(0)
	s_barrier
	s_setprio 1
	s_waitcnt lgkmcnt(0)
	v_mfma_f32_16x16x32_bf16 v[124:127], v[160:163], v[192:195], v[124:127]
	v_mfma_f32_16x16x32_bf16 v[124:127], v[164:167], v[196:199], v[124:127]
	v_mfma_f32_16x16x32_bf16 v[116:119], v[172:175], v[196:199], v[116:119]
	v_mfma_f32_16x16x32_bf16 v[116:119], v[168:171], v[192:195], v[116:119]
	v_mfma_f32_16x16x32_bf16 v[100:103], v[168:171], v[200:203], v[100:103]
	v_mfma_f32_16x16x32_bf16 v[100:103], v[172:175], v[204:207], v[100:103]
	v_mfma_f32_16x16x32_bf16 v[108:111], v[164:167], v[204:207], v[108:111]
	v_mfma_f32_16x16x32_bf16 v[108:111], v[160:163], v[200:203], v[108:111]
	v_mfma_f32_16x16x32_bf16 v[92:95], v[160:163], v[208:211], v[92:95]
	v_mfma_f32_16x16x32_bf16 v[92:95], v[164:167], v[212:215], v[92:95]
	v_mfma_f32_16x16x32_bf16 v[84:87], v[172:175], v[212:215], v[84:87]
	v_mfma_f32_16x16x32_bf16 v[84:87], v[168:171], v[208:211], v[84:87]
	v_mfma_f32_16x16x32_bf16 v[68:71], v[168:171], v[216:219], v[68:71]
	v_mfma_f32_16x16x32_bf16 v[68:71], v[172:175], v[220:223], v[68:71]
	v_mfma_f32_16x16x32_bf16 v[76:79], v[164:167], v[220:223], v[76:79]
	v_mfma_f32_16x16x32_bf16 v[76:79], v[160:163], v[216:219], v[76:79]
	s_setprio 0
	s_setprio 1
	v_mfma_f32_16x16x32_bf16 v[120:123], v[176:179], v[192:195], v[120:123]
	v_mfma_f32_16x16x32_bf16 v[120:123], v[180:183], v[196:199], v[120:123]
	v_mfma_f32_16x16x32_bf16 v[112:115], v[188:191], v[196:199], v[112:115]
	v_mfma_f32_16x16x32_bf16 v[112:115], v[184:187], v[192:195], v[112:115]
	v_mfma_f32_16x16x32_bf16 v[96:99], v[184:187], v[200:203], v[96:99]
	v_mfma_f32_16x16x32_bf16 v[96:99], v[188:191], v[204:207], v[96:99]
	v_mfma_f32_16x16x32_bf16 v[104:107], v[180:183], v[204:207], v[104:107]
	v_mfma_f32_16x16x32_bf16 v[104:107], v[176:179], v[200:203], v[104:107]
	v_mfma_f32_16x16x32_bf16 v[88:91], v[176:179], v[208:211], v[88:91]
	v_mfma_f32_16x16x32_bf16 v[88:91], v[180:183], v[212:215], v[88:91]
	v_mfma_f32_16x16x32_bf16 v[80:83], v[188:191], v[212:215], v[80:83]
	v_mfma_f32_16x16x32_bf16 v[80:83], v[184:187], v[208:211], v[80:83]
	v_mfma_f32_16x16x32_bf16 v[64:67], v[184:187], v[216:219], v[64:67]
	v_mfma_f32_16x16x32_bf16 v[64:67], v[188:191], v[220:223], v[64:67]
	v_mfma_f32_16x16x32_bf16 v[72:75], v[180:183], v[220:223], v[72:75]
	v_mfma_f32_16x16x32_bf16 v[72:75], v[176:179], v[216:219], v[72:75]
	s_setprio 0
	s_barrier
	s_add_i32 s71, s61, s49
	v_lshl_add_u64 v[154:155], s[44:45], 0, v[132:133]
	s_mov_b32 m0, s71
	ds_read_b128 v[192:195], v150 offset:16384
	v_xor_b32_e32 v253, 64, v150
	ds_read_b128 v[196:199], v253 offset:16384
	ds_read_b128 v[200:203], v150 offset:18432
	ds_read_b128 v[204:207], v253 offset:18432
	ds_read_b128 v[208:211], v150 offset:20480
	ds_read_b128 v[212:215], v253 offset:20480
	ds_read_b128 v[216:219], v150 offset:22528
	ds_read_b128 v[220:223], v253 offset:22528
	global_load_lds_dwordx4 v[154:155], off
	s_add_i32 m0, s71, 0x2000
	s_add_u32 s72, s44, 0x40000
	v_lshl_add_u64 v[224:225], s[44:45], 0, v[128:129]
	s_addc_u32 s73, s45, 0
	s_add_i32 s71, s62, s49
	global_load_lds_dwordx4 v[224:225], off
	v_lshl_add_u64 v[226:227], s[72:73], 0, v[132:133]
	s_mov_b32 m0, s71
	v_lshl_add_u64 v[228:229], s[46:47], 0, v[130:131]
	global_load_lds_dwordx4 v[226:227], off
	v_lshl_add_u64 v[226:227], s[72:73], 0, v[128:129]
	s_add_i32 m0, s71, 0x2000
	s_nop 0
	global_load_lds_dwordx4 v[226:227], off
	v_lshl_add_u64 v[226:227], s[46:47], 0, v[134:135]
	s_mov_b32 m0, s52
	s_nop 0
	global_load_lds_dwordx4 v[226:227], off
	s_mov_b32 m0, s53
	s_nop 0
	global_load_lds_dwordx4 v[228:229], off
	s_waitcnt vmcnt(8)
	s_waitcnt lgkmcnt(0)
	s_barrier
	s_setprio 1
	s_waitcnt lgkmcnt(0)
	v_mfma_f32_16x16x32_bf16 v[60:63], v[160:163], v[192:195], v[60:63]
	v_mfma_f32_16x16x32_bf16 v[60:63], v[164:167], v[196:199], v[60:63]
	v_mfma_f32_16x16x32_bf16 v[52:55], v[172:175], v[196:199], v[52:55]
	v_mfma_f32_16x16x32_bf16 v[52:55], v[168:171], v[192:195], v[52:55]
	v_mfma_f32_16x16x32_bf16 v[36:39], v[168:171], v[200:203], v[36:39]
	v_mfma_f32_16x16x32_bf16 v[36:39], v[172:175], v[204:207], v[36:39]
	v_mfma_f32_16x16x32_bf16 v[44:47], v[164:167], v[204:207], v[44:47]
	v_mfma_f32_16x16x32_bf16 v[44:47], v[160:163], v[200:203], v[44:47]
	v_mfma_f32_16x16x32_bf16 v[28:31], v[160:163], v[208:211], v[28:31]
	v_mfma_f32_16x16x32_bf16 v[28:31], v[164:167], v[212:215], v[28:31]
	v_mfma_f32_16x16x32_bf16 v[20:23], v[172:175], v[212:215], v[20:23]
	v_mfma_f32_16x16x32_bf16 v[20:23], v[168:171], v[208:211], v[20:23]
	v_mfma_f32_16x16x32_bf16 v[4:7], v[168:171], v[216:219], v[4:7]
	v_mfma_f32_16x16x32_bf16 v[4:7], v[172:175], v[220:223], v[4:7]
	v_mfma_f32_16x16x32_bf16 v[12:15], v[164:167], v[220:223], v[12:15]
	v_mfma_f32_16x16x32_bf16 v[12:15], v[160:163], v[216:219], v[12:15]
	s_setprio 0
	s_setprio 1
	v_mfma_f32_16x16x32_bf16 v[56:59], v[176:179], v[192:195], v[56:59]
	v_mfma_f32_16x16x32_bf16 v[56:59], v[180:183], v[196:199], v[56:59]
	v_mfma_f32_16x16x32_bf16 v[48:51], v[188:191], v[196:199], v[48:51]
	v_mfma_f32_16x16x32_bf16 v[48:51], v[184:187], v[192:195], v[48:51]
	v_mfma_f32_16x16x32_bf16 v[32:35], v[184:187], v[200:203], v[32:35]
	v_mfma_f32_16x16x32_bf16 v[32:35], v[188:191], v[204:207], v[32:35]
	v_mfma_f32_16x16x32_bf16 v[40:43], v[180:183], v[204:207], v[40:43]
	v_mfma_f32_16x16x32_bf16 v[40:43], v[176:179], v[200:203], v[40:43]
	v_mfma_f32_16x16x32_bf16 v[24:27], v[176:179], v[208:211], v[24:27]
	v_mfma_f32_16x16x32_bf16 v[24:27], v[180:183], v[212:215], v[24:27]
	v_mfma_f32_16x16x32_bf16 v[16:19], v[188:191], v[212:215], v[16:19]
	v_mfma_f32_16x16x32_bf16 v[16:19], v[184:187], v[208:211], v[16:19]
	v_mfma_f32_16x16x32_bf16 v[0:3], v[184:187], v[216:219], v[0:3]
	v_mfma_f32_16x16x32_bf16 v[0:3], v[188:191], v[220:223], v[0:3]
	v_mfma_f32_16x16x32_bf16 v[8:11], v[180:183], v[220:223], v[8:11]
	v_mfma_f32_16x16x32_bf16 v[8:11], v[176:179], v[216:219], v[8:11]
	s_setprio 0
	s_barrier
	s_add_i32 s71, 0, 0x18000
	v_add_u32_e32 v153, s71, v147
	s_add_i32 s72, 0, 0x1c000
	ds_read_b128 v[160:163], v153
	v_xor_b32_e32 v253, 64, v153
	ds_read_b128 v[164:167], v253
	ds_read_b128 v[168:171], v153 offset:2048
	ds_read_b128 v[172:175], v253 offset:2048
	v_add_u32_e32 v153, s72, v147
	ds_read_b128 v[176:179], v153
	v_xor_b32_e32 v253, 64, v153
	ds_read_b128 v[180:183], v253
	ds_read_b128 v[184:187], v153 offset:2048
	ds_read_b128 v[188:191], v253 offset:2048
	s_add_u32 s46, s46, 0x40000
	s_addc_u32 s47, s47, 0
	s_mov_b32 m0, s54
	v_lshl_add_u64 v[230:231], s[46:47], 0, v[134:135]
	ds_read_b128 v[192:195], v150 offset:32768
	v_xor_b32_e32 v253, 64, v150
	ds_read_b128 v[196:199], v253 offset:32768
	ds_read_b128 v[200:203], v150 offset:34816
	ds_read_b128 v[204:207], v253 offset:34816
	ds_read_b128 v[208:211], v150 offset:36864
	ds_read_b128 v[212:215], v253 offset:36864
	ds_read_b128 v[216:219], v150 offset:38912
	ds_read_b128 v[220:223], v253 offset:38912
	global_load_lds_dwordx4 v[230:231], off
	v_lshl_add_u64 v[230:231], s[46:47], 0, v[130:131]
	s_mov_b32 m0, s55
	s_nop 0
	global_load_lds_dwordx4 v[230:231], off
	s_waitcnt vmcnt(8)
	s_waitcnt lgkmcnt(0)
	s_barrier
	s_setprio 1
	s_waitcnt lgkmcnt(0)
	v_mfma_f32_16x16x32_bf16 v[124:127], v[160:163], v[192:195], v[124:127]
	v_mfma_f32_16x16x32_bf16 v[124:127], v[164:167], v[196:199], v[124:127]
	v_mfma_f32_16x16x32_bf16 v[116:119], v[172:175], v[196:199], v[116:119]
	v_mfma_f32_16x16x32_bf16 v[116:119], v[168:171], v[192:195], v[116:119]
	v_mfma_f32_16x16x32_bf16 v[100:103], v[168:171], v[200:203], v[100:103]
	v_mfma_f32_16x16x32_bf16 v[100:103], v[172:175], v[204:207], v[100:103]
	v_mfma_f32_16x16x32_bf16 v[108:111], v[164:167], v[204:207], v[108:111]
	v_mfma_f32_16x16x32_bf16 v[108:111], v[160:163], v[200:203], v[108:111]
	v_mfma_f32_16x16x32_bf16 v[92:95], v[160:163], v[208:211], v[92:95]
	v_mfma_f32_16x16x32_bf16 v[92:95], v[164:167], v[212:215], v[92:95]
	v_mfma_f32_16x16x32_bf16 v[84:87], v[172:175], v[212:215], v[84:87]
	v_mfma_f32_16x16x32_bf16 v[84:87], v[168:171], v[208:211], v[84:87]
	v_mfma_f32_16x16x32_bf16 v[68:71], v[168:171], v[216:219], v[68:71]
	v_mfma_f32_16x16x32_bf16 v[68:71], v[172:175], v[220:223], v[68:71]
	v_mfma_f32_16x16x32_bf16 v[76:79], v[164:167], v[220:223], v[76:79]
	v_mfma_f32_16x16x32_bf16 v[76:79], v[160:163], v[216:219], v[76:79]
	s_setprio 0
	s_setprio 1
	v_mfma_f32_16x16x32_bf16 v[120:123], v[176:179], v[192:195], v[120:123]
	v_mfma_f32_16x16x32_bf16 v[120:123], v[180:183], v[196:199], v[120:123]
	v_mfma_f32_16x16x32_bf16 v[112:115], v[188:191], v[196:199], v[112:115]
	v_mfma_f32_16x16x32_bf16 v[112:115], v[184:187], v[192:195], v[112:115]
	v_mfma_f32_16x16x32_bf16 v[96:99], v[184:187], v[200:203], v[96:99]
	v_mfma_f32_16x16x32_bf16 v[96:99], v[188:191], v[204:207], v[96:99]
	v_mfma_f32_16x16x32_bf16 v[104:107], v[180:183], v[204:207], v[104:107]
	v_mfma_f32_16x16x32_bf16 v[104:107], v[176:179], v[200:203], v[104:107]
	v_mfma_f32_16x16x32_bf16 v[88:91], v[176:179], v[208:211], v[88:91]
	v_mfma_f32_16x16x32_bf16 v[88:91], v[180:183], v[212:215], v[88:91]
	v_mfma_f32_16x16x32_bf16 v[80:83], v[188:191], v[212:215], v[80:83]
	v_mfma_f32_16x16x32_bf16 v[80:83], v[184:187], v[208:211], v[80:83]
	v_mfma_f32_16x16x32_bf16 v[64:67], v[184:187], v[216:219], v[64:67]
	v_mfma_f32_16x16x32_bf16 v[64:67], v[188:191], v[220:223], v[64:67]
	v_mfma_f32_16x16x32_bf16 v[72:75], v[180:183], v[220:223], v[72:75]
	v_mfma_f32_16x16x32_bf16 v[72:75], v[176:179], v[216:219], v[72:75]
	s_setprio 0
	s_barrier
	s_add_i32 s46, s71, s49
	v_lshl_add_u64 v[154:155], v[154:155], 0, s[14:15]
	s_mov_b32 m0, s46
	ds_read_b128 v[192:195], v150 offset:49152
	v_xor_b32_e32 v253, 64, v150
	ds_read_b128 v[196:199], v253 offset:49152
	ds_read_b128 v[200:203], v150 offset:51200
	ds_read_b128 v[204:207], v253 offset:51200
	ds_read_b128 v[208:211], v150 offset:53248
	ds_read_b128 v[212:215], v253 offset:53248
	ds_read_b128 v[216:219], v150 offset:55296
	ds_read_b128 v[220:223], v253 offset:55296
	global_load_lds_dwordx4 v[154:155], off
	s_add_i32 m0, s46, 0x2000
	s_add_u32 s44, s44, 0x40080
	v_lshl_add_u64 v[154:155], v[224:225], 0, s[14:15]
	s_addc_u32 s45, s45, 0
	s_add_i32 s46, s72, s49
	global_load_lds_dwordx4 v[154:155], off
	v_lshl_add_u64 v[154:155], s[44:45], 0, v[132:133]
	s_mov_b32 m0, s46
	s_nop 0
	global_load_lds_dwordx4 v[154:155], off
	v_lshl_add_u64 v[154:155], s[44:45], 0, v[128:129]
	s_add_i32 m0, s46, 0x2000
	s_nop 0
	global_load_lds_dwordx4 v[154:155], off
	v_lshl_add_u64 v[154:155], v[226:227], 0, s[14:15]
	s_mov_b32 m0, s57
	s_nop 0
	global_load_lds_dwordx4 v[154:155], off
	v_lshl_add_u64 v[154:155], v[228:229], 0, s[14:15]
	s_mov_b32 m0, s58
	s_nop 0
	global_load_lds_dwordx4 v[154:155], off
	s_waitcnt vmcnt(8)
	s_waitcnt lgkmcnt(0)
	s_barrier
	s_setprio 1
	s_waitcnt lgkmcnt(0)
	v_mfma_f32_16x16x32_bf16 v[60:63], v[160:163], v[192:195], v[60:63]
	v_mfma_f32_16x16x32_bf16 v[60:63], v[164:167], v[196:199], v[60:63]
	v_mfma_f32_16x16x32_bf16 v[52:55], v[172:175], v[196:199], v[52:55]
	v_mfma_f32_16x16x32_bf16 v[52:55], v[168:171], v[192:195], v[52:55]
	v_mfma_f32_16x16x32_bf16 v[36:39], v[168:171], v[200:203], v[36:39]
	v_mfma_f32_16x16x32_bf16 v[36:39], v[172:175], v[204:207], v[36:39]
	v_mfma_f32_16x16x32_bf16 v[44:47], v[164:167], v[204:207], v[44:47]
	v_mfma_f32_16x16x32_bf16 v[44:47], v[160:163], v[200:203], v[44:47]
	v_mfma_f32_16x16x32_bf16 v[28:31], v[160:163], v[208:211], v[28:31]
	v_mfma_f32_16x16x32_bf16 v[28:31], v[164:167], v[212:215], v[28:31]
	v_mfma_f32_16x16x32_bf16 v[20:23], v[172:175], v[212:215], v[20:23]
	v_mfma_f32_16x16x32_bf16 v[20:23], v[168:171], v[208:211], v[20:23]
	v_mfma_f32_16x16x32_bf16 v[4:7], v[168:171], v[216:219], v[4:7]
	v_mfma_f32_16x16x32_bf16 v[4:7], v[172:175], v[220:223], v[4:7]
	v_mfma_f32_16x16x32_bf16 v[12:15], v[164:167], v[220:223], v[12:15]
	v_mfma_f32_16x16x32_bf16 v[12:15], v[160:163], v[216:219], v[12:15]
	s_setprio 0
	s_setprio 1
	v_mfma_f32_16x16x32_bf16 v[56:59], v[176:179], v[192:195], v[56:59]
	v_mfma_f32_16x16x32_bf16 v[56:59], v[180:183], v[196:199], v[56:59]
	v_mfma_f32_16x16x32_bf16 v[48:51], v[188:191], v[196:199], v[48:51]
	v_mfma_f32_16x16x32_bf16 v[48:51], v[184:187], v[192:195], v[48:51]
	v_mfma_f32_16x16x32_bf16 v[32:35], v[184:187], v[200:203], v[32:35]
	v_mfma_f32_16x16x32_bf16 v[32:35], v[188:191], v[204:207], v[32:35]
	v_mfma_f32_16x16x32_bf16 v[40:43], v[180:183], v[204:207], v[40:43]
	v_mfma_f32_16x16x32_bf16 v[40:43], v[176:179], v[200:203], v[40:43]
	v_mfma_f32_16x16x32_bf16 v[24:27], v[176:179], v[208:211], v[24:27]
	v_mfma_f32_16x16x32_bf16 v[24:27], v[180:183], v[212:215], v[24:27]
	v_mfma_f32_16x16x32_bf16 v[16:19], v[188:191], v[212:215], v[16:19]
	v_mfma_f32_16x16x32_bf16 v[16:19], v[184:187], v[208:211], v[16:19]
	v_mfma_f32_16x16x32_bf16 v[0:3], v[184:187], v[216:219], v[0:3]
	v_mfma_f32_16x16x32_bf16 v[0:3], v[188:191], v[220:223], v[0:3]
	v_mfma_f32_16x16x32_bf16 v[8:11], v[180:183], v[220:223], v[8:11]
	v_mfma_f32_16x16x32_bf16 v[8:11], v[176:179], v[216:219], v[8:11]
	s_setprio 0
	s_barrier
	s_add_i32 s70, s70, 2
	s_add_u32 s68, s68, 0x100
	s_addc_u32 s69, s69, 0
	s_add_u32 s30, s30, 0x100
	s_addc_u32 s31, s31, 0
	s_cmp_gt_u32 s70, 13
	s_cbranch_scc1 .LBB0_1100

.Llast_10:
	v_add_u32_e32 v153, s61, v147
	ds_read_b128 v[160:163], v153
	v_xor_b32_e32 v253, 64, v153
	ds_read_b128 v[164:167], v253
	ds_read_b128 v[168:171], v153 offset:2048
	ds_read_b128 v[172:175], v253 offset:2048
	v_add_u32_e32 v153, s62, v147
	ds_read_b128 v[176:179], v153
	v_xor_b32_e32 v253, 64, v153
	ds_read_b128 v[180:183], v253
	ds_read_b128 v[184:187], v153 offset:2048
	ds_read_b128 v[188:191], v253 offset:2048
	s_add_u32 s46, s30, 0xfffc0080
	s_addc_u32 s47, s31, -1
	s_and_b64 s[44:45], s[44:45], exec
	s_cselect_b32 s47, s25, s47
	s_cselect_b32 s46, s65, s46
	s_cselect_b32 s45, s66, s69
	s_cselect_b32 s44, s67, s68
	v_lshl_add_u64 v[154:155], s[30:31], 0, v[138:139]
	s_add_i32 m0, s52, 0xc000
	ds_read_b128 v[192:195], v150
	v_xor_b32_e32 v253, 64, v150
	ds_read_b128 v[196:199], v253
	ds_read_b128 v[200:203], v150 offset:2048
	ds_read_b128 v[204:207], v253 offset:2048
	ds_read_b128 v[208:211], v150 offset:4096
	ds_read_b128 v[212:215], v253 offset:4096
	ds_read_b128 v[216:219], v150 offset:6144
	ds_read_b128 v[220:223], v253 offset:6144
	global_load_lds_dwordx4 v[154:155], off
	v_lshl_add_u64 v[154:155], s[30:31], 0, v[136:137]
	s_add_i32 m0, s52, 0xe000
	s_nop 0
	global_load_lds_dwordx4 v[154:155], off
	s_waitcnt vmcnt(8)
	s_waitcnt lgkmcnt(0)
	s_barrier
	s_setprio 1
	s_waitcnt lgkmcnt(0)
	v_mfma_f32_16x16x32_bf16 v[124:127], v[160:163], v[192:195], v[124:127]
	v_mfma_f32_16x16x32_bf16 v[124:127], v[164:167], v[196:199], v[124:127]
	v_mfma_f32_16x16x32_bf16 v[116:119], v[172:175], v[196:199], v[116:119]
	v_mfma_f32_16x16x32_bf16 v[116:119], v[168:171], v[192:195], v[116:119]
	v_mfma_f32_16x16x32_bf16 v[100:103], v[168:171], v[200:203], v[100:103]
	v_mfma_f32_16x16x32_bf16 v[100:103], v[172:175], v[204:207], v[100:103]
	v_mfma_f32_16x16x32_bf16 v[108:111], v[164:167], v[204:207], v[108:111]
	v_mfma_f32_16x16x32_bf16 v[108:111], v[160:163], v[200:203], v[108:111]
	v_mfma_f32_16x16x32_bf16 v[92:95], v[160:163], v[208:211], v[92:95]
	v_mfma_f32_16x16x32_bf16 v[92:95], v[164:167], v[212:215], v[92:95]
	v_mfma_f32_16x16x32_bf16 v[84:87], v[172:175], v[212:215], v[84:87]
	v_mfma_f32_16x16x32_bf16 v[84:87], v[168:171], v[208:211], v[84:87]
	v_mfma_f32_16x16x32_bf16 v[68:71], v[168:171], v[216:219], v[68:71]
	v_mfma_f32_16x16x32_bf16 v[68:71], v[172:175], v[220:223], v[68:71]
	v_mfma_f32_16x16x32_bf16 v[76:79], v[164:167], v[220:223], v[76:79]
	v_mfma_f32_16x16x32_bf16 v[76:79], v[160:163], v[216:219], v[76:79]
	s_setprio 0
	s_setprio 1
	v_mfma_f32_16x16x32_bf16 v[120:123], v[176:179], v[192:195], v[120:123]
	v_mfma_f32_16x16x32_bf16 v[120:123], v[180:183], v[196:199], v[120:123]
	v_mfma_f32_16x16x32_bf16 v[112:115], v[188:191], v[196:199], v[112:115]
	v_mfma_f32_16x16x32_bf16 v[112:115], v[184:187], v[192:195], v[112:115]
	v_mfma_f32_16x16x32_bf16 v[96:99], v[184:187], v[200:203], v[96:99]
	v_mfma_f32_16x16x32_bf16 v[96:99], v[188:191], v[204:207], v[96:99]
	v_mfma_f32_16x16x32_bf16 v[104:107], v[180:183], v[204:207], v[104:107]
	v_mfma_f32_16x16x32_bf16 v[104:107], v[176:179], v[200:203], v[104:107]
	v_mfma_f32_16x16x32_bf16 v[88:91], v[176:179], v[208:211], v[88:91]
	v_mfma_f32_16x16x32_bf16 v[88:91], v[180:183], v[212:215], v[88:91]
	v_mfma_f32_16x16x32_bf16 v[80:83], v[188:191], v[212:215], v[80:83]
	v_mfma_f32_16x16x32_bf16 v[80:83], v[184:187], v[208:211], v[80:83]
	v_mfma_f32_16x16x32_bf16 v[64:67], v[184:187], v[216:219], v[64:67]
	v_mfma_f32_16x16x32_bf16 v[64:67], v[188:191], v[220:223], v[64:67]
	v_mfma_f32_16x16x32_bf16 v[72:75], v[180:183], v[220:223], v[72:75]
	v_mfma_f32_16x16x32_bf16 v[72:75], v[176:179], v[216:219], v[72:75]
	s_setprio 0
	s_barrier
	s_add_i32 s71, s61, s49
	v_lshl_add_u64 v[154:155], s[44:45], 0, v[132:133]
	s_mov_b32 m0, s71
	ds_read_b128 v[192:195], v150 offset:16384
	v_xor_b32_e32 v253, 64, v150
	ds_read_b128 v[196:199], v253 offset:16384
	ds_read_b128 v[200:203], v150 offset:18432
	ds_read_b128 v[204:207], v253 offset:18432
	ds_read_b128 v[208:211], v150 offset:20480
	ds_read_b128 v[212:215], v253 offset:20480
	ds_read_b128 v[216:219], v150 offset:22528
	ds_read_b128 v[220:223], v253 offset:22528
	global_load_lds_dwordx4 v[154:155], off
	s_add_i32 m0, s71, 0x2000
	s_add_u32 s72, s44, 0x40000
	v_lshl_add_u64 v[224:225], s[44:45], 0, v[128:129]
	s_addc_u32 s73, s45, 0
	s_add_i32 s71, s62, s49
	global_load_lds_dwordx4 v[224:225], off
	v_lshl_add_u64 v[226:227], s[72:73], 0, v[132:133]
	s_mov_b32 m0, s71
	v_lshl_add_u64 v[228:229], s[46:47], 0, v[130:131]
	global_load_lds_dwordx4 v[226:227], off
	v_lshl_add_u64 v[226:227], s[72:73], 0, v[128:129]
	s_add_i32 m0, s71, 0x2000
	s_nop 0
	global_load_lds_dwordx4 v[226:227], off
	v_lshl_add_u64 v[226:227], s[46:47], 0, v[134:135]
	s_mov_b32 m0, s52
	s_nop 0
	global_load_lds_dwordx4 v[226:227], off
	s_mov_b32 m0, s53
	s_nop 0
	global_load_lds_dwordx4 v[228:229], off
	s_waitcnt vmcnt(8)
	s_waitcnt lgkmcnt(0)
	s_barrier
	s_setprio 1
	s_waitcnt lgkmcnt(0)
	v_mfma_f32_16x16x32_bf16 v[60:63], v[160:163], v[192:195], v[60:63]
	v_mfma_f32_16x16x32_bf16 v[60:63], v[164:167], v[196:199], v[60:63]
	v_mfma_f32_16x16x32_bf16 v[52:55], v[172:175], v[196:199], v[52:55]
	v_mfma_f32_16x16x32_bf16 v[52:55], v[168:171], v[192:195], v[52:55]
	v_mfma_f32_16x16x32_bf16 v[36:39], v[168:171], v[200:203], v[36:39]
	v_mfma_f32_16x16x32_bf16 v[36:39], v[172:175], v[204:207], v[36:39]
	v_mfma_f32_16x16x32_bf16 v[44:47], v[164:167], v[204:207], v[44:47]
	v_mfma_f32_16x16x32_bf16 v[44:47], v[160:163], v[200:203], v[44:47]
	v_mfma_f32_16x16x32_bf16 v[28:31], v[160:163], v[208:211], v[28:31]
	v_mfma_f32_16x16x32_bf16 v[28:31], v[164:167], v[212:215], v[28:31]
	v_mfma_f32_16x16x32_bf16 v[20:23], v[172:175], v[212:215], v[20:23]
	v_mfma_f32_16x16x32_bf16 v[20:23], v[168:171], v[208:211], v[20:23]
	v_mfma_f32_16x16x32_bf16 v[4:7], v[168:171], v[216:219], v[4:7]
	v_mfma_f32_16x16x32_bf16 v[4:7], v[172:175], v[220:223], v[4:7]
	v_mfma_f32_16x16x32_bf16 v[12:15], v[164:167], v[220:223], v[12:15]
	v_mfma_f32_16x16x32_bf16 v[12:15], v[160:163], v[216:219], v[12:15]
	s_setprio 0
	s_setprio 1
	v_mfma_f32_16x16x32_bf16 v[56:59], v[176:179], v[192:195], v[56:59]
	v_mfma_f32_16x16x32_bf16 v[56:59], v[180:183], v[196:199], v[56:59]
	v_mfma_f32_16x16x32_bf16 v[48:51], v[188:191], v[196:199], v[48:51]
	v_mfma_f32_16x16x32_bf16 v[48:51], v[184:187], v[192:195], v[48:51]
	v_mfma_f32_16x16x32_bf16 v[32:35], v[184:187], v[200:203], v[32:35]
	v_mfma_f32_16x16x32_bf16 v[32:35], v[188:191], v[204:207], v[32:35]
	v_mfma_f32_16x16x32_bf16 v[40:43], v[180:183], v[204:207], v[40:43]
	v_mfma_f32_16x16x32_bf16 v[40:43], v[176:179], v[200:203], v[40:43]
	v_mfma_f32_16x16x32_bf16 v[24:27], v[176:179], v[208:211], v[24:27]
	v_mfma_f32_16x16x32_bf16 v[24:27], v[180:183], v[212:215], v[24:27]
	v_mfma_f32_16x16x32_bf16 v[16:19], v[188:191], v[212:215], v[16:19]
	v_mfma_f32_16x16x32_bf16 v[16:19], v[184:187], v[208:211], v[16:19]
	v_mfma_f32_16x16x32_bf16 v[0:3], v[184:187], v[216:219], v[0:3]
	v_mfma_f32_16x16x32_bf16 v[0:3], v[188:191], v[220:223], v[0:3]
	v_mfma_f32_16x16x32_bf16 v[8:11], v[180:183], v[220:223], v[8:11]
	v_mfma_f32_16x16x32_bf16 v[8:11], v[176:179], v[216:219], v[8:11]
	s_setprio 0
	s_barrier
	s_add_i32 s71, 0, 0x18000
	v_add_u32_e32 v153, s71, v147
	s_add_i32 s72, 0, 0x1c000
	ds_read_b128 v[160:163], v153
	v_xor_b32_e32 v253, 64, v153
	ds_read_b128 v[164:167], v253
	ds_read_b128 v[168:171], v153 offset:2048
	ds_read_b128 v[172:175], v253 offset:2048
	v_add_u32_e32 v153, s72, v147
	ds_read_b128 v[176:179], v153
	v_xor_b32_e32 v253, 64, v153
	ds_read_b128 v[180:183], v253
	ds_read_b128 v[184:187], v153 offset:2048
	ds_read_b128 v[188:191], v253 offset:2048
	s_add_u32 s46, s46, 0x40000
	s_addc_u32 s47, s47, 0
	s_mov_b32 m0, s54
	v_lshl_add_u64 v[230:231], s[46:47], 0, v[134:135]
	ds_read_b128 v[192:195], v150 offset:32768
	v_xor_b32_e32 v253, 64, v150
	ds_read_b128 v[196:199], v253 offset:32768
	ds_read_b128 v[200:203], v150 offset:34816
	ds_read_b128 v[204:207], v253 offset:34816
	ds_read_b128 v[208:211], v150 offset:36864
	ds_read_b128 v[212:215], v253 offset:36864
	ds_read_b128 v[216:219], v150 offset:38912
	ds_read_b128 v[220:223], v253 offset:38912
	global_load_lds_dwordx4 v[230:231], off
	v_lshl_add_u64 v[230:231], s[46:47], 0, v[130:131]
	s_mov_b32 m0, s55
	s_nop 0
	global_load_lds_dwordx4 v[230:231], off
	s_waitcnt vmcnt(8)
	s_waitcnt lgkmcnt(0)
	s_barrier
	s_setprio 1
	s_waitcnt lgkmcnt(0)
	v_mfma_f32_16x16x32_bf16 v[124:127], v[160:163], v[192:195], v[124:127]
	v_mfma_f32_16x16x32_bf16 v[124:127], v[164:167], v[196:199], v[124:127]
	v_mfma_f32_16x16x32_bf16 v[116:119], v[172:175], v[196:199], v[116:119]
	v_mfma_f32_16x16x32_bf16 v[116:119], v[168:171], v[192:195], v[116:119]
	v_mfma_f32_16x16x32_bf16 v[100:103], v[168:171], v[200:203], v[100:103]
	v_mfma_f32_16x16x32_bf16 v[100:103], v[172:175], v[204:207], v[100:103]
	v_mfma_f32_16x16x32_bf16 v[108:111], v[164:167], v[204:207], v[108:111]
	v_mfma_f32_16x16x32_bf16 v[108:111], v[160:163], v[200:203], v[108:111]
	v_mfma_f32_16x16x32_bf16 v[92:95], v[160:163], v[208:211], v[92:95]
	v_mfma_f32_16x16x32_bf16 v[92:95], v[164:167], v[212:215], v[92:95]
	v_mfma_f32_16x16x32_bf16 v[84:87], v[172:175], v[212:215], v[84:87]
	v_mfma_f32_16x16x32_bf16 v[84:87], v[168:171], v[208:211], v[84:87]
	v_mfma_f32_16x16x32_bf16 v[68:71], v[168:171], v[216:219], v[68:71]
	v_mfma_f32_16x16x32_bf16 v[68:71], v[172:175], v[220:223], v[68:71]
	v_mfma_f32_16x16x32_bf16 v[76:79], v[164:167], v[220:223], v[76:79]
	v_mfma_f32_16x16x32_bf16 v[76:79], v[160:163], v[216:219], v[76:79]
	s_setprio 0
	s_setprio 1
	v_mfma_f32_16x16x32_bf16 v[120:123], v[176:179], v[192:195], v[120:123]
	v_mfma_f32_16x16x32_bf16 v[120:123], v[180:183], v[196:199], v[120:123]
	v_mfma_f32_16x16x32_bf16 v[112:115], v[188:191], v[196:199], v[112:115]
	v_mfma_f32_16x16x32_bf16 v[112:115], v[184:187], v[192:195], v[112:115]
	v_mfma_f32_16x16x32_bf16 v[96:99], v[184:187], v[200:203], v[96:99]
	v_mfma_f32_16x16x32_bf16 v[96:99], v[188:191], v[204:207], v[96:99]
	v_mfma_f32_16x16x32_bf16 v[104:107], v[180:183], v[204:207], v[104:107]
	v_mfma_f32_16x16x32_bf16 v[104:107], v[176:179], v[200:203], v[104:107]
	v_mfma_f32_16x16x32_bf16 v[88:91], v[176:179], v[208:211], v[88:91]
	v_mfma_f32_16x16x32_bf16 v[88:91], v[180:183], v[212:215], v[88:91]
	v_mfma_f32_16x16x32_bf16 v[80:83], v[188:191], v[212:215], v[80:83]
	v_mfma_f32_16x16x32_bf16 v[80:83], v[184:187], v[208:211], v[80:83]
	v_mfma_f32_16x16x32_bf16 v[64:67], v[184:187], v[216:219], v[64:67]
	v_mfma_f32_16x16x32_bf16 v[64:67], v[188:191], v[220:223], v[64:67]
	v_mfma_f32_16x16x32_bf16 v[72:75], v[180:183], v[220:223], v[72:75]
	v_mfma_f32_16x16x32_bf16 v[72:75], v[176:179], v[216:219], v[72:75]
	s_setprio 0
	s_barrier
	v_add_u32_e32 v234, 0x21000, v151
	ds_read_b128 v[236:239], v234
	ds_read_b128 v[240:243], v234 offset:256
	ds_read_b128 v[244:247], v234 offset:512
	ds_read_b128 v[248:251], v234 offset:768
	v_add_u32_e32 v235, s23, v146
	v_mul_u32_u24_e32 v235, 0x1600, v235
	v_lshl_or_b32 v234, s64, 7, v149
	v_lshl_add_u32 v235, v234, 1, v235
	s_add_i32 s46, s71, s49
	v_lshl_add_u64 v[154:155], v[154:155], 0, s[14:15]
	s_mov_b32 m0, s46
	ds_read_b128 v[192:195], v150 offset:49152
	v_xor_b32_e32 v253, 64, v150
	ds_read_b128 v[196:199], v253 offset:49152
	ds_read_b128 v[200:203], v150 offset:51200
	ds_read_b128 v[204:207], v253 offset:51200
	ds_read_b128 v[208:211], v150 offset:53248
	ds_read_b128 v[212:215], v253 offset:53248
	ds_read_b128 v[216:219], v150 offset:55296
	ds_read_b128 v[220:223], v253 offset:55296
	global_load_lds_dwordx4 v[154:155], off
	s_add_i32 m0, s46, 0x2000
	s_add_u32 s44, s44, 0x40080
	v_lshl_add_u64 v[154:155], v[224:225], 0, s[14:15]
	s_addc_u32 s45, s45, 0
	s_add_i32 s46, s72, s49
	global_load_lds_dwordx4 v[154:155], off
	v_lshl_add_u64 v[154:155], s[44:45], 0, v[132:133]
	s_mov_b32 m0, s46
	s_nop 0
	global_load_lds_dwordx4 v[154:155], off
	v_lshl_add_u64 v[154:155], s[44:45], 0, v[128:129]
	s_add_i32 m0, s46, 0x2000
	s_nop 0
	global_load_lds_dwordx4 v[154:155], off
	v_lshl_add_u64 v[154:155], v[226:227], 0, s[14:15]
	s_mov_b32 m0, s57
	s_nop 0
	global_load_lds_dwordx4 v[154:155], off
	v_lshl_add_u64 v[154:155], v[228:229], 0, s[14:15]
	s_mov_b32 m0, s58
	s_nop 0
	global_load_lds_dwordx4 v[154:155], off
	s_waitcnt lgkmcnt(8)
	v_add_f32_e32 v236, v236, v237
	v_add_f32_e32 v238, v238, v239
	v_add_f32_e32 v240, v240, v241
	v_add_f32_e32 v242, v242, v243
	v_add_f32_e32 v244, v244, v245
	v_add_f32_e32 v246, v246, v247
	v_add_f32_e32 v248, v248, v249
	v_add_f32_e32 v250, v250, v251
	v_add_f32_e32 v236, v236, v238
	v_add_f32_e32 v240, v240, v242
	v_add_f32_e32 v244, v244, v246
	v_add_f32_e32 v248, v248, v250
	v_fmamk_f32 v236, v236, 0x3a800000, v152
	v_fmamk_f32 v240, v240, 0x3a800000, v152
	v_fmamk_f32 v244, v244, 0x3a800000, v152
	v_fmamk_f32 v248, v248, 0x3a800000, v152
	v_rsq_f32_e32 v236, v236
	v_rsq_f32_e32 v240, v240
	v_rsq_f32_e32 v244, v244
	v_rsq_f32_e32 v248, v248
	v_mul_f32_e32 v252, 0xbfb8aa3b, v236
	v_mul_f32_e32 v254, v236, v236
	v_pk_mul_f32 v[120:121], v[124:125], v[120:121]
	v_pk_mul_f32 v[122:123], v[126:127], v[122:123]
	v_pk_mul_f32 v[112:113], v[116:117], v[112:113]
	v_pk_mul_f32 v[114:115], v[118:119], v[114:115]
	v_pk_mul_f32 v[124:125], v[124:125], v[252:253] op_sel_hi:[1,0]
	v_pk_mul_f32 v[126:127], v[126:127], v[252:253] op_sel_hi:[1,0]
	v_pk_mul_f32 v[116:117], v[116:117], v[252:253] op_sel_hi:[1,0]
	v_pk_mul_f32 v[118:119], v[118:119], v[252:253] op_sel_hi:[1,0]
	v_exp_f32_e32 v124, v124
	v_exp_f32_e32 v125, v125
	v_exp_f32_e32 v126, v126
	v_exp_f32_e32 v127, v127
	v_exp_f32_e32 v116, v116
	v_exp_f32_e32 v117, v117
	v_exp_f32_e32 v118, v118
	v_exp_f32_e32 v119, v119
	v_pk_add_f32 v[124:125], v[124:125], 1.0 op_sel_hi:[1,0]
	v_pk_add_f32 v[126:127], v[126:127], 1.0 op_sel_hi:[1,0]
	v_pk_add_f32 v[116:117], v[116:117], 1.0 op_sel_hi:[1,0]
	v_pk_add_f32 v[118:119], v[118:119], 1.0 op_sel_hi:[1,0]
	v_rcp_f32_e32 v124, v124
	v_rcp_f32_e32 v125, v125
	v_rcp_f32_e32 v126, v126
	v_rcp_f32_e32 v127, v127
	v_rcp_f32_e32 v116, v116
	v_rcp_f32_e32 v117, v117
	v_rcp_f32_e32 v118, v118
	v_rcp_f32_e32 v119, v119
	v_pk_mul_f32 v[120:121], v[120:121], v[254:255] op_sel_hi:[1,0]
	v_pk_mul_f32 v[122:123], v[122:123], v[254:255] op_sel_hi:[1,0]
	v_pk_mul_f32 v[112:113], v[112:113], v[254:255] op_sel_hi:[1,0]
	v_pk_mul_f32 v[114:115], v[114:115], v[254:255] op_sel_hi:[1,0]
	v_pk_mul_f32 v[120:121], v[120:121], v[124:125]
	v_pk_mul_f32 v[122:123], v[122:123], v[126:127]
	v_pk_mul_f32 v[112:113], v[112:113], v[116:117]
	v_pk_mul_f32 v[114:115], v[114:115], v[118:119]
	v_cvt_pk_bf16_f32 v120, v120, v121
	v_cvt_pk_bf16_f32 v121, v122, v123
	v_cvt_pk_bf16_f32 v122, v112, v113
	v_cvt_pk_bf16_f32 v123, v114, v115
	global_store_dwordx4 v235, v[120:123], s[10:11]
	v_add_u32_e32 v234, 0x16000, v235
	v_mul_f32_e32 v252, 0xbfb8aa3b, v240
	v_mul_f32_e32 v254, v240, v240
	v_pk_mul_f32 v[104:105], v[108:109], v[104:105]
	v_pk_mul_f32 v[106:107], v[110:111], v[106:107]
	v_pk_mul_f32 v[96:97], v[100:101], v[96:97]
	v_pk_mul_f32 v[98:99], v[102:103], v[98:99]
	v_pk_mul_f32 v[108:109], v[108:109], v[252:253] op_sel_hi:[1,0]
	v_pk_mul_f32 v[110:111], v[110:111], v[252:253] op_sel_hi:[1,0]
	v_pk_mul_f32 v[100:101], v[100:101], v[252:253] op_sel_hi:[1,0]
	v_pk_mul_f32 v[102:103], v[102:103], v[252:253] op_sel_hi:[1,0]
	v_exp_f32_e32 v108, v108
	v_exp_f32_e32 v109, v109
	v_exp_f32_e32 v110, v110
	v_exp_f32_e32 v111, v111
	v_exp_f32_e32 v100, v100
	v_exp_f32_e32 v101, v101
	v_exp_f32_e32 v102, v102
	v_exp_f32_e32 v103, v103
	v_pk_add_f32 v[108:109], v[108:109], 1.0 op_sel_hi:[1,0]
	v_pk_add_f32 v[110:111], v[110:111], 1.0 op_sel_hi:[1,0]
	v_pk_add_f32 v[100:101], v[100:101], 1.0 op_sel_hi:[1,0]
	v_pk_add_f32 v[102:103], v[102:103], 1.0 op_sel_hi:[1,0]
	v_rcp_f32_e32 v108, v108
	v_rcp_f32_e32 v109, v109
	v_rcp_f32_e32 v110, v110
	v_rcp_f32_e32 v111, v111
	v_rcp_f32_e32 v100, v100
	v_rcp_f32_e32 v101, v101
	v_rcp_f32_e32 v102, v102
	v_rcp_f32_e32 v103, v103
	v_pk_mul_f32 v[104:105], v[104:105], v[254:255] op_sel_hi:[1,0]
	v_pk_mul_f32 v[106:107], v[106:107], v[254:255] op_sel_hi:[1,0]
	v_pk_mul_f32 v[96:97], v[96:97], v[254:255] op_sel_hi:[1,0]
	v_pk_mul_f32 v[98:99], v[98:99], v[254:255] op_sel_hi:[1,0]
	v_pk_mul_f32 v[104:105], v[104:105], v[108:109]
	v_pk_mul_f32 v[106:107], v[106:107], v[110:111]
	v_pk_mul_f32 v[96:97], v[96:97], v[100:101]
	v_pk_mul_f32 v[98:99], v[98:99], v[102:103]
	v_cvt_pk_bf16_f32 v104, v104, v105
	v_cvt_pk_bf16_f32 v105, v106, v107
	v_cvt_pk_bf16_f32 v106, v96, v97
	v_cvt_pk_bf16_f32 v107, v98, v99
	global_store_dwordx4 v234, v[104:107], s[10:11]
	v_add_u32_e32 v235, 0x16000, v234
	v_mul_f32_e32 v252, 0xbfb8aa3b, v244
	v_mul_f32_e32 v254, v244, v244
	v_pk_mul_f32 v[88:89], v[92:93], v[88:89]
	v_pk_mul_f32 v[90:91], v[94:95], v[90:91]
	v_pk_mul_f32 v[80:81], v[84:85], v[80:81]
	v_pk_mul_f32 v[82:83], v[86:87], v[82:83]
	v_pk_mul_f32 v[92:93], v[92:93], v[252:253] op_sel_hi:[1,0]
	v_pk_mul_f32 v[94:95], v[94:95], v[252:253] op_sel_hi:[1,0]
	v_pk_mul_f32 v[84:85], v[84:85], v[252:253] op_sel_hi:[1,0]
	v_pk_mul_f32 v[86:87], v[86:87], v[252:253] op_sel_hi:[1,0]
	v_exp_f32_e32 v92, v92
	v_exp_f32_e32 v93, v93
	v_exp_f32_e32 v94, v94
	v_exp_f32_e32 v95, v95
	v_exp_f32_e32 v84, v84
	v_exp_f32_e32 v85, v85
	v_exp_f32_e32 v86, v86
	v_exp_f32_e32 v87, v87
	v_pk_add_f32 v[92:93], v[92:93], 1.0 op_sel_hi:[1,0]
	v_pk_add_f32 v[94:95], v[94:95], 1.0 op_sel_hi:[1,0]
	v_pk_add_f32 v[84:85], v[84:85], 1.0 op_sel_hi:[1,0]
	v_pk_add_f32 v[86:87], v[86:87], 1.0 op_sel_hi:[1,0]
	v_rcp_f32_e32 v92, v92
	v_rcp_f32_e32 v93, v93
	v_rcp_f32_e32 v94, v94
	v_rcp_f32_e32 v95, v95
	v_rcp_f32_e32 v84, v84
	v_rcp_f32_e32 v85, v85
	v_rcp_f32_e32 v86, v86
	v_rcp_f32_e32 v87, v87
	v_pk_mul_f32 v[88:89], v[88:89], v[254:255] op_sel_hi:[1,0]
	v_pk_mul_f32 v[90:91], v[90:91], v[254:255] op_sel_hi:[1,0]
	v_pk_mul_f32 v[80:81], v[80:81], v[254:255] op_sel_hi:[1,0]
	v_pk_mul_f32 v[82:83], v[82:83], v[254:255] op_sel_hi:[1,0]
	v_pk_mul_f32 v[88:89], v[88:89], v[92:93]
	v_pk_mul_f32 v[90:91], v[90:91], v[94:95]
	v_pk_mul_f32 v[80:81], v[80:81], v[84:85]
	v_pk_mul_f32 v[82:83], v[82:83], v[86:87]
	v_cvt_pk_bf16_f32 v88, v88, v89
	v_cvt_pk_bf16_f32 v89, v90, v91
	v_cvt_pk_bf16_f32 v90, v80, v81
	v_cvt_pk_bf16_f32 v91, v82, v83
	global_store_dwordx4 v235, v[88:91], s[10:11]
	v_add_u32_e32 v234, 0x16000, v235
	v_mul_f32_e32 v252, 0xbfb8aa3b, v248
	v_mul_f32_e32 v254, v248, v248
	v_pk_mul_f32 v[72:73], v[76:77], v[72:73]
	v_pk_mul_f32 v[74:75], v[78:79], v[74:75]
	v_pk_mul_f32 v[64:65], v[68:69], v[64:65]
	v_pk_mul_f32 v[66:67], v[70:71], v[66:67]
	v_pk_mul_f32 v[76:77], v[76:77], v[252:253] op_sel_hi:[1,0]
	v_pk_mul_f32 v[78:79], v[78:79], v[252:253] op_sel_hi:[1,0]
	v_pk_mul_f32 v[68:69], v[68:69], v[252:253] op_sel_hi:[1,0]
	v_pk_mul_f32 v[70:71], v[70:71], v[252:253] op_sel_hi:[1,0]
	v_exp_f32_e32 v76, v76
	v_exp_f32_e32 v77, v77
	v_exp_f32_e32 v78, v78
	v_exp_f32_e32 v79, v79
	v_exp_f32_e32 v68, v68
	v_exp_f32_e32 v69, v69
	v_exp_f32_e32 v70, v70
	v_exp_f32_e32 v71, v71
	v_pk_add_f32 v[76:77], v[76:77], 1.0 op_sel_hi:[1,0]
	v_pk_add_f32 v[78:79], v[78:79], 1.0 op_sel_hi:[1,0]
	v_pk_add_f32 v[68:69], v[68:69], 1.0 op_sel_hi:[1,0]
	v_pk_add_f32 v[70:71], v[70:71], 1.0 op_sel_hi:[1,0]
	v_rcp_f32_e32 v76, v76
	v_rcp_f32_e32 v77, v77
	v_rcp_f32_e32 v78, v78
	v_rcp_f32_e32 v79, v79
	v_rcp_f32_e32 v68, v68
	v_rcp_f32_e32 v69, v69
	v_rcp_f32_e32 v70, v70
	v_rcp_f32_e32 v71, v71
	v_pk_mul_f32 v[72:73], v[72:73], v[254:255] op_sel_hi:[1,0]
	v_pk_mul_f32 v[74:75], v[74:75], v[254:255] op_sel_hi:[1,0]
	v_pk_mul_f32 v[64:65], v[64:65], v[254:255] op_sel_hi:[1,0]
	v_pk_mul_f32 v[66:67], v[66:67], v[254:255] op_sel_hi:[1,0]
	v_pk_mul_f32 v[72:73], v[72:73], v[76:77]
	v_pk_mul_f32 v[74:75], v[74:75], v[78:79]
	v_pk_mul_f32 v[64:65], v[64:65], v[68:69]
	v_pk_mul_f32 v[66:67], v[66:67], v[70:71]
	v_cvt_pk_bf16_f32 v72, v72, v73
	v_cvt_pk_bf16_f32 v73, v74, v75
	v_cvt_pk_bf16_f32 v74, v64, v65
	v_cvt_pk_bf16_f32 v75, v66, v67
	global_store_dwordx4 v234, v[72:75], s[10:11]
	s_waitcnt vmcnt(12)
	s_waitcnt lgkmcnt(0)
	s_barrier
	s_setprio 1
	s_waitcnt lgkmcnt(0)
	v_mfma_f32_16x16x32_bf16 v[60:63], v[160:163], v[192:195], v[60:63]
	v_mfma_f32_16x16x32_bf16 v[60:63], v[164:167], v[196:199], v[60:63]
	v_mfma_f32_16x16x32_bf16 v[52:55], v[172:175], v[196:199], v[52:55]
	v_mfma_f32_16x16x32_bf16 v[52:55], v[168:171], v[192:195], v[52:55]
	v_mfma_f32_16x16x32_bf16 v[36:39], v[168:171], v[200:203], v[36:39]
	v_mfma_f32_16x16x32_bf16 v[36:39], v[172:175], v[204:207], v[36:39]
	v_mfma_f32_16x16x32_bf16 v[44:47], v[164:167], v[204:207], v[44:47]
	v_mfma_f32_16x16x32_bf16 v[44:47], v[160:163], v[200:203], v[44:47]
	v_mfma_f32_16x16x32_bf16 v[28:31], v[160:163], v[208:211], v[28:31]
	v_mfma_f32_16x16x32_bf16 v[28:31], v[164:167], v[212:215], v[28:31]
	v_mfma_f32_16x16x32_bf16 v[20:23], v[172:175], v[212:215], v[20:23]
	v_mfma_f32_16x16x32_bf16 v[20:23], v[168:171], v[208:211], v[20:23]
	v_mfma_f32_16x16x32_bf16 v[4:7], v[168:171], v[216:219], v[4:7]
	v_mfma_f32_16x16x32_bf16 v[4:7], v[172:175], v[220:223], v[4:7]
	v_mfma_f32_16x16x32_bf16 v[12:15], v[164:167], v[220:223], v[12:15]
	v_mfma_f32_16x16x32_bf16 v[12:15], v[160:163], v[216:219], v[12:15]
	s_setprio 0
	s_setprio 1
	v_mfma_f32_16x16x32_bf16 v[56:59], v[176:179], v[192:195], v[56:59]
	v_mfma_f32_16x16x32_bf16 v[56:59], v[180:183], v[196:199], v[56:59]
	v_mfma_f32_16x16x32_bf16 v[48:51], v[188:191], v[196:199], v[48:51]
	v_mfma_f32_16x16x32_bf16 v[48:51], v[184:187], v[192:195], v[48:51]
	v_mfma_f32_16x16x32_bf16 v[32:35], v[184:187], v[200:203], v[32:35]
	v_mfma_f32_16x16x32_bf16 v[32:35], v[188:191], v[204:207], v[32:35]
	v_mfma_f32_16x16x32_bf16 v[40:43], v[180:183], v[204:207], v[40:43]
	v_mfma_f32_16x16x32_bf16 v[40:43], v[176:179], v[200:203], v[40:43]
	v_mfma_f32_16x16x32_bf16 v[24:27], v[176:179], v[208:211], v[24:27]
	v_mfma_f32_16x16x32_bf16 v[24:27], v[180:183], v[212:215], v[24:27]
	v_mfma_f32_16x16x32_bf16 v[16:19], v[188:191], v[212:215], v[16:19]
	v_mfma_f32_16x16x32_bf16 v[16:19], v[184:187], v[208:211], v[16:19]
	v_mfma_f32_16x16x32_bf16 v[0:3], v[184:187], v[216:219], v[0:3]
	v_mfma_f32_16x16x32_bf16 v[0:3], v[188:191], v[220:223], v[0:3]
	v_mfma_f32_16x16x32_bf16 v[8:11], v[180:183], v[220:223], v[8:11]
	v_mfma_f32_16x16x32_bf16 v[8:11], v[176:179], v[216:219], v[8:11]
	s_setprio 0
	s_barrier
	s_add_i32 s70, s70, 2
	s_add_u32 s68, s68, 0x100
	s_addc_u32 s69, s69, 0
	s_add_u32 s30, s30, 0x100
	s_addc_u32 s31, s31, 0

.LBB0_1180:
	s_add_u32 s72, s50, 0x100
	s_addc_u32 s73, s51, 0
	s_mov_b32 s74, -2
	s_waitcnt lgkmcnt(0)
	s_cmp_eq_u32 s63, 1
	s_cbranch_scc1 .Lfa_11
	ds_read_b128 v[128:131], v188
	v_xor_b32_e32 v253, 64, v188
	ds_read_b128 v[132:135], v253
	ds_read_b128 v[136:139], v188 offset:2048
	ds_read_b128 v[140:143], v253 offset:2048
	ds_read_b128 v[144:147], v189
	v_xor_b32_e32 v253, 64, v189
	ds_read_b128 v[148:151], v253
	ds_read_b128 v[172:175], v189 offset:2048
	ds_read_b128 v[176:179], v253 offset:2048
	s_add_u32 s50, s48, 0x100
	s_addc_u32 s51, s49, 0
	s_cmp_eq_u32 s74, 40
	s_cselect_b32 s55, s11, s51
	s_cselect_b32 s54, s10, s50
	s_cselect_b32 s53, s47, s73
	s_cselect_b32 s52, s46, s72
	v_lshl_add_u64 v[220:221], s[48:49], 0, v[166:167]
	s_add_i32 m0, s59, 0xc000
	ds_read_b128 v[180:183], v190
	v_xor_b32_e32 v253, 64, v190
	ds_read_b128 v[192:195], v253
	ds_read_b128 v[196:199], v190 offset:2048
	ds_read_b128 v[200:203], v253 offset:2048
	ds_read_b128 v[204:207], v190 offset:4096
	ds_read_b128 v[208:211], v253 offset:4096
	ds_read_b128 v[212:215], v190 offset:6144
	ds_read_b128 v[216:219], v253 offset:6144
	global_load_lds_dwordx4 v[220:221], off
	v_lshl_add_u64 v[220:221], s[48:49], 0, v[164:165]
	s_add_i32 m0, s59, 0xe000
	s_nop 0
	global_load_lds_dwordx4 v[220:221], off
	s_waitcnt vmcnt(24)
	s_waitcnt lgkmcnt(0)
	s_barrier
	s_setprio 1
	s_waitcnt lgkmcnt(0)
	v_mfma_f32_16x16x32_bf16 v[124:127], v[128:131], v[180:183], 0
	v_mfma_f32_16x16x32_bf16 v[120:123], v[136:139], v[180:183], 0
	v_mfma_f32_16x16x32_bf16 v[108:111], v[128:131], v[196:199], 0
	v_mfma_f32_16x16x32_bf16 v[104:107], v[136:139], v[196:199], 0
	v_mfma_f32_16x16x32_bf16 v[92:95], v[128:131], v[204:207], 0
	v_mfma_f32_16x16x32_bf16 v[88:91], v[136:139], v[204:207], 0
	v_mfma_f32_16x16x32_bf16 v[76:79], v[128:131], v[212:215], 0
	v_mfma_f32_16x16x32_bf16 v[72:75], v[136:139], v[212:215], 0
	v_mfma_f32_16x16x32_bf16 v[124:127], v[132:135], v[192:195], v[124:127]
	v_mfma_f32_16x16x32_bf16 v[120:123], v[140:143], v[192:195], v[120:123]
	v_mfma_f32_16x16x32_bf16 v[108:111], v[132:135], v[200:203], v[108:111]
	v_mfma_f32_16x16x32_bf16 v[104:107], v[140:143], v[200:203], v[104:107]
	v_mfma_f32_16x16x32_bf16 v[92:95], v[132:135], v[208:211], v[92:95]
	v_mfma_f32_16x16x32_bf16 v[88:91], v[140:143], v[208:211], v[88:91]
	v_mfma_f32_16x16x32_bf16 v[76:79], v[132:135], v[216:219], v[76:79]
	v_mfma_f32_16x16x32_bf16 v[72:75], v[140:143], v[216:219], v[72:75]
	s_setprio 0
	s_setprio 1
	v_mfma_f32_16x16x32_bf16 v[116:119], v[144:147], v[180:183], 0
	v_mfma_f32_16x16x32_bf16 v[112:115], v[172:175], v[180:183], 0
	v_mfma_f32_16x16x32_bf16 v[100:103], v[144:147], v[196:199], 0
	v_mfma_f32_16x16x32_bf16 v[96:99], v[172:175], v[196:199], 0
	v_mfma_f32_16x16x32_bf16 v[84:87], v[144:147], v[204:207], 0
	v_mfma_f32_16x16x32_bf16 v[80:83], v[172:175], v[204:207], 0
	v_mfma_f32_16x16x32_bf16 v[68:71], v[144:147], v[212:215], 0
	v_mfma_f32_16x16x32_bf16 v[64:67], v[172:175], v[212:215], 0
	v_mfma_f32_16x16x32_bf16 v[116:119], v[148:151], v[192:195], v[116:119]
	v_mfma_f32_16x16x32_bf16 v[112:115], v[176:179], v[192:195], v[112:115]
	v_mfma_f32_16x16x32_bf16 v[100:103], v[148:151], v[200:203], v[100:103]
	v_mfma_f32_16x16x32_bf16 v[96:99], v[176:179], v[200:203], v[96:99]
	v_mfma_f32_16x16x32_bf16 v[84:87], v[148:151], v[208:211], v[84:87]
	v_mfma_f32_16x16x32_bf16 v[80:83], v[176:179], v[208:211], v[80:83]
	v_mfma_f32_16x16x32_bf16 v[68:71], v[148:151], v[216:219], v[68:71]
	v_mfma_f32_16x16x32_bf16 v[64:67], v[176:179], v[216:219], v[64:67]
	s_setprio 0
	s_barrier
	s_add_i32 s48, s68, s58
	v_lshl_add_u64 v[220:221], s[52:53], 0, v[154:155]
	s_mov_b32 m0, s48
	ds_read_b128 v[180:183], v190 offset:16384
	v_xor_b32_e32 v253, 64, v190
	ds_read_b128 v[192:195], v253 offset:16384
	ds_read_b128 v[196:199], v190 offset:18432
	ds_read_b128 v[200:203], v253 offset:18432
	ds_read_b128 v[204:207], v190 offset:20480
	ds_read_b128 v[208:211], v253 offset:20480
	ds_read_b128 v[212:215], v190 offset:22528
	ds_read_b128 v[216:219], v253 offset:22528
	global_load_lds_dwordx4 v[220:221], off
	s_add_i32 m0, s48, 0x2000
	s_add_u32 s48, s52, 0xb0000
	v_lshl_add_u64 v[222:223], s[52:53], 0, v[162:163]
	s_addc_u32 s49, s53, 0
	s_add_i32 s75, s69, s58
	global_load_lds_dwordx4 v[222:223], off
	v_lshl_add_u64 v[224:225], s[48:49], 0, v[154:155]
	s_mov_b32 m0, s75
	v_lshl_add_u64 v[226:227], s[54:55], 0, v[160:161]
	global_load_lds_dwordx4 v[224:225], off
	v_lshl_add_u64 v[224:225], s[48:49], 0, v[162:163]
	s_add_i32 m0, s75, 0x2000
	s_nop 0
	global_load_lds_dwordx4 v[224:225], off
	v_lshl_add_u64 v[224:225], s[54:55], 0, v[152:153]
	s_mov_b32 m0, s59
	s_nop 0
	global_load_lds_dwordx4 v[224:225], off
	s_mov_b32 m0, s60
	s_nop 0
	global_load_lds_dwordx4 v[226:227], off
	s_waitcnt vmcnt(24)
	s_waitcnt lgkmcnt(0)
	s_barrier
	s_setprio 1
	s_waitcnt lgkmcnt(0)
	v_mfma_f32_16x16x32_bf16 v[60:63], v[128:131], v[180:183], 0
	v_mfma_f32_16x16x32_bf16 v[56:59], v[136:139], v[180:183], 0
	v_mfma_f32_16x16x32_bf16 v[44:47], v[128:131], v[196:199], 0
	v_mfma_f32_16x16x32_bf16 v[40:43], v[136:139], v[196:199], 0
	v_mfma_f32_16x16x32_bf16 v[28:31], v[128:131], v[204:207], 0
	v_mfma_f32_16x16x32_bf16 v[24:27], v[136:139], v[204:207], 0
	v_mfma_f32_16x16x32_bf16 v[12:15], v[128:131], v[212:215], 0
	v_mfma_f32_16x16x32_bf16 v[8:11], v[136:139], v[212:215], 0
	v_mfma_f32_16x16x32_bf16 v[60:63], v[132:135], v[192:195], v[60:63]
	v_mfma_f32_16x16x32_bf16 v[56:59], v[140:143], v[192:195], v[56:59]
	v_mfma_f32_16x16x32_bf16 v[44:47], v[132:135], v[200:203], v[44:47]
	v_mfma_f32_16x16x32_bf16 v[40:43], v[140:143], v[200:203], v[40:43]
	v_mfma_f32_16x16x32_bf16 v[28:31], v[132:135], v[208:211], v[28:31]
	v_mfma_f32_16x16x32_bf16 v[24:27], v[140:143], v[208:211], v[24:27]
	v_mfma_f32_16x16x32_bf16 v[12:15], v[132:135], v[216:219], v[12:15]
	v_mfma_f32_16x16x32_bf16 v[8:11], v[140:143], v[216:219], v[8:11]
	s_setprio 0
	s_setprio 1
	v_mfma_f32_16x16x32_bf16 v[52:55], v[144:147], v[180:183], 0
	v_mfma_f32_16x16x32_bf16 v[48:51], v[172:175], v[180:183], 0
	v_mfma_f32_16x16x32_bf16 v[36:39], v[144:147], v[196:199], 0
	v_mfma_f32_16x16x32_bf16 v[32:35], v[172:175], v[196:199], 0
	v_mfma_f32_16x16x32_bf16 v[20:23], v[144:147], v[204:207], 0
	v_mfma_f32_16x16x32_bf16 v[16:19], v[172:175], v[204:207], 0
	v_mfma_f32_16x16x32_bf16 v[4:7], v[144:147], v[212:215], 0
	v_mfma_f32_16x16x32_bf16 v[0:3], v[172:175], v[212:215], 0
	v_mfma_f32_16x16x32_bf16 v[52:55], v[148:151], v[192:195], v[52:55]
	v_mfma_f32_16x16x32_bf16 v[48:51], v[176:179], v[192:195], v[48:51]
	v_mfma_f32_16x16x32_bf16 v[36:39], v[148:151], v[200:203], v[36:39]
	v_mfma_f32_16x16x32_bf16 v[32:35], v[176:179], v[200:203], v[32:35]
	v_mfma_f32_16x16x32_bf16 v[20:23], v[148:151], v[208:211], v[20:23]
	v_mfma_f32_16x16x32_bf16 v[16:19], v[176:179], v[208:211], v[16:19]
	v_mfma_f32_16x16x32_bf16 v[4:7], v[148:151], v[216:219], v[4:7]
	v_mfma_f32_16x16x32_bf16 v[0:3], v[176:179], v[216:219], v[0:3]
	s_setprio 0
	s_barrier
	s_add_i32 s75, 0, 0x18000
	s_add_i32 s76, 0, 0x1c000
	v_add_u32_e32 v140, s75, v185
	v_add_u32_e32 v176, s76, v185
	ds_read_b128 v[128:131], v140
	v_xor_b32_e32 v253, 64, v140
	ds_read_b128 v[132:135], v253
	ds_read_b128 v[136:139], v140 offset:2048
	ds_read_b128 v[140:143], v253 offset:2048
	ds_read_b128 v[144:147], v176
	v_xor_b32_e32 v253, 64, v176
	ds_read_b128 v[148:151], v253
	ds_read_b128 v[172:175], v176 offset:2048
	ds_read_b128 v[176:179], v253 offset:2048
	s_add_u32 s48, s54, 0xb0000
	s_addc_u32 s49, s55, 0
	s_mov_b32 m0, s61
	v_lshl_add_u64 v[228:229], s[48:49], 0, v[152:153]
	ds_read_b128 v[180:183], v190 offset:32768
	v_xor_b32_e32 v253, 64, v190
	ds_read_b128 v[192:195], v253 offset:32768
	ds_read_b128 v[196:199], v190 offset:34816
	ds_read_b128 v[200:203], v253 offset:34816
	ds_read_b128 v[204:207], v190 offset:36864
	ds_read_b128 v[208:211], v253 offset:36864
	ds_read_b128 v[212:215], v190 offset:38912
	ds_read_b128 v[216:219], v253 offset:38912
	global_load_lds_dwordx4 v[228:229], off
	v_lshl_add_u64 v[228:229], s[48:49], 0, v[160:161]
	s_mov_b32 m0, s62
	s_nop 0
	global_load_lds_dwordx4 v[228:229], off
	s_waitcnt vmcnt(8)
	s_waitcnt lgkmcnt(0)
	s_barrier
	s_setprio 1
	s_waitcnt lgkmcnt(0)
	v_mfma_f32_16x16x32_bf16 v[124:127], v[128:131], v[180:183], v[124:127]
	v_mfma_f32_16x16x32_bf16 v[124:127], v[132:135], v[192:195], v[124:127]
	v_mfma_f32_16x16x32_bf16 v[120:123], v[140:143], v[192:195], v[120:123]
	v_mfma_f32_16x16x32_bf16 v[120:123], v[136:139], v[180:183], v[120:123]
	v_mfma_f32_16x16x32_bf16 v[104:107], v[136:139], v[196:199], v[104:107]
	v_mfma_f32_16x16x32_bf16 v[104:107], v[140:143], v[200:203], v[104:107]
	v_mfma_f32_16x16x32_bf16 v[108:111], v[132:135], v[200:203], v[108:111]
	v_mfma_f32_16x16x32_bf16 v[108:111], v[128:131], v[196:199], v[108:111]
	v_mfma_f32_16x16x32_bf16 v[92:95], v[128:131], v[204:207], v[92:95]
	v_mfma_f32_16x16x32_bf16 v[92:95], v[132:135], v[208:211], v[92:95]
	v_mfma_f32_16x16x32_bf16 v[88:91], v[140:143], v[208:211], v[88:91]
	v_mfma_f32_16x16x32_bf16 v[88:91], v[136:139], v[204:207], v[88:91]
	v_mfma_f32_16x16x32_bf16 v[72:75], v[136:139], v[212:215], v[72:75]
	v_mfma_f32_16x16x32_bf16 v[72:75], v[140:143], v[216:219], v[72:75]
	v_mfma_f32_16x16x32_bf16 v[76:79], v[132:135], v[216:219], v[76:79]
	v_mfma_f32_16x16x32_bf16 v[76:79], v[128:131], v[212:215], v[76:79]
	s_setprio 0
	s_setprio 1
	v_mfma_f32_16x16x32_bf16 v[116:119], v[144:147], v[180:183], v[116:119]
	v_mfma_f32_16x16x32_bf16 v[116:119], v[148:151], v[192:195], v[116:119]
	v_mfma_f32_16x16x32_bf16 v[112:115], v[176:179], v[192:195], v[112:115]
	v_mfma_f32_16x16x32_bf16 v[112:115], v[172:175], v[180:183], v[112:115]
	v_mfma_f32_16x16x32_bf16 v[96:99], v[172:175], v[196:199], v[96:99]
	v_mfma_f32_16x16x32_bf16 v[96:99], v[176:179], v[200:203], v[96:99]
	v_mfma_f32_16x16x32_bf16 v[100:103], v[148:151], v[200:203], v[100:103]
	v_mfma_f32_16x16x32_bf16 v[100:103], v[144:147], v[196:199], v[100:103]
	v_mfma_f32_16x16x32_bf16 v[84:87], v[144:147], v[204:207], v[84:87]
	v_mfma_f32_16x16x32_bf16 v[84:87], v[148:151], v[208:211], v[84:87]
	v_mfma_f32_16x16x32_bf16 v[80:83], v[176:179], v[208:211], v[80:83]
	v_mfma_f32_16x16x32_bf16 v[80:83], v[172:175], v[204:207], v[80:83]
	v_mfma_f32_16x16x32_bf16 v[64:67], v[172:175], v[212:215], v[64:67]
	v_mfma_f32_16x16x32_bf16 v[64:67], v[176:179], v[216:219], v[64:67]
	v_mfma_f32_16x16x32_bf16 v[68:71], v[148:151], v[216:219], v[68:71]
	v_mfma_f32_16x16x32_bf16 v[68:71], v[144:147], v[212:215], v[68:71]
	s_setprio 0
	s_barrier
	s_add_i32 s48, s75, s58
	v_lshl_add_u64 v[220:221], v[220:221], 0, s[22:23]
	s_mov_b32 m0, s48
	ds_read_b128 v[180:183], v190 offset:49152
	v_xor_b32_e32 v253, 64, v190
	ds_read_b128 v[192:195], v253 offset:49152
	ds_read_b128 v[196:199], v190 offset:51200
	ds_read_b128 v[200:203], v253 offset:51200
	ds_read_b128 v[204:207], v190 offset:53248
	ds_read_b128 v[208:211], v253 offset:53248
	ds_read_b128 v[212:215], v190 offset:55296
	ds_read_b128 v[216:219], v253 offset:55296
	global_load_lds_dwordx4 v[220:221], off
	s_add_i32 m0, s48, 0x2000
	s_add_u32 s48, s52, 0xb0080
	v_lshl_add_u64 v[220:221], v[222:223], 0, s[22:23]
	s_addc_u32 s49, s53, 0
	s_add_i32 s52, s76, s58
	global_load_lds_dwordx4 v[220:221], off
	v_lshl_add_u64 v[220:221], s[48:49], 0, v[154:155]
	s_mov_b32 m0, s52
	s_nop 0
	global_load_lds_dwordx4 v[220:221], off
	v_lshl_add_u64 v[220:221], s[48:49], 0, v[162:163]
	s_add_i32 m0, s52, 0x2000
	s_nop 0
	global_load_lds_dwordx4 v[220:221], off
	v_lshl_add_u64 v[220:221], v[224:225], 0, s[22:23]
	s_mov_b32 m0, s3
	s_nop 0
	global_load_lds_dwordx4 v[220:221], off
	v_lshl_add_u64 v[220:221], v[226:227], 0, s[22:23]
	s_mov_b32 m0, s64
	s_nop 0
	global_load_lds_dwordx4 v[220:221], off
	s_waitcnt vmcnt(8)
	s_waitcnt lgkmcnt(0)
	s_barrier
	s_setprio 1
	s_waitcnt lgkmcnt(0)
	v_mfma_f32_16x16x32_bf16 v[60:63], v[128:131], v[180:183], v[60:63]
	v_mfma_f32_16x16x32_bf16 v[60:63], v[132:135], v[192:195], v[60:63]
	v_mfma_f32_16x16x32_bf16 v[56:59], v[140:143], v[192:195], v[56:59]
	v_mfma_f32_16x16x32_bf16 v[56:59], v[136:139], v[180:183], v[56:59]
	v_mfma_f32_16x16x32_bf16 v[40:43], v[136:139], v[196:199], v[40:43]
	v_mfma_f32_16x16x32_bf16 v[40:43], v[140:143], v[200:203], v[40:43]
	v_mfma_f32_16x16x32_bf16 v[44:47], v[132:135], v[200:203], v[44:47]
	v_mfma_f32_16x16x32_bf16 v[44:47], v[128:131], v[196:199], v[44:47]
	v_mfma_f32_16x16x32_bf16 v[28:31], v[128:131], v[204:207], v[28:31]
	v_mfma_f32_16x16x32_bf16 v[28:31], v[132:135], v[208:211], v[28:31]
	v_mfma_f32_16x16x32_bf16 v[24:27], v[140:143], v[208:211], v[24:27]
	v_mfma_f32_16x16x32_bf16 v[24:27], v[136:139], v[204:207], v[24:27]
	v_mfma_f32_16x16x32_bf16 v[8:11], v[136:139], v[212:215], v[8:11]
	v_mfma_f32_16x16x32_bf16 v[8:11], v[140:143], v[216:219], v[8:11]
	v_mfma_f32_16x16x32_bf16 v[12:15], v[132:135], v[216:219], v[12:15]
	v_mfma_f32_16x16x32_bf16 v[12:15], v[128:131], v[212:215], v[12:15]
	s_setprio 0
	s_setprio 1
	v_mfma_f32_16x16x32_bf16 v[52:55], v[144:147], v[180:183], v[52:55]
	v_mfma_f32_16x16x32_bf16 v[52:55], v[148:151], v[192:195], v[52:55]
	v_mfma_f32_16x16x32_bf16 v[48:51], v[176:179], v[192:195], v[48:51]
	v_mfma_f32_16x16x32_bf16 v[48:51], v[172:175], v[180:183], v[48:51]
	v_mfma_f32_16x16x32_bf16 v[32:35], v[172:175], v[196:199], v[32:35]
	v_mfma_f32_16x16x32_bf16 v[32:35], v[176:179], v[200:203], v[32:35]
	v_mfma_f32_16x16x32_bf16 v[36:39], v[148:151], v[200:203], v[36:39]
	v_mfma_f32_16x16x32_bf16 v[36:39], v[144:147], v[196:199], v[36:39]
	v_mfma_f32_16x16x32_bf16 v[20:23], v[144:147], v[204:207], v[20:23]
	v_mfma_f32_16x16x32_bf16 v[20:23], v[148:151], v[208:211], v[20:23]
	v_mfma_f32_16x16x32_bf16 v[16:19], v[176:179], v[208:211], v[16:19]
	v_mfma_f32_16x16x32_bf16 v[16:19], v[172:175], v[204:207], v[16:19]
	v_mfma_f32_16x16x32_bf16 v[0:3], v[172:175], v[212:215], v[0:3]
	v_mfma_f32_16x16x32_bf16 v[0:3], v[176:179], v[216:219], v[0:3]
	v_mfma_f32_16x16x32_bf16 v[4:7], v[148:151], v[216:219], v[4:7]
	v_mfma_f32_16x16x32_bf16 v[4:7], v[144:147], v[212:215], v[4:7]
	s_setprio 0
	s_barrier
	s_add_i32 s74, s74, 2
	s_add_u32 s72, s72, 0x100
	s_addc_u32 s73, s73, 0
	s_cmp_gt_u32 s74, 41
	s_mov_b64 s[48:49], s[50:51]
	s_branch .LBB0_1181
.Lfa_11:
	ds_read_b128 v[128:131], v188
	v_xor_b32_e32 v253, 64, v188
	ds_read_b128 v[132:135], v253
	ds_read_b128 v[136:139], v188 offset:2048
	ds_read_b128 v[140:143], v253 offset:2048
	ds_read_b128 v[144:147], v189
	v_xor_b32_e32 v253, 64, v189
	ds_read_b128 v[148:151], v253
	ds_read_b128 v[172:175], v189 offset:2048
	ds_read_b128 v[176:179], v253 offset:2048
	s_add_u32 s50, s48, 0x100
	s_addc_u32 s51, s49, 0
	s_cmp_eq_u32 s74, 40
	s_cselect_b32 s55, s11, s51
	s_cselect_b32 s54, s10, s50
	s_cselect_b32 s53, s47, s73
	s_cselect_b32 s52, s46, s72
	v_lshl_add_u64 v[220:221], s[48:49], 0, v[166:167]
	s_add_i32 m0, s59, 0xc000
	ds_read_b128 v[180:183], v190
	v_xor_b32_e32 v253, 64, v190
	ds_read_b128 v[192:195], v253
	ds_read_b128 v[196:199], v190 offset:2048
	ds_read_b128 v[200:203], v253 offset:2048
	ds_read_b128 v[204:207], v190 offset:4096
	ds_read_b128 v[208:211], v253 offset:4096
	ds_read_b128 v[212:215], v190 offset:6144
	ds_read_b128 v[216:219], v253 offset:6144
	global_load_lds_dwordx4 v[220:221], off
	v_lshl_add_u64 v[220:221], s[48:49], 0, v[164:165]
	s_add_i32 m0, s59, 0xe000
	s_nop 0
	global_load_lds_dwordx4 v[220:221], off
	s_waitcnt vmcnt(8)
	s_waitcnt lgkmcnt(0)
	s_barrier
	s_setprio 1
	s_waitcnt lgkmcnt(0)
	v_mfma_f32_16x16x32_bf16 v[124:127], v[128:131], v[180:183], 0
	v_mfma_f32_16x16x32_bf16 v[120:123], v[136:139], v[180:183], 0
	v_mfma_f32_16x16x32_bf16 v[108:111], v[128:131], v[196:199], 0
	v_mfma_f32_16x16x32_bf16 v[104:107], v[136:139], v[196:199], 0
	v_mfma_f32_16x16x32_bf16 v[92:95], v[128:131], v[204:207], 0
	v_mfma_f32_16x16x32_bf16 v[88:91], v[136:139], v[204:207], 0
	v_mfma_f32_16x16x32_bf16 v[76:79], v[128:131], v[212:215], 0
	v_mfma_f32_16x16x32_bf16 v[72:75], v[136:139], v[212:215], 0
	v_mfma_f32_16x16x32_bf16 v[124:127], v[132:135], v[192:195], v[124:127]
	v_mfma_f32_16x16x32_bf16 v[120:123], v[140:143], v[192:195], v[120:123]
	v_mfma_f32_16x16x32_bf16 v[108:111], v[132:135], v[200:203], v[108:111]
	v_mfma_f32_16x16x32_bf16 v[104:107], v[140:143], v[200:203], v[104:107]
	v_mfma_f32_16x16x32_bf16 v[92:95], v[132:135], v[208:211], v[92:95]
	v_mfma_f32_16x16x32_bf16 v[88:91], v[140:143], v[208:211], v[88:91]
	v_mfma_f32_16x16x32_bf16 v[76:79], v[132:135], v[216:219], v[76:79]
	v_mfma_f32_16x16x32_bf16 v[72:75], v[140:143], v[216:219], v[72:75]
	s_setprio 0
	s_setprio 1
	v_mfma_f32_16x16x32_bf16 v[116:119], v[144:147], v[180:183], 0
	v_mfma_f32_16x16x32_bf16 v[112:115], v[172:175], v[180:183], 0
	v_mfma_f32_16x16x32_bf16 v[100:103], v[144:147], v[196:199], 0
	v_mfma_f32_16x16x32_bf16 v[96:99], v[172:175], v[196:199], 0
	v_mfma_f32_16x16x32_bf16 v[84:87], v[144:147], v[204:207], 0
	v_mfma_f32_16x16x32_bf16 v[80:83], v[172:175], v[204:207], 0
	v_mfma_f32_16x16x32_bf16 v[68:71], v[144:147], v[212:215], 0
	v_mfma_f32_16x16x32_bf16 v[64:67], v[172:175], v[212:215], 0
	v_mfma_f32_16x16x32_bf16 v[116:119], v[148:151], v[192:195], v[116:119]
	v_mfma_f32_16x16x32_bf16 v[112:115], v[176:179], v[192:195], v[112:115]
	v_mfma_f32_16x16x32_bf16 v[100:103], v[148:151], v[200:203], v[100:103]
	v_mfma_f32_16x16x32_bf16 v[96:99], v[176:179], v[200:203], v[96:99]
	v_mfma_f32_16x16x32_bf16 v[84:87], v[148:151], v[208:211], v[84:87]
	v_mfma_f32_16x16x32_bf16 v[80:83], v[176:179], v[208:211], v[80:83]
	v_mfma_f32_16x16x32_bf16 v[68:71], v[148:151], v[216:219], v[68:71]
	v_mfma_f32_16x16x32_bf16 v[64:67], v[176:179], v[216:219], v[64:67]
	s_setprio 0
	s_barrier
	s_add_i32 s48, s68, s58
	v_lshl_add_u64 v[220:221], s[52:53], 0, v[154:155]
	s_mov_b32 m0, s48
	ds_read_b128 v[180:183], v190 offset:16384
	v_xor_b32_e32 v253, 64, v190
	ds_read_b128 v[192:195], v253 offset:16384
	ds_read_b128 v[196:199], v190 offset:18432
	ds_read_b128 v[200:203], v253 offset:18432
	ds_read_b128 v[204:207], v190 offset:20480
	ds_read_b128 v[208:211], v253 offset:20480
	ds_read_b128 v[212:215], v190 offset:22528
	ds_read_b128 v[216:219], v253 offset:22528
	global_load_lds_dwordx4 v[220:221], off
	s_add_i32 m0, s48, 0x2000
	s_add_u32 s48, s52, 0xb0000
	v_lshl_add_u64 v[222:223], s[52:53], 0, v[162:163]
	s_addc_u32 s49, s53, 0
	s_add_i32 s75, s69, s58
	global_load_lds_dwordx4 v[222:223], off
	v_lshl_add_u64 v[224:225], s[48:49], 0, v[154:155]
	s_mov_b32 m0, s75
	v_lshl_add_u64 v[226:227], s[54:55], 0, v[160:161]
	global_load_lds_dwordx4 v[224:225], off
	v_lshl_add_u64 v[224:225], s[48:49], 0, v[162:163]
	s_add_i32 m0, s75, 0x2000
	s_nop 0
	global_load_lds_dwordx4 v[224:225], off
	v_lshl_add_u64 v[224:225], s[54:55], 0, v[152:153]
	s_mov_b32 m0, s59
	s_nop 0
	global_load_lds_dwordx4 v[224:225], off
	s_mov_b32 m0, s60
	s_nop 0
	global_load_lds_dwordx4 v[226:227], off
	s_waitcnt vmcnt(8)
	s_waitcnt lgkmcnt(0)
	s_barrier
	s_setprio 1
	s_waitcnt lgkmcnt(0)
	v_mfma_f32_16x16x32_bf16 v[60:63], v[128:131], v[180:183], 0
	v_mfma_f32_16x16x32_bf16 v[56:59], v[136:139], v[180:183], 0
	v_mfma_f32_16x16x32_bf16 v[44:47], v[128:131], v[196:199], 0
	v_mfma_f32_16x16x32_bf16 v[40:43], v[136:139], v[196:199], 0
	v_mfma_f32_16x16x32_bf16 v[28:31], v[128:131], v[204:207], 0
	v_mfma_f32_16x16x32_bf16 v[24:27], v[136:139], v[204:207], 0
	v_mfma_f32_16x16x32_bf16 v[12:15], v[128:131], v[212:215], 0
	v_mfma_f32_16x16x32_bf16 v[8:11], v[136:139], v[212:215], 0
	v_mfma_f32_16x16x32_bf16 v[60:63], v[132:135], v[192:195], v[60:63]
	v_mfma_f32_16x16x32_bf16 v[56:59], v[140:143], v[192:195], v[56:59]
	v_mfma_f32_16x16x32_bf16 v[44:47], v[132:135], v[200:203], v[44:47]
	v_mfma_f32_16x16x32_bf16 v[40:43], v[140:143], v[200:203], v[40:43]
	v_mfma_f32_16x16x32_bf16 v[28:31], v[132:135], v[208:211], v[28:31]
	v_mfma_f32_16x16x32_bf16 v[24:27], v[140:143], v[208:211], v[24:27]
	v_mfma_f32_16x16x32_bf16 v[12:15], v[132:135], v[216:219], v[12:15]
	v_mfma_f32_16x16x32_bf16 v[8:11], v[140:143], v[216:219], v[8:11]
	s_setprio 0
	s_setprio 1
	v_mfma_f32_16x16x32_bf16 v[52:55], v[144:147], v[180:183], 0
	v_mfma_f32_16x16x32_bf16 v[48:51], v[172:175], v[180:183], 0
	v_mfma_f32_16x16x32_bf16 v[36:39], v[144:147], v[196:199], 0
	v_mfma_f32_16x16x32_bf16 v[32:35], v[172:175], v[196:199], 0
	v_mfma_f32_16x16x32_bf16 v[20:23], v[144:147], v[204:207], 0
	v_mfma_f32_16x16x32_bf16 v[16:19], v[172:175], v[204:207], 0
	v_mfma_f32_16x16x32_bf16 v[4:7], v[144:147], v[212:215], 0
	v_mfma_f32_16x16x32_bf16 v[0:3], v[172:175], v[212:215], 0
	v_mfma_f32_16x16x32_bf16 v[52:55], v[148:151], v[192:195], v[52:55]
	v_mfma_f32_16x16x32_bf16 v[48:51], v[176:179], v[192:195], v[48:51]
	v_mfma_f32_16x16x32_bf16 v[36:39], v[148:151], v[200:203], v[36:39]
	v_mfma_f32_16x16x32_bf16 v[32:35], v[176:179], v[200:203], v[32:35]
	v_mfma_f32_16x16x32_bf16 v[20:23], v[148:151], v[208:211], v[20:23]
	v_mfma_f32_16x16x32_bf16 v[16:19], v[176:179], v[208:211], v[16:19]
	v_mfma_f32_16x16x32_bf16 v[4:7], v[148:151], v[216:219], v[4:7]
	v_mfma_f32_16x16x32_bf16 v[0:3], v[176:179], v[216:219], v[0:3]
	s_setprio 0
	s_barrier
	s_add_i32 s75, 0, 0x18000
	s_add_i32 s76, 0, 0x1c000
	v_add_u32_e32 v140, s75, v185
	v_add_u32_e32 v176, s76, v185
	ds_read_b128 v[128:131], v140
	v_xor_b32_e32 v253, 64, v140
	ds_read_b128 v[132:135], v253
	ds_read_b128 v[136:139], v140 offset:2048
	ds_read_b128 v[140:143], v253 offset:2048
	ds_read_b128 v[144:147], v176
	v_xor_b32_e32 v253, 64, v176
	ds_read_b128 v[148:151], v253
	ds_read_b128 v[172:175], v176 offset:2048
	ds_read_b128 v[176:179], v253 offset:2048
	s_add_u32 s48, s54, 0xb0000
	s_addc_u32 s49, s55, 0
	s_mov_b32 m0, s61
	v_lshl_add_u64 v[228:229], s[48:49], 0, v[152:153]
	ds_read_b128 v[180:183], v190 offset:32768
	v_xor_b32_e32 v253, 64, v190
	ds_read_b128 v[192:195], v253 offset:32768
	ds_read_b128 v[196:199], v190 offset:34816
	ds_read_b128 v[200:203], v253 offset:34816
	ds_read_b128 v[204:207], v190 offset:36864
	ds_read_b128 v[208:211], v253 offset:36864
	ds_read_b128 v[212:215], v190 offset:38912
	ds_read_b128 v[216:219], v253 offset:38912
	global_load_lds_dwordx4 v[228:229], off
	v_lshl_add_u64 v[228:229], s[48:49], 0, v[160:161]
	s_mov_b32 m0, s62
	s_nop 0
	global_load_lds_dwordx4 v[228:229], off
	s_waitcnt vmcnt(8)
	s_waitcnt lgkmcnt(0)
	s_barrier
	s_setprio 1
	s_waitcnt lgkmcnt(0)
	v_mfma_f32_16x16x32_bf16 v[124:127], v[128:131], v[180:183], v[124:127]
	v_mfma_f32_16x16x32_bf16 v[124:127], v[132:135], v[192:195], v[124:127]
	v_mfma_f32_16x16x32_bf16 v[120:123], v[140:143], v[192:195], v[120:123]
	v_mfma_f32_16x16x32_bf16 v[120:123], v[136:139], v[180:183], v[120:123]
	v_mfma_f32_16x16x32_bf16 v[104:107], v[136:139], v[196:199], v[104:107]
	v_mfma_f32_16x16x32_bf16 v[104:107], v[140:143], v[200:203], v[104:107]
	v_mfma_f32_16x16x32_bf16 v[108:111], v[132:135], v[200:203], v[108:111]
	v_mfma_f32_16x16x32_bf16 v[108:111], v[128:131], v[196:199], v[108:111]
	v_mfma_f32_16x16x32_bf16 v[92:95], v[128:131], v[204:207], v[92:95]
	v_mfma_f32_16x16x32_bf16 v[92:95], v[132:135], v[208:211], v[92:95]
	v_mfma_f32_16x16x32_bf16 v[88:91], v[140:143], v[208:211], v[88:91]
	v_mfma_f32_16x16x32_bf16 v[88:91], v[136:139], v[204:207], v[88:91]
	v_mfma_f32_16x16x32_bf16 v[72:75], v[136:139], v[212:215], v[72:75]
	v_mfma_f32_16x16x32_bf16 v[72:75], v[140:143], v[216:219], v[72:75]
	v_mfma_f32_16x16x32_bf16 v[76:79], v[132:135], v[216:219], v[76:79]
	v_mfma_f32_16x16x32_bf16 v[76:79], v[128:131], v[212:215], v[76:79]
	s_setprio 0
	s_setprio 1
	v_mfma_f32_16x16x32_bf16 v[116:119], v[144:147], v[180:183], v[116:119]
	v_mfma_f32_16x16x32_bf16 v[116:119], v[148:151], v[192:195], v[116:119]
	v_mfma_f32_16x16x32_bf16 v[112:115], v[176:179], v[192:195], v[112:115]
	v_mfma_f32_16x16x32_bf16 v[112:115], v[172:175], v[180:183], v[112:115]
	v_mfma_f32_16x16x32_bf16 v[96:99], v[172:175], v[196:199], v[96:99]
	v_mfma_f32_16x16x32_bf16 v[96:99], v[176:179], v[200:203], v[96:99]
	v_mfma_f32_16x16x32_bf16 v[100:103], v[148:151], v[200:203], v[100:103]
	v_mfma_f32_16x16x32_bf16 v[100:103], v[144:147], v[196:199], v[100:103]
	v_mfma_f32_16x16x32_bf16 v[84:87], v[144:147], v[204:207], v[84:87]
	v_mfma_f32_16x16x32_bf16 v[84:87], v[148:151], v[208:211], v[84:87]
	v_mfma_f32_16x16x32_bf16 v[80:83], v[176:179], v[208:211], v[80:83]
	v_mfma_f32_16x16x32_bf16 v[80:83], v[172:175], v[204:207], v[80:83]
	v_mfma_f32_16x16x32_bf16 v[64:67], v[172:175], v[212:215], v[64:67]
	v_mfma_f32_16x16x32_bf16 v[64:67], v[176:179], v[216:219], v[64:67]
	v_mfma_f32_16x16x32_bf16 v[68:71], v[148:151], v[216:219], v[68:71]
	v_mfma_f32_16x16x32_bf16 v[68:71], v[144:147], v[212:215], v[68:71]
	s_setprio 0
	s_barrier
	s_add_i32 s48, s75, s58
	v_lshl_add_u64 v[220:221], v[220:221], 0, s[22:23]
	s_mov_b32 m0, s48
	ds_read_b128 v[180:183], v190 offset:49152
	v_xor_b32_e32 v253, 64, v190
	ds_read_b128 v[192:195], v253 offset:49152
	ds_read_b128 v[196:199], v190 offset:51200
	ds_read_b128 v[200:203], v253 offset:51200
	ds_read_b128 v[204:207], v190 offset:53248
	ds_read_b128 v[208:211], v253 offset:53248
	ds_read_b128 v[212:215], v190 offset:55296
	ds_read_b128 v[216:219], v253 offset:55296
	global_load_lds_dwordx4 v[220:221], off
	s_add_i32 m0, s48, 0x2000
	s_add_u32 s48, s52, 0xb0080
	v_lshl_add_u64 v[220:221], v[222:223], 0, s[22:23]
	s_addc_u32 s49, s53, 0
	s_add_i32 s52, s76, s58
	global_load_lds_dwordx4 v[220:221], off
	v_lshl_add_u64 v[220:221], s[48:49], 0, v[154:155]
	s_mov_b32 m0, s52
	s_nop 0
	global_load_lds_dwordx4 v[220:221], off
	v_lshl_add_u64 v[220:221], s[48:49], 0, v[162:163]
	s_add_i32 m0, s52, 0x2000
	s_nop 0
	global_load_lds_dwordx4 v[220:221], off
	v_lshl_add_u64 v[220:221], v[224:225], 0, s[22:23]
	s_mov_b32 m0, s3
	s_nop 0
	global_load_lds_dwordx4 v[220:221], off
	v_lshl_add_u64 v[220:221], v[226:227], 0, s[22:23]
	s_mov_b32 m0, s64
	s_nop 0
	global_load_lds_dwordx4 v[220:221], off
	s_waitcnt vmcnt(8)
	s_waitcnt lgkmcnt(0)
	s_barrier
	s_setprio 1
	s_waitcnt lgkmcnt(0)
	v_mfma_f32_16x16x32_bf16 v[60:63], v[128:131], v[180:183], v[60:63]
	v_mfma_f32_16x16x32_bf16 v[60:63], v[132:135], v[192:195], v[60:63]
	v_mfma_f32_16x16x32_bf16 v[56:59], v[140:143], v[192:195], v[56:59]
	v_mfma_f32_16x16x32_bf16 v[56:59], v[136:139], v[180:183], v[56:59]
	v_mfma_f32_16x16x32_bf16 v[40:43], v[136:139], v[196:199], v[40:43]
	v_mfma_f32_16x16x32_bf16 v[40:43], v[140:143], v[200:203], v[40:43]
	v_mfma_f32_16x16x32_bf16 v[44:47], v[132:135], v[200:203], v[44:47]
	v_mfma_f32_16x16x32_bf16 v[44:47], v[128:131], v[196:199], v[44:47]
	v_mfma_f32_16x16x32_bf16 v[28:31], v[128:131], v[204:207], v[28:31]
	v_mfma_f32_16x16x32_bf16 v[28:31], v[132:135], v[208:211], v[28:31]
	v_mfma_f32_16x16x32_bf16 v[24:27], v[140:143], v[208:211], v[24:27]
	v_mfma_f32_16x16x32_bf16 v[24:27], v[136:139], v[204:207], v[24:27]
	v_mfma_f32_16x16x32_bf16 v[8:11], v[136:139], v[212:215], v[8:11]
	v_mfma_f32_16x16x32_bf16 v[8:11], v[140:143], v[216:219], v[8:11]
	v_mfma_f32_16x16x32_bf16 v[12:15], v[132:135], v[216:219], v[12:15]
	v_mfma_f32_16x16x32_bf16 v[12:15], v[128:131], v[212:215], v[12:15]
	s_setprio 0
	s_setprio 1
	v_mfma_f32_16x16x32_bf16 v[52:55], v[144:147], v[180:183], v[52:55]
	v_mfma_f32_16x16x32_bf16 v[52:55], v[148:151], v[192:195], v[52:55]
	v_mfma_f32_16x16x32_bf16 v[48:51], v[176:179], v[192:195], v[48:51]
	v_mfma_f32_16x16x32_bf16 v[48:51], v[172:175], v[180:183], v[48:51]
	v_mfma_f32_16x16x32_bf16 v[32:35], v[172:175], v[196:199], v[32:35]
	v_mfma_f32_16x16x32_bf16 v[32:35], v[176:179], v[200:203], v[32:35]
	v_mfma_f32_16x16x32_bf16 v[36:39], v[148:151], v[200:203], v[36:39]
	v_mfma_f32_16x16x32_bf16 v[36:39], v[144:147], v[196:199], v[36:39]
	v_mfma_f32_16x16x32_bf16 v[20:23], v[144:147], v[204:207], v[20:23]
	v_mfma_f32_16x16x32_bf16 v[20:23], v[148:151], v[208:211], v[20:23]
	v_mfma_f32_16x16x32_bf16 v[16:19], v[176:179], v[208:211], v[16:19]
	v_mfma_f32_16x16x32_bf16 v[16:19], v[172:175], v[204:207], v[16:19]
	v_mfma_f32_16x16x32_bf16 v[0:3], v[172:175], v[212:215], v[0:3]
	v_mfma_f32_16x16x32_bf16 v[0:3], v[176:179], v[216:219], v[0:3]
	v_mfma_f32_16x16x32_bf16 v[4:7], v[148:151], v[216:219], v[4:7]
	v_mfma_f32_16x16x32_bf16 v[4:7], v[144:147], v[212:215], v[4:7]
	s_setprio 0
	s_barrier
	s_add_i32 s74, s74, 2
	s_add_u32 s72, s72, 0x100
	s_addc_u32 s73, s73, 0
	s_cmp_gt_u32 s74, 41
	s_mov_b64 s[48:49], s[50:51]
.LBB0_1181:
	ds_read_b128 v[128:131], v188
	v_xor_b32_e32 v253, 64, v188
	ds_read_b128 v[132:135], v253
	ds_read_b128 v[136:139], v188 offset:2048
	ds_read_b128 v[140:143], v253 offset:2048
	ds_read_b128 v[144:147], v189
	v_xor_b32_e32 v253, 64, v189
	ds_read_b128 v[148:151], v253
	ds_read_b128 v[172:175], v189 offset:2048
	ds_read_b128 v[176:179], v253 offset:2048
	s_add_u32 s50, s48, 0x100
	s_addc_u32 s51, s49, 0
	s_cmp_eq_u32 s74, 40
	s_cselect_b32 s55, s11, s51
	s_cselect_b32 s54, s10, s50
	s_cselect_b32 s53, s47, s73
	s_cselect_b32 s52, s46, s72
	v_lshl_add_u64 v[220:221], s[48:49], 0, v[166:167]
	s_add_i32 m0, s59, 0xc000
	ds_read_b128 v[180:183], v190
	v_xor_b32_e32 v253, 64, v190
	ds_read_b128 v[192:195], v253
	ds_read_b128 v[196:199], v190 offset:2048
	ds_read_b128 v[200:203], v253 offset:2048
	ds_read_b128 v[204:207], v190 offset:4096
	ds_read_b128 v[208:211], v253 offset:4096
	ds_read_b128 v[212:215], v190 offset:6144
	ds_read_b128 v[216:219], v253 offset:6144
	global_load_lds_dwordx4 v[220:221], off
	v_lshl_add_u64 v[220:221], s[48:49], 0, v[164:165]
	s_add_i32 m0, s59, 0xe000
	s_nop 0
	global_load_lds_dwordx4 v[220:221], off
	s_waitcnt vmcnt(8)
	s_waitcnt lgkmcnt(0)
	s_barrier
	s_setprio 1
	s_waitcnt lgkmcnt(0)
	v_mfma_f32_16x16x32_bf16 v[124:127], v[128:131], v[180:183], v[124:127]
	v_mfma_f32_16x16x32_bf16 v[124:127], v[132:135], v[192:195], v[124:127]
	v_mfma_f32_16x16x32_bf16 v[120:123], v[140:143], v[192:195], v[120:123]
	v_mfma_f32_16x16x32_bf16 v[120:123], v[136:139], v[180:183], v[120:123]
	v_mfma_f32_16x16x32_bf16 v[104:107], v[136:139], v[196:199], v[104:107]
	v_mfma_f32_16x16x32_bf16 v[104:107], v[140:143], v[200:203], v[104:107]
	v_mfma_f32_16x16x32_bf16 v[108:111], v[132:135], v[200:203], v[108:111]
	v_mfma_f32_16x16x32_bf16 v[108:111], v[128:131], v[196:199], v[108:111]
	v_mfma_f32_16x16x32_bf16 v[92:95], v[128:131], v[204:207], v[92:95]
	v_mfma_f32_16x16x32_bf16 v[92:95], v[132:135], v[208:211], v[92:95]
	v_mfma_f32_16x16x32_bf16 v[88:91], v[140:143], v[208:211], v[88:91]
	v_mfma_f32_16x16x32_bf16 v[88:91], v[136:139], v[204:207], v[88:91]
	v_mfma_f32_16x16x32_bf16 v[72:75], v[136:139], v[212:215], v[72:75]
	v_mfma_f32_16x16x32_bf16 v[72:75], v[140:143], v[216:219], v[72:75]
	v_mfma_f32_16x16x32_bf16 v[76:79], v[132:135], v[216:219], v[76:79]
	v_mfma_f32_16x16x32_bf16 v[76:79], v[128:131], v[212:215], v[76:79]
	s_setprio 0
	s_setprio 1
	v_mfma_f32_16x16x32_bf16 v[116:119], v[144:147], v[180:183], v[116:119]
	v_mfma_f32_16x16x32_bf16 v[116:119], v[148:151], v[192:195], v[116:119]
	v_mfma_f32_16x16x32_bf16 v[112:115], v[176:179], v[192:195], v[112:115]
	v_mfma_f32_16x16x32_bf16 v[112:115], v[172:175], v[180:183], v[112:115]
	v_mfma_f32_16x16x32_bf16 v[96:99], v[172:175], v[196:199], v[96:99]
	v_mfma_f32_16x16x32_bf16 v[96:99], v[176:179], v[200:203], v[96:99]
	v_mfma_f32_16x16x32_bf16 v[100:103], v[148:151], v[200:203], v[100:103]
	v_mfma_f32_16x16x32_bf16 v[100:103], v[144:147], v[196:199], v[100:103]
	v_mfma_f32_16x16x32_bf16 v[84:87], v[144:147], v[204:207], v[84:87]
	v_mfma_f32_16x16x32_bf16 v[84:87], v[148:151], v[208:211], v[84:87]
	v_mfma_f32_16x16x32_bf16 v[80:83], v[176:179], v[208:211], v[80:83]
	v_mfma_f32_16x16x32_bf16 v[80:83], v[172:175], v[204:207], v[80:83]
	v_mfma_f32_16x16x32_bf16 v[64:67], v[172:175], v[212:215], v[64:67]
	v_mfma_f32_16x16x32_bf16 v[64:67], v[176:179], v[216:219], v[64:67]
	v_mfma_f32_16x16x32_bf16 v[68:71], v[148:151], v[216:219], v[68:71]
	v_mfma_f32_16x16x32_bf16 v[68:71], v[144:147], v[212:215], v[68:71]
	s_setprio 0
	s_barrier
	s_add_i32 s48, s68, s58
	v_lshl_add_u64 v[220:221], s[52:53], 0, v[154:155]
	s_mov_b32 m0, s48
	ds_read_b128 v[180:183], v190 offset:16384
	v_xor_b32_e32 v253, 64, v190
	ds_read_b128 v[192:195], v253 offset:16384
	ds_read_b128 v[196:199], v190 offset:18432
	ds_read_b128 v[200:203], v253 offset:18432
	ds_read_b128 v[204:207], v190 offset:20480
	ds_read_b128 v[208:211], v253 offset:20480
	ds_read_b128 v[212:215], v190 offset:22528
	ds_read_b128 v[216:219], v253 offset:22528
	global_load_lds_dwordx4 v[220:221], off
	s_add_i32 m0, s48, 0x2000
	s_add_u32 s48, s52, 0xb0000
	v_lshl_add_u64 v[222:223], s[52:53], 0, v[162:163]
	s_addc_u32 s49, s53, 0
	s_add_i32 s75, s69, s58
	global_load_lds_dwordx4 v[222:223], off
	v_lshl_add_u64 v[224:225], s[48:49], 0, v[154:155]
	s_mov_b32 m0, s75
	v_lshl_add_u64 v[226:227], s[54:55], 0, v[160:161]
	global_load_lds_dwordx4 v[224:225], off
	v_lshl_add_u64 v[224:225], s[48:49], 0, v[162:163]
	s_add_i32 m0, s75, 0x2000
	s_nop 0
	global_load_lds_dwordx4 v[224:225], off
	v_lshl_add_u64 v[224:225], s[54:55], 0, v[152:153]
	s_mov_b32 m0, s59
	s_nop 0
	global_load_lds_dwordx4 v[224:225], off
	s_mov_b32 m0, s60
	s_nop 0
	global_load_lds_dwordx4 v[226:227], off
	s_waitcnt vmcnt(8)
	s_waitcnt lgkmcnt(0)
	s_barrier
	s_setprio 1
	s_waitcnt lgkmcnt(0)
	v_mfma_f32_16x16x32_bf16 v[60:63], v[128:131], v[180:183], v[60:63]
	v_mfma_f32_16x16x32_bf16 v[60:63], v[132:135], v[192:195], v[60:63]
	v_mfma_f32_16x16x32_bf16 v[56:59], v[140:143], v[192:195], v[56:59]
	v_mfma_f32_16x16x32_bf16 v[56:59], v[136:139], v[180:183], v[56:59]
	v_mfma_f32_16x16x32_bf16 v[40:43], v[136:139], v[196:199], v[40:43]
	v_mfma_f32_16x16x32_bf16 v[40:43], v[140:143], v[200:203], v[40:43]
	v_mfma_f32_16x16x32_bf16 v[44:47], v[132:135], v[200:203], v[44:47]
	v_mfma_f32_16x16x32_bf16 v[44:47], v[128:131], v[196:199], v[44:47]
	v_mfma_f32_16x16x32_bf16 v[28:31], v[128:131], v[204:207], v[28:31]
	v_mfma_f32_16x16x32_bf16 v[28:31], v[132:135], v[208:211], v[28:31]
	v_mfma_f32_16x16x32_bf16 v[24:27], v[140:143], v[208:211], v[24:27]
	v_mfma_f32_16x16x32_bf16 v[24:27], v[136:139], v[204:207], v[24:27]
	v_mfma_f32_16x16x32_bf16 v[8:11], v[136:139], v[212:215], v[8:11]
	v_mfma_f32_16x16x32_bf16 v[8:11], v[140:143], v[216:219], v[8:11]
	v_mfma_f32_16x16x32_bf16 v[12:15], v[132:135], v[216:219], v[12:15]
	v_mfma_f32_16x16x32_bf16 v[12:15], v[128:131], v[212:215], v[12:15]
	s_setprio 0
	s_setprio 1
	v_mfma_f32_16x16x32_bf16 v[52:55], v[144:147], v[180:183], v[52:55]
	v_mfma_f32_16x16x32_bf16 v[52:55], v[148:151], v[192:195], v[52:55]
	v_mfma_f32_16x16x32_bf16 v[48:51], v[176:179], v[192:195], v[48:51]
	v_mfma_f32_16x16x32_bf16 v[48:51], v[172:175], v[180:183], v[48:51]
	v_mfma_f32_16x16x32_bf16 v[32:35], v[172:175], v[196:199], v[32:35]
	v_mfma_f32_16x16x32_bf16 v[32:35], v[176:179], v[200:203], v[32:35]
	v_mfma_f32_16x16x32_bf16 v[36:39], v[148:151], v[200:203], v[36:39]
	v_mfma_f32_16x16x32_bf16 v[36:39], v[144:147], v[196:199], v[36:39]
	v_mfma_f32_16x16x32_bf16 v[20:23], v[144:147], v[204:207], v[20:23]
	v_mfma_f32_16x16x32_bf16 v[20:23], v[148:151], v[208:211], v[20:23]
	v_mfma_f32_16x16x32_bf16 v[16:19], v[176:179], v[208:211], v[16:19]
	v_mfma_f32_16x16x32_bf16 v[16:19], v[172:175], v[204:207], v[16:19]
	v_mfma_f32_16x16x32_bf16 v[0:3], v[172:175], v[212:215], v[0:3]
	v_mfma_f32_16x16x32_bf16 v[0:3], v[176:179], v[216:219], v[0:3]
	v_mfma_f32_16x16x32_bf16 v[4:7], v[148:151], v[216:219], v[4:7]
	v_mfma_f32_16x16x32_bf16 v[4:7], v[144:147], v[212:215], v[4:7]
	s_setprio 0
	s_barrier
	s_add_i32 s75, 0, 0x18000
	s_add_i32 s76, 0, 0x1c000
	v_add_u32_e32 v140, s75, v185
	v_add_u32_e32 v176, s76, v185
	ds_read_b128 v[128:131], v140
	v_xor_b32_e32 v253, 64, v140
	ds_read_b128 v[132:135], v253
	ds_read_b128 v[136:139], v140 offset:2048
	ds_read_b128 v[140:143], v253 offset:2048
	ds_read_b128 v[144:147], v176
	v_xor_b32_e32 v253, 64, v176
	ds_read_b128 v[148:151], v253
	ds_read_b128 v[172:175], v176 offset:2048
	ds_read_b128 v[176:179], v253 offset:2048
	s_add_u32 s48, s54, 0xb0000
	s_addc_u32 s49, s55, 0
	s_mov_b32 m0, s61
	v_lshl_add_u64 v[228:229], s[48:49], 0, v[152:153]
	ds_read_b128 v[180:183], v190 offset:32768
	v_xor_b32_e32 v253, 64, v190
	ds_read_b128 v[192:195], v253 offset:32768
	ds_read_b128 v[196:199], v190 offset:34816
	ds_read_b128 v[200:203], v253 offset:34816
	ds_read_b128 v[204:207], v190 offset:36864
	ds_read_b128 v[208:211], v253 offset:36864
	ds_read_b128 v[212:215], v190 offset:38912
	ds_read_b128 v[216:219], v253 offset:38912
	global_load_lds_dwordx4 v[228:229], off
	v_lshl_add_u64 v[228:229], s[48:49], 0, v[160:161]
	s_mov_b32 m0, s62
	s_nop 0
	global_load_lds_dwordx4 v[228:229], off
	s_waitcnt vmcnt(8)
	s_waitcnt lgkmcnt(0)
	s_barrier
	s_setprio 1
	s_waitcnt lgkmcnt(0)
	v_mfma_f32_16x16x32_bf16 v[124:127], v[128:131], v[180:183], v[124:127]
	v_mfma_f32_16x16x32_bf16 v[124:127], v[132:135], v[192:195], v[124:127]
	v_mfma_f32_16x16x32_bf16 v[120:123], v[140:143], v[192:195], v[120:123]
	v_mfma_f32_16x16x32_bf16 v[120:123], v[136:139], v[180:183], v[120:123]
	v_mfma_f32_16x16x32_bf16 v[104:107], v[136:139], v[196:199], v[104:107]
	v_mfma_f32_16x16x32_bf16 v[104:107], v[140:143], v[200:203], v[104:107]
	v_mfma_f32_16x16x32_bf16 v[108:111], v[132:135], v[200:203], v[108:111]
	v_mfma_f32_16x16x32_bf16 v[108:111], v[128:131], v[196:199], v[108:111]
	v_mfma_f32_16x16x32_bf16 v[92:95], v[128:131], v[204:207], v[92:95]
	v_mfma_f32_16x16x32_bf16 v[92:95], v[132:135], v[208:211], v[92:95]
	v_mfma_f32_16x16x32_bf16 v[88:91], v[140:143], v[208:211], v[88:91]
	v_mfma_f32_16x16x32_bf16 v[88:91], v[136:139], v[204:207], v[88:91]
	v_mfma_f32_16x16x32_bf16 v[72:75], v[136:139], v[212:215], v[72:75]
	v_mfma_f32_16x16x32_bf16 v[72:75], v[140:143], v[216:219], v[72:75]
	v_mfma_f32_16x16x32_bf16 v[76:79], v[132:135], v[216:219], v[76:79]
	v_mfma_f32_16x16x32_bf16 v[76:79], v[128:131], v[212:215], v[76:79]
	s_setprio 0
	s_setprio 1
	v_mfma_f32_16x16x32_bf16 v[116:119], v[144:147], v[180:183], v[116:119]
	v_mfma_f32_16x16x32_bf16 v[116:119], v[148:151], v[192:195], v[116:119]
	v_mfma_f32_16x16x32_bf16 v[112:115], v[176:179], v[192:195], v[112:115]
	v_mfma_f32_16x16x32_bf16 v[112:115], v[172:175], v[180:183], v[112:115]
	v_mfma_f32_16x16x32_bf16 v[96:99], v[172:175], v[196:199], v[96:99]
	v_mfma_f32_16x16x32_bf16 v[96:99], v[176:179], v[200:203], v[96:99]
	v_mfma_f32_16x16x32_bf16 v[100:103], v[148:151], v[200:203], v[100:103]
	v_mfma_f32_16x16x32_bf16 v[100:103], v[144:147], v[196:199], v[100:103]
	v_mfma_f32_16x16x32_bf16 v[84:87], v[144:147], v[204:207], v[84:87]
	v_mfma_f32_16x16x32_bf16 v[84:87], v[148:151], v[208:211], v[84:87]
	v_mfma_f32_16x16x32_bf16 v[80:83], v[176:179], v[208:211], v[80:83]
	v_mfma_f32_16x16x32_bf16 v[80:83], v[172:175], v[204:207], v[80:83]
	v_mfma_f32_16x16x32_bf16 v[64:67], v[172:175], v[212:215], v[64:67]
	v_mfma_f32_16x16x32_bf16 v[64:67], v[176:179], v[216:219], v[64:67]
	v_mfma_f32_16x16x32_bf16 v[68:71], v[148:151], v[216:219], v[68:71]
	v_mfma_f32_16x16x32_bf16 v[68:71], v[144:147], v[212:215], v[68:71]
	s_setprio 0
	s_barrier
	s_add_i32 s48, s75, s58
	v_lshl_add_u64 v[220:221], v[220:221], 0, s[22:23]
	s_mov_b32 m0, s48
	ds_read_b128 v[180:183], v190 offset:49152
	v_xor_b32_e32 v253, 64, v190
	ds_read_b128 v[192:195], v253 offset:49152
	ds_read_b128 v[196:199], v190 offset:51200
	ds_read_b128 v[200:203], v253 offset:51200
	ds_read_b128 v[204:207], v190 offset:53248
	ds_read_b128 v[208:211], v253 offset:53248
	ds_read_b128 v[212:215], v190 offset:55296
	ds_read_b128 v[216:219], v253 offset:55296
	global_load_lds_dwordx4 v[220:221], off
	s_add_i32 m0, s48, 0x2000
	s_add_u32 s48, s52, 0xb0080
	v_lshl_add_u64 v[220:221], v[222:223], 0, s[22:23]
	s_addc_u32 s49, s53, 0
	s_add_i32 s52, s76, s58
	global_load_lds_dwordx4 v[220:221], off
	v_lshl_add_u64 v[220:221], s[48:49], 0, v[154:155]
	s_mov_b32 m0, s52
	s_nop 0
	global_load_lds_dwordx4 v[220:221], off
	v_lshl_add_u64 v[220:221], s[48:49], 0, v[162:163]
	s_add_i32 m0, s52, 0x2000
	s_nop 0
	global_load_lds_dwordx4 v[220:221], off
	v_lshl_add_u64 v[220:221], v[224:225], 0, s[22:23]
	s_mov_b32 m0, s3
	s_nop 0
	global_load_lds_dwordx4 v[220:221], off
	v_lshl_add_u64 v[220:221], v[226:227], 0, s[22:23]
	s_mov_b32 m0, s64
	s_nop 0
	global_load_lds_dwordx4 v[220:221], off
	s_waitcnt vmcnt(8)
	s_waitcnt lgkmcnt(0)
	s_barrier
	s_setprio 1
	s_waitcnt lgkmcnt(0)
	v_mfma_f32_16x16x32_bf16 v[60:63], v[128:131], v[180:183], v[60:63]
	v_mfma_f32_16x16x32_bf16 v[60:63], v[132:135], v[192:195], v[60:63]
	v_mfma_f32_16x16x32_bf16 v[56:59], v[140:143], v[192:195], v[56:59]
	v_mfma_f32_16x16x32_bf16 v[56:59], v[136:139], v[180:183], v[56:59]
	v_mfma_f32_16x16x32_bf16 v[40:43], v[136:139], v[196:199], v[40:43]
	v_mfma_f32_16x16x32_bf16 v[40:43], v[140:143], v[200:203], v[40:43]
	v_mfma_f32_16x16x32_bf16 v[44:47], v[132:135], v[200:203], v[44:47]
	v_mfma_f32_16x16x32_bf16 v[44:47], v[128:131], v[196:199], v[44:47]
	v_mfma_f32_16x16x32_bf16 v[28:31], v[128:131], v[204:207], v[28:31]
	v_mfma_f32_16x16x32_bf16 v[28:31], v[132:135], v[208:211], v[28:31]
	v_mfma_f32_16x16x32_bf16 v[24:27], v[140:143], v[208:211], v[24:27]
	v_mfma_f32_16x16x32_bf16 v[24:27], v[136:139], v[204:207], v[24:27]
	v_mfma_f32_16x16x32_bf16 v[8:11], v[136:139], v[212:215], v[8:11]
	v_mfma_f32_16x16x32_bf16 v[8:11], v[140:143], v[216:219], v[8:11]
	v_mfma_f32_16x16x32_bf16 v[12:15], v[132:135], v[216:219], v[12:15]
	v_mfma_f32_16x16x32_bf16 v[12:15], v[128:131], v[212:215], v[12:15]
	s_setprio 0
	s_setprio 1
	v_mfma_f32_16x16x32_bf16 v[52:55], v[144:147], v[180:183], v[52:55]
	v_mfma_f32_16x16x32_bf16 v[52:55], v[148:151], v[192:195], v[52:55]
	v_mfma_f32_16x16x32_bf16 v[48:51], v[176:179], v[192:195], v[48:51]
	v_mfma_f32_16x16x32_bf16 v[48:51], v[172:175], v[180:183], v[48:51]
	v_mfma_f32_16x16x32_bf16 v[32:35], v[172:175], v[196:199], v[32:35]
	v_mfma_f32_16x16x32_bf16 v[32:35], v[176:179], v[200:203], v[32:35]
	v_mfma_f32_16x16x32_bf16 v[36:39], v[148:151], v[200:203], v[36:39]
	v_mfma_f32_16x16x32_bf16 v[36:39], v[144:147], v[196:199], v[36:39]
	v_mfma_f32_16x16x32_bf16 v[20:23], v[144:147], v[204:207], v[20:23]
	v_mfma_f32_16x16x32_bf16 v[20:23], v[148:151], v[208:211], v[20:23]
	v_mfma_f32_16x16x32_bf16 v[16:19], v[176:179], v[208:211], v[16:19]
	v_mfma_f32_16x16x32_bf16 v[16:19], v[172:175], v[204:207], v[16:19]
	v_mfma_f32_16x16x32_bf16 v[0:3], v[172:175], v[212:215], v[0:3]
	v_mfma_f32_16x16x32_bf16 v[0:3], v[176:179], v[216:219], v[0:3]
	v_mfma_f32_16x16x32_bf16 v[4:7], v[148:151], v[216:219], v[4:7]
	v_mfma_f32_16x16x32_bf16 v[4:7], v[144:147], v[212:215], v[4:7]
	s_setprio 0
	s_barrier
	s_add_i32 s74, s74, 2
	s_add_u32 s72, s72, 0x100
	s_addc_u32 s73, s73, 0
	s_cmp_gt_u32 s74, 41
	s_mov_b64 s[48:49], s[50:51]
	s_cbranch_scc0 .LBB0_1181
	s_and_b64 vcc, exec, s[24:25]
	s_cbranch_vccz .LBB0_1184
	s_barrier
